# C1: wave groups alternate DMA duty and epilogue stores (stores far from counted DMA waits), epilogue window 4 steps
# speedup vs baseline: 1.1618x; 1.0035x over previous
.Lc1_start:
	v_mov_b32_e32 v238, 0x200f0
	ds_read_b64 v[236:237], v238
	s_waitcnt lgkmcnt(0)
	v_readfirstlane_b32 s20, v236
	v_readfirstlane_b32 s21, v237
	s_barrier
	v_and_b32_e32 v236, 63, v0
	v_lshrrev_b32_e32 v237, 6, v0
	v_lshrrev_b32_e32 v238, 3, v236
	v_lshrrev_b32_e32 v239, 4, v236
	v_and_b32_e32 v1, 3, v237
	v_readfirstlane_b32 s0, v237
	v_add_u32_e32 v200, 0, v239
	v_xor_b32_e32 v200, v200, v236
	v_and_b32_e32 v200, 7, v200
	v_lshlrev_b32_e32 v200, 4, v200
	v_lshl_add_u32 v130, v1, 6, v238
	v_add_u32_e32 v130, 0, v130
	v_lshl_add_u32 v200, v130, 11, v200
	v_add_u32_e32 v201, 4, v239
	v_xor_b32_e32 v201, v201, v236
	v_and_b32_e32 v201, 7, v201
	v_lshlrev_b32_e32 v201, 4, v201
	v_lshl_add_u32 v130, v1, 6, v238
	v_add_u32_e32 v130, 8, v130
	v_lshl_add_u32 v201, v130, 11, v201
	v_add_u32_e32 v202, 8, v239
	v_xor_b32_e32 v202, v202, v236
	v_and_b32_e32 v202, 7, v202
	v_lshlrev_b32_e32 v202, 4, v202
	v_lshl_add_u32 v130, v1, 6, v238
	v_add_u32_e32 v130, 16, v130
	v_lshl_add_u32 v202, v130, 11, v202
	v_add_u32_e32 v203, 12, v239
	v_xor_b32_e32 v203, v203, v236
	v_and_b32_e32 v203, 7, v203
	v_lshlrev_b32_e32 v203, 4, v203
	v_lshl_add_u32 v130, v1, 6, v238
	v_add_u32_e32 v130, 24, v130
	v_lshl_add_u32 v203, v130, 11, v203
	v_add_u32_e32 v204, 0, v239
	v_xor_b32_e32 v204, v204, v236
	v_and_b32_e32 v204, 7, v204
	v_lshlrev_b32_e32 v204, 4, v204
	v_lshl_add_u32 v130, v1, 5, v238
	v_add_u32_e32 v130, 0, v130
	v_lshl_add_u32 v204, v130, 11, v204
	v_add_u32_e32 v205, 4, v239
	v_xor_b32_e32 v205, v205, v236
	v_and_b32_e32 v205, 7, v205
	v_lshlrev_b32_e32 v205, 4, v205
	v_lshl_add_u32 v130, v1, 5, v238
	v_add_u32_e32 v130, 8, v130
	v_lshl_add_u32 v205, v130, 11, v205
	v_and_b32_e32 v238, 15, v236
	v_lshrrev_b32_e32 v130, 1, v238
	v_xor_b32_e32 v130, v130, v239
	v_lshlrev_b32_e32 v130, 4, v130
	v_lshrrev_b32_e32 v236, 1, v237
	v_lshl_add_u32 v236, v236, 6, v238
	v_lshl_add_u32 v236, v236, 7, v130
	v_and_b32_e32 v1, 1, v237
	v_lshl_add_u32 v1, v1, 6, v238
	v_lshl_add_u32 v1, v1, 7, v130
	v_add_u32_e32 v218, 0x100, v236
	v_xor_b32_e32 v225, 64, v218
	v_add_u32_e32 v230, 0x8100, v1
	v_xor_b32_e32 v233, 64, v230
	v_add_u32_e32 v219, 0xc100, v236
	v_xor_b32_e32 v228, 64, v219
	v_add_u32_e32 v231, 0x14100, v1
	v_xor_b32_e32 v234, 64, v231
	v_add_u32_e32 v224, 0x18100, v236
	v_xor_b32_e32 v229, 64, v224
	v_add_u32_e32 v232, 0x20100, v1
	v_xor_b32_e32 v235, 64, v232
	s_and_b32 s1, s0, 3
	s_lshl_b32 s8, s1, 13
	s_add_u32 s8, s8, 0x100
	s_lshl_b32 s9, s1, 12
	s_add_u32 s9, s9, 0x8100
	v_lshlrev_b32_e32 v240, 13, v237
	v_lshl_add_u32 v240, v238, 7, v240
	v_lshl_add_u32 v240, v239, 5, v240
	v_add_u32_e32 v241, 0x1000, v240
	s_cmp_ge_u32 s0, 4
	s_cbranch_scc1 .Lc1_grpB0
	s_and_b32 s1, s2, 7
	s_lshr_b32 s22, s2, 3
	s_and_b32 s23, s22, 3
	s_lshl_b32 s1, s1, 2
	s_add_u32 s1, s1, s23
	s_lshr_b32 s22, s22, 2
	s_lshl_b32 s23, s1, 19
	s_add_u32 s4, s26, s23
	s_addc_u32 s5, s27, 0
	v_readlane_b32 s6, v254, 57
	v_readlane_b32 s7, v254, 58
	s_lshl_b32 s23, s22, 20
	s_add_u32 s23, s23, 0x640000
	s_nop 0
	s_add_u32 s6, s6, s23
	s_addc_u32 s7, s7, 0
	s_lshr_b32 s23, s22, 1
	s_lshl_b32 s23, s23, 5
	s_add_u32 s23, s23, s1
	s_lshl_b32 s23, s23, 3
	s_and_b32 s24, s22, 1
	s_lshl_b32 s24, s24, 2
	s_add_u32 s23, s23, s24
	s_lshl_b32 s13, s23, 16
	s_mov_b32 s12, 0xbfb8aa3b
	s_barrier
	ds_read_b128 v[136:139], v218 offset:0
	ds_read_b128 v[140:143], v218 offset:2048
	ds_read_b128 v[144:147], v218 offset:4096
	ds_read_b128 v[148:151], v218 offset:6144
	ds_read_b128 v[152:155], v230 offset:0
	ds_read_b128 v[156:159], v230 offset:2048
	ds_read_b128 v[160:163], v230 offset:4096
	ds_read_b128 v[164:167], v230 offset:6144
	s_waitcnt lgkmcnt(0)
	v_mfma_f32_16x16x32_bf16 v[2:5], v[152:155], v[136:139], 0
	ds_read_b128 v[168:171], v225 offset:0
	v_mfma_f32_16x16x32_bf16 v[6:9], v[156:159], v[136:139], 0
	ds_read_b128 v[172:175], v225 offset:2048
	v_mfma_f32_16x16x32_bf16 v[10:13], v[160:163], v[136:139], 0
	ds_read_b128 v[176:179], v225 offset:4096
	v_mfma_f32_16x16x32_bf16 v[14:17], v[164:167], v[136:139], 0
	ds_read_b128 v[180:183], v225 offset:6144
	v_mfma_f32_16x16x32_bf16 v[18:21], v[152:155], v[140:143], 0
	ds_read_b128 v[184:187], v233 offset:0
	v_mfma_f32_16x16x32_bf16 v[22:25], v[156:159], v[140:143], 0
	ds_read_b128 v[188:191], v233 offset:2048
	v_mfma_f32_16x16x32_bf16 v[26:29], v[160:163], v[140:143], 0
	ds_read_b128 v[192:195], v233 offset:4096
	v_mfma_f32_16x16x32_bf16 v[30:33], v[164:167], v[140:143], 0
	ds_read_b128 v[196:199], v233 offset:6144
	v_mfma_f32_16x16x32_bf16 v[34:37], v[152:155], v[144:147], 0
	v_mfma_f32_16x16x32_bf16 v[38:41], v[156:159], v[144:147], 0
	v_mfma_f32_16x16x32_bf16 v[42:45], v[160:163], v[144:147], 0
	v_mfma_f32_16x16x32_bf16 v[46:49], v[164:167], v[144:147], 0
	v_mfma_f32_16x16x32_bf16 v[50:53], v[152:155], v[148:151], 0
	v_mfma_f32_16x16x32_bf16 v[54:57], v[156:159], v[148:151], 0
	v_mfma_f32_16x16x32_bf16 v[58:61], v[160:163], v[148:151], 0
	v_mfma_f32_16x16x32_bf16 v[62:65], v[164:167], v[148:151], 0
	s_waitcnt lgkmcnt(0)
	s_barrier
	v_mfma_f32_16x16x32_bf16 v[2:5], v[184:187], v[168:171], v[2:5]
	ds_read_b128 v[136:139], v219 offset:0
	v_mfma_f32_16x16x32_bf16 v[6:9], v[188:191], v[168:171], v[6:9]
	ds_read_b128 v[140:143], v219 offset:2048
	v_mfma_f32_16x16x32_bf16 v[10:13], v[192:195], v[168:171], v[10:13]
	ds_read_b128 v[144:147], v219 offset:4096
	v_mfma_f32_16x16x32_bf16 v[14:17], v[196:199], v[168:171], v[14:17]
	ds_read_b128 v[148:151], v219 offset:6144
	v_mfma_f32_16x16x32_bf16 v[18:21], v[184:187], v[172:175], v[18:21]
	ds_read_b128 v[152:155], v231 offset:0
	v_mfma_f32_16x16x32_bf16 v[22:25], v[188:191], v[172:175], v[22:25]
	ds_read_b128 v[156:159], v231 offset:2048
	v_mfma_f32_16x16x32_bf16 v[26:29], v[192:195], v[172:175], v[26:29]
	ds_read_b128 v[160:163], v231 offset:4096
	v_mfma_f32_16x16x32_bf16 v[30:33], v[196:199], v[172:175], v[30:33]
	ds_read_b128 v[164:167], v231 offset:6144
	v_mfma_f32_16x16x32_bf16 v[34:37], v[184:187], v[176:179], v[34:37]
	v_mfma_f32_16x16x32_bf16 v[38:41], v[188:191], v[176:179], v[38:41]
	v_mfma_f32_16x16x32_bf16 v[42:45], v[192:195], v[176:179], v[42:45]
	v_mfma_f32_16x16x32_bf16 v[46:49], v[196:199], v[176:179], v[46:49]
	v_mfma_f32_16x16x32_bf16 v[50:53], v[184:187], v[180:183], v[50:53]
	v_mfma_f32_16x16x32_bf16 v[54:57], v[188:191], v[180:183], v[54:57]
	v_mfma_f32_16x16x32_bf16 v[58:61], v[192:195], v[180:183], v[58:61]
	v_mfma_f32_16x16x32_bf16 v[62:65], v[196:199], v[180:183], v[62:65]
	s_waitcnt lgkmcnt(0)
	v_mfma_f32_16x16x32_bf16 v[2:5], v[152:155], v[136:139], v[2:5]
	ds_read_b128 v[168:171], v228 offset:0
	v_mfma_f32_16x16x32_bf16 v[6:9], v[156:159], v[136:139], v[6:9]
	ds_read_b128 v[172:175], v228 offset:2048
	v_mfma_f32_16x16x32_bf16 v[10:13], v[160:163], v[136:139], v[10:13]
	ds_read_b128 v[176:179], v228 offset:4096
	v_mfma_f32_16x16x32_bf16 v[14:17], v[164:167], v[136:139], v[14:17]
	ds_read_b128 v[180:183], v228 offset:6144
	v_mfma_f32_16x16x32_bf16 v[18:21], v[152:155], v[140:143], v[18:21]
	ds_read_b128 v[184:187], v234 offset:0
	v_mfma_f32_16x16x32_bf16 v[22:25], v[156:159], v[140:143], v[22:25]
	ds_read_b128 v[188:191], v234 offset:2048
	v_mfma_f32_16x16x32_bf16 v[26:29], v[160:163], v[140:143], v[26:29]
	ds_read_b128 v[192:195], v234 offset:4096
	v_mfma_f32_16x16x32_bf16 v[30:33], v[164:167], v[140:143], v[30:33]
	ds_read_b128 v[196:199], v234 offset:6144
	v_mfma_f32_16x16x32_bf16 v[34:37], v[152:155], v[144:147], v[34:37]
	v_mfma_f32_16x16x32_bf16 v[38:41], v[156:159], v[144:147], v[38:41]
	v_mfma_f32_16x16x32_bf16 v[42:45], v[160:163], v[144:147], v[42:45]
	v_mfma_f32_16x16x32_bf16 v[46:49], v[164:167], v[144:147], v[46:49]
	v_mfma_f32_16x16x32_bf16 v[50:53], v[152:155], v[148:151], v[50:53]
	v_mfma_f32_16x16x32_bf16 v[54:57], v[156:159], v[148:151], v[54:57]
	v_mfma_f32_16x16x32_bf16 v[58:61], v[160:163], v[148:151], v[58:61]
	v_mfma_f32_16x16x32_bf16 v[62:65], v[164:167], v[148:151], v[62:65]
	s_waitcnt lgkmcnt(0)
	s_barrier
	v_mfma_f32_16x16x32_bf16 v[2:5], v[184:187], v[168:171], v[2:5]
	ds_read_b128 v[136:139], v224 offset:0
	v_mfma_f32_16x16x32_bf16 v[6:9], v[188:191], v[168:171], v[6:9]
	ds_read_b128 v[140:143], v224 offset:2048
	v_mfma_f32_16x16x32_bf16 v[10:13], v[192:195], v[168:171], v[10:13]
	ds_read_b128 v[144:147], v224 offset:4096
	v_mfma_f32_16x16x32_bf16 v[14:17], v[196:199], v[168:171], v[14:17]
	ds_read_b128 v[148:151], v224 offset:6144
	v_mfma_f32_16x16x32_bf16 v[18:21], v[184:187], v[172:175], v[18:21]
	ds_read_b128 v[152:155], v232 offset:0
	v_mfma_f32_16x16x32_bf16 v[22:25], v[188:191], v[172:175], v[22:25]
	ds_read_b128 v[156:159], v232 offset:2048
	v_mfma_f32_16x16x32_bf16 v[26:29], v[192:195], v[172:175], v[26:29]
	ds_read_b128 v[160:163], v232 offset:4096
	v_mfma_f32_16x16x32_bf16 v[30:33], v[196:199], v[172:175], v[30:33]
	ds_read_b128 v[164:167], v232 offset:6144
	v_mfma_f32_16x16x32_bf16 v[34:37], v[184:187], v[176:179], v[34:37]
	v_mfma_f32_16x16x32_bf16 v[38:41], v[188:191], v[176:179], v[38:41]
	v_mfma_f32_16x16x32_bf16 v[42:45], v[192:195], v[176:179], v[42:45]
	v_mfma_f32_16x16x32_bf16 v[46:49], v[196:199], v[176:179], v[46:49]
	v_mfma_f32_16x16x32_bf16 v[50:53], v[184:187], v[180:183], v[50:53]
	v_mfma_f32_16x16x32_bf16 v[54:57], v[188:191], v[180:183], v[54:57]
	v_mfma_f32_16x16x32_bf16 v[58:61], v[192:195], v[180:183], v[58:61]
	v_mfma_f32_16x16x32_bf16 v[62:65], v[196:199], v[180:183], v[62:65]
	s_waitcnt lgkmcnt(0)
	v_mfma_f32_16x16x32_bf16 v[2:5], v[152:155], v[136:139], v[2:5]
	ds_read_b128 v[168:171], v229 offset:0
	v_mfma_f32_16x16x32_bf16 v[6:9], v[156:159], v[136:139], v[6:9]
	ds_read_b128 v[172:175], v229 offset:2048
	v_mfma_f32_16x16x32_bf16 v[10:13], v[160:163], v[136:139], v[10:13]
	ds_read_b128 v[176:179], v229 offset:4096
	v_mfma_f32_16x16x32_bf16 v[14:17], v[164:167], v[136:139], v[14:17]
	ds_read_b128 v[180:183], v229 offset:6144
	v_mfma_f32_16x16x32_bf16 v[18:21], v[152:155], v[140:143], v[18:21]
	ds_read_b128 v[184:187], v235 offset:0
	v_mfma_f32_16x16x32_bf16 v[22:25], v[156:159], v[140:143], v[22:25]
	ds_read_b128 v[188:191], v235 offset:2048
	v_mfma_f32_16x16x32_bf16 v[26:29], v[160:163], v[140:143], v[26:29]
	ds_read_b128 v[192:195], v235 offset:4096
	v_mfma_f32_16x16x32_bf16 v[30:33], v[164:167], v[140:143], v[30:33]
	ds_read_b128 v[196:199], v235 offset:6144
	v_mfma_f32_16x16x32_bf16 v[34:37], v[152:155], v[144:147], v[34:37]
	v_mfma_f32_16x16x32_bf16 v[38:41], v[156:159], v[144:147], v[38:41]
	v_mfma_f32_16x16x32_bf16 v[42:45], v[160:163], v[144:147], v[42:45]
	v_mfma_f32_16x16x32_bf16 v[46:49], v[164:167], v[144:147], v[46:49]
	v_mfma_f32_16x16x32_bf16 v[50:53], v[152:155], v[148:151], v[50:53]
	v_mfma_f32_16x16x32_bf16 v[54:57], v[156:159], v[148:151], v[54:57]
	v_mfma_f32_16x16x32_bf16 v[58:61], v[160:163], v[148:151], v[58:61]
	v_mfma_f32_16x16x32_bf16 v[62:65], v[164:167], v[148:151], v[62:65]
	s_waitcnt lgkmcnt(0)
	s_barrier
	v_mfma_f32_16x16x32_bf16 v[2:5], v[184:187], v[168:171], v[2:5]
	ds_read_b128 v[136:139], v218 offset:0
	v_mfma_f32_16x16x32_bf16 v[6:9], v[188:191], v[168:171], v[6:9]
	ds_read_b128 v[140:143], v218 offset:2048
	v_mfma_f32_16x16x32_bf16 v[10:13], v[192:195], v[168:171], v[10:13]
	ds_read_b128 v[144:147], v218 offset:4096
	v_mfma_f32_16x16x32_bf16 v[14:17], v[196:199], v[168:171], v[14:17]
	ds_read_b128 v[148:151], v218 offset:6144
	v_mfma_f32_16x16x32_bf16 v[18:21], v[184:187], v[172:175], v[18:21]
	ds_read_b128 v[152:155], v230 offset:0
	v_mfma_f32_16x16x32_bf16 v[22:25], v[188:191], v[172:175], v[22:25]
	ds_read_b128 v[156:159], v230 offset:2048
	v_mfma_f32_16x16x32_bf16 v[26:29], v[192:195], v[172:175], v[26:29]
	ds_read_b128 v[160:163], v230 offset:4096
	v_mfma_f32_16x16x32_bf16 v[30:33], v[196:199], v[172:175], v[30:33]
	ds_read_b128 v[164:167], v230 offset:6144
	v_mfma_f32_16x16x32_bf16 v[34:37], v[184:187], v[176:179], v[34:37]
	v_mfma_f32_16x16x32_bf16 v[38:41], v[188:191], v[176:179], v[38:41]
	v_mfma_f32_16x16x32_bf16 v[42:45], v[192:195], v[176:179], v[42:45]
	v_mfma_f32_16x16x32_bf16 v[46:49], v[196:199], v[176:179], v[46:49]
	v_mfma_f32_16x16x32_bf16 v[50:53], v[184:187], v[180:183], v[50:53]
	v_mfma_f32_16x16x32_bf16 v[54:57], v[188:191], v[180:183], v[54:57]
	v_mfma_f32_16x16x32_bf16 v[58:61], v[192:195], v[180:183], v[58:61]
	v_mfma_f32_16x16x32_bf16 v[62:65], v[196:199], v[180:183], v[62:65]
	s_waitcnt lgkmcnt(0)
	v_mfma_f32_16x16x32_bf16 v[2:5], v[152:155], v[136:139], v[2:5]
	ds_read_b128 v[168:171], v225 offset:0
	v_mfma_f32_16x16x32_bf16 v[6:9], v[156:159], v[136:139], v[6:9]
	ds_read_b128 v[172:175], v225 offset:2048
	v_mfma_f32_16x16x32_bf16 v[10:13], v[160:163], v[136:139], v[10:13]
	ds_read_b128 v[176:179], v225 offset:4096
	v_mfma_f32_16x16x32_bf16 v[14:17], v[164:167], v[136:139], v[14:17]
	ds_read_b128 v[180:183], v225 offset:6144
	v_mfma_f32_16x16x32_bf16 v[18:21], v[152:155], v[140:143], v[18:21]
	ds_read_b128 v[184:187], v233 offset:0
	v_mfma_f32_16x16x32_bf16 v[22:25], v[156:159], v[140:143], v[22:25]
	ds_read_b128 v[188:191], v233 offset:2048
	v_mfma_f32_16x16x32_bf16 v[26:29], v[160:163], v[140:143], v[26:29]
	ds_read_b128 v[192:195], v233 offset:4096
	v_mfma_f32_16x16x32_bf16 v[30:33], v[164:167], v[140:143], v[30:33]
	ds_read_b128 v[196:199], v233 offset:6144
	v_mfma_f32_16x16x32_bf16 v[34:37], v[152:155], v[144:147], v[34:37]
	v_mfma_f32_16x16x32_bf16 v[38:41], v[156:159], v[144:147], v[38:41]
	v_mfma_f32_16x16x32_bf16 v[42:45], v[160:163], v[144:147], v[42:45]
	v_mfma_f32_16x16x32_bf16 v[46:49], v[164:167], v[144:147], v[46:49]
	v_mfma_f32_16x16x32_bf16 v[50:53], v[152:155], v[148:151], v[50:53]
	v_mfma_f32_16x16x32_bf16 v[54:57], v[156:159], v[148:151], v[54:57]
	v_mfma_f32_16x16x32_bf16 v[58:61], v[160:163], v[148:151], v[58:61]
	v_mfma_f32_16x16x32_bf16 v[62:65], v[164:167], v[148:151], v[62:65]
	s_waitcnt lgkmcnt(0)
	s_barrier
	v_mfma_f32_16x16x32_bf16 v[2:5], v[184:187], v[168:171], v[2:5]
	ds_read_b128 v[136:139], v219 offset:0
	v_mfma_f32_16x16x32_bf16 v[6:9], v[188:191], v[168:171], v[6:9]
	ds_read_b128 v[140:143], v219 offset:2048
	v_mfma_f32_16x16x32_bf16 v[10:13], v[192:195], v[168:171], v[10:13]
	ds_read_b128 v[144:147], v219 offset:4096
	v_mfma_f32_16x16x32_bf16 v[14:17], v[196:199], v[168:171], v[14:17]
	ds_read_b128 v[148:151], v219 offset:6144
	v_mfma_f32_16x16x32_bf16 v[18:21], v[184:187], v[172:175], v[18:21]
	ds_read_b128 v[152:155], v231 offset:0
	v_mfma_f32_16x16x32_bf16 v[22:25], v[188:191], v[172:175], v[22:25]
	ds_read_b128 v[156:159], v231 offset:2048
	v_mfma_f32_16x16x32_bf16 v[26:29], v[192:195], v[172:175], v[26:29]
	ds_read_b128 v[160:163], v231 offset:4096
	v_mfma_f32_16x16x32_bf16 v[30:33], v[196:199], v[172:175], v[30:33]
	ds_read_b128 v[164:167], v231 offset:6144
	v_mfma_f32_16x16x32_bf16 v[34:37], v[184:187], v[176:179], v[34:37]
	v_mfma_f32_16x16x32_bf16 v[38:41], v[188:191], v[176:179], v[38:41]
	v_mfma_f32_16x16x32_bf16 v[42:45], v[192:195], v[176:179], v[42:45]
	v_mfma_f32_16x16x32_bf16 v[46:49], v[196:199], v[176:179], v[46:49]
	v_mfma_f32_16x16x32_bf16 v[50:53], v[184:187], v[180:183], v[50:53]
	v_mfma_f32_16x16x32_bf16 v[54:57], v[188:191], v[180:183], v[54:57]
	v_mfma_f32_16x16x32_bf16 v[58:61], v[192:195], v[180:183], v[58:61]
	v_mfma_f32_16x16x32_bf16 v[62:65], v[196:199], v[180:183], v[62:65]
	s_waitcnt lgkmcnt(0)
	v_mfma_f32_16x16x32_bf16 v[2:5], v[152:155], v[136:139], v[2:5]
	ds_read_b128 v[168:171], v228 offset:0
	v_mfma_f32_16x16x32_bf16 v[6:9], v[156:159], v[136:139], v[6:9]
	ds_read_b128 v[172:175], v228 offset:2048
	v_mfma_f32_16x16x32_bf16 v[10:13], v[160:163], v[136:139], v[10:13]
	ds_read_b128 v[176:179], v228 offset:4096
	v_mfma_f32_16x16x32_bf16 v[14:17], v[164:167], v[136:139], v[14:17]
	ds_read_b128 v[180:183], v228 offset:6144
	v_mfma_f32_16x16x32_bf16 v[18:21], v[152:155], v[140:143], v[18:21]
	ds_read_b128 v[184:187], v234 offset:0
	v_mfma_f32_16x16x32_bf16 v[22:25], v[156:159], v[140:143], v[22:25]
	ds_read_b128 v[188:191], v234 offset:2048
	v_mfma_f32_16x16x32_bf16 v[26:29], v[160:163], v[140:143], v[26:29]
	ds_read_b128 v[192:195], v234 offset:4096
	v_mfma_f32_16x16x32_bf16 v[30:33], v[164:167], v[140:143], v[30:33]
	ds_read_b128 v[196:199], v234 offset:6144
	v_mfma_f32_16x16x32_bf16 v[34:37], v[152:155], v[144:147], v[34:37]
	v_mfma_f32_16x16x32_bf16 v[38:41], v[156:159], v[144:147], v[38:41]
	v_mfma_f32_16x16x32_bf16 v[42:45], v[160:163], v[144:147], v[42:45]
	v_mfma_f32_16x16x32_bf16 v[46:49], v[164:167], v[144:147], v[46:49]
	v_mfma_f32_16x16x32_bf16 v[50:53], v[152:155], v[148:151], v[50:53]
	v_mfma_f32_16x16x32_bf16 v[54:57], v[156:159], v[148:151], v[54:57]
	v_mfma_f32_16x16x32_bf16 v[58:61], v[160:163], v[148:151], v[58:61]
	v_mfma_f32_16x16x32_bf16 v[62:65], v[164:167], v[148:151], v[62:65]
	s_waitcnt lgkmcnt(0)
	s_barrier
	v_mfma_f32_16x16x32_bf16 v[2:5], v[184:187], v[168:171], v[2:5]
	ds_read_b128 v[136:139], v224 offset:0
	v_mfma_f32_16x16x32_bf16 v[6:9], v[188:191], v[168:171], v[6:9]
	ds_read_b128 v[140:143], v224 offset:2048
	v_mfma_f32_16x16x32_bf16 v[10:13], v[192:195], v[168:171], v[10:13]
	ds_read_b128 v[144:147], v224 offset:4096
	v_mfma_f32_16x16x32_bf16 v[14:17], v[196:199], v[168:171], v[14:17]
	ds_read_b128 v[148:151], v224 offset:6144
	v_mfma_f32_16x16x32_bf16 v[18:21], v[184:187], v[172:175], v[18:21]
	ds_read_b128 v[152:155], v232 offset:0
	v_mfma_f32_16x16x32_bf16 v[22:25], v[188:191], v[172:175], v[22:25]
	ds_read_b128 v[156:159], v232 offset:2048
	v_mfma_f32_16x16x32_bf16 v[26:29], v[192:195], v[172:175], v[26:29]
	ds_read_b128 v[160:163], v232 offset:4096
	v_mfma_f32_16x16x32_bf16 v[30:33], v[196:199], v[172:175], v[30:33]
	ds_read_b128 v[164:167], v232 offset:6144
	v_mfma_f32_16x16x32_bf16 v[34:37], v[184:187], v[176:179], v[34:37]
	v_mfma_f32_16x16x32_bf16 v[38:41], v[188:191], v[176:179], v[38:41]
	v_mfma_f32_16x16x32_bf16 v[42:45], v[192:195], v[176:179], v[42:45]
	v_mfma_f32_16x16x32_bf16 v[46:49], v[196:199], v[176:179], v[46:49]
	v_mfma_f32_16x16x32_bf16 v[50:53], v[184:187], v[180:183], v[50:53]
	v_mfma_f32_16x16x32_bf16 v[54:57], v[188:191], v[180:183], v[54:57]
	v_mfma_f32_16x16x32_bf16 v[58:61], v[192:195], v[180:183], v[58:61]
	v_mfma_f32_16x16x32_bf16 v[62:65], v[196:199], v[180:183], v[62:65]
	s_waitcnt lgkmcnt(0)
	v_mfma_f32_16x16x32_bf16 v[2:5], v[152:155], v[136:139], v[2:5]
	ds_read_b128 v[168:171], v229 offset:0
	v_mfma_f32_16x16x32_bf16 v[6:9], v[156:159], v[136:139], v[6:9]
	ds_read_b128 v[172:175], v229 offset:2048
	v_mfma_f32_16x16x32_bf16 v[10:13], v[160:163], v[136:139], v[10:13]
	ds_read_b128 v[176:179], v229 offset:4096
	v_mfma_f32_16x16x32_bf16 v[14:17], v[164:167], v[136:139], v[14:17]
	ds_read_b128 v[180:183], v229 offset:6144
	v_mfma_f32_16x16x32_bf16 v[18:21], v[152:155], v[140:143], v[18:21]
	ds_read_b128 v[184:187], v235 offset:0
	v_mfma_f32_16x16x32_bf16 v[22:25], v[156:159], v[140:143], v[22:25]
	ds_read_b128 v[188:191], v235 offset:2048
	v_mfma_f32_16x16x32_bf16 v[26:29], v[160:163], v[140:143], v[26:29]
	ds_read_b128 v[192:195], v235 offset:4096
	v_mfma_f32_16x16x32_bf16 v[30:33], v[164:167], v[140:143], v[30:33]
	ds_read_b128 v[196:199], v235 offset:6144
	v_mfma_f32_16x16x32_bf16 v[34:37], v[152:155], v[144:147], v[34:37]
	v_mfma_f32_16x16x32_bf16 v[38:41], v[156:159], v[144:147], v[38:41]
	v_mfma_f32_16x16x32_bf16 v[42:45], v[160:163], v[144:147], v[42:45]
	v_mfma_f32_16x16x32_bf16 v[46:49], v[164:167], v[144:147], v[46:49]
	v_mfma_f32_16x16x32_bf16 v[50:53], v[152:155], v[148:151], v[50:53]
	v_mfma_f32_16x16x32_bf16 v[54:57], v[156:159], v[148:151], v[54:57]
	v_mfma_f32_16x16x32_bf16 v[58:61], v[160:163], v[148:151], v[58:61]
	v_mfma_f32_16x16x32_bf16 v[62:65], v[164:167], v[148:151], v[62:65]
	s_waitcnt lgkmcnt(0)
	s_barrier
	v_mfma_f32_16x16x32_bf16 v[2:5], v[184:187], v[168:171], v[2:5]
	ds_read_b128 v[136:139], v218 offset:0
	v_mfma_f32_16x16x32_bf16 v[6:9], v[188:191], v[168:171], v[6:9]
	ds_read_b128 v[140:143], v218 offset:2048
	v_mfma_f32_16x16x32_bf16 v[10:13], v[192:195], v[168:171], v[10:13]
	ds_read_b128 v[144:147], v218 offset:4096
	v_mfma_f32_16x16x32_bf16 v[14:17], v[196:199], v[168:171], v[14:17]
	ds_read_b128 v[148:151], v218 offset:6144
	v_mfma_f32_16x16x32_bf16 v[18:21], v[184:187], v[172:175], v[18:21]
	ds_read_b128 v[152:155], v230 offset:0
	v_mfma_f32_16x16x32_bf16 v[22:25], v[188:191], v[172:175], v[22:25]
	ds_read_b128 v[156:159], v230 offset:2048
	v_mfma_f32_16x16x32_bf16 v[26:29], v[192:195], v[172:175], v[26:29]
	ds_read_b128 v[160:163], v230 offset:4096
	v_mfma_f32_16x16x32_bf16 v[30:33], v[196:199], v[172:175], v[30:33]
	ds_read_b128 v[164:167], v230 offset:6144
	v_mfma_f32_16x16x32_bf16 v[34:37], v[184:187], v[176:179], v[34:37]
	v_mfma_f32_16x16x32_bf16 v[38:41], v[188:191], v[176:179], v[38:41]
	v_mfma_f32_16x16x32_bf16 v[42:45], v[192:195], v[176:179], v[42:45]
	v_mfma_f32_16x16x32_bf16 v[46:49], v[196:199], v[176:179], v[46:49]
	v_mfma_f32_16x16x32_bf16 v[50:53], v[184:187], v[180:183], v[50:53]
	v_mfma_f32_16x16x32_bf16 v[54:57], v[188:191], v[180:183], v[54:57]
	v_mfma_f32_16x16x32_bf16 v[58:61], v[192:195], v[180:183], v[58:61]
	v_mfma_f32_16x16x32_bf16 v[62:65], v[196:199], v[180:183], v[62:65]
	s_waitcnt lgkmcnt(0)
	v_mfma_f32_16x16x32_bf16 v[2:5], v[152:155], v[136:139], v[2:5]
	ds_read_b128 v[168:171], v225 offset:0
	v_mfma_f32_16x16x32_bf16 v[6:9], v[156:159], v[136:139], v[6:9]
	ds_read_b128 v[172:175], v225 offset:2048
	v_mfma_f32_16x16x32_bf16 v[10:13], v[160:163], v[136:139], v[10:13]
	ds_read_b128 v[176:179], v225 offset:4096
	v_mfma_f32_16x16x32_bf16 v[14:17], v[164:167], v[136:139], v[14:17]
	ds_read_b128 v[180:183], v225 offset:6144
	v_mfma_f32_16x16x32_bf16 v[18:21], v[152:155], v[140:143], v[18:21]
	ds_read_b128 v[184:187], v233 offset:0
	v_mfma_f32_16x16x32_bf16 v[22:25], v[156:159], v[140:143], v[22:25]
	ds_read_b128 v[188:191], v233 offset:2048
	v_mfma_f32_16x16x32_bf16 v[26:29], v[160:163], v[140:143], v[26:29]
	ds_read_b128 v[192:195], v233 offset:4096
	v_mfma_f32_16x16x32_bf16 v[30:33], v[164:167], v[140:143], v[30:33]
	ds_read_b128 v[196:199], v233 offset:6144
	v_mfma_f32_16x16x32_bf16 v[34:37], v[152:155], v[144:147], v[34:37]
	v_mfma_f32_16x16x32_bf16 v[38:41], v[156:159], v[144:147], v[38:41]
	v_mfma_f32_16x16x32_bf16 v[42:45], v[160:163], v[144:147], v[42:45]
	v_mfma_f32_16x16x32_bf16 v[46:49], v[164:167], v[144:147], v[46:49]
	v_mfma_f32_16x16x32_bf16 v[50:53], v[152:155], v[148:151], v[50:53]
	v_mfma_f32_16x16x32_bf16 v[54:57], v[156:159], v[148:151], v[54:57]
	v_mfma_f32_16x16x32_bf16 v[58:61], v[160:163], v[148:151], v[58:61]
	v_mfma_f32_16x16x32_bf16 v[62:65], v[164:167], v[148:151], v[62:65]
	s_waitcnt lgkmcnt(0)
	s_barrier
	v_mfma_f32_16x16x32_bf16 v[2:5], v[184:187], v[168:171], v[2:5]
	ds_read_b128 v[136:139], v219 offset:0
	v_mfma_f32_16x16x32_bf16 v[6:9], v[188:191], v[168:171], v[6:9]
	ds_read_b128 v[140:143], v219 offset:2048
	v_mfma_f32_16x16x32_bf16 v[10:13], v[192:195], v[168:171], v[10:13]
	ds_read_b128 v[144:147], v219 offset:4096
	v_mfma_f32_16x16x32_bf16 v[14:17], v[196:199], v[168:171], v[14:17]
	ds_read_b128 v[148:151], v219 offset:6144
	v_mfma_f32_16x16x32_bf16 v[18:21], v[184:187], v[172:175], v[18:21]
	ds_read_b128 v[152:155], v231 offset:0
	v_mfma_f32_16x16x32_bf16 v[22:25], v[188:191], v[172:175], v[22:25]
	ds_read_b128 v[156:159], v231 offset:2048
	v_mfma_f32_16x16x32_bf16 v[26:29], v[192:195], v[172:175], v[26:29]
	ds_read_b128 v[160:163], v231 offset:4096
	v_mfma_f32_16x16x32_bf16 v[30:33], v[196:199], v[172:175], v[30:33]
	ds_read_b128 v[164:167], v231 offset:6144
	v_mfma_f32_16x16x32_bf16 v[34:37], v[184:187], v[176:179], v[34:37]
	v_mfma_f32_16x16x32_bf16 v[38:41], v[188:191], v[176:179], v[38:41]
	v_mfma_f32_16x16x32_bf16 v[42:45], v[192:195], v[176:179], v[42:45]
	v_mfma_f32_16x16x32_bf16 v[46:49], v[196:199], v[176:179], v[46:49]
	v_mfma_f32_16x16x32_bf16 v[50:53], v[184:187], v[180:183], v[50:53]
	v_mfma_f32_16x16x32_bf16 v[54:57], v[188:191], v[180:183], v[54:57]
	v_mfma_f32_16x16x32_bf16 v[58:61], v[192:195], v[180:183], v[58:61]
	v_mfma_f32_16x16x32_bf16 v[62:65], v[196:199], v[180:183], v[62:65]
	s_waitcnt lgkmcnt(0)
	v_mfma_f32_16x16x32_bf16 v[2:5], v[152:155], v[136:139], v[2:5]
	ds_read_b128 v[168:171], v228 offset:0
	v_mfma_f32_16x16x32_bf16 v[6:9], v[156:159], v[136:139], v[6:9]
	ds_read_b128 v[172:175], v228 offset:2048
	v_mfma_f32_16x16x32_bf16 v[10:13], v[160:163], v[136:139], v[10:13]
	ds_read_b128 v[176:179], v228 offset:4096
	v_mfma_f32_16x16x32_bf16 v[14:17], v[164:167], v[136:139], v[14:17]
	ds_read_b128 v[180:183], v228 offset:6144
	v_mfma_f32_16x16x32_bf16 v[18:21], v[152:155], v[140:143], v[18:21]
	ds_read_b128 v[184:187], v234 offset:0
	v_mfma_f32_16x16x32_bf16 v[22:25], v[156:159], v[140:143], v[22:25]
	ds_read_b128 v[188:191], v234 offset:2048
	v_mfma_f32_16x16x32_bf16 v[26:29], v[160:163], v[140:143], v[26:29]
	ds_read_b128 v[192:195], v234 offset:4096
	v_mfma_f32_16x16x32_bf16 v[30:33], v[164:167], v[140:143], v[30:33]
	ds_read_b128 v[196:199], v234 offset:6144
	v_mfma_f32_16x16x32_bf16 v[34:37], v[152:155], v[144:147], v[34:37]
	v_mfma_f32_16x16x32_bf16 v[38:41], v[156:159], v[144:147], v[38:41]
	v_mfma_f32_16x16x32_bf16 v[42:45], v[160:163], v[144:147], v[42:45]
	v_mfma_f32_16x16x32_bf16 v[46:49], v[164:167], v[144:147], v[46:49]
	v_mfma_f32_16x16x32_bf16 v[50:53], v[152:155], v[148:151], v[50:53]
	v_mfma_f32_16x16x32_bf16 v[54:57], v[156:159], v[148:151], v[54:57]
	v_mfma_f32_16x16x32_bf16 v[58:61], v[160:163], v[148:151], v[58:61]
	v_mfma_f32_16x16x32_bf16 v[62:65], v[164:167], v[148:151], v[62:65]
	s_waitcnt lgkmcnt(0)
	s_barrier
	v_mfma_f32_16x16x32_bf16 v[2:5], v[184:187], v[168:171], v[2:5]
	ds_read_b128 v[136:139], v224 offset:0
	v_mfma_f32_16x16x32_bf16 v[6:9], v[188:191], v[168:171], v[6:9]
	ds_read_b128 v[140:143], v224 offset:2048
	v_mfma_f32_16x16x32_bf16 v[10:13], v[192:195], v[168:171], v[10:13]
	ds_read_b128 v[144:147], v224 offset:4096
	v_mfma_f32_16x16x32_bf16 v[14:17], v[196:199], v[168:171], v[14:17]
	ds_read_b128 v[148:151], v224 offset:6144
	v_mfma_f32_16x16x32_bf16 v[18:21], v[184:187], v[172:175], v[18:21]
	ds_read_b128 v[152:155], v232 offset:0
	v_mfma_f32_16x16x32_bf16 v[22:25], v[188:191], v[172:175], v[22:25]
	ds_read_b128 v[156:159], v232 offset:2048
	v_mfma_f32_16x16x32_bf16 v[26:29], v[192:195], v[172:175], v[26:29]
	ds_read_b128 v[160:163], v232 offset:4096
	v_mfma_f32_16x16x32_bf16 v[30:33], v[196:199], v[172:175], v[30:33]
	ds_read_b128 v[164:167], v232 offset:6144
	v_mfma_f32_16x16x32_bf16 v[34:37], v[184:187], v[176:179], v[34:37]
	v_mfma_f32_16x16x32_bf16 v[38:41], v[188:191], v[176:179], v[38:41]
	v_mfma_f32_16x16x32_bf16 v[42:45], v[192:195], v[176:179], v[42:45]
	v_mfma_f32_16x16x32_bf16 v[46:49], v[196:199], v[176:179], v[46:49]
	v_mfma_f32_16x16x32_bf16 v[50:53], v[184:187], v[180:183], v[50:53]
	v_mfma_f32_16x16x32_bf16 v[54:57], v[188:191], v[180:183], v[54:57]
	v_mfma_f32_16x16x32_bf16 v[58:61], v[192:195], v[180:183], v[58:61]
	v_mfma_f32_16x16x32_bf16 v[62:65], v[196:199], v[180:183], v[62:65]
	s_waitcnt lgkmcnt(0)
	v_mfma_f32_16x16x32_bf16 v[2:5], v[152:155], v[136:139], v[2:5]
	ds_read_b128 v[168:171], v229 offset:0
	v_mfma_f32_16x16x32_bf16 v[6:9], v[156:159], v[136:139], v[6:9]
	ds_read_b128 v[172:175], v229 offset:2048
	v_mfma_f32_16x16x32_bf16 v[10:13], v[160:163], v[136:139], v[10:13]
	ds_read_b128 v[176:179], v229 offset:4096
	v_mfma_f32_16x16x32_bf16 v[14:17], v[164:167], v[136:139], v[14:17]
	ds_read_b128 v[180:183], v229 offset:6144
	v_mfma_f32_16x16x32_bf16 v[18:21], v[152:155], v[140:143], v[18:21]
	ds_read_b128 v[184:187], v235 offset:0
	v_mfma_f32_16x16x32_bf16 v[22:25], v[156:159], v[140:143], v[22:25]
	ds_read_b128 v[188:191], v235 offset:2048
	v_mfma_f32_16x16x32_bf16 v[26:29], v[160:163], v[140:143], v[26:29]
	ds_read_b128 v[192:195], v235 offset:4096
	v_mfma_f32_16x16x32_bf16 v[30:33], v[164:167], v[140:143], v[30:33]
	ds_read_b128 v[196:199], v235 offset:6144
	v_mfma_f32_16x16x32_bf16 v[34:37], v[152:155], v[144:147], v[34:37]
	v_mfma_f32_16x16x32_bf16 v[38:41], v[156:159], v[144:147], v[38:41]
	v_mfma_f32_16x16x32_bf16 v[42:45], v[160:163], v[144:147], v[42:45]
	v_mfma_f32_16x16x32_bf16 v[46:49], v[164:167], v[144:147], v[46:49]
	v_mfma_f32_16x16x32_bf16 v[50:53], v[152:155], v[148:151], v[50:53]
	v_mfma_f32_16x16x32_bf16 v[54:57], v[156:159], v[148:151], v[54:57]
	v_mfma_f32_16x16x32_bf16 v[58:61], v[160:163], v[148:151], v[58:61]
	v_mfma_f32_16x16x32_bf16 v[62:65], v[164:167], v[148:151], v[62:65]
	s_waitcnt lgkmcnt(0)
	s_barrier
	s_add_u32 s14, s4, 0x580
	s_addc_u32 s15, s5, 0
	v_mfma_f32_16x16x32_bf16 v[2:5], v[184:187], v[168:171], v[2:5]
	ds_read_b128 v[136:139], v218 offset:0
	s_add_u32 s22, s4, 0x10580
	s_addc_u32 s23, s5, 0
	v_mfma_f32_16x16x32_bf16 v[6:9], v[188:191], v[168:171], v[6:9]
	ds_read_b128 v[140:143], v218 offset:2048
	s_add_u32 s24, s6, 0x580
	s_addc_u32 s25, s7, 0
	v_mfma_f32_16x16x32_bf16 v[10:13], v[192:195], v[168:171], v[10:13]
	ds_read_b128 v[144:147], v218 offset:4096
	s_add_u32 s52, s6, 0x8580
	s_addc_u32 s53, s7, 0
	v_mfma_f32_16x16x32_bf16 v[14:17], v[196:199], v[168:171], v[14:17]
	ds_read_b128 v[148:151], v218 offset:6144
	s_add_u32 m0, s8, 0x18000
	v_mfma_f32_16x16x32_bf16 v[18:21], v[184:187], v[172:175], v[18:21]
	global_load_lds_dwordx4 v200, s[14:15]
	ds_read_b128 v[152:155], v230 offset:0
	s_add_u32 m0, s8, 0x18400
	v_mfma_f32_16x16x32_bf16 v[22:25], v[188:191], v[172:175], v[22:25]
	global_load_lds_dwordx4 v201, s[14:15]
	ds_read_b128 v[156:159], v230 offset:2048
	s_add_u32 m0, s8, 0x18800
	v_mfma_f32_16x16x32_bf16 v[26:29], v[192:195], v[172:175], v[26:29]
	global_load_lds_dwordx4 v202, s[14:15]
	ds_read_b128 v[160:163], v230 offset:4096
	s_add_u32 m0, s8, 0x18c00
	v_mfma_f32_16x16x32_bf16 v[30:33], v[196:199], v[172:175], v[30:33]
	global_load_lds_dwordx4 v203, s[14:15]
	ds_read_b128 v[164:167], v230 offset:6144
	s_add_u32 m0, s8, 0x19000
	v_mfma_f32_16x16x32_bf16 v[34:37], v[184:187], v[176:179], v[34:37]
	global_load_lds_dwordx4 v200, s[22:23]
	s_add_u32 m0, s8, 0x19400
	v_mfma_f32_16x16x32_bf16 v[38:41], v[188:191], v[176:179], v[38:41]
	global_load_lds_dwordx4 v201, s[22:23]
	s_add_u32 m0, s8, 0x19800
	v_mfma_f32_16x16x32_bf16 v[42:45], v[192:195], v[176:179], v[42:45]
	global_load_lds_dwordx4 v202, s[22:23]
	s_add_u32 m0, s8, 0x19c00
	v_mfma_f32_16x16x32_bf16 v[46:49], v[196:199], v[176:179], v[46:49]
	global_load_lds_dwordx4 v203, s[22:23]
	s_add_u32 m0, s9, 0x18000
	v_mfma_f32_16x16x32_bf16 v[50:53], v[184:187], v[180:183], v[50:53]
	global_load_lds_dwordx4 v204, s[24:25]
	s_add_u32 m0, s9, 0x18400
	v_mfma_f32_16x16x32_bf16 v[54:57], v[188:191], v[180:183], v[54:57]
	global_load_lds_dwordx4 v205, s[24:25]
	s_add_u32 m0, s9, 0x18800
	v_mfma_f32_16x16x32_bf16 v[58:61], v[192:195], v[180:183], v[58:61]
	global_load_lds_dwordx4 v204, s[52:53]
	s_add_u32 m0, s9, 0x18c00
	v_mfma_f32_16x16x32_bf16 v[62:65], v[196:199], v[180:183], v[62:65]
	global_load_lds_dwordx4 v205, s[52:53]
	s_waitcnt lgkmcnt(0)
	v_mfma_f32_16x16x32_bf16 v[2:5], v[152:155], v[136:139], v[2:5]
	ds_read_b128 v[168:171], v225 offset:0
	v_mfma_f32_16x16x32_bf16 v[6:9], v[156:159], v[136:139], v[6:9]
	ds_read_b128 v[172:175], v225 offset:2048
	v_mfma_f32_16x16x32_bf16 v[10:13], v[160:163], v[136:139], v[10:13]
	ds_read_b128 v[176:179], v225 offset:4096
	v_mfma_f32_16x16x32_bf16 v[14:17], v[164:167], v[136:139], v[14:17]
	ds_read_b128 v[180:183], v225 offset:6144
	v_mfma_f32_16x16x32_bf16 v[18:21], v[152:155], v[140:143], v[18:21]
	ds_read_b128 v[184:187], v233 offset:0
	v_mfma_f32_16x16x32_bf16 v[22:25], v[156:159], v[140:143], v[22:25]
	ds_read_b128 v[188:191], v233 offset:2048
	v_mfma_f32_16x16x32_bf16 v[26:29], v[160:163], v[140:143], v[26:29]
	ds_read_b128 v[192:195], v233 offset:4096
	v_mfma_f32_16x16x32_bf16 v[30:33], v[164:167], v[140:143], v[30:33]
	ds_read_b128 v[196:199], v233 offset:6144
	v_mfma_f32_16x16x32_bf16 v[34:37], v[152:155], v[144:147], v[34:37]
	v_mfma_f32_16x16x32_bf16 v[38:41], v[156:159], v[144:147], v[38:41]
	v_mfma_f32_16x16x32_bf16 v[42:45], v[160:163], v[144:147], v[42:45]
	v_mfma_f32_16x16x32_bf16 v[46:49], v[164:167], v[144:147], v[46:49]
	v_mfma_f32_16x16x32_bf16 v[50:53], v[152:155], v[148:151], v[50:53]
	v_mfma_f32_16x16x32_bf16 v[54:57], v[156:159], v[148:151], v[54:57]
	v_mfma_f32_16x16x32_bf16 v[58:61], v[160:163], v[148:151], v[58:61]
	v_mfma_f32_16x16x32_bf16 v[62:65], v[164:167], v[148:151], v[62:65]
	s_waitcnt lgkmcnt(0)
	s_barrier
	s_add_u32 s14, s4, 0x600
	s_addc_u32 s15, s5, 0
	v_mfma_f32_16x16x32_bf16 v[2:5], v[184:187], v[168:171], v[2:5]
	ds_read_b128 v[136:139], v219 offset:0
	s_add_u32 s22, s4, 0x10600
	s_addc_u32 s23, s5, 0
	v_mfma_f32_16x16x32_bf16 v[6:9], v[188:191], v[168:171], v[6:9]
	ds_read_b128 v[140:143], v219 offset:2048
	s_add_u32 s24, s6, 0x600
	s_addc_u32 s25, s7, 0
	v_mfma_f32_16x16x32_bf16 v[10:13], v[192:195], v[168:171], v[10:13]
	ds_read_b128 v[144:147], v219 offset:4096
	s_add_u32 s52, s6, 0x8600
	s_addc_u32 s53, s7, 0
	v_mfma_f32_16x16x32_bf16 v[14:17], v[196:199], v[168:171], v[14:17]
	ds_read_b128 v[148:151], v219 offset:6144
	s_mov_b32 m0, s8
	v_mfma_f32_16x16x32_bf16 v[18:21], v[184:187], v[172:175], v[18:21]
	global_load_lds_dwordx4 v200, s[14:15]
	ds_read_b128 v[152:155], v231 offset:0
	s_add_u32 m0, s8, 0x400
	v_mfma_f32_16x16x32_bf16 v[22:25], v[188:191], v[172:175], v[22:25]
	global_load_lds_dwordx4 v201, s[14:15]
	ds_read_b128 v[156:159], v231 offset:2048
	s_add_u32 m0, s8, 0x800
	v_mfma_f32_16x16x32_bf16 v[26:29], v[192:195], v[172:175], v[26:29]
	global_load_lds_dwordx4 v202, s[14:15]
	ds_read_b128 v[160:163], v231 offset:4096
	s_add_u32 m0, s8, 0xc00
	v_mfma_f32_16x16x32_bf16 v[30:33], v[196:199], v[172:175], v[30:33]
	global_load_lds_dwordx4 v203, s[14:15]
	ds_read_b128 v[164:167], v231 offset:6144
	s_add_u32 m0, s8, 0x1000
	v_mfma_f32_16x16x32_bf16 v[34:37], v[184:187], v[176:179], v[34:37]
	global_load_lds_dwordx4 v200, s[22:23]
	s_add_u32 m0, s8, 0x1400
	v_mfma_f32_16x16x32_bf16 v[38:41], v[188:191], v[176:179], v[38:41]
	global_load_lds_dwordx4 v201, s[22:23]
	s_add_u32 m0, s8, 0x1800
	v_mfma_f32_16x16x32_bf16 v[42:45], v[192:195], v[176:179], v[42:45]
	global_load_lds_dwordx4 v202, s[22:23]
	s_add_u32 m0, s8, 0x1c00
	v_mfma_f32_16x16x32_bf16 v[46:49], v[196:199], v[176:179], v[46:49]
	global_load_lds_dwordx4 v203, s[22:23]
	s_mov_b32 m0, s9
	v_mfma_f32_16x16x32_bf16 v[50:53], v[184:187], v[180:183], v[50:53]
	global_load_lds_dwordx4 v204, s[24:25]
	s_add_u32 m0, s9, 0x400
	v_mfma_f32_16x16x32_bf16 v[54:57], v[188:191], v[180:183], v[54:57]
	global_load_lds_dwordx4 v205, s[24:25]
	s_add_u32 m0, s9, 0x800
	v_mfma_f32_16x16x32_bf16 v[58:61], v[192:195], v[180:183], v[58:61]
	global_load_lds_dwordx4 v204, s[52:53]
	s_add_u32 m0, s9, 0xc00
	v_mfma_f32_16x16x32_bf16 v[62:65], v[196:199], v[180:183], v[62:65]
	global_load_lds_dwordx4 v205, s[52:53]
	s_waitcnt lgkmcnt(0)
	v_mfma_f32_16x16x32_bf16 v[2:5], v[152:155], v[136:139], v[2:5]
	ds_read_b128 v[168:171], v228 offset:0
	v_mfma_f32_16x16x32_bf16 v[6:9], v[156:159], v[136:139], v[6:9]
	ds_read_b128 v[172:175], v228 offset:2048
	v_mfma_f32_16x16x32_bf16 v[10:13], v[160:163], v[136:139], v[10:13]
	ds_read_b128 v[176:179], v228 offset:4096
	v_mfma_f32_16x16x32_bf16 v[14:17], v[164:167], v[136:139], v[14:17]
	ds_read_b128 v[180:183], v228 offset:6144
	v_mfma_f32_16x16x32_bf16 v[18:21], v[152:155], v[140:143], v[18:21]
	ds_read_b128 v[184:187], v234 offset:0
	v_mfma_f32_16x16x32_bf16 v[22:25], v[156:159], v[140:143], v[22:25]
	ds_read_b128 v[188:191], v234 offset:2048
	v_mfma_f32_16x16x32_bf16 v[26:29], v[160:163], v[140:143], v[26:29]
	ds_read_b128 v[192:195], v234 offset:4096
	v_mfma_f32_16x16x32_bf16 v[30:33], v[164:167], v[140:143], v[30:33]
	ds_read_b128 v[196:199], v234 offset:6144
	v_mfma_f32_16x16x32_bf16 v[34:37], v[152:155], v[144:147], v[34:37]
	v_mfma_f32_16x16x32_bf16 v[38:41], v[156:159], v[144:147], v[38:41]
	v_mfma_f32_16x16x32_bf16 v[42:45], v[160:163], v[144:147], v[42:45]
	v_mfma_f32_16x16x32_bf16 v[46:49], v[164:167], v[144:147], v[46:49]
	v_mfma_f32_16x16x32_bf16 v[50:53], v[152:155], v[148:151], v[50:53]
	v_mfma_f32_16x16x32_bf16 v[54:57], v[156:159], v[148:151], v[54:57]
	v_mfma_f32_16x16x32_bf16 v[58:61], v[160:163], v[148:151], v[58:61]
	v_mfma_f32_16x16x32_bf16 v[62:65], v[164:167], v[148:151], v[62:65]
	s_waitcnt vmcnt(12) lgkmcnt(0)
	s_barrier
	s_add_u32 s14, s4, 0x680
	s_addc_u32 s15, s5, 0
	v_mfma_f32_16x16x32_bf16 v[2:5], v[184:187], v[168:171], v[2:5]
	ds_read_b128 v[136:139], v224 offset:0
	s_add_u32 s22, s4, 0x10680
	s_addc_u32 s23, s5, 0
	v_mfma_f32_16x16x32_bf16 v[6:9], v[188:191], v[168:171], v[6:9]
	ds_read_b128 v[140:143], v224 offset:2048
	s_add_u32 s24, s6, 0x680
	s_addc_u32 s25, s7, 0
	v_mfma_f32_16x16x32_bf16 v[10:13], v[192:195], v[168:171], v[10:13]
	ds_read_b128 v[144:147], v224 offset:4096
	s_add_u32 s52, s6, 0x8680
	s_addc_u32 s53, s7, 0
	v_mfma_f32_16x16x32_bf16 v[14:17], v[196:199], v[168:171], v[14:17]
	ds_read_b128 v[148:151], v224 offset:6144
	s_add_u32 m0, s8, 0xc000
	v_mfma_f32_16x16x32_bf16 v[18:21], v[184:187], v[172:175], v[18:21]
	global_load_lds_dwordx4 v200, s[14:15]
	ds_read_b128 v[152:155], v232 offset:0
	s_add_u32 m0, s8, 0xc400
	v_mfma_f32_16x16x32_bf16 v[22:25], v[188:191], v[172:175], v[22:25]
	global_load_lds_dwordx4 v201, s[14:15]
	ds_read_b128 v[156:159], v232 offset:2048
	s_add_u32 m0, s8, 0xc800
	v_mfma_f32_16x16x32_bf16 v[26:29], v[192:195], v[172:175], v[26:29]
	global_load_lds_dwordx4 v202, s[14:15]
	ds_read_b128 v[160:163], v232 offset:4096
	s_add_u32 m0, s8, 0xcc00
	v_mfma_f32_16x16x32_bf16 v[30:33], v[196:199], v[172:175], v[30:33]
	global_load_lds_dwordx4 v203, s[14:15]
	ds_read_b128 v[164:167], v232 offset:6144
	s_add_u32 m0, s8, 0xd000
	v_mfma_f32_16x16x32_bf16 v[34:37], v[184:187], v[176:179], v[34:37]
	global_load_lds_dwordx4 v200, s[22:23]
	s_add_u32 m0, s8, 0xd400
	v_mfma_f32_16x16x32_bf16 v[38:41], v[188:191], v[176:179], v[38:41]
	global_load_lds_dwordx4 v201, s[22:23]
	s_add_u32 m0, s8, 0xd800
	v_mfma_f32_16x16x32_bf16 v[42:45], v[192:195], v[176:179], v[42:45]
	global_load_lds_dwordx4 v202, s[22:23]
	s_add_u32 m0, s8, 0xdc00
	v_mfma_f32_16x16x32_bf16 v[46:49], v[196:199], v[176:179], v[46:49]
	global_load_lds_dwordx4 v203, s[22:23]
	s_add_u32 m0, s9, 0xc000
	v_mfma_f32_16x16x32_bf16 v[50:53], v[184:187], v[180:183], v[50:53]
	global_load_lds_dwordx4 v204, s[24:25]
	s_add_u32 m0, s9, 0xc400
	v_mfma_f32_16x16x32_bf16 v[54:57], v[188:191], v[180:183], v[54:57]
	global_load_lds_dwordx4 v205, s[24:25]
	s_add_u32 m0, s9, 0xc800
	v_mfma_f32_16x16x32_bf16 v[58:61], v[192:195], v[180:183], v[58:61]
	global_load_lds_dwordx4 v204, s[52:53]
	s_add_u32 m0, s9, 0xcc00
	v_mfma_f32_16x16x32_bf16 v[62:65], v[196:199], v[180:183], v[62:65]
	global_load_lds_dwordx4 v205, s[52:53]
	s_waitcnt lgkmcnt(0)
	v_mfma_f32_16x16x32_bf16 v[2:5], v[152:155], v[136:139], v[2:5]
	ds_read_b128 v[168:171], v229 offset:0
	v_mfma_f32_16x16x32_bf16 v[6:9], v[156:159], v[136:139], v[6:9]
	ds_read_b128 v[172:175], v229 offset:2048
	v_mfma_f32_16x16x32_bf16 v[10:13], v[160:163], v[136:139], v[10:13]
	ds_read_b128 v[176:179], v229 offset:4096
	v_mfma_f32_16x16x32_bf16 v[14:17], v[164:167], v[136:139], v[14:17]
	ds_read_b128 v[180:183], v229 offset:6144
	v_mfma_f32_16x16x32_bf16 v[18:21], v[152:155], v[140:143], v[18:21]
	ds_read_b128 v[184:187], v235 offset:0
	v_mfma_f32_16x16x32_bf16 v[22:25], v[156:159], v[140:143], v[22:25]
	ds_read_b128 v[188:191], v235 offset:2048
	v_mfma_f32_16x16x32_bf16 v[26:29], v[160:163], v[140:143], v[26:29]
	ds_read_b128 v[192:195], v235 offset:4096
	v_mfma_f32_16x16x32_bf16 v[30:33], v[164:167], v[140:143], v[30:33]
	ds_read_b128 v[196:199], v235 offset:6144
	v_mfma_f32_16x16x32_bf16 v[34:37], v[152:155], v[144:147], v[34:37]
	v_mfma_f32_16x16x32_bf16 v[38:41], v[156:159], v[144:147], v[38:41]
	v_mfma_f32_16x16x32_bf16 v[42:45], v[160:163], v[144:147], v[42:45]
	v_mfma_f32_16x16x32_bf16 v[46:49], v[164:167], v[144:147], v[46:49]
	v_mfma_f32_16x16x32_bf16 v[50:53], v[152:155], v[148:151], v[50:53]
	v_mfma_f32_16x16x32_bf16 v[54:57], v[156:159], v[148:151], v[54:57]
	v_mfma_f32_16x16x32_bf16 v[58:61], v[160:163], v[148:151], v[58:61]
	v_mfma_f32_16x16x32_bf16 v[62:65], v[164:167], v[148:151], v[62:65]
	s_waitcnt vmcnt(12) lgkmcnt(0)
	s_barrier
	s_add_u32 s14, s4, 0x700
	s_addc_u32 s15, s5, 0
	v_mfma_f32_16x16x32_bf16 v[2:5], v[184:187], v[168:171], v[2:5]
	ds_read_b128 v[136:139], v218 offset:0
	s_add_u32 s22, s4, 0x10700
	s_addc_u32 s23, s5, 0
	v_mfma_f32_16x16x32_bf16 v[6:9], v[188:191], v[168:171], v[6:9]
	ds_read_b128 v[140:143], v218 offset:2048
	s_add_u32 s24, s6, 0x700
	s_addc_u32 s25, s7, 0
	v_mfma_f32_16x16x32_bf16 v[10:13], v[192:195], v[168:171], v[10:13]
	ds_read_b128 v[144:147], v218 offset:4096
	s_add_u32 s52, s6, 0x8700
	s_addc_u32 s53, s7, 0
	v_mfma_f32_16x16x32_bf16 v[14:17], v[196:199], v[168:171], v[14:17]
	ds_read_b128 v[148:151], v218 offset:6144
	s_add_u32 m0, s8, 0x18000
	v_mfma_f32_16x16x32_bf16 v[18:21], v[184:187], v[172:175], v[18:21]
	global_load_lds_dwordx4 v200, s[14:15]
	ds_read_b128 v[152:155], v230 offset:0
	s_add_u32 m0, s8, 0x18400
	v_mfma_f32_16x16x32_bf16 v[22:25], v[188:191], v[172:175], v[22:25]
	global_load_lds_dwordx4 v201, s[14:15]
	ds_read_b128 v[156:159], v230 offset:2048
	s_add_u32 m0, s8, 0x18800
	v_mfma_f32_16x16x32_bf16 v[26:29], v[192:195], v[172:175], v[26:29]
	global_load_lds_dwordx4 v202, s[14:15]
	ds_read_b128 v[160:163], v230 offset:4096
	s_add_u32 m0, s8, 0x18c00
	v_mfma_f32_16x16x32_bf16 v[30:33], v[196:199], v[172:175], v[30:33]
	global_load_lds_dwordx4 v203, s[14:15]
	ds_read_b128 v[164:167], v230 offset:6144
	s_add_u32 m0, s8, 0x19000
	v_mfma_f32_16x16x32_bf16 v[34:37], v[184:187], v[176:179], v[34:37]
	global_load_lds_dwordx4 v200, s[22:23]
	s_add_u32 m0, s8, 0x19400
	v_mfma_f32_16x16x32_bf16 v[38:41], v[188:191], v[176:179], v[38:41]
	global_load_lds_dwordx4 v201, s[22:23]
	s_add_u32 m0, s8, 0x19800
	v_mfma_f32_16x16x32_bf16 v[42:45], v[192:195], v[176:179], v[42:45]
	global_load_lds_dwordx4 v202, s[22:23]
	s_add_u32 m0, s8, 0x19c00
	v_mfma_f32_16x16x32_bf16 v[46:49], v[196:199], v[176:179], v[46:49]
	global_load_lds_dwordx4 v203, s[22:23]
	s_add_u32 m0, s9, 0x18000
	v_mfma_f32_16x16x32_bf16 v[50:53], v[184:187], v[180:183], v[50:53]
	global_load_lds_dwordx4 v204, s[24:25]
	s_add_u32 m0, s9, 0x18400
	v_mfma_f32_16x16x32_bf16 v[54:57], v[188:191], v[180:183], v[54:57]
	global_load_lds_dwordx4 v205, s[24:25]
	s_add_u32 m0, s9, 0x18800
	v_mfma_f32_16x16x32_bf16 v[58:61], v[192:195], v[180:183], v[58:61]
	global_load_lds_dwordx4 v204, s[52:53]
	s_add_u32 m0, s9, 0x18c00
	v_mfma_f32_16x16x32_bf16 v[62:65], v[196:199], v[180:183], v[62:65]
	global_load_lds_dwordx4 v205, s[52:53]
	s_waitcnt lgkmcnt(0)
	v_mfma_f32_16x16x32_bf16 v[2:5], v[152:155], v[136:139], v[2:5]
	ds_read_b128 v[168:171], v225 offset:0
	v_mfma_f32_16x16x32_bf16 v[6:9], v[156:159], v[136:139], v[6:9]
	ds_read_b128 v[172:175], v225 offset:2048
	v_mfma_f32_16x16x32_bf16 v[10:13], v[160:163], v[136:139], v[10:13]
	ds_read_b128 v[176:179], v225 offset:4096
	v_mfma_f32_16x16x32_bf16 v[14:17], v[164:167], v[136:139], v[14:17]
	ds_read_b128 v[180:183], v225 offset:6144
	v_mfma_f32_16x16x32_bf16 v[18:21], v[152:155], v[140:143], v[18:21]
	ds_read_b128 v[184:187], v233 offset:0
	v_mfma_f32_16x16x32_bf16 v[22:25], v[156:159], v[140:143], v[22:25]
	ds_read_b128 v[188:191], v233 offset:2048
	v_mfma_f32_16x16x32_bf16 v[26:29], v[160:163], v[140:143], v[26:29]
	ds_read_b128 v[192:195], v233 offset:4096
	v_mfma_f32_16x16x32_bf16 v[30:33], v[164:167], v[140:143], v[30:33]
	ds_read_b128 v[196:199], v233 offset:6144
	v_mfma_f32_16x16x32_bf16 v[34:37], v[152:155], v[144:147], v[34:37]
	v_mfma_f32_16x16x32_bf16 v[38:41], v[156:159], v[144:147], v[38:41]
	v_mfma_f32_16x16x32_bf16 v[42:45], v[160:163], v[144:147], v[42:45]
	v_mfma_f32_16x16x32_bf16 v[46:49], v[164:167], v[144:147], v[46:49]
	v_mfma_f32_16x16x32_bf16 v[50:53], v[152:155], v[148:151], v[50:53]
	v_mfma_f32_16x16x32_bf16 v[54:57], v[156:159], v[148:151], v[54:57]
	v_mfma_f32_16x16x32_bf16 v[58:61], v[160:163], v[148:151], v[58:61]
	v_mfma_f32_16x16x32_bf16 v[62:65], v[164:167], v[148:151], v[62:65]
	s_waitcnt vmcnt(12) lgkmcnt(0)
	s_barrier
	s_add_u32 s14, s4, 0x780
	s_addc_u32 s15, s5, 0
	v_mfma_f32_16x16x32_bf16 v[2:5], v[184:187], v[168:171], v[2:5]
	ds_read_b128 v[136:139], v219 offset:0
	s_add_u32 s22, s4, 0x10780
	s_addc_u32 s23, s5, 0
	v_mfma_f32_16x16x32_bf16 v[6:9], v[188:191], v[168:171], v[6:9]
	ds_read_b128 v[140:143], v219 offset:2048
	s_add_u32 s24, s6, 0x780
	s_addc_u32 s25, s7, 0
	v_mfma_f32_16x16x32_bf16 v[10:13], v[192:195], v[168:171], v[10:13]
	ds_read_b128 v[144:147], v219 offset:4096
	s_add_u32 s52, s6, 0x8780
	s_addc_u32 s53, s7, 0
	v_mfma_f32_16x16x32_bf16 v[14:17], v[196:199], v[168:171], v[14:17]
	ds_read_b128 v[148:151], v219 offset:6144
	s_mov_b32 m0, s8
	v_mfma_f32_16x16x32_bf16 v[18:21], v[184:187], v[172:175], v[18:21]
	global_load_lds_dwordx4 v200, s[14:15]
	ds_read_b128 v[152:155], v231 offset:0
	s_add_u32 m0, s8, 0x400
	v_mfma_f32_16x16x32_bf16 v[22:25], v[188:191], v[172:175], v[22:25]
	global_load_lds_dwordx4 v201, s[14:15]
	ds_read_b128 v[156:159], v231 offset:2048
	s_add_u32 m0, s8, 0x800
	v_mfma_f32_16x16x32_bf16 v[26:29], v[192:195], v[172:175], v[26:29]
	global_load_lds_dwordx4 v202, s[14:15]
	ds_read_b128 v[160:163], v231 offset:4096
	s_add_u32 m0, s8, 0xc00
	v_mfma_f32_16x16x32_bf16 v[30:33], v[196:199], v[172:175], v[30:33]
	global_load_lds_dwordx4 v203, s[14:15]
	ds_read_b128 v[164:167], v231 offset:6144
	s_add_u32 m0, s8, 0x1000
	v_mfma_f32_16x16x32_bf16 v[34:37], v[184:187], v[176:179], v[34:37]
	global_load_lds_dwordx4 v200, s[22:23]
	s_add_u32 m0, s8, 0x1400
	v_mfma_f32_16x16x32_bf16 v[38:41], v[188:191], v[176:179], v[38:41]
	global_load_lds_dwordx4 v201, s[22:23]
	s_add_u32 m0, s8, 0x1800
	v_mfma_f32_16x16x32_bf16 v[42:45], v[192:195], v[176:179], v[42:45]
	global_load_lds_dwordx4 v202, s[22:23]
	s_add_u32 m0, s8, 0x1c00
	v_mfma_f32_16x16x32_bf16 v[46:49], v[196:199], v[176:179], v[46:49]
	global_load_lds_dwordx4 v203, s[22:23]
	s_mov_b32 m0, s9
	v_mfma_f32_16x16x32_bf16 v[50:53], v[184:187], v[180:183], v[50:53]
	global_load_lds_dwordx4 v204, s[24:25]
	s_add_u32 m0, s9, 0x400
	v_mfma_f32_16x16x32_bf16 v[54:57], v[188:191], v[180:183], v[54:57]
	global_load_lds_dwordx4 v205, s[24:25]
	s_add_u32 m0, s9, 0x800
	v_mfma_f32_16x16x32_bf16 v[58:61], v[192:195], v[180:183], v[58:61]
	global_load_lds_dwordx4 v204, s[52:53]
	s_add_u32 m0, s9, 0xc00
	v_mfma_f32_16x16x32_bf16 v[62:65], v[196:199], v[180:183], v[62:65]
	global_load_lds_dwordx4 v205, s[52:53]
	s_waitcnt lgkmcnt(0)
	v_mfma_f32_16x16x32_bf16 v[2:5], v[152:155], v[136:139], v[2:5]
	ds_read_b128 v[168:171], v228 offset:0
	v_mfma_f32_16x16x32_bf16 v[6:9], v[156:159], v[136:139], v[6:9]
	ds_read_b128 v[172:175], v228 offset:2048
	v_mfma_f32_16x16x32_bf16 v[10:13], v[160:163], v[136:139], v[10:13]
	ds_read_b128 v[176:179], v228 offset:4096
	v_mfma_f32_16x16x32_bf16 v[14:17], v[164:167], v[136:139], v[14:17]
	ds_read_b128 v[180:183], v228 offset:6144
	v_mfma_f32_16x16x32_bf16 v[18:21], v[152:155], v[140:143], v[18:21]
	ds_read_b128 v[184:187], v234 offset:0
	v_mfma_f32_16x16x32_bf16 v[22:25], v[156:159], v[140:143], v[22:25]
	ds_read_b128 v[188:191], v234 offset:2048
	v_mfma_f32_16x16x32_bf16 v[26:29], v[160:163], v[140:143], v[26:29]
	ds_read_b128 v[192:195], v234 offset:4096
	v_mfma_f32_16x16x32_bf16 v[30:33], v[164:167], v[140:143], v[30:33]
	ds_read_b128 v[196:199], v234 offset:6144
	v_mfma_f32_16x16x32_bf16 v[34:37], v[152:155], v[144:147], v[34:37]
	v_mfma_f32_16x16x32_bf16 v[38:41], v[156:159], v[144:147], v[38:41]
	v_mfma_f32_16x16x32_bf16 v[42:45], v[160:163], v[144:147], v[42:45]
	v_mfma_f32_16x16x32_bf16 v[46:49], v[164:167], v[144:147], v[46:49]
	v_mfma_f32_16x16x32_bf16 v[50:53], v[152:155], v[148:151], v[50:53]
	v_mfma_f32_16x16x32_bf16 v[54:57], v[156:159], v[148:151], v[54:57]
	v_mfma_f32_16x16x32_bf16 v[58:61], v[160:163], v[148:151], v[58:61]
	v_mfma_f32_16x16x32_bf16 v[62:65], v[164:167], v[148:151], v[62:65]
	s_waitcnt vmcnt(12) lgkmcnt(0)
	s_barrier
	s_add_u32 s14, s4, 0x0
	s_addc_u32 s15, s5, 0
	v_mfma_f32_16x16x32_bf16 v[2:5], v[184:187], v[168:171], v[2:5]
	ds_read_b128 v[136:139], v224 offset:0
	s_add_u32 s22, s4, 0x10000
	s_addc_u32 s23, s5, 0
	v_mfma_f32_16x16x32_bf16 v[6:9], v[188:191], v[168:171], v[6:9]
	ds_read_b128 v[140:143], v224 offset:2048
	s_add_u32 s24, s6, 0x40000
	s_addc_u32 s25, s7, 0
	v_mfma_f32_16x16x32_bf16 v[10:13], v[192:195], v[168:171], v[10:13]
	ds_read_b128 v[144:147], v224 offset:4096
	s_add_u32 s52, s6, 0x48000
	s_addc_u32 s53, s7, 0
	v_mfma_f32_16x16x32_bf16 v[14:17], v[196:199], v[168:171], v[14:17]
	ds_read_b128 v[148:151], v224 offset:6144
	s_add_u32 m0, s8, 0xc000
	v_mfma_f32_16x16x32_bf16 v[18:21], v[184:187], v[172:175], v[18:21]
	global_load_lds_dwordx4 v200, s[14:15]
	ds_read_b128 v[152:155], v232 offset:0
	s_add_u32 m0, s8, 0xc400
	v_mfma_f32_16x16x32_bf16 v[22:25], v[188:191], v[172:175], v[22:25]
	global_load_lds_dwordx4 v201, s[14:15]
	ds_read_b128 v[156:159], v232 offset:2048
	s_add_u32 m0, s8, 0xc800
	v_mfma_f32_16x16x32_bf16 v[26:29], v[192:195], v[172:175], v[26:29]
	global_load_lds_dwordx4 v202, s[14:15]
	ds_read_b128 v[160:163], v232 offset:4096
	s_add_u32 m0, s8, 0xcc00
	v_mfma_f32_16x16x32_bf16 v[30:33], v[196:199], v[172:175], v[30:33]
	global_load_lds_dwordx4 v203, s[14:15]
	ds_read_b128 v[164:167], v232 offset:6144
	s_add_u32 m0, s8, 0xd000
	v_mfma_f32_16x16x32_bf16 v[34:37], v[184:187], v[176:179], v[34:37]
	global_load_lds_dwordx4 v200, s[22:23]
	s_add_u32 m0, s8, 0xd400
	v_mfma_f32_16x16x32_bf16 v[38:41], v[188:191], v[176:179], v[38:41]
	global_load_lds_dwordx4 v201, s[22:23]
	s_add_u32 m0, s8, 0xd800
	v_mfma_f32_16x16x32_bf16 v[42:45], v[192:195], v[176:179], v[42:45]
	global_load_lds_dwordx4 v202, s[22:23]
	s_add_u32 m0, s8, 0xdc00
	v_mfma_f32_16x16x32_bf16 v[46:49], v[196:199], v[176:179], v[46:49]
	global_load_lds_dwordx4 v203, s[22:23]
	s_add_u32 m0, s9, 0xc000
	v_mfma_f32_16x16x32_bf16 v[50:53], v[184:187], v[180:183], v[50:53]
	global_load_lds_dwordx4 v204, s[24:25]
	s_add_u32 m0, s9, 0xc400
	v_mfma_f32_16x16x32_bf16 v[54:57], v[188:191], v[180:183], v[54:57]
	global_load_lds_dwordx4 v205, s[24:25]
	s_add_u32 m0, s9, 0xc800
	v_mfma_f32_16x16x32_bf16 v[58:61], v[192:195], v[180:183], v[58:61]
	global_load_lds_dwordx4 v204, s[52:53]
	s_add_u32 m0, s9, 0xcc00
	v_mfma_f32_16x16x32_bf16 v[62:65], v[196:199], v[180:183], v[62:65]
	global_load_lds_dwordx4 v205, s[52:53]
	s_waitcnt lgkmcnt(0)
	v_mfma_f32_16x16x32_bf16 v[2:5], v[152:155], v[136:139], v[2:5]
	ds_read_b128 v[168:171], v229 offset:0
	v_mfma_f32_16x16x32_bf16 v[6:9], v[156:159], v[136:139], v[6:9]
	ds_read_b128 v[172:175], v229 offset:2048
	v_mfma_f32_16x16x32_bf16 v[10:13], v[160:163], v[136:139], v[10:13]
	ds_read_b128 v[176:179], v229 offset:4096
	v_mfma_f32_16x16x32_bf16 v[14:17], v[164:167], v[136:139], v[14:17]
	ds_read_b128 v[180:183], v229 offset:6144
	v_mfma_f32_16x16x32_bf16 v[18:21], v[152:155], v[140:143], v[18:21]
	ds_read_b128 v[184:187], v235 offset:0
	v_mfma_f32_16x16x32_bf16 v[22:25], v[156:159], v[140:143], v[22:25]
	ds_read_b128 v[188:191], v235 offset:2048
	v_mfma_f32_16x16x32_bf16 v[26:29], v[160:163], v[140:143], v[26:29]
	ds_read_b128 v[192:195], v235 offset:4096
	v_mfma_f32_16x16x32_bf16 v[30:33], v[164:167], v[140:143], v[30:33]
	ds_read_b128 v[196:199], v235 offset:6144
	v_mfma_f32_16x16x32_bf16 v[34:37], v[152:155], v[144:147], v[34:37]
	v_mfma_f32_16x16x32_bf16 v[38:41], v[156:159], v[144:147], v[38:41]
	v_mfma_f32_16x16x32_bf16 v[42:45], v[160:163], v[144:147], v[42:45]
	v_mfma_f32_16x16x32_bf16 v[46:49], v[164:167], v[144:147], v[46:49]
	v_mfma_f32_16x16x32_bf16 v[50:53], v[152:155], v[148:151], v[50:53]
	v_mfma_f32_16x16x32_bf16 v[54:57], v[156:159], v[148:151], v[54:57]
	v_mfma_f32_16x16x32_bf16 v[58:61], v[160:163], v[148:151], v[58:61]
	v_mfma_f32_16x16x32_bf16 v[62:65], v[164:167], v[148:151], v[62:65]
	s_waitcnt vmcnt(12) lgkmcnt(0)
	s_barrier
	s_add_u32 s14, s4, 0x80
	s_addc_u32 s15, s5, 0
	v_mfma_f32_16x16x32_bf16 v[2:5], v[184:187], v[168:171], v[2:5]
	ds_read_b128 v[136:139], v218 offset:0
	s_add_u32 s22, s4, 0x10080
	s_addc_u32 s23, s5, 0
	v_mfma_f32_16x16x32_bf16 v[6:9], v[188:191], v[168:171], v[6:9]
	ds_read_b128 v[140:143], v218 offset:2048
	s_add_u32 s24, s6, 0x40080
	s_addc_u32 s25, s7, 0
	v_mfma_f32_16x16x32_bf16 v[10:13], v[192:195], v[168:171], v[10:13]
	ds_read_b128 v[144:147], v218 offset:4096
	s_add_u32 s52, s6, 0x48080
	s_addc_u32 s53, s7, 0
	v_mfma_f32_16x16x32_bf16 v[14:17], v[196:199], v[168:171], v[14:17]
	ds_read_b128 v[148:151], v218 offset:6144
	s_add_u32 m0, s8, 0x18000
	v_mfma_f32_16x16x32_bf16 v[18:21], v[184:187], v[172:175], v[18:21]
	global_load_lds_dwordx4 v200, s[14:15]
	ds_read_b128 v[152:155], v230 offset:0
	s_add_u32 m0, s8, 0x18400
	v_mfma_f32_16x16x32_bf16 v[22:25], v[188:191], v[172:175], v[22:25]
	global_load_lds_dwordx4 v201, s[14:15]
	ds_read_b128 v[156:159], v230 offset:2048
	s_add_u32 m0, s8, 0x18800
	v_mfma_f32_16x16x32_bf16 v[26:29], v[192:195], v[172:175], v[26:29]
	global_load_lds_dwordx4 v202, s[14:15]
	ds_read_b128 v[160:163], v230 offset:4096
	s_add_u32 m0, s8, 0x18c00
	v_mfma_f32_16x16x32_bf16 v[30:33], v[196:199], v[172:175], v[30:33]
	global_load_lds_dwordx4 v203, s[14:15]
	ds_read_b128 v[164:167], v230 offset:6144
	s_add_u32 m0, s8, 0x19000
	v_mfma_f32_16x16x32_bf16 v[34:37], v[184:187], v[176:179], v[34:37]
	global_load_lds_dwordx4 v200, s[22:23]
	s_add_u32 m0, s8, 0x19400
	v_mfma_f32_16x16x32_bf16 v[38:41], v[188:191], v[176:179], v[38:41]
	global_load_lds_dwordx4 v201, s[22:23]
	s_add_u32 m0, s8, 0x19800
	v_mfma_f32_16x16x32_bf16 v[42:45], v[192:195], v[176:179], v[42:45]
	global_load_lds_dwordx4 v202, s[22:23]
	s_add_u32 m0, s8, 0x19c00
	v_mfma_f32_16x16x32_bf16 v[46:49], v[196:199], v[176:179], v[46:49]
	global_load_lds_dwordx4 v203, s[22:23]
	s_add_u32 m0, s9, 0x18000
	v_mfma_f32_16x16x32_bf16 v[50:53], v[184:187], v[180:183], v[50:53]
	global_load_lds_dwordx4 v204, s[24:25]
	s_add_u32 m0, s9, 0x18400
	v_mfma_f32_16x16x32_bf16 v[54:57], v[188:191], v[180:183], v[54:57]
	global_load_lds_dwordx4 v205, s[24:25]
	s_add_u32 m0, s9, 0x18800
	v_mfma_f32_16x16x32_bf16 v[58:61], v[192:195], v[180:183], v[58:61]
	global_load_lds_dwordx4 v204, s[52:53]
	s_add_u32 m0, s9, 0x18c00
	v_mfma_f32_16x16x32_bf16 v[62:65], v[196:199], v[180:183], v[62:65]
	global_load_lds_dwordx4 v205, s[52:53]
	s_waitcnt lgkmcnt(0)
	v_mfma_f32_16x16x32_bf16 v[2:5], v[152:155], v[136:139], v[2:5]
	ds_read_b128 v[168:171], v225 offset:0
	v_mfma_f32_16x16x32_bf16 v[6:9], v[156:159], v[136:139], v[6:9]
	ds_read_b128 v[172:175], v225 offset:2048
	v_mfma_f32_16x16x32_bf16 v[10:13], v[160:163], v[136:139], v[10:13]
	ds_read_b128 v[176:179], v225 offset:4096
	v_mfma_f32_16x16x32_bf16 v[14:17], v[164:167], v[136:139], v[14:17]
	ds_read_b128 v[180:183], v225 offset:6144
	v_mfma_f32_16x16x32_bf16 v[18:21], v[152:155], v[140:143], v[18:21]
	ds_read_b128 v[184:187], v233 offset:0
	v_mfma_f32_16x16x32_bf16 v[22:25], v[156:159], v[140:143], v[22:25]
	ds_read_b128 v[188:191], v233 offset:2048
	v_mfma_f32_16x16x32_bf16 v[26:29], v[160:163], v[140:143], v[26:29]
	ds_read_b128 v[192:195], v233 offset:4096
	v_mfma_f32_16x16x32_bf16 v[30:33], v[164:167], v[140:143], v[30:33]
	ds_read_b128 v[196:199], v233 offset:6144
	v_mfma_f32_16x16x32_bf16 v[34:37], v[152:155], v[144:147], v[34:37]
	v_mfma_f32_16x16x32_bf16 v[38:41], v[156:159], v[144:147], v[38:41]
	v_mfma_f32_16x16x32_bf16 v[42:45], v[160:163], v[144:147], v[42:45]
	v_mfma_f32_16x16x32_bf16 v[46:49], v[164:167], v[144:147], v[46:49]
	v_mfma_f32_16x16x32_bf16 v[50:53], v[152:155], v[148:151], v[50:53]
	v_mfma_f32_16x16x32_bf16 v[54:57], v[156:159], v[148:151], v[54:57]
	v_mfma_f32_16x16x32_bf16 v[58:61], v[160:163], v[148:151], v[58:61]
	v_mfma_f32_16x16x32_bf16 v[62:65], v[164:167], v[148:151], v[62:65]
	s_waitcnt vmcnt(12) lgkmcnt(0)
	s_barrier
	s_add_u32 s14, s4, 0x100
	s_addc_u32 s15, s5, 0
	v_mfma_f32_16x16x32_bf16 v[2:5], v[184:187], v[168:171], v[2:5]
	ds_read_b128 v[136:139], v219 offset:0
	s_add_u32 s22, s4, 0x10100
	s_addc_u32 s23, s5, 0
	v_mfma_f32_16x16x32_bf16 v[6:9], v[188:191], v[168:171], v[6:9]
	ds_read_b128 v[140:143], v219 offset:2048
	s_add_u32 s24, s6, 0x40100
	s_addc_u32 s25, s7, 0
	v_mfma_f32_16x16x32_bf16 v[10:13], v[192:195], v[168:171], v[10:13]
	ds_read_b128 v[144:147], v219 offset:4096
	s_add_u32 s52, s6, 0x48100
	s_addc_u32 s53, s7, 0
	v_mfma_f32_16x16x32_bf16 v[14:17], v[196:199], v[168:171], v[14:17]
	ds_read_b128 v[148:151], v219 offset:6144
	s_mov_b32 m0, s8
	v_mfma_f32_16x16x32_bf16 v[18:21], v[184:187], v[172:175], v[18:21]
	global_load_lds_dwordx4 v200, s[14:15]
	ds_read_b128 v[152:155], v231 offset:0
	s_add_u32 m0, s8, 0x400
	v_mfma_f32_16x16x32_bf16 v[22:25], v[188:191], v[172:175], v[22:25]
	global_load_lds_dwordx4 v201, s[14:15]
	ds_read_b128 v[156:159], v231 offset:2048
	s_add_u32 m0, s8, 0x800
	v_mfma_f32_16x16x32_bf16 v[26:29], v[192:195], v[172:175], v[26:29]
	global_load_lds_dwordx4 v202, s[14:15]
	ds_read_b128 v[160:163], v231 offset:4096
	s_add_u32 m0, s8, 0xc00
	v_mfma_f32_16x16x32_bf16 v[30:33], v[196:199], v[172:175], v[30:33]
	global_load_lds_dwordx4 v203, s[14:15]
	ds_read_b128 v[164:167], v231 offset:6144
	s_add_u32 m0, s8, 0x1000
	v_mfma_f32_16x16x32_bf16 v[34:37], v[184:187], v[176:179], v[34:37]
	global_load_lds_dwordx4 v200, s[22:23]
	s_add_u32 m0, s8, 0x1400
	v_mfma_f32_16x16x32_bf16 v[38:41], v[188:191], v[176:179], v[38:41]
	global_load_lds_dwordx4 v201, s[22:23]
	s_add_u32 m0, s8, 0x1800
	v_mfma_f32_16x16x32_bf16 v[42:45], v[192:195], v[176:179], v[42:45]
	global_load_lds_dwordx4 v202, s[22:23]
	s_add_u32 m0, s8, 0x1c00
	v_mfma_f32_16x16x32_bf16 v[46:49], v[196:199], v[176:179], v[46:49]
	global_load_lds_dwordx4 v203, s[22:23]
	s_mov_b32 m0, s9
	v_mfma_f32_16x16x32_bf16 v[50:53], v[184:187], v[180:183], v[50:53]
	global_load_lds_dwordx4 v204, s[24:25]
	s_add_u32 m0, s9, 0x400
	v_mfma_f32_16x16x32_bf16 v[54:57], v[188:191], v[180:183], v[54:57]
	global_load_lds_dwordx4 v205, s[24:25]
	s_add_u32 m0, s9, 0x800
	v_mfma_f32_16x16x32_bf16 v[58:61], v[192:195], v[180:183], v[58:61]
	global_load_lds_dwordx4 v204, s[52:53]
	s_add_u32 m0, s9, 0xc00
	v_mfma_f32_16x16x32_bf16 v[62:65], v[196:199], v[180:183], v[62:65]
	global_load_lds_dwordx4 v205, s[52:53]
	s_waitcnt lgkmcnt(0)
	v_mfma_f32_16x16x32_bf16 v[66:69], v[152:155], v[136:139], 0
	ds_read_b128 v[168:171], v228 offset:0
	s_add_u32 s10, s28, s13
	s_addc_u32 s11, s29, 0
	s_add_u32 s13, s13, 0x10000
	v_mfma_f32_16x16x32_bf16 v[70:73], v[156:159], v[136:139], 0
	ds_read_b128 v[172:175], v228 offset:2048
	v_mul_f32_e32 v2, s12, v2
	v_mul_f32_e32 v3, s12, v3
	v_mfma_f32_16x16x32_bf16 v[74:77], v[160:163], v[136:139], 0
	ds_read_b128 v[176:179], v228 offset:4096
	v_mul_f32_e32 v4, s12, v4
	v_mul_f32_e32 v5, s12, v5
	v_mul_f32_e32 v6, s12, v6
	v_mfma_f32_16x16x32_bf16 v[78:81], v[164:167], v[136:139], 0
	ds_read_b128 v[180:183], v228 offset:6144
	v_mul_f32_e32 v7, s12, v7
	v_mul_f32_e32 v8, s12, v8
	v_mfma_f32_16x16x32_bf16 v[82:85], v[152:155], v[140:143], 0
	ds_read_b128 v[184:187], v234 offset:0
	v_mul_f32_e32 v9, s12, v9
	v_exp_f32_e32 v2, v2
	v_mfma_f32_16x16x32_bf16 v[86:89], v[156:159], v[140:143], 0
	ds_read_b128 v[188:191], v234 offset:2048
	v_exp_f32_e32 v3, v3
	v_exp_f32_e32 v4, v4
	v_exp_f32_e32 v5, v5
	v_mfma_f32_16x16x32_bf16 v[90:93], v[160:163], v[140:143], 0
	ds_read_b128 v[192:195], v234 offset:4096
	v_exp_f32_e32 v6, v6
	v_exp_f32_e32 v7, v7
	v_mfma_f32_16x16x32_bf16 v[94:97], v[164:167], v[140:143], 0
	ds_read_b128 v[196:199], v234 offset:6144
	v_exp_f32_e32 v8, v8
	v_exp_f32_e32 v9, v9
	v_add_f32_e32 v2, 1.0, v2
	v_mfma_f32_16x16x32_bf16 v[98:101], v[152:155], v[144:147], 0
	v_add_f32_e32 v3, 1.0, v3
	v_add_f32_e32 v4, 1.0, v4
	v_mfma_f32_16x16x32_bf16 v[102:105], v[156:159], v[144:147], 0
	v_add_f32_e32 v5, 1.0, v5
	v_add_f32_e32 v6, 1.0, v6
	v_mfma_f32_16x16x32_bf16 v[106:109], v[160:163], v[144:147], 0
	v_add_f32_e32 v7, 1.0, v7
	v_add_f32_e32 v8, 1.0, v8
	v_add_f32_e32 v9, 1.0, v9
	v_mfma_f32_16x16x32_bf16 v[110:113], v[164:167], v[144:147], 0
	v_rcp_f32_e32 v2, v2
	v_rcp_f32_e32 v3, v3
	v_mfma_f32_16x16x32_bf16 v[114:117], v[152:155], v[148:151], 0
	v_rcp_f32_e32 v4, v4
	v_rcp_f32_e32 v5, v5
	v_mfma_f32_16x16x32_bf16 v[118:121], v[156:159], v[148:151], 0
	v_rcp_f32_e32 v6, v6
	v_rcp_f32_e32 v7, v7
	v_rcp_f32_e32 v8, v8
	v_mfma_f32_16x16x32_bf16 v[122:125], v[160:163], v[148:151], 0
	v_rcp_f32_e32 v9, v9
	v_cvt_pk_bf16_f32 v2, v2, v3
	v_mfma_f32_16x16x32_bf16 v[126:129], v[164:167], v[148:151], 0
	v_cvt_pk_bf16_f32 v3, v4, v5
	v_cvt_pk_bf16_f32 v4, v6, v7
	v_cvt_pk_bf16_f32 v5, v8, v9
	s_waitcnt vmcnt(12) lgkmcnt(0)
	s_barrier
	v_mfma_f32_16x16x32_bf16 v[66:69], v[184:187], v[168:171], v[66:69]
	ds_read_b128 v[136:139], v224 offset:0
	global_store_dwordx4 v240, v[2:5], s[10:11] offset:0
	v_mul_f32_e32 v10, s12, v10
	v_mfma_f32_16x16x32_bf16 v[70:73], v[188:191], v[168:171], v[70:73]
	ds_read_b128 v[140:143], v224 offset:2048
	v_mul_f32_e32 v11, s12, v11
	v_mul_f32_e32 v12, s12, v12
	v_mfma_f32_16x16x32_bf16 v[74:77], v[192:195], v[168:171], v[74:77]
	ds_read_b128 v[144:147], v224 offset:4096
	v_mul_f32_e32 v13, s12, v13
	v_mul_f32_e32 v14, s12, v14
	v_mfma_f32_16x16x32_bf16 v[78:81], v[196:199], v[168:171], v[78:81]
	ds_read_b128 v[148:151], v224 offset:6144
	v_mul_f32_e32 v15, s12, v15
	v_mul_f32_e32 v16, s12, v16
	v_mul_f32_e32 v17, s12, v17
	v_mfma_f32_16x16x32_bf16 v[82:85], v[184:187], v[172:175], v[82:85]
	ds_read_b128 v[152:155], v232 offset:0
	v_exp_f32_e32 v10, v10
	v_exp_f32_e32 v11, v11
	v_mfma_f32_16x16x32_bf16 v[86:89], v[188:191], v[172:175], v[86:89]
	ds_read_b128 v[156:159], v232 offset:2048
	v_exp_f32_e32 v12, v12
	v_exp_f32_e32 v13, v13
	v_mfma_f32_16x16x32_bf16 v[90:93], v[192:195], v[172:175], v[90:93]
	ds_read_b128 v[160:163], v232 offset:4096
	v_exp_f32_e32 v14, v14
	v_exp_f32_e32 v15, v15
	v_exp_f32_e32 v16, v16
	v_mfma_f32_16x16x32_bf16 v[94:97], v[196:199], v[172:175], v[94:97]
	ds_read_b128 v[164:167], v232 offset:6144
	v_exp_f32_e32 v17, v17
	v_add_f32_e32 v10, 1.0, v10
	v_mfma_f32_16x16x32_bf16 v[98:101], v[184:187], v[176:179], v[98:101]
	v_add_f32_e32 v11, 1.0, v11
	v_add_f32_e32 v12, 1.0, v12
	v_mfma_f32_16x16x32_bf16 v[102:105], v[188:191], v[176:179], v[102:105]
	v_add_f32_e32 v13, 1.0, v13
	v_add_f32_e32 v14, 1.0, v14
	v_add_f32_e32 v15, 1.0, v15
	v_mfma_f32_16x16x32_bf16 v[106:109], v[192:195], v[176:179], v[106:109]
	v_add_f32_e32 v16, 1.0, v16
	v_add_f32_e32 v17, 1.0, v17
	v_mfma_f32_16x16x32_bf16 v[110:113], v[196:199], v[176:179], v[110:113]
	v_rcp_f32_e32 v10, v10
	v_rcp_f32_e32 v11, v11
	v_mfma_f32_16x16x32_bf16 v[114:117], v[184:187], v[180:183], v[114:117]
	v_rcp_f32_e32 v12, v12
	v_rcp_f32_e32 v13, v13
	v_rcp_f32_e32 v14, v14
	v_mfma_f32_16x16x32_bf16 v[118:121], v[188:191], v[180:183], v[118:121]
	v_rcp_f32_e32 v15, v15
	v_rcp_f32_e32 v16, v16
	v_mfma_f32_16x16x32_bf16 v[122:125], v[192:195], v[180:183], v[122:125]
	v_rcp_f32_e32 v17, v17
	v_cvt_pk_bf16_f32 v10, v10, v11
	v_mfma_f32_16x16x32_bf16 v[126:129], v[196:199], v[180:183], v[126:129]
	v_cvt_pk_bf16_f32 v11, v12, v13
	v_cvt_pk_bf16_f32 v12, v14, v15
	v_cvt_pk_bf16_f32 v13, v16, v17
	s_waitcnt lgkmcnt(0)
	v_mfma_f32_16x16x32_bf16 v[66:69], v[152:155], v[136:139], v[66:69]
	ds_read_b128 v[168:171], v229 offset:0
	global_store_dwordx4 v240, v[10:13], s[10:11] offset:16
	v_mul_f32_e32 v18, s12, v18
	v_mfma_f32_16x16x32_bf16 v[70:73], v[156:159], v[136:139], v[70:73]
	ds_read_b128 v[172:175], v229 offset:2048
	v_mul_f32_e32 v19, s12, v19
	v_mul_f32_e32 v20, s12, v20
	v_mfma_f32_16x16x32_bf16 v[74:77], v[160:163], v[136:139], v[74:77]
	ds_read_b128 v[176:179], v229 offset:4096
	v_mul_f32_e32 v21, s12, v21
	v_mul_f32_e32 v22, s12, v22
	v_mul_f32_e32 v23, s12, v23
	v_mfma_f32_16x16x32_bf16 v[78:81], v[164:167], v[136:139], v[78:81]
	ds_read_b128 v[180:183], v229 offset:6144
	v_mul_f32_e32 v24, s12, v24
	v_mul_f32_e32 v25, s12, v25
	v_mfma_f32_16x16x32_bf16 v[82:85], v[152:155], v[140:143], v[82:85]
	ds_read_b128 v[184:187], v235 offset:0
	v_exp_f32_e32 v18, v18
	v_exp_f32_e32 v19, v19
	v_mfma_f32_16x16x32_bf16 v[86:89], v[156:159], v[140:143], v[86:89]
	ds_read_b128 v[188:191], v235 offset:2048
	v_exp_f32_e32 v20, v20
	v_exp_f32_e32 v21, v21
	v_exp_f32_e32 v22, v22
	v_mfma_f32_16x16x32_bf16 v[90:93], v[160:163], v[140:143], v[90:93]
	ds_read_b128 v[192:195], v235 offset:4096
	v_exp_f32_e32 v23, v23
	v_exp_f32_e32 v24, v24
	v_mfma_f32_16x16x32_bf16 v[94:97], v[164:167], v[140:143], v[94:97]
	ds_read_b128 v[196:199], v235 offset:6144
	v_exp_f32_e32 v25, v25
	v_add_f32_e32 v18, 1.0, v18
	v_add_f32_e32 v19, 1.0, v19
	v_mfma_f32_16x16x32_bf16 v[98:101], v[152:155], v[144:147], v[98:101]
	v_add_f32_e32 v20, 1.0, v20
	v_add_f32_e32 v21, 1.0, v21
	v_mfma_f32_16x16x32_bf16 v[102:105], v[156:159], v[144:147], v[102:105]
	v_add_f32_e32 v22, 1.0, v22
	v_add_f32_e32 v23, 1.0, v23
	v_mfma_f32_16x16x32_bf16 v[106:109], v[160:163], v[144:147], v[106:109]
	v_add_f32_e32 v24, 1.0, v24
	v_add_f32_e32 v25, 1.0, v25
	v_rcp_f32_e32 v18, v18
	v_mfma_f32_16x16x32_bf16 v[110:113], v[164:167], v[144:147], v[110:113]
	v_rcp_f32_e32 v19, v19
	v_rcp_f32_e32 v20, v20
	v_mfma_f32_16x16x32_bf16 v[114:117], v[152:155], v[148:151], v[114:117]
	v_rcp_f32_e32 v21, v21
	v_rcp_f32_e32 v22, v22
	v_mfma_f32_16x16x32_bf16 v[118:121], v[156:159], v[148:151], v[118:121]
	v_rcp_f32_e32 v23, v23
	v_rcp_f32_e32 v24, v24
	v_rcp_f32_e32 v25, v25
	v_mfma_f32_16x16x32_bf16 v[122:125], v[160:163], v[148:151], v[122:125]
	v_cvt_pk_bf16_f32 v18, v18, v19
	v_cvt_pk_bf16_f32 v19, v20, v21
	v_mfma_f32_16x16x32_bf16 v[126:129], v[164:167], v[148:151], v[126:129]
	v_cvt_pk_bf16_f32 v20, v22, v23
	v_cvt_pk_bf16_f32 v21, v24, v25
	global_store_dwordx4 v240, v[18:21], s[10:11] offset:2048
	s_waitcnt vmcnt(3) lgkmcnt(0)
	s_barrier
	v_mfma_f32_16x16x32_bf16 v[66:69], v[184:187], v[168:171], v[66:69]
	ds_read_b128 v[136:139], v218 offset:0
	v_mul_f32_e32 v26, s12, v26
	v_mul_f32_e32 v27, s12, v27
	v_mfma_f32_16x16x32_bf16 v[70:73], v[188:191], v[168:171], v[70:73]
	ds_read_b128 v[140:143], v218 offset:2048
	v_mul_f32_e32 v28, s12, v28
	v_mul_f32_e32 v29, s12, v29
	v_mfma_f32_16x16x32_bf16 v[74:77], v[192:195], v[168:171], v[74:77]
	ds_read_b128 v[144:147], v218 offset:4096
	v_mul_f32_e32 v30, s12, v30
	v_mul_f32_e32 v31, s12, v31
	v_mfma_f32_16x16x32_bf16 v[78:81], v[196:199], v[168:171], v[78:81]
	ds_read_b128 v[148:151], v218 offset:6144
	v_mul_f32_e32 v32, s12, v32
	v_mul_f32_e32 v33, s12, v33
	v_exp_f32_e32 v26, v26
	v_mfma_f32_16x16x32_bf16 v[82:85], v[184:187], v[172:175], v[82:85]
	ds_read_b128 v[152:155], v230 offset:0
	v_exp_f32_e32 v27, v27
	v_exp_f32_e32 v28, v28
	v_mfma_f32_16x16x32_bf16 v[86:89], v[188:191], v[172:175], v[86:89]
	ds_read_b128 v[156:159], v230 offset:2048
	v_exp_f32_e32 v29, v29
	v_exp_f32_e32 v30, v30
	v_mfma_f32_16x16x32_bf16 v[90:93], v[192:195], v[172:175], v[90:93]
	ds_read_b128 v[160:163], v230 offset:4096
	v_exp_f32_e32 v31, v31
	v_exp_f32_e32 v32, v32
	v_exp_f32_e32 v33, v33
	v_mfma_f32_16x16x32_bf16 v[94:97], v[196:199], v[172:175], v[94:97]
	ds_read_b128 v[164:167], v230 offset:6144
	v_add_f32_e32 v26, 1.0, v26
	v_add_f32_e32 v27, 1.0, v27
	v_mfma_f32_16x16x32_bf16 v[98:101], v[184:187], v[176:179], v[98:101]
	v_add_f32_e32 v28, 1.0, v28
	v_add_f32_e32 v29, 1.0, v29
	v_mfma_f32_16x16x32_bf16 v[102:105], v[188:191], v[176:179], v[102:105]
	v_add_f32_e32 v30, 1.0, v30
	v_add_f32_e32 v31, 1.0, v31
	v_add_f32_e32 v32, 1.0, v32
	v_mfma_f32_16x16x32_bf16 v[106:109], v[192:195], v[176:179], v[106:109]
	v_add_f32_e32 v33, 1.0, v33
	v_rcp_f32_e32 v26, v26
	v_mfma_f32_16x16x32_bf16 v[110:113], v[196:199], v[176:179], v[110:113]
	v_rcp_f32_e32 v27, v27
	v_rcp_f32_e32 v28, v28
	v_mfma_f32_16x16x32_bf16 v[114:117], v[184:187], v[180:183], v[114:117]
	v_rcp_f32_e32 v29, v29
	v_rcp_f32_e32 v30, v30
	v_rcp_f32_e32 v31, v31
	v_mfma_f32_16x16x32_bf16 v[118:121], v[188:191], v[180:183], v[118:121]
	v_rcp_f32_e32 v32, v32
	v_rcp_f32_e32 v33, v33
	v_mfma_f32_16x16x32_bf16 v[122:125], v[192:195], v[180:183], v[122:125]
	v_cvt_pk_bf16_f32 v26, v26, v27
	v_cvt_pk_bf16_f32 v27, v28, v29
	v_mfma_f32_16x16x32_bf16 v[126:129], v[196:199], v[180:183], v[126:129]
	v_cvt_pk_bf16_f32 v28, v30, v31
	v_cvt_pk_bf16_f32 v29, v32, v33
	global_store_dwordx4 v240, v[26:29], s[10:11] offset:2064
	s_waitcnt lgkmcnt(0)
	v_mfma_f32_16x16x32_bf16 v[66:69], v[152:155], v[136:139], v[66:69]
	ds_read_b128 v[168:171], v225 offset:0
	v_mul_f32_e32 v34, s12, v34
	v_mul_f32_e32 v35, s12, v35
	v_mfma_f32_16x16x32_bf16 v[70:73], v[156:159], v[136:139], v[70:73]
	ds_read_b128 v[172:175], v225 offset:2048
	v_mul_f32_e32 v36, s12, v36
	v_mul_f32_e32 v37, s12, v37
	v_mfma_f32_16x16x32_bf16 v[74:77], v[160:163], v[136:139], v[74:77]
	ds_read_b128 v[176:179], v225 offset:4096
	v_mul_f32_e32 v38, s12, v38
	v_mul_f32_e32 v39, s12, v39
	v_mfma_f32_16x16x32_bf16 v[78:81], v[164:167], v[136:139], v[78:81]
	ds_read_b128 v[180:183], v225 offset:6144
	v_mul_f32_e32 v40, s12, v40
	v_mul_f32_e32 v41, s12, v41
	v_exp_f32_e32 v34, v34
	v_mfma_f32_16x16x32_bf16 v[82:85], v[152:155], v[140:143], v[82:85]
	ds_read_b128 v[184:187], v233 offset:0
	v_exp_f32_e32 v35, v35
	v_exp_f32_e32 v36, v36
	v_mfma_f32_16x16x32_bf16 v[86:89], v[156:159], v[140:143], v[86:89]
	ds_read_b128 v[188:191], v233 offset:2048
	v_exp_f32_e32 v37, v37
	v_exp_f32_e32 v38, v38
	v_mfma_f32_16x16x32_bf16 v[90:93], v[160:163], v[140:143], v[90:93]
	ds_read_b128 v[192:195], v233 offset:4096
	v_exp_f32_e32 v39, v39
	v_exp_f32_e32 v40, v40
	v_exp_f32_e32 v41, v41
	v_mfma_f32_16x16x32_bf16 v[94:97], v[164:167], v[140:143], v[94:97]
	ds_read_b128 v[196:199], v233 offset:6144
	v_add_f32_e32 v34, 1.0, v34
	v_add_f32_e32 v35, 1.0, v35
	v_mfma_f32_16x16x32_bf16 v[98:101], v[152:155], v[144:147], v[98:101]
	v_add_f32_e32 v36, 1.0, v36
	v_add_f32_e32 v37, 1.0, v37
	v_mfma_f32_16x16x32_bf16 v[102:105], v[156:159], v[144:147], v[102:105]
	v_add_f32_e32 v38, 1.0, v38
	v_add_f32_e32 v39, 1.0, v39
	v_add_f32_e32 v40, 1.0, v40
	v_mfma_f32_16x16x32_bf16 v[106:109], v[160:163], v[144:147], v[106:109]
	v_add_f32_e32 v41, 1.0, v41
	v_rcp_f32_e32 v34, v34
	v_mfma_f32_16x16x32_bf16 v[110:113], v[164:167], v[144:147], v[110:113]
	v_rcp_f32_e32 v35, v35
	v_rcp_f32_e32 v36, v36
	v_mfma_f32_16x16x32_bf16 v[114:117], v[152:155], v[148:151], v[114:117]
	v_rcp_f32_e32 v37, v37
	v_rcp_f32_e32 v38, v38
	v_rcp_f32_e32 v39, v39
	v_mfma_f32_16x16x32_bf16 v[118:121], v[156:159], v[148:151], v[118:121]
	v_rcp_f32_e32 v40, v40
	v_rcp_f32_e32 v41, v41
	v_mfma_f32_16x16x32_bf16 v[122:125], v[160:163], v[148:151], v[122:125]
	v_cvt_pk_bf16_f32 v34, v34, v35
	v_cvt_pk_bf16_f32 v35, v36, v37
	v_mfma_f32_16x16x32_bf16 v[126:129], v[164:167], v[148:151], v[126:129]
	v_cvt_pk_bf16_f32 v36, v38, v39
	v_cvt_pk_bf16_f32 v37, v40, v41
	global_store_dwordx4 v241, v[34:37], s[10:11] offset:0
	s_waitcnt lgkmcnt(0)
	s_barrier
	v_mfma_f32_16x16x32_bf16 v[66:69], v[184:187], v[168:171], v[66:69]
	ds_read_b128 v[136:139], v219 offset:0
	v_mul_f32_e32 v42, s12, v42
	v_mul_f32_e32 v43, s12, v43
	v_mfma_f32_16x16x32_bf16 v[70:73], v[188:191], v[168:171], v[70:73]
	ds_read_b128 v[140:143], v219 offset:2048
	v_mul_f32_e32 v44, s12, v44
	v_mul_f32_e32 v45, s12, v45
	v_mfma_f32_16x16x32_bf16 v[74:77], v[192:195], v[168:171], v[74:77]
	ds_read_b128 v[144:147], v219 offset:4096
	v_mul_f32_e32 v46, s12, v46
	v_mul_f32_e32 v47, s12, v47
	v_mfma_f32_16x16x32_bf16 v[78:81], v[196:199], v[168:171], v[78:81]
	ds_read_b128 v[148:151], v219 offset:6144
	v_mul_f32_e32 v48, s12, v48
	v_mul_f32_e32 v49, s12, v49
	v_exp_f32_e32 v42, v42
	v_mfma_f32_16x16x32_bf16 v[82:85], v[184:187], v[172:175], v[82:85]
	ds_read_b128 v[152:155], v231 offset:0
	v_exp_f32_e32 v43, v43
	v_exp_f32_e32 v44, v44
	v_mfma_f32_16x16x32_bf16 v[86:89], v[188:191], v[172:175], v[86:89]
	ds_read_b128 v[156:159], v231 offset:2048
	v_exp_f32_e32 v45, v45
	v_exp_f32_e32 v46, v46
	v_mfma_f32_16x16x32_bf16 v[90:93], v[192:195], v[172:175], v[90:93]
	ds_read_b128 v[160:163], v231 offset:4096
	v_exp_f32_e32 v47, v47
	v_exp_f32_e32 v48, v48
	v_exp_f32_e32 v49, v49
	v_mfma_f32_16x16x32_bf16 v[94:97], v[196:199], v[172:175], v[94:97]
	ds_read_b128 v[164:167], v231 offset:6144
	v_add_f32_e32 v42, 1.0, v42
	v_add_f32_e32 v43, 1.0, v43
	v_mfma_f32_16x16x32_bf16 v[98:101], v[184:187], v[176:179], v[98:101]
	v_add_f32_e32 v44, 1.0, v44
	v_add_f32_e32 v45, 1.0, v45
	v_mfma_f32_16x16x32_bf16 v[102:105], v[188:191], v[176:179], v[102:105]
	v_add_f32_e32 v46, 1.0, v46
	v_add_f32_e32 v47, 1.0, v47
	v_add_f32_e32 v48, 1.0, v48
	v_mfma_f32_16x16x32_bf16 v[106:109], v[192:195], v[176:179], v[106:109]
	v_add_f32_e32 v49, 1.0, v49
	v_rcp_f32_e32 v42, v42
	v_mfma_f32_16x16x32_bf16 v[110:113], v[196:199], v[176:179], v[110:113]
	v_rcp_f32_e32 v43, v43
	v_rcp_f32_e32 v44, v44
	v_mfma_f32_16x16x32_bf16 v[114:117], v[184:187], v[180:183], v[114:117]
	v_rcp_f32_e32 v45, v45
	v_rcp_f32_e32 v46, v46
	v_rcp_f32_e32 v47, v47
	v_mfma_f32_16x16x32_bf16 v[118:121], v[188:191], v[180:183], v[118:121]
	v_rcp_f32_e32 v48, v48
	v_rcp_f32_e32 v49, v49
	v_mfma_f32_16x16x32_bf16 v[122:125], v[192:195], v[180:183], v[122:125]
	v_cvt_pk_bf16_f32 v42, v42, v43
	v_cvt_pk_bf16_f32 v43, v44, v45
	v_mfma_f32_16x16x32_bf16 v[126:129], v[196:199], v[180:183], v[126:129]
	v_cvt_pk_bf16_f32 v44, v46, v47
	v_cvt_pk_bf16_f32 v45, v48, v49
	global_store_dwordx4 v241, v[42:45], s[10:11] offset:16
	s_waitcnt lgkmcnt(0)
	v_mfma_f32_16x16x32_bf16 v[66:69], v[152:155], v[136:139], v[66:69]
	ds_read_b128 v[168:171], v228 offset:0
	v_mul_f32_e32 v50, s12, v50
	v_mul_f32_e32 v51, s12, v51
	v_mfma_f32_16x16x32_bf16 v[70:73], v[156:159], v[136:139], v[70:73]
	ds_read_b128 v[172:175], v228 offset:2048
	v_mul_f32_e32 v52, s12, v52
	v_mul_f32_e32 v53, s12, v53
	v_mfma_f32_16x16x32_bf16 v[74:77], v[160:163], v[136:139], v[74:77]
	ds_read_b128 v[176:179], v228 offset:4096
	v_mul_f32_e32 v54, s12, v54
	v_mul_f32_e32 v55, s12, v55
	v_mfma_f32_16x16x32_bf16 v[78:81], v[164:167], v[136:139], v[78:81]
	ds_read_b128 v[180:183], v228 offset:6144
	v_mul_f32_e32 v56, s12, v56
	v_mul_f32_e32 v57, s12, v57
	v_exp_f32_e32 v50, v50
	v_mfma_f32_16x16x32_bf16 v[82:85], v[152:155], v[140:143], v[82:85]
	ds_read_b128 v[184:187], v234 offset:0
	v_exp_f32_e32 v51, v51
	v_exp_f32_e32 v52, v52
	v_mfma_f32_16x16x32_bf16 v[86:89], v[156:159], v[140:143], v[86:89]
	ds_read_b128 v[188:191], v234 offset:2048
	v_exp_f32_e32 v53, v53
	v_exp_f32_e32 v54, v54
	v_mfma_f32_16x16x32_bf16 v[90:93], v[160:163], v[140:143], v[90:93]
	ds_read_b128 v[192:195], v234 offset:4096
	v_exp_f32_e32 v55, v55
	v_exp_f32_e32 v56, v56
	v_exp_f32_e32 v57, v57
	v_mfma_f32_16x16x32_bf16 v[94:97], v[164:167], v[140:143], v[94:97]
	ds_read_b128 v[196:199], v234 offset:6144
	v_add_f32_e32 v50, 1.0, v50
	v_add_f32_e32 v51, 1.0, v51
	v_mfma_f32_16x16x32_bf16 v[98:101], v[152:155], v[144:147], v[98:101]
	v_add_f32_e32 v52, 1.0, v52
	v_add_f32_e32 v53, 1.0, v53
	v_mfma_f32_16x16x32_bf16 v[102:105], v[156:159], v[144:147], v[102:105]
	v_add_f32_e32 v54, 1.0, v54
	v_add_f32_e32 v55, 1.0, v55
	v_add_f32_e32 v56, 1.0, v56
	v_mfma_f32_16x16x32_bf16 v[106:109], v[160:163], v[144:147], v[106:109]
	v_add_f32_e32 v57, 1.0, v57
	v_rcp_f32_e32 v50, v50
	v_mfma_f32_16x16x32_bf16 v[110:113], v[164:167], v[144:147], v[110:113]
	v_rcp_f32_e32 v51, v51
	v_rcp_f32_e32 v52, v52
	v_mfma_f32_16x16x32_bf16 v[114:117], v[152:155], v[148:151], v[114:117]
	v_rcp_f32_e32 v53, v53
	v_rcp_f32_e32 v54, v54
	v_rcp_f32_e32 v55, v55
	v_mfma_f32_16x16x32_bf16 v[118:121], v[156:159], v[148:151], v[118:121]
	v_rcp_f32_e32 v56, v56
	v_rcp_f32_e32 v57, v57
	v_mfma_f32_16x16x32_bf16 v[122:125], v[160:163], v[148:151], v[122:125]
	v_cvt_pk_bf16_f32 v50, v50, v51
	v_cvt_pk_bf16_f32 v51, v52, v53
	v_mfma_f32_16x16x32_bf16 v[126:129], v[164:167], v[148:151], v[126:129]
	v_cvt_pk_bf16_f32 v52, v54, v55
	v_cvt_pk_bf16_f32 v53, v56, v57
	global_store_dwordx4 v241, v[50:53], s[10:11] offset:2048
	s_waitcnt lgkmcnt(0)
	s_barrier
	v_mfma_f32_16x16x32_bf16 v[66:69], v[184:187], v[168:171], v[66:69]
	ds_read_b128 v[136:139], v224 offset:0
	v_mul_f32_e32 v58, s12, v58
	v_mul_f32_e32 v59, s12, v59
	v_mfma_f32_16x16x32_bf16 v[70:73], v[188:191], v[168:171], v[70:73]
	ds_read_b128 v[140:143], v224 offset:2048
	v_mul_f32_e32 v60, s12, v60
	v_mul_f32_e32 v61, s12, v61
	v_mfma_f32_16x16x32_bf16 v[74:77], v[192:195], v[168:171], v[74:77]
	ds_read_b128 v[144:147], v224 offset:4096
	v_mul_f32_e32 v62, s12, v62
	v_mul_f32_e32 v63, s12, v63
	v_mfma_f32_16x16x32_bf16 v[78:81], v[196:199], v[168:171], v[78:81]
	ds_read_b128 v[148:151], v224 offset:6144
	v_mul_f32_e32 v64, s12, v64
	v_mul_f32_e32 v65, s12, v65
	v_exp_f32_e32 v58, v58
	v_mfma_f32_16x16x32_bf16 v[82:85], v[184:187], v[172:175], v[82:85]
	ds_read_b128 v[152:155], v232 offset:0
	v_exp_f32_e32 v59, v59
	v_exp_f32_e32 v60, v60
	v_mfma_f32_16x16x32_bf16 v[86:89], v[188:191], v[172:175], v[86:89]
	ds_read_b128 v[156:159], v232 offset:2048
	v_exp_f32_e32 v61, v61
	v_exp_f32_e32 v62, v62
	v_mfma_f32_16x16x32_bf16 v[90:93], v[192:195], v[172:175], v[90:93]
	ds_read_b128 v[160:163], v232 offset:4096
	v_exp_f32_e32 v63, v63
	v_exp_f32_e32 v64, v64
	v_exp_f32_e32 v65, v65
	v_mfma_f32_16x16x32_bf16 v[94:97], v[196:199], v[172:175], v[94:97]
	ds_read_b128 v[164:167], v232 offset:6144
	v_add_f32_e32 v58, 1.0, v58
	v_add_f32_e32 v59, 1.0, v59
	v_mfma_f32_16x16x32_bf16 v[98:101], v[184:187], v[176:179], v[98:101]
	v_add_f32_e32 v60, 1.0, v60
	v_add_f32_e32 v61, 1.0, v61
	v_mfma_f32_16x16x32_bf16 v[102:105], v[188:191], v[176:179], v[102:105]
	v_add_f32_e32 v62, 1.0, v62
	v_add_f32_e32 v63, 1.0, v63
	v_add_f32_e32 v64, 1.0, v64
	v_mfma_f32_16x16x32_bf16 v[106:109], v[192:195], v[176:179], v[106:109]
	v_add_f32_e32 v65, 1.0, v65
	v_rcp_f32_e32 v58, v58
	v_mfma_f32_16x16x32_bf16 v[110:113], v[196:199], v[176:179], v[110:113]
	v_rcp_f32_e32 v59, v59
	v_rcp_f32_e32 v60, v60
	v_mfma_f32_16x16x32_bf16 v[114:117], v[184:187], v[180:183], v[114:117]
	v_rcp_f32_e32 v61, v61
	v_rcp_f32_e32 v62, v62
	v_rcp_f32_e32 v63, v63
	v_mfma_f32_16x16x32_bf16 v[118:121], v[188:191], v[180:183], v[118:121]
	v_rcp_f32_e32 v64, v64
	v_rcp_f32_e32 v65, v65
	v_mfma_f32_16x16x32_bf16 v[122:125], v[192:195], v[180:183], v[122:125]
	v_cvt_pk_bf16_f32 v58, v58, v59
	v_cvt_pk_bf16_f32 v59, v60, v61
	v_mfma_f32_16x16x32_bf16 v[126:129], v[196:199], v[180:183], v[126:129]
	v_cvt_pk_bf16_f32 v60, v62, v63
	v_cvt_pk_bf16_f32 v61, v64, v65
	global_store_dwordx4 v241, v[58:61], s[10:11] offset:2064
	s_waitcnt lgkmcnt(0)
	v_mfma_f32_16x16x32_bf16 v[66:69], v[152:155], v[136:139], v[66:69]
	ds_read_b128 v[168:171], v229 offset:0
	v_mfma_f32_16x16x32_bf16 v[70:73], v[156:159], v[136:139], v[70:73]
	ds_read_b128 v[172:175], v229 offset:2048
	v_mfma_f32_16x16x32_bf16 v[74:77], v[160:163], v[136:139], v[74:77]
	ds_read_b128 v[176:179], v229 offset:4096
	v_mfma_f32_16x16x32_bf16 v[78:81], v[164:167], v[136:139], v[78:81]
	ds_read_b128 v[180:183], v229 offset:6144
	v_mfma_f32_16x16x32_bf16 v[82:85], v[152:155], v[140:143], v[82:85]
	ds_read_b128 v[184:187], v235 offset:0
	v_mfma_f32_16x16x32_bf16 v[86:89], v[156:159], v[140:143], v[86:89]
	ds_read_b128 v[188:191], v235 offset:2048
	v_mfma_f32_16x16x32_bf16 v[90:93], v[160:163], v[140:143], v[90:93]
	ds_read_b128 v[192:195], v235 offset:4096
	v_mfma_f32_16x16x32_bf16 v[94:97], v[164:167], v[140:143], v[94:97]
	ds_read_b128 v[196:199], v235 offset:6144
	v_mfma_f32_16x16x32_bf16 v[98:101], v[152:155], v[144:147], v[98:101]
	v_mfma_f32_16x16x32_bf16 v[102:105], v[156:159], v[144:147], v[102:105]
	v_mfma_f32_16x16x32_bf16 v[106:109], v[160:163], v[144:147], v[106:109]
	v_mfma_f32_16x16x32_bf16 v[110:113], v[164:167], v[144:147], v[110:113]
	v_mfma_f32_16x16x32_bf16 v[114:117], v[152:155], v[148:151], v[114:117]
	v_mfma_f32_16x16x32_bf16 v[118:121], v[156:159], v[148:151], v[118:121]
	v_mfma_f32_16x16x32_bf16 v[122:125], v[160:163], v[148:151], v[122:125]
	v_mfma_f32_16x16x32_bf16 v[126:129], v[164:167], v[148:151], v[126:129]
	s_waitcnt lgkmcnt(0)
	s_barrier
	v_mfma_f32_16x16x32_bf16 v[66:69], v[184:187], v[168:171], v[66:69]
	ds_read_b128 v[136:139], v218 offset:0
	v_mfma_f32_16x16x32_bf16 v[70:73], v[188:191], v[168:171], v[70:73]
	ds_read_b128 v[140:143], v218 offset:2048
	v_mfma_f32_16x16x32_bf16 v[74:77], v[192:195], v[168:171], v[74:77]
	ds_read_b128 v[144:147], v218 offset:4096
	v_mfma_f32_16x16x32_bf16 v[78:81], v[196:199], v[168:171], v[78:81]
	ds_read_b128 v[148:151], v218 offset:6144
	v_mfma_f32_16x16x32_bf16 v[82:85], v[184:187], v[172:175], v[82:85]
	ds_read_b128 v[152:155], v230 offset:0
	v_mfma_f32_16x16x32_bf16 v[86:89], v[188:191], v[172:175], v[86:89]
	ds_read_b128 v[156:159], v230 offset:2048
	v_mfma_f32_16x16x32_bf16 v[90:93], v[192:195], v[172:175], v[90:93]
	ds_read_b128 v[160:163], v230 offset:4096
	v_mfma_f32_16x16x32_bf16 v[94:97], v[196:199], v[172:175], v[94:97]
	ds_read_b128 v[164:167], v230 offset:6144
	v_mfma_f32_16x16x32_bf16 v[98:101], v[184:187], v[176:179], v[98:101]
	v_mfma_f32_16x16x32_bf16 v[102:105], v[188:191], v[176:179], v[102:105]
	v_mfma_f32_16x16x32_bf16 v[106:109], v[192:195], v[176:179], v[106:109]
	v_mfma_f32_16x16x32_bf16 v[110:113], v[196:199], v[176:179], v[110:113]
	v_mfma_f32_16x16x32_bf16 v[114:117], v[184:187], v[180:183], v[114:117]
	v_mfma_f32_16x16x32_bf16 v[118:121], v[188:191], v[180:183], v[118:121]
	v_mfma_f32_16x16x32_bf16 v[122:125], v[192:195], v[180:183], v[122:125]
	v_mfma_f32_16x16x32_bf16 v[126:129], v[196:199], v[180:183], v[126:129]
	s_waitcnt lgkmcnt(0)
	v_mfma_f32_16x16x32_bf16 v[66:69], v[152:155], v[136:139], v[66:69]
	ds_read_b128 v[168:171], v225 offset:0
	v_mfma_f32_16x16x32_bf16 v[70:73], v[156:159], v[136:139], v[70:73]
	ds_read_b128 v[172:175], v225 offset:2048
	v_mfma_f32_16x16x32_bf16 v[74:77], v[160:163], v[136:139], v[74:77]
	ds_read_b128 v[176:179], v225 offset:4096
	v_mfma_f32_16x16x32_bf16 v[78:81], v[164:167], v[136:139], v[78:81]
	ds_read_b128 v[180:183], v225 offset:6144
	v_mfma_f32_16x16x32_bf16 v[82:85], v[152:155], v[140:143], v[82:85]
	ds_read_b128 v[184:187], v233 offset:0
	v_mfma_f32_16x16x32_bf16 v[86:89], v[156:159], v[140:143], v[86:89]
	ds_read_b128 v[188:191], v233 offset:2048
	v_mfma_f32_16x16x32_bf16 v[90:93], v[160:163], v[140:143], v[90:93]
	ds_read_b128 v[192:195], v233 offset:4096
	v_mfma_f32_16x16x32_bf16 v[94:97], v[164:167], v[140:143], v[94:97]
	ds_read_b128 v[196:199], v233 offset:6144
	v_mfma_f32_16x16x32_bf16 v[98:101], v[152:155], v[144:147], v[98:101]
	v_mfma_f32_16x16x32_bf16 v[102:105], v[156:159], v[144:147], v[102:105]
	v_mfma_f32_16x16x32_bf16 v[106:109], v[160:163], v[144:147], v[106:109]
	v_mfma_f32_16x16x32_bf16 v[110:113], v[164:167], v[144:147], v[110:113]
	v_mfma_f32_16x16x32_bf16 v[114:117], v[152:155], v[148:151], v[114:117]
	v_mfma_f32_16x16x32_bf16 v[118:121], v[156:159], v[148:151], v[118:121]
	v_mfma_f32_16x16x32_bf16 v[122:125], v[160:163], v[148:151], v[122:125]
	v_mfma_f32_16x16x32_bf16 v[126:129], v[164:167], v[148:151], v[126:129]
	s_waitcnt lgkmcnt(0)
	s_barrier
	v_mfma_f32_16x16x32_bf16 v[66:69], v[184:187], v[168:171], v[66:69]
	ds_read_b128 v[136:139], v219 offset:0
	v_mfma_f32_16x16x32_bf16 v[70:73], v[188:191], v[168:171], v[70:73]
	ds_read_b128 v[140:143], v219 offset:2048
	v_mfma_f32_16x16x32_bf16 v[74:77], v[192:195], v[168:171], v[74:77]
	ds_read_b128 v[144:147], v219 offset:4096
	v_mfma_f32_16x16x32_bf16 v[78:81], v[196:199], v[168:171], v[78:81]
	ds_read_b128 v[148:151], v219 offset:6144
	v_mfma_f32_16x16x32_bf16 v[82:85], v[184:187], v[172:175], v[82:85]
	ds_read_b128 v[152:155], v231 offset:0
	v_mfma_f32_16x16x32_bf16 v[86:89], v[188:191], v[172:175], v[86:89]
	ds_read_b128 v[156:159], v231 offset:2048
	v_mfma_f32_16x16x32_bf16 v[90:93], v[192:195], v[172:175], v[90:93]
	ds_read_b128 v[160:163], v231 offset:4096
	v_mfma_f32_16x16x32_bf16 v[94:97], v[196:199], v[172:175], v[94:97]
	ds_read_b128 v[164:167], v231 offset:6144
	v_mfma_f32_16x16x32_bf16 v[98:101], v[184:187], v[176:179], v[98:101]
	v_mfma_f32_16x16x32_bf16 v[102:105], v[188:191], v[176:179], v[102:105]
	v_mfma_f32_16x16x32_bf16 v[106:109], v[192:195], v[176:179], v[106:109]
	v_mfma_f32_16x16x32_bf16 v[110:113], v[196:199], v[176:179], v[110:113]
	v_mfma_f32_16x16x32_bf16 v[114:117], v[184:187], v[180:183], v[114:117]
	v_mfma_f32_16x16x32_bf16 v[118:121], v[188:191], v[180:183], v[118:121]
	v_mfma_f32_16x16x32_bf16 v[122:125], v[192:195], v[180:183], v[122:125]
	v_mfma_f32_16x16x32_bf16 v[126:129], v[196:199], v[180:183], v[126:129]
	s_waitcnt lgkmcnt(0)
	v_mfma_f32_16x16x32_bf16 v[66:69], v[152:155], v[136:139], v[66:69]
	ds_read_b128 v[168:171], v228 offset:0
	v_mfma_f32_16x16x32_bf16 v[70:73], v[156:159], v[136:139], v[70:73]
	ds_read_b128 v[172:175], v228 offset:2048
	v_mfma_f32_16x16x32_bf16 v[74:77], v[160:163], v[136:139], v[74:77]
	ds_read_b128 v[176:179], v228 offset:4096
	v_mfma_f32_16x16x32_bf16 v[78:81], v[164:167], v[136:139], v[78:81]
	ds_read_b128 v[180:183], v228 offset:6144
	v_mfma_f32_16x16x32_bf16 v[82:85], v[152:155], v[140:143], v[82:85]
	ds_read_b128 v[184:187], v234 offset:0
	v_mfma_f32_16x16x32_bf16 v[86:89], v[156:159], v[140:143], v[86:89]
	ds_read_b128 v[188:191], v234 offset:2048
	v_mfma_f32_16x16x32_bf16 v[90:93], v[160:163], v[140:143], v[90:93]
	ds_read_b128 v[192:195], v234 offset:4096
	v_mfma_f32_16x16x32_bf16 v[94:97], v[164:167], v[140:143], v[94:97]
	ds_read_b128 v[196:199], v234 offset:6144
	v_mfma_f32_16x16x32_bf16 v[98:101], v[152:155], v[144:147], v[98:101]
	v_mfma_f32_16x16x32_bf16 v[102:105], v[156:159], v[144:147], v[102:105]
	v_mfma_f32_16x16x32_bf16 v[106:109], v[160:163], v[144:147], v[106:109]
	v_mfma_f32_16x16x32_bf16 v[110:113], v[164:167], v[144:147], v[110:113]
	v_mfma_f32_16x16x32_bf16 v[114:117], v[152:155], v[148:151], v[114:117]
	v_mfma_f32_16x16x32_bf16 v[118:121], v[156:159], v[148:151], v[118:121]
	v_mfma_f32_16x16x32_bf16 v[122:125], v[160:163], v[148:151], v[122:125]
	v_mfma_f32_16x16x32_bf16 v[126:129], v[164:167], v[148:151], v[126:129]
	s_waitcnt lgkmcnt(0)
	s_barrier
	v_mfma_f32_16x16x32_bf16 v[66:69], v[184:187], v[168:171], v[66:69]
	ds_read_b128 v[136:139], v224 offset:0
	v_mfma_f32_16x16x32_bf16 v[70:73], v[188:191], v[168:171], v[70:73]
	ds_read_b128 v[140:143], v224 offset:2048
	v_mfma_f32_16x16x32_bf16 v[74:77], v[192:195], v[168:171], v[74:77]
	ds_read_b128 v[144:147], v224 offset:4096
	v_mfma_f32_16x16x32_bf16 v[78:81], v[196:199], v[168:171], v[78:81]
	ds_read_b128 v[148:151], v224 offset:6144
	v_mfma_f32_16x16x32_bf16 v[82:85], v[184:187], v[172:175], v[82:85]
	ds_read_b128 v[152:155], v232 offset:0
	v_mfma_f32_16x16x32_bf16 v[86:89], v[188:191], v[172:175], v[86:89]
	ds_read_b128 v[156:159], v232 offset:2048
	v_mfma_f32_16x16x32_bf16 v[90:93], v[192:195], v[172:175], v[90:93]
	ds_read_b128 v[160:163], v232 offset:4096
	v_mfma_f32_16x16x32_bf16 v[94:97], v[196:199], v[172:175], v[94:97]
	ds_read_b128 v[164:167], v232 offset:6144
	v_mfma_f32_16x16x32_bf16 v[98:101], v[184:187], v[176:179], v[98:101]
	v_mfma_f32_16x16x32_bf16 v[102:105], v[188:191], v[176:179], v[102:105]
	v_mfma_f32_16x16x32_bf16 v[106:109], v[192:195], v[176:179], v[106:109]
	v_mfma_f32_16x16x32_bf16 v[110:113], v[196:199], v[176:179], v[110:113]
	v_mfma_f32_16x16x32_bf16 v[114:117], v[184:187], v[180:183], v[114:117]
	v_mfma_f32_16x16x32_bf16 v[118:121], v[188:191], v[180:183], v[118:121]
	v_mfma_f32_16x16x32_bf16 v[122:125], v[192:195], v[180:183], v[122:125]
	v_mfma_f32_16x16x32_bf16 v[126:129], v[196:199], v[180:183], v[126:129]
	s_waitcnt lgkmcnt(0)
	v_mfma_f32_16x16x32_bf16 v[66:69], v[152:155], v[136:139], v[66:69]
	ds_read_b128 v[168:171], v229 offset:0
	v_mfma_f32_16x16x32_bf16 v[70:73], v[156:159], v[136:139], v[70:73]
	ds_read_b128 v[172:175], v229 offset:2048
	v_mfma_f32_16x16x32_bf16 v[74:77], v[160:163], v[136:139], v[74:77]
	ds_read_b128 v[176:179], v229 offset:4096
	v_mfma_f32_16x16x32_bf16 v[78:81], v[164:167], v[136:139], v[78:81]
	ds_read_b128 v[180:183], v229 offset:6144
	v_mfma_f32_16x16x32_bf16 v[82:85], v[152:155], v[140:143], v[82:85]
	ds_read_b128 v[184:187], v235 offset:0
	v_mfma_f32_16x16x32_bf16 v[86:89], v[156:159], v[140:143], v[86:89]
	ds_read_b128 v[188:191], v235 offset:2048
	v_mfma_f32_16x16x32_bf16 v[90:93], v[160:163], v[140:143], v[90:93]
	ds_read_b128 v[192:195], v235 offset:4096
	v_mfma_f32_16x16x32_bf16 v[94:97], v[164:167], v[140:143], v[94:97]
	ds_read_b128 v[196:199], v235 offset:6144
	v_mfma_f32_16x16x32_bf16 v[98:101], v[152:155], v[144:147], v[98:101]
	v_mfma_f32_16x16x32_bf16 v[102:105], v[156:159], v[144:147], v[102:105]
	v_mfma_f32_16x16x32_bf16 v[106:109], v[160:163], v[144:147], v[106:109]
	v_mfma_f32_16x16x32_bf16 v[110:113], v[164:167], v[144:147], v[110:113]
	v_mfma_f32_16x16x32_bf16 v[114:117], v[152:155], v[148:151], v[114:117]
	v_mfma_f32_16x16x32_bf16 v[118:121], v[156:159], v[148:151], v[118:121]
	v_mfma_f32_16x16x32_bf16 v[122:125], v[160:163], v[148:151], v[122:125]
	v_mfma_f32_16x16x32_bf16 v[126:129], v[164:167], v[148:151], v[126:129]
	s_waitcnt lgkmcnt(0)
	s_barrier
	v_mfma_f32_16x16x32_bf16 v[66:69], v[184:187], v[168:171], v[66:69]
	ds_read_b128 v[136:139], v218 offset:0
	v_mfma_f32_16x16x32_bf16 v[70:73], v[188:191], v[168:171], v[70:73]
	ds_read_b128 v[140:143], v218 offset:2048
	v_mfma_f32_16x16x32_bf16 v[74:77], v[192:195], v[168:171], v[74:77]
	ds_read_b128 v[144:147], v218 offset:4096
	v_mfma_f32_16x16x32_bf16 v[78:81], v[196:199], v[168:171], v[78:81]
	ds_read_b128 v[148:151], v218 offset:6144
	v_mfma_f32_16x16x32_bf16 v[82:85], v[184:187], v[172:175], v[82:85]
	ds_read_b128 v[152:155], v230 offset:0
	v_mfma_f32_16x16x32_bf16 v[86:89], v[188:191], v[172:175], v[86:89]
	ds_read_b128 v[156:159], v230 offset:2048
	v_mfma_f32_16x16x32_bf16 v[90:93], v[192:195], v[172:175], v[90:93]
	ds_read_b128 v[160:163], v230 offset:4096
	v_mfma_f32_16x16x32_bf16 v[94:97], v[196:199], v[172:175], v[94:97]
	ds_read_b128 v[164:167], v230 offset:6144
	v_mfma_f32_16x16x32_bf16 v[98:101], v[184:187], v[176:179], v[98:101]
	v_mfma_f32_16x16x32_bf16 v[102:105], v[188:191], v[176:179], v[102:105]
	v_mfma_f32_16x16x32_bf16 v[106:109], v[192:195], v[176:179], v[106:109]
	v_mfma_f32_16x16x32_bf16 v[110:113], v[196:199], v[176:179], v[110:113]
	v_mfma_f32_16x16x32_bf16 v[114:117], v[184:187], v[180:183], v[114:117]
	v_mfma_f32_16x16x32_bf16 v[118:121], v[188:191], v[180:183], v[118:121]
	v_mfma_f32_16x16x32_bf16 v[122:125], v[192:195], v[180:183], v[122:125]
	v_mfma_f32_16x16x32_bf16 v[126:129], v[196:199], v[180:183], v[126:129]
	s_waitcnt lgkmcnt(0)
	v_mfma_f32_16x16x32_bf16 v[66:69], v[152:155], v[136:139], v[66:69]
	ds_read_b128 v[168:171], v225 offset:0
	v_mfma_f32_16x16x32_bf16 v[70:73], v[156:159], v[136:139], v[70:73]
	ds_read_b128 v[172:175], v225 offset:2048
	v_mfma_f32_16x16x32_bf16 v[74:77], v[160:163], v[136:139], v[74:77]
	ds_read_b128 v[176:179], v225 offset:4096
	v_mfma_f32_16x16x32_bf16 v[78:81], v[164:167], v[136:139], v[78:81]
	ds_read_b128 v[180:183], v225 offset:6144
	v_mfma_f32_16x16x32_bf16 v[82:85], v[152:155], v[140:143], v[82:85]
	ds_read_b128 v[184:187], v233 offset:0
	v_mfma_f32_16x16x32_bf16 v[86:89], v[156:159], v[140:143], v[86:89]
	ds_read_b128 v[188:191], v233 offset:2048
	v_mfma_f32_16x16x32_bf16 v[90:93], v[160:163], v[140:143], v[90:93]
	ds_read_b128 v[192:195], v233 offset:4096
	v_mfma_f32_16x16x32_bf16 v[94:97], v[164:167], v[140:143], v[94:97]
	ds_read_b128 v[196:199], v233 offset:6144
	v_mfma_f32_16x16x32_bf16 v[98:101], v[152:155], v[144:147], v[98:101]
	v_mfma_f32_16x16x32_bf16 v[102:105], v[156:159], v[144:147], v[102:105]
	v_mfma_f32_16x16x32_bf16 v[106:109], v[160:163], v[144:147], v[106:109]
	v_mfma_f32_16x16x32_bf16 v[110:113], v[164:167], v[144:147], v[110:113]
	v_mfma_f32_16x16x32_bf16 v[114:117], v[152:155], v[148:151], v[114:117]
	v_mfma_f32_16x16x32_bf16 v[118:121], v[156:159], v[148:151], v[118:121]
	v_mfma_f32_16x16x32_bf16 v[122:125], v[160:163], v[148:151], v[122:125]
	v_mfma_f32_16x16x32_bf16 v[126:129], v[164:167], v[148:151], v[126:129]
	s_waitcnt lgkmcnt(0)
	s_barrier
	s_add_u32 s14, s4, 0x580
	s_addc_u32 s15, s5, 0
	v_mfma_f32_16x16x32_bf16 v[66:69], v[184:187], v[168:171], v[66:69]
	ds_read_b128 v[136:139], v219 offset:0
	s_add_u32 s22, s4, 0x10580
	s_addc_u32 s23, s5, 0
	v_mfma_f32_16x16x32_bf16 v[70:73], v[188:191], v[168:171], v[70:73]
	ds_read_b128 v[140:143], v219 offset:2048
	s_add_u32 s24, s6, 0x40580
	s_addc_u32 s25, s7, 0
	v_mfma_f32_16x16x32_bf16 v[74:77], v[192:195], v[168:171], v[74:77]
	ds_read_b128 v[144:147], v219 offset:4096
	s_add_u32 s52, s6, 0x48580
	s_addc_u32 s53, s7, 0
	v_mfma_f32_16x16x32_bf16 v[78:81], v[196:199], v[168:171], v[78:81]
	ds_read_b128 v[148:151], v219 offset:6144
	s_mov_b32 m0, s8
	v_mfma_f32_16x16x32_bf16 v[82:85], v[184:187], v[172:175], v[82:85]
	global_load_lds_dwordx4 v200, s[14:15]
	ds_read_b128 v[152:155], v231 offset:0
	s_add_u32 m0, s8, 0x400
	v_mfma_f32_16x16x32_bf16 v[86:89], v[188:191], v[172:175], v[86:89]
	global_load_lds_dwordx4 v201, s[14:15]
	ds_read_b128 v[156:159], v231 offset:2048
	s_add_u32 m0, s8, 0x800
	v_mfma_f32_16x16x32_bf16 v[90:93], v[192:195], v[172:175], v[90:93]
	global_load_lds_dwordx4 v202, s[14:15]
	ds_read_b128 v[160:163], v231 offset:4096
	s_add_u32 m0, s8, 0xc00
	v_mfma_f32_16x16x32_bf16 v[94:97], v[196:199], v[172:175], v[94:97]
	global_load_lds_dwordx4 v203, s[14:15]
	ds_read_b128 v[164:167], v231 offset:6144
	s_add_u32 m0, s8, 0x1000
	v_mfma_f32_16x16x32_bf16 v[98:101], v[184:187], v[176:179], v[98:101]
	global_load_lds_dwordx4 v200, s[22:23]
	s_add_u32 m0, s8, 0x1400
	v_mfma_f32_16x16x32_bf16 v[102:105], v[188:191], v[176:179], v[102:105]
	global_load_lds_dwordx4 v201, s[22:23]
	s_add_u32 m0, s8, 0x1800
	v_mfma_f32_16x16x32_bf16 v[106:109], v[192:195], v[176:179], v[106:109]
	global_load_lds_dwordx4 v202, s[22:23]
	s_add_u32 m0, s8, 0x1c00
	v_mfma_f32_16x16x32_bf16 v[110:113], v[196:199], v[176:179], v[110:113]
	global_load_lds_dwordx4 v203, s[22:23]
	s_mov_b32 m0, s9
	v_mfma_f32_16x16x32_bf16 v[114:117], v[184:187], v[180:183], v[114:117]
	global_load_lds_dwordx4 v204, s[24:25]
	s_add_u32 m0, s9, 0x400
	v_mfma_f32_16x16x32_bf16 v[118:121], v[188:191], v[180:183], v[118:121]
	global_load_lds_dwordx4 v205, s[24:25]
	s_add_u32 m0, s9, 0x800
	v_mfma_f32_16x16x32_bf16 v[122:125], v[192:195], v[180:183], v[122:125]
	global_load_lds_dwordx4 v204, s[52:53]
	s_add_u32 m0, s9, 0xc00
	v_mfma_f32_16x16x32_bf16 v[126:129], v[196:199], v[180:183], v[126:129]
	global_load_lds_dwordx4 v205, s[52:53]
	s_waitcnt lgkmcnt(0)
	v_mfma_f32_16x16x32_bf16 v[66:69], v[152:155], v[136:139], v[66:69]
	ds_read_b128 v[168:171], v228 offset:0
	v_mfma_f32_16x16x32_bf16 v[70:73], v[156:159], v[136:139], v[70:73]
	ds_read_b128 v[172:175], v228 offset:2048
	v_mfma_f32_16x16x32_bf16 v[74:77], v[160:163], v[136:139], v[74:77]
	ds_read_b128 v[176:179], v228 offset:4096
	v_mfma_f32_16x16x32_bf16 v[78:81], v[164:167], v[136:139], v[78:81]
	ds_read_b128 v[180:183], v228 offset:6144
	v_mfma_f32_16x16x32_bf16 v[82:85], v[152:155], v[140:143], v[82:85]
	ds_read_b128 v[184:187], v234 offset:0
	v_mfma_f32_16x16x32_bf16 v[86:89], v[156:159], v[140:143], v[86:89]
	ds_read_b128 v[188:191], v234 offset:2048
	v_mfma_f32_16x16x32_bf16 v[90:93], v[160:163], v[140:143], v[90:93]
	ds_read_b128 v[192:195], v234 offset:4096
	v_mfma_f32_16x16x32_bf16 v[94:97], v[164:167], v[140:143], v[94:97]
	ds_read_b128 v[196:199], v234 offset:6144
	v_mfma_f32_16x16x32_bf16 v[98:101], v[152:155], v[144:147], v[98:101]
	v_mfma_f32_16x16x32_bf16 v[102:105], v[156:159], v[144:147], v[102:105]
	v_mfma_f32_16x16x32_bf16 v[106:109], v[160:163], v[144:147], v[106:109]
	v_mfma_f32_16x16x32_bf16 v[110:113], v[164:167], v[144:147], v[110:113]
	v_mfma_f32_16x16x32_bf16 v[114:117], v[152:155], v[148:151], v[114:117]
	v_mfma_f32_16x16x32_bf16 v[118:121], v[156:159], v[148:151], v[118:121]
	v_mfma_f32_16x16x32_bf16 v[122:125], v[160:163], v[148:151], v[122:125]
	v_mfma_f32_16x16x32_bf16 v[126:129], v[164:167], v[148:151], v[126:129]
	s_waitcnt lgkmcnt(0)
	s_barrier
	s_add_u32 s14, s4, 0x600
	s_addc_u32 s15, s5, 0
	v_mfma_f32_16x16x32_bf16 v[66:69], v[184:187], v[168:171], v[66:69]
	ds_read_b128 v[136:139], v224 offset:0
	s_add_u32 s22, s4, 0x10600
	s_addc_u32 s23, s5, 0
	v_mfma_f32_16x16x32_bf16 v[70:73], v[188:191], v[168:171], v[70:73]
	ds_read_b128 v[140:143], v224 offset:2048
	s_add_u32 s24, s6, 0x40600
	s_addc_u32 s25, s7, 0
	v_mfma_f32_16x16x32_bf16 v[74:77], v[192:195], v[168:171], v[74:77]
	ds_read_b128 v[144:147], v224 offset:4096
	s_add_u32 s52, s6, 0x48600
	s_addc_u32 s53, s7, 0
	v_mfma_f32_16x16x32_bf16 v[78:81], v[196:199], v[168:171], v[78:81]
	ds_read_b128 v[148:151], v224 offset:6144
	s_add_u32 m0, s8, 0xc000
	v_mfma_f32_16x16x32_bf16 v[82:85], v[184:187], v[172:175], v[82:85]
	global_load_lds_dwordx4 v200, s[14:15]
	ds_read_b128 v[152:155], v232 offset:0
	s_add_u32 m0, s8, 0xc400
	v_mfma_f32_16x16x32_bf16 v[86:89], v[188:191], v[172:175], v[86:89]
	global_load_lds_dwordx4 v201, s[14:15]
	ds_read_b128 v[156:159], v232 offset:2048
	s_add_u32 m0, s8, 0xc800
	v_mfma_f32_16x16x32_bf16 v[90:93], v[192:195], v[172:175], v[90:93]
	global_load_lds_dwordx4 v202, s[14:15]
	ds_read_b128 v[160:163], v232 offset:4096
	s_add_u32 m0, s8, 0xcc00
	v_mfma_f32_16x16x32_bf16 v[94:97], v[196:199], v[172:175], v[94:97]
	global_load_lds_dwordx4 v203, s[14:15]
	ds_read_b128 v[164:167], v232 offset:6144
	s_add_u32 m0, s8, 0xd000
	v_mfma_f32_16x16x32_bf16 v[98:101], v[184:187], v[176:179], v[98:101]
	global_load_lds_dwordx4 v200, s[22:23]
	s_add_u32 m0, s8, 0xd400
	v_mfma_f32_16x16x32_bf16 v[102:105], v[188:191], v[176:179], v[102:105]
	global_load_lds_dwordx4 v201, s[22:23]
	s_add_u32 m0, s8, 0xd800
	v_mfma_f32_16x16x32_bf16 v[106:109], v[192:195], v[176:179], v[106:109]
	global_load_lds_dwordx4 v202, s[22:23]
	s_add_u32 m0, s8, 0xdc00
	v_mfma_f32_16x16x32_bf16 v[110:113], v[196:199], v[176:179], v[110:113]
	global_load_lds_dwordx4 v203, s[22:23]
	s_add_u32 m0, s9, 0xc000
	v_mfma_f32_16x16x32_bf16 v[114:117], v[184:187], v[180:183], v[114:117]
	global_load_lds_dwordx4 v204, s[24:25]
	s_add_u32 m0, s9, 0xc400
	v_mfma_f32_16x16x32_bf16 v[118:121], v[188:191], v[180:183], v[118:121]
	global_load_lds_dwordx4 v205, s[24:25]
	s_add_u32 m0, s9, 0xc800
	v_mfma_f32_16x16x32_bf16 v[122:125], v[192:195], v[180:183], v[122:125]
	global_load_lds_dwordx4 v204, s[52:53]
	s_add_u32 m0, s9, 0xcc00
	v_mfma_f32_16x16x32_bf16 v[126:129], v[196:199], v[180:183], v[126:129]
	global_load_lds_dwordx4 v205, s[52:53]
	s_waitcnt lgkmcnt(0)
	v_mfma_f32_16x16x32_bf16 v[66:69], v[152:155], v[136:139], v[66:69]
	ds_read_b128 v[168:171], v229 offset:0
	v_mfma_f32_16x16x32_bf16 v[70:73], v[156:159], v[136:139], v[70:73]
	ds_read_b128 v[172:175], v229 offset:2048
	v_mfma_f32_16x16x32_bf16 v[74:77], v[160:163], v[136:139], v[74:77]
	ds_read_b128 v[176:179], v229 offset:4096
	v_mfma_f32_16x16x32_bf16 v[78:81], v[164:167], v[136:139], v[78:81]
	ds_read_b128 v[180:183], v229 offset:6144
	v_mfma_f32_16x16x32_bf16 v[82:85], v[152:155], v[140:143], v[82:85]
	ds_read_b128 v[184:187], v235 offset:0
	v_mfma_f32_16x16x32_bf16 v[86:89], v[156:159], v[140:143], v[86:89]
	ds_read_b128 v[188:191], v235 offset:2048
	v_mfma_f32_16x16x32_bf16 v[90:93], v[160:163], v[140:143], v[90:93]
	ds_read_b128 v[192:195], v235 offset:4096
	v_mfma_f32_16x16x32_bf16 v[94:97], v[164:167], v[140:143], v[94:97]
	ds_read_b128 v[196:199], v235 offset:6144
	v_mfma_f32_16x16x32_bf16 v[98:101], v[152:155], v[144:147], v[98:101]
	v_mfma_f32_16x16x32_bf16 v[102:105], v[156:159], v[144:147], v[102:105]
	v_mfma_f32_16x16x32_bf16 v[106:109], v[160:163], v[144:147], v[106:109]
	v_mfma_f32_16x16x32_bf16 v[110:113], v[164:167], v[144:147], v[110:113]
	v_mfma_f32_16x16x32_bf16 v[114:117], v[152:155], v[148:151], v[114:117]
	v_mfma_f32_16x16x32_bf16 v[118:121], v[156:159], v[148:151], v[118:121]
	v_mfma_f32_16x16x32_bf16 v[122:125], v[160:163], v[148:151], v[122:125]
	v_mfma_f32_16x16x32_bf16 v[126:129], v[164:167], v[148:151], v[126:129]
	s_waitcnt vmcnt(12) lgkmcnt(0)
	s_barrier
	s_add_u32 s14, s4, 0x680
	s_addc_u32 s15, s5, 0
	v_mfma_f32_16x16x32_bf16 v[66:69], v[184:187], v[168:171], v[66:69]
	ds_read_b128 v[136:139], v218 offset:0
	s_add_u32 s22, s4, 0x10680
	s_addc_u32 s23, s5, 0
	v_mfma_f32_16x16x32_bf16 v[70:73], v[188:191], v[168:171], v[70:73]
	ds_read_b128 v[140:143], v218 offset:2048
	s_add_u32 s24, s6, 0x40680
	s_addc_u32 s25, s7, 0
	v_mfma_f32_16x16x32_bf16 v[74:77], v[192:195], v[168:171], v[74:77]
	ds_read_b128 v[144:147], v218 offset:4096
	s_add_u32 s52, s6, 0x48680
	s_addc_u32 s53, s7, 0
	v_mfma_f32_16x16x32_bf16 v[78:81], v[196:199], v[168:171], v[78:81]
	ds_read_b128 v[148:151], v218 offset:6144
	s_add_u32 m0, s8, 0x18000
	v_mfma_f32_16x16x32_bf16 v[82:85], v[184:187], v[172:175], v[82:85]
	global_load_lds_dwordx4 v200, s[14:15]
	ds_read_b128 v[152:155], v230 offset:0
	s_add_u32 m0, s8, 0x18400
	v_mfma_f32_16x16x32_bf16 v[86:89], v[188:191], v[172:175], v[86:89]
	global_load_lds_dwordx4 v201, s[14:15]
	ds_read_b128 v[156:159], v230 offset:2048
	s_add_u32 m0, s8, 0x18800
	v_mfma_f32_16x16x32_bf16 v[90:93], v[192:195], v[172:175], v[90:93]
	global_load_lds_dwordx4 v202, s[14:15]
	ds_read_b128 v[160:163], v230 offset:4096
	s_add_u32 m0, s8, 0x18c00
	v_mfma_f32_16x16x32_bf16 v[94:97], v[196:199], v[172:175], v[94:97]
	global_load_lds_dwordx4 v203, s[14:15]
	ds_read_b128 v[164:167], v230 offset:6144
	s_add_u32 m0, s8, 0x19000
	v_mfma_f32_16x16x32_bf16 v[98:101], v[184:187], v[176:179], v[98:101]
	global_load_lds_dwordx4 v200, s[22:23]
	s_add_u32 m0, s8, 0x19400
	v_mfma_f32_16x16x32_bf16 v[102:105], v[188:191], v[176:179], v[102:105]
	global_load_lds_dwordx4 v201, s[22:23]
	s_add_u32 m0, s8, 0x19800
	v_mfma_f32_16x16x32_bf16 v[106:109], v[192:195], v[176:179], v[106:109]
	global_load_lds_dwordx4 v202, s[22:23]
	s_add_u32 m0, s8, 0x19c00
	v_mfma_f32_16x16x32_bf16 v[110:113], v[196:199], v[176:179], v[110:113]
	global_load_lds_dwordx4 v203, s[22:23]
	s_add_u32 m0, s9, 0x18000
	v_mfma_f32_16x16x32_bf16 v[114:117], v[184:187], v[180:183], v[114:117]
	global_load_lds_dwordx4 v204, s[24:25]
	s_add_u32 m0, s9, 0x18400
	v_mfma_f32_16x16x32_bf16 v[118:121], v[188:191], v[180:183], v[118:121]
	global_load_lds_dwordx4 v205, s[24:25]
	s_add_u32 m0, s9, 0x18800
	v_mfma_f32_16x16x32_bf16 v[122:125], v[192:195], v[180:183], v[122:125]
	global_load_lds_dwordx4 v204, s[52:53]
	s_add_u32 m0, s9, 0x18c00
	v_mfma_f32_16x16x32_bf16 v[126:129], v[196:199], v[180:183], v[126:129]
	global_load_lds_dwordx4 v205, s[52:53]
	s_waitcnt lgkmcnt(0)
	v_mfma_f32_16x16x32_bf16 v[66:69], v[152:155], v[136:139], v[66:69]
	ds_read_b128 v[168:171], v225 offset:0
	v_mfma_f32_16x16x32_bf16 v[70:73], v[156:159], v[136:139], v[70:73]
	ds_read_b128 v[172:175], v225 offset:2048
	v_mfma_f32_16x16x32_bf16 v[74:77], v[160:163], v[136:139], v[74:77]
	ds_read_b128 v[176:179], v225 offset:4096
	v_mfma_f32_16x16x32_bf16 v[78:81], v[164:167], v[136:139], v[78:81]
	ds_read_b128 v[180:183], v225 offset:6144
	v_mfma_f32_16x16x32_bf16 v[82:85], v[152:155], v[140:143], v[82:85]
	ds_read_b128 v[184:187], v233 offset:0
	v_mfma_f32_16x16x32_bf16 v[86:89], v[156:159], v[140:143], v[86:89]
	ds_read_b128 v[188:191], v233 offset:2048
	v_mfma_f32_16x16x32_bf16 v[90:93], v[160:163], v[140:143], v[90:93]
	ds_read_b128 v[192:195], v233 offset:4096
	v_mfma_f32_16x16x32_bf16 v[94:97], v[164:167], v[140:143], v[94:97]
	ds_read_b128 v[196:199], v233 offset:6144
	v_mfma_f32_16x16x32_bf16 v[98:101], v[152:155], v[144:147], v[98:101]
	v_mfma_f32_16x16x32_bf16 v[102:105], v[156:159], v[144:147], v[102:105]
	v_mfma_f32_16x16x32_bf16 v[106:109], v[160:163], v[144:147], v[106:109]
	v_mfma_f32_16x16x32_bf16 v[110:113], v[164:167], v[144:147], v[110:113]
	v_mfma_f32_16x16x32_bf16 v[114:117], v[152:155], v[148:151], v[114:117]
	v_mfma_f32_16x16x32_bf16 v[118:121], v[156:159], v[148:151], v[118:121]
	v_mfma_f32_16x16x32_bf16 v[122:125], v[160:163], v[148:151], v[122:125]
	v_mfma_f32_16x16x32_bf16 v[126:129], v[164:167], v[148:151], v[126:129]
	s_waitcnt vmcnt(12) lgkmcnt(0)
	s_barrier
	s_add_u32 s14, s4, 0x700
	s_addc_u32 s15, s5, 0
	v_mfma_f32_16x16x32_bf16 v[66:69], v[184:187], v[168:171], v[66:69]
	ds_read_b128 v[136:139], v219 offset:0
	s_add_u32 s22, s4, 0x10700
	s_addc_u32 s23, s5, 0
	v_mfma_f32_16x16x32_bf16 v[70:73], v[188:191], v[168:171], v[70:73]
	ds_read_b128 v[140:143], v219 offset:2048
	s_add_u32 s24, s6, 0x40700
	s_addc_u32 s25, s7, 0
	v_mfma_f32_16x16x32_bf16 v[74:77], v[192:195], v[168:171], v[74:77]
	ds_read_b128 v[144:147], v219 offset:4096
	s_add_u32 s52, s6, 0x48700
	s_addc_u32 s53, s7, 0
	v_mfma_f32_16x16x32_bf16 v[78:81], v[196:199], v[168:171], v[78:81]
	ds_read_b128 v[148:151], v219 offset:6144
	s_mov_b32 m0, s8
	v_mfma_f32_16x16x32_bf16 v[82:85], v[184:187], v[172:175], v[82:85]
	global_load_lds_dwordx4 v200, s[14:15]
	ds_read_b128 v[152:155], v231 offset:0
	s_add_u32 m0, s8, 0x400
	v_mfma_f32_16x16x32_bf16 v[86:89], v[188:191], v[172:175], v[86:89]
	global_load_lds_dwordx4 v201, s[14:15]
	ds_read_b128 v[156:159], v231 offset:2048
	s_add_u32 m0, s8, 0x800
	v_mfma_f32_16x16x32_bf16 v[90:93], v[192:195], v[172:175], v[90:93]
	global_load_lds_dwordx4 v202, s[14:15]
	ds_read_b128 v[160:163], v231 offset:4096
	s_add_u32 m0, s8, 0xc00
	v_mfma_f32_16x16x32_bf16 v[94:97], v[196:199], v[172:175], v[94:97]
	global_load_lds_dwordx4 v203, s[14:15]
	ds_read_b128 v[164:167], v231 offset:6144
	s_add_u32 m0, s8, 0x1000
	v_mfma_f32_16x16x32_bf16 v[98:101], v[184:187], v[176:179], v[98:101]
	global_load_lds_dwordx4 v200, s[22:23]
	s_add_u32 m0, s8, 0x1400
	v_mfma_f32_16x16x32_bf16 v[102:105], v[188:191], v[176:179], v[102:105]
	global_load_lds_dwordx4 v201, s[22:23]
	s_add_u32 m0, s8, 0x1800
	v_mfma_f32_16x16x32_bf16 v[106:109], v[192:195], v[176:179], v[106:109]
	global_load_lds_dwordx4 v202, s[22:23]
	s_add_u32 m0, s8, 0x1c00
	v_mfma_f32_16x16x32_bf16 v[110:113], v[196:199], v[176:179], v[110:113]
	global_load_lds_dwordx4 v203, s[22:23]
	s_mov_b32 m0, s9
	v_mfma_f32_16x16x32_bf16 v[114:117], v[184:187], v[180:183], v[114:117]
	global_load_lds_dwordx4 v204, s[24:25]
	s_add_u32 m0, s9, 0x400
	v_mfma_f32_16x16x32_bf16 v[118:121], v[188:191], v[180:183], v[118:121]
	global_load_lds_dwordx4 v205, s[24:25]
	s_add_u32 m0, s9, 0x800
	v_mfma_f32_16x16x32_bf16 v[122:125], v[192:195], v[180:183], v[122:125]
	global_load_lds_dwordx4 v204, s[52:53]
	s_add_u32 m0, s9, 0xc00
	v_mfma_f32_16x16x32_bf16 v[126:129], v[196:199], v[180:183], v[126:129]
	global_load_lds_dwordx4 v205, s[52:53]
	s_waitcnt lgkmcnt(0)
	v_mfma_f32_16x16x32_bf16 v[66:69], v[152:155], v[136:139], v[66:69]
	ds_read_b128 v[168:171], v228 offset:0
	v_mfma_f32_16x16x32_bf16 v[70:73], v[156:159], v[136:139], v[70:73]
	ds_read_b128 v[172:175], v228 offset:2048
	v_mfma_f32_16x16x32_bf16 v[74:77], v[160:163], v[136:139], v[74:77]
	ds_read_b128 v[176:179], v228 offset:4096
	v_mfma_f32_16x16x32_bf16 v[78:81], v[164:167], v[136:139], v[78:81]
	ds_read_b128 v[180:183], v228 offset:6144
	v_mfma_f32_16x16x32_bf16 v[82:85], v[152:155], v[140:143], v[82:85]
	ds_read_b128 v[184:187], v234 offset:0
	v_mfma_f32_16x16x32_bf16 v[86:89], v[156:159], v[140:143], v[86:89]
	ds_read_b128 v[188:191], v234 offset:2048
	v_mfma_f32_16x16x32_bf16 v[90:93], v[160:163], v[140:143], v[90:93]
	ds_read_b128 v[192:195], v234 offset:4096
	v_mfma_f32_16x16x32_bf16 v[94:97], v[164:167], v[140:143], v[94:97]
	ds_read_b128 v[196:199], v234 offset:6144
	v_mfma_f32_16x16x32_bf16 v[98:101], v[152:155], v[144:147], v[98:101]
	v_mfma_f32_16x16x32_bf16 v[102:105], v[156:159], v[144:147], v[102:105]
	v_mfma_f32_16x16x32_bf16 v[106:109], v[160:163], v[144:147], v[106:109]
	v_mfma_f32_16x16x32_bf16 v[110:113], v[164:167], v[144:147], v[110:113]
	v_mfma_f32_16x16x32_bf16 v[114:117], v[152:155], v[148:151], v[114:117]
	v_mfma_f32_16x16x32_bf16 v[118:121], v[156:159], v[148:151], v[118:121]
	v_mfma_f32_16x16x32_bf16 v[122:125], v[160:163], v[148:151], v[122:125]
	v_mfma_f32_16x16x32_bf16 v[126:129], v[164:167], v[148:151], v[126:129]
	s_waitcnt vmcnt(12) lgkmcnt(0)
	s_barrier
	s_add_u32 s14, s4, 0x780
	s_addc_u32 s15, s5, 0
	v_mfma_f32_16x16x32_bf16 v[66:69], v[184:187], v[168:171], v[66:69]
	ds_read_b128 v[136:139], v224 offset:0
	s_add_u32 s22, s4, 0x10780
	s_addc_u32 s23, s5, 0
	v_mfma_f32_16x16x32_bf16 v[70:73], v[188:191], v[168:171], v[70:73]
	ds_read_b128 v[140:143], v224 offset:2048
	s_add_u32 s24, s6, 0x40780
	s_addc_u32 s25, s7, 0
	v_mfma_f32_16x16x32_bf16 v[74:77], v[192:195], v[168:171], v[74:77]
	ds_read_b128 v[144:147], v224 offset:4096
	s_add_u32 s52, s6, 0x48780
	s_addc_u32 s53, s7, 0
	v_mfma_f32_16x16x32_bf16 v[78:81], v[196:199], v[168:171], v[78:81]
	ds_read_b128 v[148:151], v224 offset:6144
	s_add_u32 m0, s8, 0xc000
	v_mfma_f32_16x16x32_bf16 v[82:85], v[184:187], v[172:175], v[82:85]
	global_load_lds_dwordx4 v200, s[14:15]
	ds_read_b128 v[152:155], v232 offset:0
	s_add_u32 m0, s8, 0xc400
	v_mfma_f32_16x16x32_bf16 v[86:89], v[188:191], v[172:175], v[86:89]
	global_load_lds_dwordx4 v201, s[14:15]
	ds_read_b128 v[156:159], v232 offset:2048
	s_add_u32 m0, s8, 0xc800
	v_mfma_f32_16x16x32_bf16 v[90:93], v[192:195], v[172:175], v[90:93]
	global_load_lds_dwordx4 v202, s[14:15]
	ds_read_b128 v[160:163], v232 offset:4096
	s_add_u32 m0, s8, 0xcc00
	v_mfma_f32_16x16x32_bf16 v[94:97], v[196:199], v[172:175], v[94:97]
	global_load_lds_dwordx4 v203, s[14:15]
	ds_read_b128 v[164:167], v232 offset:6144
	s_add_u32 m0, s8, 0xd000
	v_mfma_f32_16x16x32_bf16 v[98:101], v[184:187], v[176:179], v[98:101]
	global_load_lds_dwordx4 v200, s[22:23]
	s_add_u32 m0, s8, 0xd400
	v_mfma_f32_16x16x32_bf16 v[102:105], v[188:191], v[176:179], v[102:105]
	global_load_lds_dwordx4 v201, s[22:23]
	s_add_u32 m0, s8, 0xd800
	v_mfma_f32_16x16x32_bf16 v[106:109], v[192:195], v[176:179], v[106:109]
	global_load_lds_dwordx4 v202, s[22:23]
	s_add_u32 m0, s8, 0xdc00
	v_mfma_f32_16x16x32_bf16 v[110:113], v[196:199], v[176:179], v[110:113]
	global_load_lds_dwordx4 v203, s[22:23]
	s_add_u32 m0, s9, 0xc000
	v_mfma_f32_16x16x32_bf16 v[114:117], v[184:187], v[180:183], v[114:117]
	global_load_lds_dwordx4 v204, s[24:25]
	s_add_u32 m0, s9, 0xc400
	v_mfma_f32_16x16x32_bf16 v[118:121], v[188:191], v[180:183], v[118:121]
	global_load_lds_dwordx4 v205, s[24:25]
	s_add_u32 m0, s9, 0xc800
	v_mfma_f32_16x16x32_bf16 v[122:125], v[192:195], v[180:183], v[122:125]
	global_load_lds_dwordx4 v204, s[52:53]
	s_add_u32 m0, s9, 0xcc00
	v_mfma_f32_16x16x32_bf16 v[126:129], v[196:199], v[180:183], v[126:129]
	global_load_lds_dwordx4 v205, s[52:53]
	s_waitcnt lgkmcnt(0)
	v_mfma_f32_16x16x32_bf16 v[66:69], v[152:155], v[136:139], v[66:69]
	ds_read_b128 v[168:171], v229 offset:0
	v_mfma_f32_16x16x32_bf16 v[70:73], v[156:159], v[136:139], v[70:73]
	ds_read_b128 v[172:175], v229 offset:2048
	v_mfma_f32_16x16x32_bf16 v[74:77], v[160:163], v[136:139], v[74:77]
	ds_read_b128 v[176:179], v229 offset:4096
	v_mfma_f32_16x16x32_bf16 v[78:81], v[164:167], v[136:139], v[78:81]
	ds_read_b128 v[180:183], v229 offset:6144
	v_mfma_f32_16x16x32_bf16 v[82:85], v[152:155], v[140:143], v[82:85]
	ds_read_b128 v[184:187], v235 offset:0
	v_mfma_f32_16x16x32_bf16 v[86:89], v[156:159], v[140:143], v[86:89]
	ds_read_b128 v[188:191], v235 offset:2048
	v_mfma_f32_16x16x32_bf16 v[90:93], v[160:163], v[140:143], v[90:93]
	ds_read_b128 v[192:195], v235 offset:4096
	v_mfma_f32_16x16x32_bf16 v[94:97], v[164:167], v[140:143], v[94:97]
	ds_read_b128 v[196:199], v235 offset:6144
	v_mfma_f32_16x16x32_bf16 v[98:101], v[152:155], v[144:147], v[98:101]
	v_mfma_f32_16x16x32_bf16 v[102:105], v[156:159], v[144:147], v[102:105]
	v_mfma_f32_16x16x32_bf16 v[106:109], v[160:163], v[144:147], v[106:109]
	v_mfma_f32_16x16x32_bf16 v[110:113], v[164:167], v[144:147], v[110:113]
	v_mfma_f32_16x16x32_bf16 v[114:117], v[152:155], v[148:151], v[114:117]
	v_mfma_f32_16x16x32_bf16 v[118:121], v[156:159], v[148:151], v[118:121]
	v_mfma_f32_16x16x32_bf16 v[122:125], v[160:163], v[148:151], v[122:125]
	v_mfma_f32_16x16x32_bf16 v[126:129], v[164:167], v[148:151], v[126:129]
	s_waitcnt vmcnt(12) lgkmcnt(0)
	s_barrier
	s_add_u32 s14, s4, 0x0
	s_addc_u32 s15, s5, 0
	v_mfma_f32_16x16x32_bf16 v[66:69], v[184:187], v[168:171], v[66:69]
	ds_read_b128 v[136:139], v218 offset:0
	s_add_u32 s22, s4, 0x10000
	s_addc_u32 s23, s5, 0
	v_mfma_f32_16x16x32_bf16 v[70:73], v[188:191], v[168:171], v[70:73]
	ds_read_b128 v[140:143], v218 offset:2048
	s_add_u32 s24, s6, 0x80000
	s_addc_u32 s25, s7, 0
	v_mfma_f32_16x16x32_bf16 v[74:77], v[192:195], v[168:171], v[74:77]
	ds_read_b128 v[144:147], v218 offset:4096
	s_add_u32 s52, s6, 0x88000
	s_addc_u32 s53, s7, 0
	v_mfma_f32_16x16x32_bf16 v[78:81], v[196:199], v[168:171], v[78:81]
	ds_read_b128 v[148:151], v218 offset:6144
	s_add_u32 m0, s8, 0x18000
	v_mfma_f32_16x16x32_bf16 v[82:85], v[184:187], v[172:175], v[82:85]
	global_load_lds_dwordx4 v200, s[14:15]
	ds_read_b128 v[152:155], v230 offset:0
	s_add_u32 m0, s8, 0x18400
	v_mfma_f32_16x16x32_bf16 v[86:89], v[188:191], v[172:175], v[86:89]
	global_load_lds_dwordx4 v201, s[14:15]
	ds_read_b128 v[156:159], v230 offset:2048
	s_add_u32 m0, s8, 0x18800
	v_mfma_f32_16x16x32_bf16 v[90:93], v[192:195], v[172:175], v[90:93]
	global_load_lds_dwordx4 v202, s[14:15]
	ds_read_b128 v[160:163], v230 offset:4096
	s_add_u32 m0, s8, 0x18c00
	v_mfma_f32_16x16x32_bf16 v[94:97], v[196:199], v[172:175], v[94:97]
	global_load_lds_dwordx4 v203, s[14:15]
	ds_read_b128 v[164:167], v230 offset:6144
	s_add_u32 m0, s8, 0x19000
	v_mfma_f32_16x16x32_bf16 v[98:101], v[184:187], v[176:179], v[98:101]
	global_load_lds_dwordx4 v200, s[22:23]
	s_add_u32 m0, s8, 0x19400
	v_mfma_f32_16x16x32_bf16 v[102:105], v[188:191], v[176:179], v[102:105]
	global_load_lds_dwordx4 v201, s[22:23]
	s_add_u32 m0, s8, 0x19800
	v_mfma_f32_16x16x32_bf16 v[106:109], v[192:195], v[176:179], v[106:109]
	global_load_lds_dwordx4 v202, s[22:23]
	s_add_u32 m0, s8, 0x19c00
	v_mfma_f32_16x16x32_bf16 v[110:113], v[196:199], v[176:179], v[110:113]
	global_load_lds_dwordx4 v203, s[22:23]
	s_add_u32 m0, s9, 0x18000
	v_mfma_f32_16x16x32_bf16 v[114:117], v[184:187], v[180:183], v[114:117]
	global_load_lds_dwordx4 v204, s[24:25]
	s_add_u32 m0, s9, 0x18400
	v_mfma_f32_16x16x32_bf16 v[118:121], v[188:191], v[180:183], v[118:121]
	global_load_lds_dwordx4 v205, s[24:25]
	s_add_u32 m0, s9, 0x18800
	v_mfma_f32_16x16x32_bf16 v[122:125], v[192:195], v[180:183], v[122:125]
	global_load_lds_dwordx4 v204, s[52:53]
	s_add_u32 m0, s9, 0x18c00
	v_mfma_f32_16x16x32_bf16 v[126:129], v[196:199], v[180:183], v[126:129]
	global_load_lds_dwordx4 v205, s[52:53]
	s_waitcnt lgkmcnt(0)
	v_mfma_f32_16x16x32_bf16 v[66:69], v[152:155], v[136:139], v[66:69]
	ds_read_b128 v[168:171], v225 offset:0
	v_mfma_f32_16x16x32_bf16 v[70:73], v[156:159], v[136:139], v[70:73]
	ds_read_b128 v[172:175], v225 offset:2048
	v_mfma_f32_16x16x32_bf16 v[74:77], v[160:163], v[136:139], v[74:77]
	ds_read_b128 v[176:179], v225 offset:4096
	v_mfma_f32_16x16x32_bf16 v[78:81], v[164:167], v[136:139], v[78:81]
	ds_read_b128 v[180:183], v225 offset:6144
	v_mfma_f32_16x16x32_bf16 v[82:85], v[152:155], v[140:143], v[82:85]
	ds_read_b128 v[184:187], v233 offset:0
	v_mfma_f32_16x16x32_bf16 v[86:89], v[156:159], v[140:143], v[86:89]
	ds_read_b128 v[188:191], v233 offset:2048
	v_mfma_f32_16x16x32_bf16 v[90:93], v[160:163], v[140:143], v[90:93]
	ds_read_b128 v[192:195], v233 offset:4096
	v_mfma_f32_16x16x32_bf16 v[94:97], v[164:167], v[140:143], v[94:97]
	ds_read_b128 v[196:199], v233 offset:6144
	v_mfma_f32_16x16x32_bf16 v[98:101], v[152:155], v[144:147], v[98:101]
	v_mfma_f32_16x16x32_bf16 v[102:105], v[156:159], v[144:147], v[102:105]
	v_mfma_f32_16x16x32_bf16 v[106:109], v[160:163], v[144:147], v[106:109]
	v_mfma_f32_16x16x32_bf16 v[110:113], v[164:167], v[144:147], v[110:113]
	v_mfma_f32_16x16x32_bf16 v[114:117], v[152:155], v[148:151], v[114:117]
	v_mfma_f32_16x16x32_bf16 v[118:121], v[156:159], v[148:151], v[118:121]
	v_mfma_f32_16x16x32_bf16 v[122:125], v[160:163], v[148:151], v[122:125]
	v_mfma_f32_16x16x32_bf16 v[126:129], v[164:167], v[148:151], v[126:129]
	s_waitcnt vmcnt(12) lgkmcnt(0)
	s_barrier
	s_add_u32 s14, s4, 0x80
	s_addc_u32 s15, s5, 0
	v_mfma_f32_16x16x32_bf16 v[66:69], v[184:187], v[168:171], v[66:69]
	ds_read_b128 v[136:139], v219 offset:0
	s_add_u32 s22, s4, 0x10080
	s_addc_u32 s23, s5, 0
	v_mfma_f32_16x16x32_bf16 v[70:73], v[188:191], v[168:171], v[70:73]
	ds_read_b128 v[140:143], v219 offset:2048
	s_add_u32 s24, s6, 0x80080
	s_addc_u32 s25, s7, 0
	v_mfma_f32_16x16x32_bf16 v[74:77], v[192:195], v[168:171], v[74:77]
	ds_read_b128 v[144:147], v219 offset:4096
	s_add_u32 s52, s6, 0x88080
	s_addc_u32 s53, s7, 0
	v_mfma_f32_16x16x32_bf16 v[78:81], v[196:199], v[168:171], v[78:81]
	ds_read_b128 v[148:151], v219 offset:6144
	s_mov_b32 m0, s8
	v_mfma_f32_16x16x32_bf16 v[82:85], v[184:187], v[172:175], v[82:85]
	global_load_lds_dwordx4 v200, s[14:15]
	ds_read_b128 v[152:155], v231 offset:0
	s_add_u32 m0, s8, 0x400
	v_mfma_f32_16x16x32_bf16 v[86:89], v[188:191], v[172:175], v[86:89]
	global_load_lds_dwordx4 v201, s[14:15]
	ds_read_b128 v[156:159], v231 offset:2048
	s_add_u32 m0, s8, 0x800
	v_mfma_f32_16x16x32_bf16 v[90:93], v[192:195], v[172:175], v[90:93]
	global_load_lds_dwordx4 v202, s[14:15]
	ds_read_b128 v[160:163], v231 offset:4096
	s_add_u32 m0, s8, 0xc00
	v_mfma_f32_16x16x32_bf16 v[94:97], v[196:199], v[172:175], v[94:97]
	global_load_lds_dwordx4 v203, s[14:15]
	ds_read_b128 v[164:167], v231 offset:6144
	s_add_u32 m0, s8, 0x1000
	v_mfma_f32_16x16x32_bf16 v[98:101], v[184:187], v[176:179], v[98:101]
	global_load_lds_dwordx4 v200, s[22:23]
	s_add_u32 m0, s8, 0x1400
	v_mfma_f32_16x16x32_bf16 v[102:105], v[188:191], v[176:179], v[102:105]
	global_load_lds_dwordx4 v201, s[22:23]
	s_add_u32 m0, s8, 0x1800
	v_mfma_f32_16x16x32_bf16 v[106:109], v[192:195], v[176:179], v[106:109]
	global_load_lds_dwordx4 v202, s[22:23]
	s_add_u32 m0, s8, 0x1c00
	v_mfma_f32_16x16x32_bf16 v[110:113], v[196:199], v[176:179], v[110:113]
	global_load_lds_dwordx4 v203, s[22:23]
	s_mov_b32 m0, s9
	v_mfma_f32_16x16x32_bf16 v[114:117], v[184:187], v[180:183], v[114:117]
	global_load_lds_dwordx4 v204, s[24:25]
	s_add_u32 m0, s9, 0x400
	v_mfma_f32_16x16x32_bf16 v[118:121], v[188:191], v[180:183], v[118:121]
	global_load_lds_dwordx4 v205, s[24:25]
	s_add_u32 m0, s9, 0x800
	v_mfma_f32_16x16x32_bf16 v[122:125], v[192:195], v[180:183], v[122:125]
	global_load_lds_dwordx4 v204, s[52:53]
	s_add_u32 m0, s9, 0xc00
	v_mfma_f32_16x16x32_bf16 v[126:129], v[196:199], v[180:183], v[126:129]
	global_load_lds_dwordx4 v205, s[52:53]
	s_waitcnt lgkmcnt(0)
	v_mfma_f32_16x16x32_bf16 v[66:69], v[152:155], v[136:139], v[66:69]
	ds_read_b128 v[168:171], v228 offset:0
	v_mfma_f32_16x16x32_bf16 v[70:73], v[156:159], v[136:139], v[70:73]
	ds_read_b128 v[172:175], v228 offset:2048
	v_mfma_f32_16x16x32_bf16 v[74:77], v[160:163], v[136:139], v[74:77]
	ds_read_b128 v[176:179], v228 offset:4096
	v_mfma_f32_16x16x32_bf16 v[78:81], v[164:167], v[136:139], v[78:81]
	ds_read_b128 v[180:183], v228 offset:6144
	v_mfma_f32_16x16x32_bf16 v[82:85], v[152:155], v[140:143], v[82:85]
	ds_read_b128 v[184:187], v234 offset:0
	v_mfma_f32_16x16x32_bf16 v[86:89], v[156:159], v[140:143], v[86:89]
	ds_read_b128 v[188:191], v234 offset:2048
	v_mfma_f32_16x16x32_bf16 v[90:93], v[160:163], v[140:143], v[90:93]
	ds_read_b128 v[192:195], v234 offset:4096
	v_mfma_f32_16x16x32_bf16 v[94:97], v[164:167], v[140:143], v[94:97]
	ds_read_b128 v[196:199], v234 offset:6144
	v_mfma_f32_16x16x32_bf16 v[98:101], v[152:155], v[144:147], v[98:101]
	v_mfma_f32_16x16x32_bf16 v[102:105], v[156:159], v[144:147], v[102:105]
	v_mfma_f32_16x16x32_bf16 v[106:109], v[160:163], v[144:147], v[106:109]
	v_mfma_f32_16x16x32_bf16 v[110:113], v[164:167], v[144:147], v[110:113]
	v_mfma_f32_16x16x32_bf16 v[114:117], v[152:155], v[148:151], v[114:117]
	v_mfma_f32_16x16x32_bf16 v[118:121], v[156:159], v[148:151], v[118:121]
	v_mfma_f32_16x16x32_bf16 v[122:125], v[160:163], v[148:151], v[122:125]
	v_mfma_f32_16x16x32_bf16 v[126:129], v[164:167], v[148:151], v[126:129]
	s_waitcnt vmcnt(12) lgkmcnt(0)
	s_barrier
	s_add_u32 s14, s4, 0x100
	s_addc_u32 s15, s5, 0
	v_mfma_f32_16x16x32_bf16 v[66:69], v[184:187], v[168:171], v[66:69]
	ds_read_b128 v[136:139], v224 offset:0
	s_add_u32 s22, s4, 0x10100
	s_addc_u32 s23, s5, 0
	v_mfma_f32_16x16x32_bf16 v[70:73], v[188:191], v[168:171], v[70:73]
	ds_read_b128 v[140:143], v224 offset:2048
	s_add_u32 s24, s6, 0x80100
	s_addc_u32 s25, s7, 0
	v_mfma_f32_16x16x32_bf16 v[74:77], v[192:195], v[168:171], v[74:77]
	ds_read_b128 v[144:147], v224 offset:4096
	s_add_u32 s52, s6, 0x88100
	s_addc_u32 s53, s7, 0
	v_mfma_f32_16x16x32_bf16 v[78:81], v[196:199], v[168:171], v[78:81]
	ds_read_b128 v[148:151], v224 offset:6144
	s_add_u32 m0, s8, 0xc000
	v_mfma_f32_16x16x32_bf16 v[82:85], v[184:187], v[172:175], v[82:85]
	global_load_lds_dwordx4 v200, s[14:15]
	ds_read_b128 v[152:155], v232 offset:0
	s_add_u32 m0, s8, 0xc400
	v_mfma_f32_16x16x32_bf16 v[86:89], v[188:191], v[172:175], v[86:89]
	global_load_lds_dwordx4 v201, s[14:15]
	ds_read_b128 v[156:159], v232 offset:2048
	s_add_u32 m0, s8, 0xc800
	v_mfma_f32_16x16x32_bf16 v[90:93], v[192:195], v[172:175], v[90:93]
	global_load_lds_dwordx4 v202, s[14:15]
	ds_read_b128 v[160:163], v232 offset:4096
	s_add_u32 m0, s8, 0xcc00
	v_mfma_f32_16x16x32_bf16 v[94:97], v[196:199], v[172:175], v[94:97]
	global_load_lds_dwordx4 v203, s[14:15]
	ds_read_b128 v[164:167], v232 offset:6144
	s_add_u32 m0, s8, 0xd000
	v_mfma_f32_16x16x32_bf16 v[98:101], v[184:187], v[176:179], v[98:101]
	global_load_lds_dwordx4 v200, s[22:23]
	s_add_u32 m0, s8, 0xd400
	v_mfma_f32_16x16x32_bf16 v[102:105], v[188:191], v[176:179], v[102:105]
	global_load_lds_dwordx4 v201, s[22:23]
	s_add_u32 m0, s8, 0xd800
	v_mfma_f32_16x16x32_bf16 v[106:109], v[192:195], v[176:179], v[106:109]
	global_load_lds_dwordx4 v202, s[22:23]
	s_add_u32 m0, s8, 0xdc00
	v_mfma_f32_16x16x32_bf16 v[110:113], v[196:199], v[176:179], v[110:113]
	global_load_lds_dwordx4 v203, s[22:23]
	s_add_u32 m0, s9, 0xc000
	v_mfma_f32_16x16x32_bf16 v[114:117], v[184:187], v[180:183], v[114:117]
	global_load_lds_dwordx4 v204, s[24:25]
	s_add_u32 m0, s9, 0xc400
	v_mfma_f32_16x16x32_bf16 v[118:121], v[188:191], v[180:183], v[118:121]
	global_load_lds_dwordx4 v205, s[24:25]
	s_add_u32 m0, s9, 0xc800
	v_mfma_f32_16x16x32_bf16 v[122:125], v[192:195], v[180:183], v[122:125]
	global_load_lds_dwordx4 v204, s[52:53]
	s_add_u32 m0, s9, 0xcc00
	v_mfma_f32_16x16x32_bf16 v[126:129], v[196:199], v[180:183], v[126:129]
	global_load_lds_dwordx4 v205, s[52:53]
	s_waitcnt lgkmcnt(0)
	v_mfma_f32_16x16x32_bf16 v[2:5], v[152:155], v[136:139], 0
	ds_read_b128 v[168:171], v229 offset:0
	s_add_u32 s10, s28, s13
	s_addc_u32 s11, s29, 0
	s_add_u32 s13, s13, 0x10000
	v_mfma_f32_16x16x32_bf16 v[6:9], v[156:159], v[136:139], 0
	ds_read_b128 v[172:175], v229 offset:2048
	v_mul_f32_e32 v66, s12, v66
	v_mul_f32_e32 v67, s12, v67
	v_mfma_f32_16x16x32_bf16 v[10:13], v[160:163], v[136:139], 0
	ds_read_b128 v[176:179], v229 offset:4096
	v_mul_f32_e32 v68, s12, v68
	v_mul_f32_e32 v69, s12, v69
	v_mul_f32_e32 v70, s12, v70
	v_mfma_f32_16x16x32_bf16 v[14:17], v[164:167], v[136:139], 0
	ds_read_b128 v[180:183], v229 offset:6144
	v_mul_f32_e32 v71, s12, v71
	v_mul_f32_e32 v72, s12, v72
	v_mfma_f32_16x16x32_bf16 v[18:21], v[152:155], v[140:143], 0
	ds_read_b128 v[184:187], v235 offset:0
	v_mul_f32_e32 v73, s12, v73
	v_exp_f32_e32 v66, v66
	v_mfma_f32_16x16x32_bf16 v[22:25], v[156:159], v[140:143], 0
	ds_read_b128 v[188:191], v235 offset:2048
	v_exp_f32_e32 v67, v67
	v_exp_f32_e32 v68, v68
	v_exp_f32_e32 v69, v69
	v_mfma_f32_16x16x32_bf16 v[26:29], v[160:163], v[140:143], 0
	ds_read_b128 v[192:195], v235 offset:4096
	v_exp_f32_e32 v70, v70
	v_exp_f32_e32 v71, v71
	v_mfma_f32_16x16x32_bf16 v[30:33], v[164:167], v[140:143], 0
	ds_read_b128 v[196:199], v235 offset:6144
	v_exp_f32_e32 v72, v72
	v_exp_f32_e32 v73, v73
	v_add_f32_e32 v66, 1.0, v66
	v_mfma_f32_16x16x32_bf16 v[34:37], v[152:155], v[144:147], 0
	v_add_f32_e32 v67, 1.0, v67
	v_add_f32_e32 v68, 1.0, v68
	v_mfma_f32_16x16x32_bf16 v[38:41], v[156:159], v[144:147], 0
	v_add_f32_e32 v69, 1.0, v69
	v_add_f32_e32 v70, 1.0, v70
	v_mfma_f32_16x16x32_bf16 v[42:45], v[160:163], v[144:147], 0
	v_add_f32_e32 v71, 1.0, v71
	v_add_f32_e32 v72, 1.0, v72
	v_add_f32_e32 v73, 1.0, v73
	v_mfma_f32_16x16x32_bf16 v[46:49], v[164:167], v[144:147], 0
	v_rcp_f32_e32 v66, v66
	v_rcp_f32_e32 v67, v67
	v_mfma_f32_16x16x32_bf16 v[50:53], v[152:155], v[148:151], 0
	v_rcp_f32_e32 v68, v68
	v_rcp_f32_e32 v69, v69
	v_mfma_f32_16x16x32_bf16 v[54:57], v[156:159], v[148:151], 0
	v_rcp_f32_e32 v70, v70
	v_rcp_f32_e32 v71, v71
	v_rcp_f32_e32 v72, v72
	v_mfma_f32_16x16x32_bf16 v[58:61], v[160:163], v[148:151], 0
	v_rcp_f32_e32 v73, v73
	v_cvt_pk_bf16_f32 v66, v66, v67
	v_mfma_f32_16x16x32_bf16 v[62:65], v[164:167], v[148:151], 0
	v_cvt_pk_bf16_f32 v67, v68, v69
	v_cvt_pk_bf16_f32 v68, v70, v71
	v_cvt_pk_bf16_f32 v69, v72, v73
	s_waitcnt vmcnt(12) lgkmcnt(0)
	s_barrier
	v_mfma_f32_16x16x32_bf16 v[2:5], v[184:187], v[168:171], v[2:5]
	ds_read_b128 v[136:139], v218 offset:0
	global_store_dwordx4 v240, v[66:69], s[10:11] offset:0
	v_mul_f32_e32 v74, s12, v74
	v_mfma_f32_16x16x32_bf16 v[6:9], v[188:191], v[168:171], v[6:9]
	ds_read_b128 v[140:143], v218 offset:2048
	v_mul_f32_e32 v75, s12, v75
	v_mul_f32_e32 v76, s12, v76
	v_mfma_f32_16x16x32_bf16 v[10:13], v[192:195], v[168:171], v[10:13]
	ds_read_b128 v[144:147], v218 offset:4096
	v_mul_f32_e32 v77, s12, v77
	v_mul_f32_e32 v78, s12, v78
	v_mfma_f32_16x16x32_bf16 v[14:17], v[196:199], v[168:171], v[14:17]
	ds_read_b128 v[148:151], v218 offset:6144
	v_mul_f32_e32 v79, s12, v79
	v_mul_f32_e32 v80, s12, v80
	v_mul_f32_e32 v81, s12, v81
	v_mfma_f32_16x16x32_bf16 v[18:21], v[184:187], v[172:175], v[18:21]
	ds_read_b128 v[152:155], v230 offset:0
	v_exp_f32_e32 v74, v74
	v_exp_f32_e32 v75, v75
	v_mfma_f32_16x16x32_bf16 v[22:25], v[188:191], v[172:175], v[22:25]
	ds_read_b128 v[156:159], v230 offset:2048
	v_exp_f32_e32 v76, v76
	v_exp_f32_e32 v77, v77
	v_mfma_f32_16x16x32_bf16 v[26:29], v[192:195], v[172:175], v[26:29]
	ds_read_b128 v[160:163], v230 offset:4096
	v_exp_f32_e32 v78, v78
	v_exp_f32_e32 v79, v79
	v_exp_f32_e32 v80, v80
	v_mfma_f32_16x16x32_bf16 v[30:33], v[196:199], v[172:175], v[30:33]
	ds_read_b128 v[164:167], v230 offset:6144
	v_exp_f32_e32 v81, v81
	v_add_f32_e32 v74, 1.0, v74
	v_mfma_f32_16x16x32_bf16 v[34:37], v[184:187], v[176:179], v[34:37]
	v_add_f32_e32 v75, 1.0, v75
	v_add_f32_e32 v76, 1.0, v76
	v_mfma_f32_16x16x32_bf16 v[38:41], v[188:191], v[176:179], v[38:41]
	v_add_f32_e32 v77, 1.0, v77
	v_add_f32_e32 v78, 1.0, v78
	v_add_f32_e32 v79, 1.0, v79
	v_mfma_f32_16x16x32_bf16 v[42:45], v[192:195], v[176:179], v[42:45]
	v_add_f32_e32 v80, 1.0, v80
	v_add_f32_e32 v81, 1.0, v81
	v_mfma_f32_16x16x32_bf16 v[46:49], v[196:199], v[176:179], v[46:49]
	v_rcp_f32_e32 v74, v74
	v_rcp_f32_e32 v75, v75
	v_mfma_f32_16x16x32_bf16 v[50:53], v[184:187], v[180:183], v[50:53]
	v_rcp_f32_e32 v76, v76
	v_rcp_f32_e32 v77, v77
	v_rcp_f32_e32 v78, v78
	v_mfma_f32_16x16x32_bf16 v[54:57], v[188:191], v[180:183], v[54:57]
	v_rcp_f32_e32 v79, v79
	v_rcp_f32_e32 v80, v80
	v_mfma_f32_16x16x32_bf16 v[58:61], v[192:195], v[180:183], v[58:61]
	v_rcp_f32_e32 v81, v81
	v_cvt_pk_bf16_f32 v74, v74, v75
	v_mfma_f32_16x16x32_bf16 v[62:65], v[196:199], v[180:183], v[62:65]
	v_cvt_pk_bf16_f32 v75, v76, v77
	v_cvt_pk_bf16_f32 v76, v78, v79
	v_cvt_pk_bf16_f32 v77, v80, v81
	s_waitcnt lgkmcnt(0)
	v_mfma_f32_16x16x32_bf16 v[2:5], v[152:155], v[136:139], v[2:5]
	ds_read_b128 v[168:171], v225 offset:0
	global_store_dwordx4 v240, v[74:77], s[10:11] offset:16
	v_mul_f32_e32 v82, s12, v82
	v_mfma_f32_16x16x32_bf16 v[6:9], v[156:159], v[136:139], v[6:9]
	ds_read_b128 v[172:175], v225 offset:2048
	v_mul_f32_e32 v83, s12, v83
	v_mul_f32_e32 v84, s12, v84
	v_mfma_f32_16x16x32_bf16 v[10:13], v[160:163], v[136:139], v[10:13]
	ds_read_b128 v[176:179], v225 offset:4096
	v_mul_f32_e32 v85, s12, v85
	v_mul_f32_e32 v86, s12, v86
	v_mul_f32_e32 v87, s12, v87
	v_mfma_f32_16x16x32_bf16 v[14:17], v[164:167], v[136:139], v[14:17]
	ds_read_b128 v[180:183], v225 offset:6144
	v_mul_f32_e32 v88, s12, v88
	v_mul_f32_e32 v89, s12, v89
	v_mfma_f32_16x16x32_bf16 v[18:21], v[152:155], v[140:143], v[18:21]
	ds_read_b128 v[184:187], v233 offset:0
	v_exp_f32_e32 v82, v82
	v_exp_f32_e32 v83, v83
	v_mfma_f32_16x16x32_bf16 v[22:25], v[156:159], v[140:143], v[22:25]
	ds_read_b128 v[188:191], v233 offset:2048
	v_exp_f32_e32 v84, v84
	v_exp_f32_e32 v85, v85
	v_exp_f32_e32 v86, v86
	v_mfma_f32_16x16x32_bf16 v[26:29], v[160:163], v[140:143], v[26:29]
	ds_read_b128 v[192:195], v233 offset:4096
	v_exp_f32_e32 v87, v87
	v_exp_f32_e32 v88, v88
	v_mfma_f32_16x16x32_bf16 v[30:33], v[164:167], v[140:143], v[30:33]
	ds_read_b128 v[196:199], v233 offset:6144
	v_exp_f32_e32 v89, v89
	v_add_f32_e32 v82, 1.0, v82
	v_add_f32_e32 v83, 1.0, v83
	v_mfma_f32_16x16x32_bf16 v[34:37], v[152:155], v[144:147], v[34:37]
	v_add_f32_e32 v84, 1.0, v84
	v_add_f32_e32 v85, 1.0, v85
	v_mfma_f32_16x16x32_bf16 v[38:41], v[156:159], v[144:147], v[38:41]
	v_add_f32_e32 v86, 1.0, v86
	v_add_f32_e32 v87, 1.0, v87
	v_mfma_f32_16x16x32_bf16 v[42:45], v[160:163], v[144:147], v[42:45]
	v_add_f32_e32 v88, 1.0, v88
	v_add_f32_e32 v89, 1.0, v89
	v_rcp_f32_e32 v82, v82
	v_mfma_f32_16x16x32_bf16 v[46:49], v[164:167], v[144:147], v[46:49]
	v_rcp_f32_e32 v83, v83
	v_rcp_f32_e32 v84, v84
	v_mfma_f32_16x16x32_bf16 v[50:53], v[152:155], v[148:151], v[50:53]
	v_rcp_f32_e32 v85, v85
	v_rcp_f32_e32 v86, v86
	v_mfma_f32_16x16x32_bf16 v[54:57], v[156:159], v[148:151], v[54:57]
	v_rcp_f32_e32 v87, v87
	v_rcp_f32_e32 v88, v88
	v_rcp_f32_e32 v89, v89
	v_mfma_f32_16x16x32_bf16 v[58:61], v[160:163], v[148:151], v[58:61]
	v_cvt_pk_bf16_f32 v82, v82, v83
	v_cvt_pk_bf16_f32 v83, v84, v85
	v_mfma_f32_16x16x32_bf16 v[62:65], v[164:167], v[148:151], v[62:65]
	v_cvt_pk_bf16_f32 v84, v86, v87
	v_cvt_pk_bf16_f32 v85, v88, v89
	global_store_dwordx4 v240, v[82:85], s[10:11] offset:2048
	s_waitcnt vmcnt(3) lgkmcnt(0)
	s_barrier
	v_mfma_f32_16x16x32_bf16 v[2:5], v[184:187], v[168:171], v[2:5]
	ds_read_b128 v[136:139], v219 offset:0
	v_mul_f32_e32 v90, s12, v90
	v_mul_f32_e32 v91, s12, v91
	v_mfma_f32_16x16x32_bf16 v[6:9], v[188:191], v[168:171], v[6:9]
	ds_read_b128 v[140:143], v219 offset:2048
	v_mul_f32_e32 v92, s12, v92
	v_mul_f32_e32 v93, s12, v93
	v_mfma_f32_16x16x32_bf16 v[10:13], v[192:195], v[168:171], v[10:13]
	ds_read_b128 v[144:147], v219 offset:4096
	v_mul_f32_e32 v94, s12, v94
	v_mul_f32_e32 v95, s12, v95
	v_mfma_f32_16x16x32_bf16 v[14:17], v[196:199], v[168:171], v[14:17]
	ds_read_b128 v[148:151], v219 offset:6144
	v_mul_f32_e32 v96, s12, v96
	v_mul_f32_e32 v97, s12, v97
	v_exp_f32_e32 v90, v90
	v_mfma_f32_16x16x32_bf16 v[18:21], v[184:187], v[172:175], v[18:21]
	ds_read_b128 v[152:155], v231 offset:0
	v_exp_f32_e32 v91, v91
	v_exp_f32_e32 v92, v92
	v_mfma_f32_16x16x32_bf16 v[22:25], v[188:191], v[172:175], v[22:25]
	ds_read_b128 v[156:159], v231 offset:2048
	v_exp_f32_e32 v93, v93
	v_exp_f32_e32 v94, v94
	v_mfma_f32_16x16x32_bf16 v[26:29], v[192:195], v[172:175], v[26:29]
	ds_read_b128 v[160:163], v231 offset:4096
	v_exp_f32_e32 v95, v95
	v_exp_f32_e32 v96, v96
	v_exp_f32_e32 v97, v97
	v_mfma_f32_16x16x32_bf16 v[30:33], v[196:199], v[172:175], v[30:33]
	ds_read_b128 v[164:167], v231 offset:6144
	v_add_f32_e32 v90, 1.0, v90
	v_add_f32_e32 v91, 1.0, v91
	v_mfma_f32_16x16x32_bf16 v[34:37], v[184:187], v[176:179], v[34:37]
	v_add_f32_e32 v92, 1.0, v92
	v_add_f32_e32 v93, 1.0, v93
	v_mfma_f32_16x16x32_bf16 v[38:41], v[188:191], v[176:179], v[38:41]
	v_add_f32_e32 v94, 1.0, v94
	v_add_f32_e32 v95, 1.0, v95
	v_add_f32_e32 v96, 1.0, v96
	v_mfma_f32_16x16x32_bf16 v[42:45], v[192:195], v[176:179], v[42:45]
	v_add_f32_e32 v97, 1.0, v97
	v_rcp_f32_e32 v90, v90
	v_mfma_f32_16x16x32_bf16 v[46:49], v[196:199], v[176:179], v[46:49]
	v_rcp_f32_e32 v91, v91
	v_rcp_f32_e32 v92, v92
	v_mfma_f32_16x16x32_bf16 v[50:53], v[184:187], v[180:183], v[50:53]
	v_rcp_f32_e32 v93, v93
	v_rcp_f32_e32 v94, v94
	v_rcp_f32_e32 v95, v95
	v_mfma_f32_16x16x32_bf16 v[54:57], v[188:191], v[180:183], v[54:57]
	v_rcp_f32_e32 v96, v96
	v_rcp_f32_e32 v97, v97
	v_mfma_f32_16x16x32_bf16 v[58:61], v[192:195], v[180:183], v[58:61]
	v_cvt_pk_bf16_f32 v90, v90, v91
	v_cvt_pk_bf16_f32 v91, v92, v93
	v_mfma_f32_16x16x32_bf16 v[62:65], v[196:199], v[180:183], v[62:65]
	v_cvt_pk_bf16_f32 v92, v94, v95
	v_cvt_pk_bf16_f32 v93, v96, v97
	global_store_dwordx4 v240, v[90:93], s[10:11] offset:2064
	s_waitcnt lgkmcnt(0)
	v_mfma_f32_16x16x32_bf16 v[2:5], v[152:155], v[136:139], v[2:5]
	ds_read_b128 v[168:171], v228 offset:0
	v_mul_f32_e32 v98, s12, v98
	v_mul_f32_e32 v99, s12, v99
	v_mfma_f32_16x16x32_bf16 v[6:9], v[156:159], v[136:139], v[6:9]
	ds_read_b128 v[172:175], v228 offset:2048
	v_mul_f32_e32 v100, s12, v100
	v_mul_f32_e32 v101, s12, v101
	v_mfma_f32_16x16x32_bf16 v[10:13], v[160:163], v[136:139], v[10:13]
	ds_read_b128 v[176:179], v228 offset:4096
	v_mul_f32_e32 v102, s12, v102
	v_mul_f32_e32 v103, s12, v103
	v_mfma_f32_16x16x32_bf16 v[14:17], v[164:167], v[136:139], v[14:17]
	ds_read_b128 v[180:183], v228 offset:6144
	v_mul_f32_e32 v104, s12, v104
	v_mul_f32_e32 v105, s12, v105
	v_exp_f32_e32 v98, v98
	v_mfma_f32_16x16x32_bf16 v[18:21], v[152:155], v[140:143], v[18:21]
	ds_read_b128 v[184:187], v234 offset:0
	v_exp_f32_e32 v99, v99
	v_exp_f32_e32 v100, v100
	v_mfma_f32_16x16x32_bf16 v[22:25], v[156:159], v[140:143], v[22:25]
	ds_read_b128 v[188:191], v234 offset:2048
	v_exp_f32_e32 v101, v101
	v_exp_f32_e32 v102, v102
	v_mfma_f32_16x16x32_bf16 v[26:29], v[160:163], v[140:143], v[26:29]
	ds_read_b128 v[192:195], v234 offset:4096
	v_exp_f32_e32 v103, v103
	v_exp_f32_e32 v104, v104
	v_exp_f32_e32 v105, v105
	v_mfma_f32_16x16x32_bf16 v[30:33], v[164:167], v[140:143], v[30:33]
	ds_read_b128 v[196:199], v234 offset:6144
	v_add_f32_e32 v98, 1.0, v98
	v_add_f32_e32 v99, 1.0, v99
	v_mfma_f32_16x16x32_bf16 v[34:37], v[152:155], v[144:147], v[34:37]
	v_add_f32_e32 v100, 1.0, v100
	v_add_f32_e32 v101, 1.0, v101
	v_mfma_f32_16x16x32_bf16 v[38:41], v[156:159], v[144:147], v[38:41]
	v_add_f32_e32 v102, 1.0, v102
	v_add_f32_e32 v103, 1.0, v103
	v_add_f32_e32 v104, 1.0, v104
	v_mfma_f32_16x16x32_bf16 v[42:45], v[160:163], v[144:147], v[42:45]
	v_add_f32_e32 v105, 1.0, v105
	v_rcp_f32_e32 v98, v98
	v_mfma_f32_16x16x32_bf16 v[46:49], v[164:167], v[144:147], v[46:49]
	v_rcp_f32_e32 v99, v99
	v_rcp_f32_e32 v100, v100
	v_mfma_f32_16x16x32_bf16 v[50:53], v[152:155], v[148:151], v[50:53]
	v_rcp_f32_e32 v101, v101
	v_rcp_f32_e32 v102, v102
	v_rcp_f32_e32 v103, v103
	v_mfma_f32_16x16x32_bf16 v[54:57], v[156:159], v[148:151], v[54:57]
	v_rcp_f32_e32 v104, v104
	v_rcp_f32_e32 v105, v105
	v_mfma_f32_16x16x32_bf16 v[58:61], v[160:163], v[148:151], v[58:61]
	v_cvt_pk_bf16_f32 v98, v98, v99
	v_cvt_pk_bf16_f32 v99, v100, v101
	v_mfma_f32_16x16x32_bf16 v[62:65], v[164:167], v[148:151], v[62:65]
	v_cvt_pk_bf16_f32 v100, v102, v103
	v_cvt_pk_bf16_f32 v101, v104, v105
	global_store_dwordx4 v241, v[98:101], s[10:11] offset:0
	s_waitcnt lgkmcnt(0)
	s_barrier
	v_mfma_f32_16x16x32_bf16 v[2:5], v[184:187], v[168:171], v[2:5]
	ds_read_b128 v[136:139], v224 offset:0
	v_mul_f32_e32 v106, s12, v106
	v_mul_f32_e32 v107, s12, v107
	v_mfma_f32_16x16x32_bf16 v[6:9], v[188:191], v[168:171], v[6:9]
	ds_read_b128 v[140:143], v224 offset:2048
	v_mul_f32_e32 v108, s12, v108
	v_mul_f32_e32 v109, s12, v109
	v_mfma_f32_16x16x32_bf16 v[10:13], v[192:195], v[168:171], v[10:13]
	ds_read_b128 v[144:147], v224 offset:4096
	v_mul_f32_e32 v110, s12, v110
	v_mul_f32_e32 v111, s12, v111
	v_mfma_f32_16x16x32_bf16 v[14:17], v[196:199], v[168:171], v[14:17]
	ds_read_b128 v[148:151], v224 offset:6144
	v_mul_f32_e32 v112, s12, v112
	v_mul_f32_e32 v113, s12, v113
	v_exp_f32_e32 v106, v106
	v_mfma_f32_16x16x32_bf16 v[18:21], v[184:187], v[172:175], v[18:21]
	ds_read_b128 v[152:155], v232 offset:0
	v_exp_f32_e32 v107, v107
	v_exp_f32_e32 v108, v108
	v_mfma_f32_16x16x32_bf16 v[22:25], v[188:191], v[172:175], v[22:25]
	ds_read_b128 v[156:159], v232 offset:2048
	v_exp_f32_e32 v109, v109
	v_exp_f32_e32 v110, v110
	v_mfma_f32_16x16x32_bf16 v[26:29], v[192:195], v[172:175], v[26:29]
	ds_read_b128 v[160:163], v232 offset:4096
	v_exp_f32_e32 v111, v111
	v_exp_f32_e32 v112, v112
	v_exp_f32_e32 v113, v113
	v_mfma_f32_16x16x32_bf16 v[30:33], v[196:199], v[172:175], v[30:33]
	ds_read_b128 v[164:167], v232 offset:6144
	v_add_f32_e32 v106, 1.0, v106
	v_add_f32_e32 v107, 1.0, v107
	v_mfma_f32_16x16x32_bf16 v[34:37], v[184:187], v[176:179], v[34:37]
	v_add_f32_e32 v108, 1.0, v108
	v_add_f32_e32 v109, 1.0, v109
	v_mfma_f32_16x16x32_bf16 v[38:41], v[188:191], v[176:179], v[38:41]
	v_add_f32_e32 v110, 1.0, v110
	v_add_f32_e32 v111, 1.0, v111
	v_add_f32_e32 v112, 1.0, v112
	v_mfma_f32_16x16x32_bf16 v[42:45], v[192:195], v[176:179], v[42:45]
	v_add_f32_e32 v113, 1.0, v113
	v_rcp_f32_e32 v106, v106
	v_mfma_f32_16x16x32_bf16 v[46:49], v[196:199], v[176:179], v[46:49]
	v_rcp_f32_e32 v107, v107
	v_rcp_f32_e32 v108, v108
	v_mfma_f32_16x16x32_bf16 v[50:53], v[184:187], v[180:183], v[50:53]
	v_rcp_f32_e32 v109, v109
	v_rcp_f32_e32 v110, v110
	v_rcp_f32_e32 v111, v111
	v_mfma_f32_16x16x32_bf16 v[54:57], v[188:191], v[180:183], v[54:57]
	v_rcp_f32_e32 v112, v112
	v_rcp_f32_e32 v113, v113
	v_mfma_f32_16x16x32_bf16 v[58:61], v[192:195], v[180:183], v[58:61]
	v_cvt_pk_bf16_f32 v106, v106, v107
	v_cvt_pk_bf16_f32 v107, v108, v109
	v_mfma_f32_16x16x32_bf16 v[62:65], v[196:199], v[180:183], v[62:65]
	v_cvt_pk_bf16_f32 v108, v110, v111
	v_cvt_pk_bf16_f32 v109, v112, v113
	global_store_dwordx4 v241, v[106:109], s[10:11] offset:16
	s_waitcnt lgkmcnt(0)
	v_mfma_f32_16x16x32_bf16 v[2:5], v[152:155], v[136:139], v[2:5]
	ds_read_b128 v[168:171], v229 offset:0
	v_mul_f32_e32 v114, s12, v114
	v_mul_f32_e32 v115, s12, v115
	v_mfma_f32_16x16x32_bf16 v[6:9], v[156:159], v[136:139], v[6:9]
	ds_read_b128 v[172:175], v229 offset:2048
	v_mul_f32_e32 v116, s12, v116
	v_mul_f32_e32 v117, s12, v117
	v_mfma_f32_16x16x32_bf16 v[10:13], v[160:163], v[136:139], v[10:13]
	ds_read_b128 v[176:179], v229 offset:4096
	v_mul_f32_e32 v118, s12, v118
	v_mul_f32_e32 v119, s12, v119
	v_mfma_f32_16x16x32_bf16 v[14:17], v[164:167], v[136:139], v[14:17]
	ds_read_b128 v[180:183], v229 offset:6144
	v_mul_f32_e32 v120, s12, v120
	v_mul_f32_e32 v121, s12, v121
	v_exp_f32_e32 v114, v114
	v_mfma_f32_16x16x32_bf16 v[18:21], v[152:155], v[140:143], v[18:21]
	ds_read_b128 v[184:187], v235 offset:0
	v_exp_f32_e32 v115, v115
	v_exp_f32_e32 v116, v116
	v_mfma_f32_16x16x32_bf16 v[22:25], v[156:159], v[140:143], v[22:25]
	ds_read_b128 v[188:191], v235 offset:2048
	v_exp_f32_e32 v117, v117
	v_exp_f32_e32 v118, v118
	v_mfma_f32_16x16x32_bf16 v[26:29], v[160:163], v[140:143], v[26:29]
	ds_read_b128 v[192:195], v235 offset:4096
	v_exp_f32_e32 v119, v119
	v_exp_f32_e32 v120, v120
	v_exp_f32_e32 v121, v121
	v_mfma_f32_16x16x32_bf16 v[30:33], v[164:167], v[140:143], v[30:33]
	ds_read_b128 v[196:199], v235 offset:6144
	v_add_f32_e32 v114, 1.0, v114
	v_add_f32_e32 v115, 1.0, v115
	v_mfma_f32_16x16x32_bf16 v[34:37], v[152:155], v[144:147], v[34:37]
	v_add_f32_e32 v116, 1.0, v116
	v_add_f32_e32 v117, 1.0, v117
	v_mfma_f32_16x16x32_bf16 v[38:41], v[156:159], v[144:147], v[38:41]
	v_add_f32_e32 v118, 1.0, v118
	v_add_f32_e32 v119, 1.0, v119
	v_add_f32_e32 v120, 1.0, v120
	v_mfma_f32_16x16x32_bf16 v[42:45], v[160:163], v[144:147], v[42:45]
	v_add_f32_e32 v121, 1.0, v121
	v_rcp_f32_e32 v114, v114
	v_mfma_f32_16x16x32_bf16 v[46:49], v[164:167], v[144:147], v[46:49]
	v_rcp_f32_e32 v115, v115
	v_rcp_f32_e32 v116, v116
	v_mfma_f32_16x16x32_bf16 v[50:53], v[152:155], v[148:151], v[50:53]
	v_rcp_f32_e32 v117, v117
	v_rcp_f32_e32 v118, v118
	v_rcp_f32_e32 v119, v119
	v_mfma_f32_16x16x32_bf16 v[54:57], v[156:159], v[148:151], v[54:57]
	v_rcp_f32_e32 v120, v120
	v_rcp_f32_e32 v121, v121
	v_mfma_f32_16x16x32_bf16 v[58:61], v[160:163], v[148:151], v[58:61]
	v_cvt_pk_bf16_f32 v114, v114, v115
	v_cvt_pk_bf16_f32 v115, v116, v117
	v_mfma_f32_16x16x32_bf16 v[62:65], v[164:167], v[148:151], v[62:65]
	v_cvt_pk_bf16_f32 v116, v118, v119
	v_cvt_pk_bf16_f32 v117, v120, v121
	global_store_dwordx4 v241, v[114:117], s[10:11] offset:2048
	s_waitcnt lgkmcnt(0)
	s_barrier
	v_mfma_f32_16x16x32_bf16 v[2:5], v[184:187], v[168:171], v[2:5]
	ds_read_b128 v[136:139], v218 offset:0
	v_mul_f32_e32 v122, s12, v122
	v_mul_f32_e32 v123, s12, v123
	v_mfma_f32_16x16x32_bf16 v[6:9], v[188:191], v[168:171], v[6:9]
	ds_read_b128 v[140:143], v218 offset:2048
	v_mul_f32_e32 v124, s12, v124
	v_mul_f32_e32 v125, s12, v125
	v_mfma_f32_16x16x32_bf16 v[10:13], v[192:195], v[168:171], v[10:13]
	ds_read_b128 v[144:147], v218 offset:4096
	v_mul_f32_e32 v126, s12, v126
	v_mul_f32_e32 v127, s12, v127
	v_mfma_f32_16x16x32_bf16 v[14:17], v[196:199], v[168:171], v[14:17]
	ds_read_b128 v[148:151], v218 offset:6144
	v_mul_f32_e32 v128, s12, v128
	v_mul_f32_e32 v129, s12, v129
	v_exp_f32_e32 v122, v122
	v_mfma_f32_16x16x32_bf16 v[18:21], v[184:187], v[172:175], v[18:21]
	ds_read_b128 v[152:155], v230 offset:0
	v_exp_f32_e32 v123, v123
	v_exp_f32_e32 v124, v124
	v_mfma_f32_16x16x32_bf16 v[22:25], v[188:191], v[172:175], v[22:25]
	ds_read_b128 v[156:159], v230 offset:2048
	v_exp_f32_e32 v125, v125
	v_exp_f32_e32 v126, v126
	v_mfma_f32_16x16x32_bf16 v[26:29], v[192:195], v[172:175], v[26:29]
	ds_read_b128 v[160:163], v230 offset:4096
	v_exp_f32_e32 v127, v127
	v_exp_f32_e32 v128, v128
	v_exp_f32_e32 v129, v129
	v_mfma_f32_16x16x32_bf16 v[30:33], v[196:199], v[172:175], v[30:33]
	ds_read_b128 v[164:167], v230 offset:6144
	v_add_f32_e32 v122, 1.0, v122
	v_add_f32_e32 v123, 1.0, v123
	v_mfma_f32_16x16x32_bf16 v[34:37], v[184:187], v[176:179], v[34:37]
	v_add_f32_e32 v124, 1.0, v124
	v_add_f32_e32 v125, 1.0, v125
	v_mfma_f32_16x16x32_bf16 v[38:41], v[188:191], v[176:179], v[38:41]
	v_add_f32_e32 v126, 1.0, v126
	v_add_f32_e32 v127, 1.0, v127
	v_add_f32_e32 v128, 1.0, v128
	v_mfma_f32_16x16x32_bf16 v[42:45], v[192:195], v[176:179], v[42:45]
	v_add_f32_e32 v129, 1.0, v129
	v_rcp_f32_e32 v122, v122
	v_mfma_f32_16x16x32_bf16 v[46:49], v[196:199], v[176:179], v[46:49]
	v_rcp_f32_e32 v123, v123
	v_rcp_f32_e32 v124, v124
	v_mfma_f32_16x16x32_bf16 v[50:53], v[184:187], v[180:183], v[50:53]
	v_rcp_f32_e32 v125, v125
	v_rcp_f32_e32 v126, v126
	v_rcp_f32_e32 v127, v127
	v_mfma_f32_16x16x32_bf16 v[54:57], v[188:191], v[180:183], v[54:57]
	v_rcp_f32_e32 v128, v128
	v_rcp_f32_e32 v129, v129
	v_mfma_f32_16x16x32_bf16 v[58:61], v[192:195], v[180:183], v[58:61]
	v_cvt_pk_bf16_f32 v122, v122, v123
	v_cvt_pk_bf16_f32 v123, v124, v125
	v_mfma_f32_16x16x32_bf16 v[62:65], v[196:199], v[180:183], v[62:65]
	v_cvt_pk_bf16_f32 v124, v126, v127
	v_cvt_pk_bf16_f32 v125, v128, v129
	global_store_dwordx4 v241, v[122:125], s[10:11] offset:2064
	s_waitcnt lgkmcnt(0)
	v_mfma_f32_16x16x32_bf16 v[2:5], v[152:155], v[136:139], v[2:5]
	ds_read_b128 v[168:171], v225 offset:0
	v_mfma_f32_16x16x32_bf16 v[6:9], v[156:159], v[136:139], v[6:9]
	ds_read_b128 v[172:175], v225 offset:2048
	v_mfma_f32_16x16x32_bf16 v[10:13], v[160:163], v[136:139], v[10:13]
	ds_read_b128 v[176:179], v225 offset:4096
	v_mfma_f32_16x16x32_bf16 v[14:17], v[164:167], v[136:139], v[14:17]
	ds_read_b128 v[180:183], v225 offset:6144
	v_mfma_f32_16x16x32_bf16 v[18:21], v[152:155], v[140:143], v[18:21]
	ds_read_b128 v[184:187], v233 offset:0
	v_mfma_f32_16x16x32_bf16 v[22:25], v[156:159], v[140:143], v[22:25]
	ds_read_b128 v[188:191], v233 offset:2048
	v_mfma_f32_16x16x32_bf16 v[26:29], v[160:163], v[140:143], v[26:29]
	ds_read_b128 v[192:195], v233 offset:4096
	v_mfma_f32_16x16x32_bf16 v[30:33], v[164:167], v[140:143], v[30:33]
	ds_read_b128 v[196:199], v233 offset:6144
	v_mfma_f32_16x16x32_bf16 v[34:37], v[152:155], v[144:147], v[34:37]
	v_mfma_f32_16x16x32_bf16 v[38:41], v[156:159], v[144:147], v[38:41]
	v_mfma_f32_16x16x32_bf16 v[42:45], v[160:163], v[144:147], v[42:45]
	v_mfma_f32_16x16x32_bf16 v[46:49], v[164:167], v[144:147], v[46:49]
	v_mfma_f32_16x16x32_bf16 v[50:53], v[152:155], v[148:151], v[50:53]
	v_mfma_f32_16x16x32_bf16 v[54:57], v[156:159], v[148:151], v[54:57]
	v_mfma_f32_16x16x32_bf16 v[58:61], v[160:163], v[148:151], v[58:61]
	v_mfma_f32_16x16x32_bf16 v[62:65], v[164:167], v[148:151], v[62:65]
	s_waitcnt lgkmcnt(0)
	s_barrier
	v_mfma_f32_16x16x32_bf16 v[2:5], v[184:187], v[168:171], v[2:5]
	ds_read_b128 v[136:139], v219 offset:0
	v_mfma_f32_16x16x32_bf16 v[6:9], v[188:191], v[168:171], v[6:9]
	ds_read_b128 v[140:143], v219 offset:2048
	v_mfma_f32_16x16x32_bf16 v[10:13], v[192:195], v[168:171], v[10:13]
	ds_read_b128 v[144:147], v219 offset:4096
	v_mfma_f32_16x16x32_bf16 v[14:17], v[196:199], v[168:171], v[14:17]
	ds_read_b128 v[148:151], v219 offset:6144
	v_mfma_f32_16x16x32_bf16 v[18:21], v[184:187], v[172:175], v[18:21]
	ds_read_b128 v[152:155], v231 offset:0
	v_mfma_f32_16x16x32_bf16 v[22:25], v[188:191], v[172:175], v[22:25]
	ds_read_b128 v[156:159], v231 offset:2048
	v_mfma_f32_16x16x32_bf16 v[26:29], v[192:195], v[172:175], v[26:29]
	ds_read_b128 v[160:163], v231 offset:4096
	v_mfma_f32_16x16x32_bf16 v[30:33], v[196:199], v[172:175], v[30:33]
	ds_read_b128 v[164:167], v231 offset:6144
	v_mfma_f32_16x16x32_bf16 v[34:37], v[184:187], v[176:179], v[34:37]
	v_mfma_f32_16x16x32_bf16 v[38:41], v[188:191], v[176:179], v[38:41]
	v_mfma_f32_16x16x32_bf16 v[42:45], v[192:195], v[176:179], v[42:45]
	v_mfma_f32_16x16x32_bf16 v[46:49], v[196:199], v[176:179], v[46:49]
	v_mfma_f32_16x16x32_bf16 v[50:53], v[184:187], v[180:183], v[50:53]
	v_mfma_f32_16x16x32_bf16 v[54:57], v[188:191], v[180:183], v[54:57]
	v_mfma_f32_16x16x32_bf16 v[58:61], v[192:195], v[180:183], v[58:61]
	v_mfma_f32_16x16x32_bf16 v[62:65], v[196:199], v[180:183], v[62:65]
	s_waitcnt lgkmcnt(0)
	v_mfma_f32_16x16x32_bf16 v[2:5], v[152:155], v[136:139], v[2:5]
	ds_read_b128 v[168:171], v228 offset:0
	v_mfma_f32_16x16x32_bf16 v[6:9], v[156:159], v[136:139], v[6:9]
	ds_read_b128 v[172:175], v228 offset:2048
	v_mfma_f32_16x16x32_bf16 v[10:13], v[160:163], v[136:139], v[10:13]
	ds_read_b128 v[176:179], v228 offset:4096
	v_mfma_f32_16x16x32_bf16 v[14:17], v[164:167], v[136:139], v[14:17]
	ds_read_b128 v[180:183], v228 offset:6144
	v_mfma_f32_16x16x32_bf16 v[18:21], v[152:155], v[140:143], v[18:21]
	ds_read_b128 v[184:187], v234 offset:0
	v_mfma_f32_16x16x32_bf16 v[22:25], v[156:159], v[140:143], v[22:25]
	ds_read_b128 v[188:191], v234 offset:2048
	v_mfma_f32_16x16x32_bf16 v[26:29], v[160:163], v[140:143], v[26:29]
	ds_read_b128 v[192:195], v234 offset:4096
	v_mfma_f32_16x16x32_bf16 v[30:33], v[164:167], v[140:143], v[30:33]
	ds_read_b128 v[196:199], v234 offset:6144
	v_mfma_f32_16x16x32_bf16 v[34:37], v[152:155], v[144:147], v[34:37]
	v_mfma_f32_16x16x32_bf16 v[38:41], v[156:159], v[144:147], v[38:41]
	v_mfma_f32_16x16x32_bf16 v[42:45], v[160:163], v[144:147], v[42:45]
	v_mfma_f32_16x16x32_bf16 v[46:49], v[164:167], v[144:147], v[46:49]
	v_mfma_f32_16x16x32_bf16 v[50:53], v[152:155], v[148:151], v[50:53]
	v_mfma_f32_16x16x32_bf16 v[54:57], v[156:159], v[148:151], v[54:57]
	v_mfma_f32_16x16x32_bf16 v[58:61], v[160:163], v[148:151], v[58:61]
	v_mfma_f32_16x16x32_bf16 v[62:65], v[164:167], v[148:151], v[62:65]
	s_waitcnt lgkmcnt(0)
	s_barrier
	v_mfma_f32_16x16x32_bf16 v[2:5], v[184:187], v[168:171], v[2:5]
	ds_read_b128 v[136:139], v224 offset:0
	v_mfma_f32_16x16x32_bf16 v[6:9], v[188:191], v[168:171], v[6:9]
	ds_read_b128 v[140:143], v224 offset:2048
	v_mfma_f32_16x16x32_bf16 v[10:13], v[192:195], v[168:171], v[10:13]
	ds_read_b128 v[144:147], v224 offset:4096
	v_mfma_f32_16x16x32_bf16 v[14:17], v[196:199], v[168:171], v[14:17]
	ds_read_b128 v[148:151], v224 offset:6144
	v_mfma_f32_16x16x32_bf16 v[18:21], v[184:187], v[172:175], v[18:21]
	ds_read_b128 v[152:155], v232 offset:0
	v_mfma_f32_16x16x32_bf16 v[22:25], v[188:191], v[172:175], v[22:25]
	ds_read_b128 v[156:159], v232 offset:2048
	v_mfma_f32_16x16x32_bf16 v[26:29], v[192:195], v[172:175], v[26:29]
	ds_read_b128 v[160:163], v232 offset:4096
	v_mfma_f32_16x16x32_bf16 v[30:33], v[196:199], v[172:175], v[30:33]
	ds_read_b128 v[164:167], v232 offset:6144
	v_mfma_f32_16x16x32_bf16 v[34:37], v[184:187], v[176:179], v[34:37]
	v_mfma_f32_16x16x32_bf16 v[38:41], v[188:191], v[176:179], v[38:41]
	v_mfma_f32_16x16x32_bf16 v[42:45], v[192:195], v[176:179], v[42:45]
	v_mfma_f32_16x16x32_bf16 v[46:49], v[196:199], v[176:179], v[46:49]
	v_mfma_f32_16x16x32_bf16 v[50:53], v[184:187], v[180:183], v[50:53]
	v_mfma_f32_16x16x32_bf16 v[54:57], v[188:191], v[180:183], v[54:57]
	v_mfma_f32_16x16x32_bf16 v[58:61], v[192:195], v[180:183], v[58:61]
	v_mfma_f32_16x16x32_bf16 v[62:65], v[196:199], v[180:183], v[62:65]
	s_waitcnt lgkmcnt(0)
	v_mfma_f32_16x16x32_bf16 v[2:5], v[152:155], v[136:139], v[2:5]
	ds_read_b128 v[168:171], v229 offset:0
	v_mfma_f32_16x16x32_bf16 v[6:9], v[156:159], v[136:139], v[6:9]
	ds_read_b128 v[172:175], v229 offset:2048
	v_mfma_f32_16x16x32_bf16 v[10:13], v[160:163], v[136:139], v[10:13]
	ds_read_b128 v[176:179], v229 offset:4096
	v_mfma_f32_16x16x32_bf16 v[14:17], v[164:167], v[136:139], v[14:17]
	ds_read_b128 v[180:183], v229 offset:6144
	v_mfma_f32_16x16x32_bf16 v[18:21], v[152:155], v[140:143], v[18:21]
	ds_read_b128 v[184:187], v235 offset:0
	v_mfma_f32_16x16x32_bf16 v[22:25], v[156:159], v[140:143], v[22:25]
	ds_read_b128 v[188:191], v235 offset:2048
	v_mfma_f32_16x16x32_bf16 v[26:29], v[160:163], v[140:143], v[26:29]
	ds_read_b128 v[192:195], v235 offset:4096
	v_mfma_f32_16x16x32_bf16 v[30:33], v[164:167], v[140:143], v[30:33]
	ds_read_b128 v[196:199], v235 offset:6144
	v_mfma_f32_16x16x32_bf16 v[34:37], v[152:155], v[144:147], v[34:37]
	v_mfma_f32_16x16x32_bf16 v[38:41], v[156:159], v[144:147], v[38:41]
	v_mfma_f32_16x16x32_bf16 v[42:45], v[160:163], v[144:147], v[42:45]
	v_mfma_f32_16x16x32_bf16 v[46:49], v[164:167], v[144:147], v[46:49]
	v_mfma_f32_16x16x32_bf16 v[50:53], v[152:155], v[148:151], v[50:53]
	v_mfma_f32_16x16x32_bf16 v[54:57], v[156:159], v[148:151], v[54:57]
	v_mfma_f32_16x16x32_bf16 v[58:61], v[160:163], v[148:151], v[58:61]
	v_mfma_f32_16x16x32_bf16 v[62:65], v[164:167], v[148:151], v[62:65]
	s_waitcnt lgkmcnt(0)
	s_barrier
	v_mfma_f32_16x16x32_bf16 v[2:5], v[184:187], v[168:171], v[2:5]
	ds_read_b128 v[136:139], v218 offset:0
	v_mfma_f32_16x16x32_bf16 v[6:9], v[188:191], v[168:171], v[6:9]
	ds_read_b128 v[140:143], v218 offset:2048
	v_mfma_f32_16x16x32_bf16 v[10:13], v[192:195], v[168:171], v[10:13]
	ds_read_b128 v[144:147], v218 offset:4096
	v_mfma_f32_16x16x32_bf16 v[14:17], v[196:199], v[168:171], v[14:17]
	ds_read_b128 v[148:151], v218 offset:6144
	v_mfma_f32_16x16x32_bf16 v[18:21], v[184:187], v[172:175], v[18:21]
	ds_read_b128 v[152:155], v230 offset:0
	v_mfma_f32_16x16x32_bf16 v[22:25], v[188:191], v[172:175], v[22:25]
	ds_read_b128 v[156:159], v230 offset:2048
	v_mfma_f32_16x16x32_bf16 v[26:29], v[192:195], v[172:175], v[26:29]
	ds_read_b128 v[160:163], v230 offset:4096
	v_mfma_f32_16x16x32_bf16 v[30:33], v[196:199], v[172:175], v[30:33]
	ds_read_b128 v[164:167], v230 offset:6144
	v_mfma_f32_16x16x32_bf16 v[34:37], v[184:187], v[176:179], v[34:37]
	v_mfma_f32_16x16x32_bf16 v[38:41], v[188:191], v[176:179], v[38:41]
	v_mfma_f32_16x16x32_bf16 v[42:45], v[192:195], v[176:179], v[42:45]
	v_mfma_f32_16x16x32_bf16 v[46:49], v[196:199], v[176:179], v[46:49]
	v_mfma_f32_16x16x32_bf16 v[50:53], v[184:187], v[180:183], v[50:53]
	v_mfma_f32_16x16x32_bf16 v[54:57], v[188:191], v[180:183], v[54:57]
	v_mfma_f32_16x16x32_bf16 v[58:61], v[192:195], v[180:183], v[58:61]
	v_mfma_f32_16x16x32_bf16 v[62:65], v[196:199], v[180:183], v[62:65]
	s_waitcnt lgkmcnt(0)
	v_mfma_f32_16x16x32_bf16 v[2:5], v[152:155], v[136:139], v[2:5]
	ds_read_b128 v[168:171], v225 offset:0
	v_mfma_f32_16x16x32_bf16 v[6:9], v[156:159], v[136:139], v[6:9]
	ds_read_b128 v[172:175], v225 offset:2048
	v_mfma_f32_16x16x32_bf16 v[10:13], v[160:163], v[136:139], v[10:13]
	ds_read_b128 v[176:179], v225 offset:4096
	v_mfma_f32_16x16x32_bf16 v[14:17], v[164:167], v[136:139], v[14:17]
	ds_read_b128 v[180:183], v225 offset:6144
	v_mfma_f32_16x16x32_bf16 v[18:21], v[152:155], v[140:143], v[18:21]
	ds_read_b128 v[184:187], v233 offset:0
	v_mfma_f32_16x16x32_bf16 v[22:25], v[156:159], v[140:143], v[22:25]
	ds_read_b128 v[188:191], v233 offset:2048
	v_mfma_f32_16x16x32_bf16 v[26:29], v[160:163], v[140:143], v[26:29]
	ds_read_b128 v[192:195], v233 offset:4096
	v_mfma_f32_16x16x32_bf16 v[30:33], v[164:167], v[140:143], v[30:33]
	ds_read_b128 v[196:199], v233 offset:6144
	v_mfma_f32_16x16x32_bf16 v[34:37], v[152:155], v[144:147], v[34:37]
	v_mfma_f32_16x16x32_bf16 v[38:41], v[156:159], v[144:147], v[38:41]
	v_mfma_f32_16x16x32_bf16 v[42:45], v[160:163], v[144:147], v[42:45]
	v_mfma_f32_16x16x32_bf16 v[46:49], v[164:167], v[144:147], v[46:49]
	v_mfma_f32_16x16x32_bf16 v[50:53], v[152:155], v[148:151], v[50:53]
	v_mfma_f32_16x16x32_bf16 v[54:57], v[156:159], v[148:151], v[54:57]
	v_mfma_f32_16x16x32_bf16 v[58:61], v[160:163], v[148:151], v[58:61]
	v_mfma_f32_16x16x32_bf16 v[62:65], v[164:167], v[148:151], v[62:65]
	s_waitcnt lgkmcnt(0)
	s_barrier
	v_mfma_f32_16x16x32_bf16 v[2:5], v[184:187], v[168:171], v[2:5]
	ds_read_b128 v[136:139], v219 offset:0
	v_mfma_f32_16x16x32_bf16 v[6:9], v[188:191], v[168:171], v[6:9]
	ds_read_b128 v[140:143], v219 offset:2048
	v_mfma_f32_16x16x32_bf16 v[10:13], v[192:195], v[168:171], v[10:13]
	ds_read_b128 v[144:147], v219 offset:4096
	v_mfma_f32_16x16x32_bf16 v[14:17], v[196:199], v[168:171], v[14:17]
	ds_read_b128 v[148:151], v219 offset:6144
	v_mfma_f32_16x16x32_bf16 v[18:21], v[184:187], v[172:175], v[18:21]
	ds_read_b128 v[152:155], v231 offset:0
	v_mfma_f32_16x16x32_bf16 v[22:25], v[188:191], v[172:175], v[22:25]
	ds_read_b128 v[156:159], v231 offset:2048
	v_mfma_f32_16x16x32_bf16 v[26:29], v[192:195], v[172:175], v[26:29]
	ds_read_b128 v[160:163], v231 offset:4096
	v_mfma_f32_16x16x32_bf16 v[30:33], v[196:199], v[172:175], v[30:33]
	ds_read_b128 v[164:167], v231 offset:6144
	v_mfma_f32_16x16x32_bf16 v[34:37], v[184:187], v[176:179], v[34:37]
	v_mfma_f32_16x16x32_bf16 v[38:41], v[188:191], v[176:179], v[38:41]
	v_mfma_f32_16x16x32_bf16 v[42:45], v[192:195], v[176:179], v[42:45]
	v_mfma_f32_16x16x32_bf16 v[46:49], v[196:199], v[176:179], v[46:49]
	v_mfma_f32_16x16x32_bf16 v[50:53], v[184:187], v[180:183], v[50:53]
	v_mfma_f32_16x16x32_bf16 v[54:57], v[188:191], v[180:183], v[54:57]
	v_mfma_f32_16x16x32_bf16 v[58:61], v[192:195], v[180:183], v[58:61]
	v_mfma_f32_16x16x32_bf16 v[62:65], v[196:199], v[180:183], v[62:65]
	s_waitcnt lgkmcnt(0)
	v_mfma_f32_16x16x32_bf16 v[2:5], v[152:155], v[136:139], v[2:5]
	ds_read_b128 v[168:171], v228 offset:0
	v_mfma_f32_16x16x32_bf16 v[6:9], v[156:159], v[136:139], v[6:9]
	ds_read_b128 v[172:175], v228 offset:2048
	v_mfma_f32_16x16x32_bf16 v[10:13], v[160:163], v[136:139], v[10:13]
	ds_read_b128 v[176:179], v228 offset:4096
	v_mfma_f32_16x16x32_bf16 v[14:17], v[164:167], v[136:139], v[14:17]
	ds_read_b128 v[180:183], v228 offset:6144
	v_mfma_f32_16x16x32_bf16 v[18:21], v[152:155], v[140:143], v[18:21]
	ds_read_b128 v[184:187], v234 offset:0
	v_mfma_f32_16x16x32_bf16 v[22:25], v[156:159], v[140:143], v[22:25]
	ds_read_b128 v[188:191], v234 offset:2048
	v_mfma_f32_16x16x32_bf16 v[26:29], v[160:163], v[140:143], v[26:29]
	ds_read_b128 v[192:195], v234 offset:4096
	v_mfma_f32_16x16x32_bf16 v[30:33], v[164:167], v[140:143], v[30:33]
	ds_read_b128 v[196:199], v234 offset:6144
	v_mfma_f32_16x16x32_bf16 v[34:37], v[152:155], v[144:147], v[34:37]
	v_mfma_f32_16x16x32_bf16 v[38:41], v[156:159], v[144:147], v[38:41]
	v_mfma_f32_16x16x32_bf16 v[42:45], v[160:163], v[144:147], v[42:45]
	v_mfma_f32_16x16x32_bf16 v[46:49], v[164:167], v[144:147], v[46:49]
	v_mfma_f32_16x16x32_bf16 v[50:53], v[152:155], v[148:151], v[50:53]
	v_mfma_f32_16x16x32_bf16 v[54:57], v[156:159], v[148:151], v[54:57]
	v_mfma_f32_16x16x32_bf16 v[58:61], v[160:163], v[148:151], v[58:61]
	v_mfma_f32_16x16x32_bf16 v[62:65], v[164:167], v[148:151], v[62:65]
	s_waitcnt lgkmcnt(0)
	s_barrier
	s_add_u32 s14, s4, 0x580
	s_addc_u32 s15, s5, 0
	v_mfma_f32_16x16x32_bf16 v[2:5], v[184:187], v[168:171], v[2:5]
	ds_read_b128 v[136:139], v224 offset:0
	s_add_u32 s22, s4, 0x10580
	s_addc_u32 s23, s5, 0
	v_mfma_f32_16x16x32_bf16 v[6:9], v[188:191], v[168:171], v[6:9]
	ds_read_b128 v[140:143], v224 offset:2048
	s_add_u32 s24, s6, 0x80580
	s_addc_u32 s25, s7, 0
	v_mfma_f32_16x16x32_bf16 v[10:13], v[192:195], v[168:171], v[10:13]
	ds_read_b128 v[144:147], v224 offset:4096
	s_add_u32 s52, s6, 0x88580
	s_addc_u32 s53, s7, 0
	v_mfma_f32_16x16x32_bf16 v[14:17], v[196:199], v[168:171], v[14:17]
	ds_read_b128 v[148:151], v224 offset:6144
	s_add_u32 m0, s8, 0xc000
	v_mfma_f32_16x16x32_bf16 v[18:21], v[184:187], v[172:175], v[18:21]
	global_load_lds_dwordx4 v200, s[14:15]
	ds_read_b128 v[152:155], v232 offset:0
	s_add_u32 m0, s8, 0xc400
	v_mfma_f32_16x16x32_bf16 v[22:25], v[188:191], v[172:175], v[22:25]
	global_load_lds_dwordx4 v201, s[14:15]
	ds_read_b128 v[156:159], v232 offset:2048
	s_add_u32 m0, s8, 0xc800
	v_mfma_f32_16x16x32_bf16 v[26:29], v[192:195], v[172:175], v[26:29]
	global_load_lds_dwordx4 v202, s[14:15]
	ds_read_b128 v[160:163], v232 offset:4096
	s_add_u32 m0, s8, 0xcc00
	v_mfma_f32_16x16x32_bf16 v[30:33], v[196:199], v[172:175], v[30:33]
	global_load_lds_dwordx4 v203, s[14:15]
	ds_read_b128 v[164:167], v232 offset:6144
	s_add_u32 m0, s8, 0xd000
	v_mfma_f32_16x16x32_bf16 v[34:37], v[184:187], v[176:179], v[34:37]
	global_load_lds_dwordx4 v200, s[22:23]
	s_add_u32 m0, s8, 0xd400
	v_mfma_f32_16x16x32_bf16 v[38:41], v[188:191], v[176:179], v[38:41]
	global_load_lds_dwordx4 v201, s[22:23]
	s_add_u32 m0, s8, 0xd800
	v_mfma_f32_16x16x32_bf16 v[42:45], v[192:195], v[176:179], v[42:45]
	global_load_lds_dwordx4 v202, s[22:23]
	s_add_u32 m0, s8, 0xdc00
	v_mfma_f32_16x16x32_bf16 v[46:49], v[196:199], v[176:179], v[46:49]
	global_load_lds_dwordx4 v203, s[22:23]
	s_add_u32 m0, s9, 0xc000
	v_mfma_f32_16x16x32_bf16 v[50:53], v[184:187], v[180:183], v[50:53]
	global_load_lds_dwordx4 v204, s[24:25]
	s_add_u32 m0, s9, 0xc400
	v_mfma_f32_16x16x32_bf16 v[54:57], v[188:191], v[180:183], v[54:57]
	global_load_lds_dwordx4 v205, s[24:25]
	s_add_u32 m0, s9, 0xc800
	v_mfma_f32_16x16x32_bf16 v[58:61], v[192:195], v[180:183], v[58:61]
	global_load_lds_dwordx4 v204, s[52:53]
	s_add_u32 m0, s9, 0xcc00
	v_mfma_f32_16x16x32_bf16 v[62:65], v[196:199], v[180:183], v[62:65]
	global_load_lds_dwordx4 v205, s[52:53]
	s_waitcnt lgkmcnt(0)
	v_mfma_f32_16x16x32_bf16 v[2:5], v[152:155], v[136:139], v[2:5]
	ds_read_b128 v[168:171], v229 offset:0
	v_mfma_f32_16x16x32_bf16 v[6:9], v[156:159], v[136:139], v[6:9]
	ds_read_b128 v[172:175], v229 offset:2048
	v_mfma_f32_16x16x32_bf16 v[10:13], v[160:163], v[136:139], v[10:13]
	ds_read_b128 v[176:179], v229 offset:4096
	v_mfma_f32_16x16x32_bf16 v[14:17], v[164:167], v[136:139], v[14:17]
	ds_read_b128 v[180:183], v229 offset:6144
	v_mfma_f32_16x16x32_bf16 v[18:21], v[152:155], v[140:143], v[18:21]
	ds_read_b128 v[184:187], v235 offset:0
	v_mfma_f32_16x16x32_bf16 v[22:25], v[156:159], v[140:143], v[22:25]
	ds_read_b128 v[188:191], v235 offset:2048
	v_mfma_f32_16x16x32_bf16 v[26:29], v[160:163], v[140:143], v[26:29]
	ds_read_b128 v[192:195], v235 offset:4096
	v_mfma_f32_16x16x32_bf16 v[30:33], v[164:167], v[140:143], v[30:33]
	ds_read_b128 v[196:199], v235 offset:6144
	v_mfma_f32_16x16x32_bf16 v[34:37], v[152:155], v[144:147], v[34:37]
	v_mfma_f32_16x16x32_bf16 v[38:41], v[156:159], v[144:147], v[38:41]
	v_mfma_f32_16x16x32_bf16 v[42:45], v[160:163], v[144:147], v[42:45]
	v_mfma_f32_16x16x32_bf16 v[46:49], v[164:167], v[144:147], v[46:49]
	v_mfma_f32_16x16x32_bf16 v[50:53], v[152:155], v[148:151], v[50:53]
	v_mfma_f32_16x16x32_bf16 v[54:57], v[156:159], v[148:151], v[54:57]
	v_mfma_f32_16x16x32_bf16 v[58:61], v[160:163], v[148:151], v[58:61]
	v_mfma_f32_16x16x32_bf16 v[62:65], v[164:167], v[148:151], v[62:65]
	s_waitcnt lgkmcnt(0)
	s_barrier
	s_add_u32 s14, s4, 0x600
	s_addc_u32 s15, s5, 0
	v_mfma_f32_16x16x32_bf16 v[2:5], v[184:187], v[168:171], v[2:5]
	ds_read_b128 v[136:139], v218 offset:0
	s_add_u32 s22, s4, 0x10600
	s_addc_u32 s23, s5, 0
	v_mfma_f32_16x16x32_bf16 v[6:9], v[188:191], v[168:171], v[6:9]
	ds_read_b128 v[140:143], v218 offset:2048
	s_add_u32 s24, s6, 0x80600
	s_addc_u32 s25, s7, 0
	v_mfma_f32_16x16x32_bf16 v[10:13], v[192:195], v[168:171], v[10:13]
	ds_read_b128 v[144:147], v218 offset:4096
	s_add_u32 s52, s6, 0x88600
	s_addc_u32 s53, s7, 0
	v_mfma_f32_16x16x32_bf16 v[14:17], v[196:199], v[168:171], v[14:17]
	ds_read_b128 v[148:151], v218 offset:6144
	s_add_u32 m0, s8, 0x18000
	v_mfma_f32_16x16x32_bf16 v[18:21], v[184:187], v[172:175], v[18:21]
	global_load_lds_dwordx4 v200, s[14:15]
	ds_read_b128 v[152:155], v230 offset:0
	s_add_u32 m0, s8, 0x18400
	v_mfma_f32_16x16x32_bf16 v[22:25], v[188:191], v[172:175], v[22:25]
	global_load_lds_dwordx4 v201, s[14:15]
	ds_read_b128 v[156:159], v230 offset:2048
	s_add_u32 m0, s8, 0x18800
	v_mfma_f32_16x16x32_bf16 v[26:29], v[192:195], v[172:175], v[26:29]
	global_load_lds_dwordx4 v202, s[14:15]
	ds_read_b128 v[160:163], v230 offset:4096
	s_add_u32 m0, s8, 0x18c00
	v_mfma_f32_16x16x32_bf16 v[30:33], v[196:199], v[172:175], v[30:33]
	global_load_lds_dwordx4 v203, s[14:15]
	ds_read_b128 v[164:167], v230 offset:6144
	s_add_u32 m0, s8, 0x19000
	v_mfma_f32_16x16x32_bf16 v[34:37], v[184:187], v[176:179], v[34:37]
	global_load_lds_dwordx4 v200, s[22:23]
	s_add_u32 m0, s8, 0x19400
	v_mfma_f32_16x16x32_bf16 v[38:41], v[188:191], v[176:179], v[38:41]
	global_load_lds_dwordx4 v201, s[22:23]
	s_add_u32 m0, s8, 0x19800
	v_mfma_f32_16x16x32_bf16 v[42:45], v[192:195], v[176:179], v[42:45]
	global_load_lds_dwordx4 v202, s[22:23]
	s_add_u32 m0, s8, 0x19c00
	v_mfma_f32_16x16x32_bf16 v[46:49], v[196:199], v[176:179], v[46:49]
	global_load_lds_dwordx4 v203, s[22:23]
	s_add_u32 m0, s9, 0x18000
	v_mfma_f32_16x16x32_bf16 v[50:53], v[184:187], v[180:183], v[50:53]
	global_load_lds_dwordx4 v204, s[24:25]
	s_add_u32 m0, s9, 0x18400
	v_mfma_f32_16x16x32_bf16 v[54:57], v[188:191], v[180:183], v[54:57]
	global_load_lds_dwordx4 v205, s[24:25]
	s_add_u32 m0, s9, 0x18800
	v_mfma_f32_16x16x32_bf16 v[58:61], v[192:195], v[180:183], v[58:61]
	global_load_lds_dwordx4 v204, s[52:53]
	s_add_u32 m0, s9, 0x18c00
	v_mfma_f32_16x16x32_bf16 v[62:65], v[196:199], v[180:183], v[62:65]
	global_load_lds_dwordx4 v205, s[52:53]
	s_waitcnt lgkmcnt(0)
	v_mfma_f32_16x16x32_bf16 v[2:5], v[152:155], v[136:139], v[2:5]
	ds_read_b128 v[168:171], v225 offset:0
	v_mfma_f32_16x16x32_bf16 v[6:9], v[156:159], v[136:139], v[6:9]
	ds_read_b128 v[172:175], v225 offset:2048
	v_mfma_f32_16x16x32_bf16 v[10:13], v[160:163], v[136:139], v[10:13]
	ds_read_b128 v[176:179], v225 offset:4096
	v_mfma_f32_16x16x32_bf16 v[14:17], v[164:167], v[136:139], v[14:17]
	ds_read_b128 v[180:183], v225 offset:6144
	v_mfma_f32_16x16x32_bf16 v[18:21], v[152:155], v[140:143], v[18:21]
	ds_read_b128 v[184:187], v233 offset:0
	v_mfma_f32_16x16x32_bf16 v[22:25], v[156:159], v[140:143], v[22:25]
	ds_read_b128 v[188:191], v233 offset:2048
	v_mfma_f32_16x16x32_bf16 v[26:29], v[160:163], v[140:143], v[26:29]
	ds_read_b128 v[192:195], v233 offset:4096
	v_mfma_f32_16x16x32_bf16 v[30:33], v[164:167], v[140:143], v[30:33]
	ds_read_b128 v[196:199], v233 offset:6144
	v_mfma_f32_16x16x32_bf16 v[34:37], v[152:155], v[144:147], v[34:37]
	v_mfma_f32_16x16x32_bf16 v[38:41], v[156:159], v[144:147], v[38:41]
	v_mfma_f32_16x16x32_bf16 v[42:45], v[160:163], v[144:147], v[42:45]
	v_mfma_f32_16x16x32_bf16 v[46:49], v[164:167], v[144:147], v[46:49]
	v_mfma_f32_16x16x32_bf16 v[50:53], v[152:155], v[148:151], v[50:53]
	v_mfma_f32_16x16x32_bf16 v[54:57], v[156:159], v[148:151], v[54:57]
	v_mfma_f32_16x16x32_bf16 v[58:61], v[160:163], v[148:151], v[58:61]
	v_mfma_f32_16x16x32_bf16 v[62:65], v[164:167], v[148:151], v[62:65]
	s_waitcnt vmcnt(12) lgkmcnt(0)
	s_barrier
	s_add_u32 s14, s4, 0x680
	s_addc_u32 s15, s5, 0
	v_mfma_f32_16x16x32_bf16 v[2:5], v[184:187], v[168:171], v[2:5]
	ds_read_b128 v[136:139], v219 offset:0
	s_add_u32 s22, s4, 0x10680
	s_addc_u32 s23, s5, 0
	v_mfma_f32_16x16x32_bf16 v[6:9], v[188:191], v[168:171], v[6:9]
	ds_read_b128 v[140:143], v219 offset:2048
	s_add_u32 s24, s6, 0x80680
	s_addc_u32 s25, s7, 0
	v_mfma_f32_16x16x32_bf16 v[10:13], v[192:195], v[168:171], v[10:13]
	ds_read_b128 v[144:147], v219 offset:4096
	s_add_u32 s52, s6, 0x88680
	s_addc_u32 s53, s7, 0
	v_mfma_f32_16x16x32_bf16 v[14:17], v[196:199], v[168:171], v[14:17]
	ds_read_b128 v[148:151], v219 offset:6144
	s_mov_b32 m0, s8
	v_mfma_f32_16x16x32_bf16 v[18:21], v[184:187], v[172:175], v[18:21]
	global_load_lds_dwordx4 v200, s[14:15]
	ds_read_b128 v[152:155], v231 offset:0
	s_add_u32 m0, s8, 0x400
	v_mfma_f32_16x16x32_bf16 v[22:25], v[188:191], v[172:175], v[22:25]
	global_load_lds_dwordx4 v201, s[14:15]
	ds_read_b128 v[156:159], v231 offset:2048
	s_add_u32 m0, s8, 0x800
	v_mfma_f32_16x16x32_bf16 v[26:29], v[192:195], v[172:175], v[26:29]
	global_load_lds_dwordx4 v202, s[14:15]
	ds_read_b128 v[160:163], v231 offset:4096
	s_add_u32 m0, s8, 0xc00
	v_mfma_f32_16x16x32_bf16 v[30:33], v[196:199], v[172:175], v[30:33]
	global_load_lds_dwordx4 v203, s[14:15]
	ds_read_b128 v[164:167], v231 offset:6144
	s_add_u32 m0, s8, 0x1000
	v_mfma_f32_16x16x32_bf16 v[34:37], v[184:187], v[176:179], v[34:37]
	global_load_lds_dwordx4 v200, s[22:23]
	s_add_u32 m0, s8, 0x1400
	v_mfma_f32_16x16x32_bf16 v[38:41], v[188:191], v[176:179], v[38:41]
	global_load_lds_dwordx4 v201, s[22:23]
	s_add_u32 m0, s8, 0x1800
	v_mfma_f32_16x16x32_bf16 v[42:45], v[192:195], v[176:179], v[42:45]
	global_load_lds_dwordx4 v202, s[22:23]
	s_add_u32 m0, s8, 0x1c00
	v_mfma_f32_16x16x32_bf16 v[46:49], v[196:199], v[176:179], v[46:49]
	global_load_lds_dwordx4 v203, s[22:23]
	s_mov_b32 m0, s9
	v_mfma_f32_16x16x32_bf16 v[50:53], v[184:187], v[180:183], v[50:53]
	global_load_lds_dwordx4 v204, s[24:25]
	s_add_u32 m0, s9, 0x400
	v_mfma_f32_16x16x32_bf16 v[54:57], v[188:191], v[180:183], v[54:57]
	global_load_lds_dwordx4 v205, s[24:25]
	s_add_u32 m0, s9, 0x800
	v_mfma_f32_16x16x32_bf16 v[58:61], v[192:195], v[180:183], v[58:61]
	global_load_lds_dwordx4 v204, s[52:53]
	s_add_u32 m0, s9, 0xc00
	v_mfma_f32_16x16x32_bf16 v[62:65], v[196:199], v[180:183], v[62:65]
	global_load_lds_dwordx4 v205, s[52:53]
	s_waitcnt lgkmcnt(0)
	v_mfma_f32_16x16x32_bf16 v[2:5], v[152:155], v[136:139], v[2:5]
	ds_read_b128 v[168:171], v228 offset:0
	v_mfma_f32_16x16x32_bf16 v[6:9], v[156:159], v[136:139], v[6:9]
	ds_read_b128 v[172:175], v228 offset:2048
	v_mfma_f32_16x16x32_bf16 v[10:13], v[160:163], v[136:139], v[10:13]
	ds_read_b128 v[176:179], v228 offset:4096
	v_mfma_f32_16x16x32_bf16 v[14:17], v[164:167], v[136:139], v[14:17]
	ds_read_b128 v[180:183], v228 offset:6144
	v_mfma_f32_16x16x32_bf16 v[18:21], v[152:155], v[140:143], v[18:21]
	ds_read_b128 v[184:187], v234 offset:0
	v_mfma_f32_16x16x32_bf16 v[22:25], v[156:159], v[140:143], v[22:25]
	ds_read_b128 v[188:191], v234 offset:2048
	v_mfma_f32_16x16x32_bf16 v[26:29], v[160:163], v[140:143], v[26:29]
	ds_read_b128 v[192:195], v234 offset:4096
	v_mfma_f32_16x16x32_bf16 v[30:33], v[164:167], v[140:143], v[30:33]
	ds_read_b128 v[196:199], v234 offset:6144
	v_mfma_f32_16x16x32_bf16 v[34:37], v[152:155], v[144:147], v[34:37]
	v_mfma_f32_16x16x32_bf16 v[38:41], v[156:159], v[144:147], v[38:41]
	v_mfma_f32_16x16x32_bf16 v[42:45], v[160:163], v[144:147], v[42:45]
	v_mfma_f32_16x16x32_bf16 v[46:49], v[164:167], v[144:147], v[46:49]
	v_mfma_f32_16x16x32_bf16 v[50:53], v[152:155], v[148:151], v[50:53]
	v_mfma_f32_16x16x32_bf16 v[54:57], v[156:159], v[148:151], v[54:57]
	v_mfma_f32_16x16x32_bf16 v[58:61], v[160:163], v[148:151], v[58:61]
	v_mfma_f32_16x16x32_bf16 v[62:65], v[164:167], v[148:151], v[62:65]
	s_waitcnt vmcnt(12) lgkmcnt(0)
	s_barrier
	s_add_u32 s14, s4, 0x700
	s_addc_u32 s15, s5, 0
	v_mfma_f32_16x16x32_bf16 v[2:5], v[184:187], v[168:171], v[2:5]
	ds_read_b128 v[136:139], v224 offset:0
	s_add_u32 s22, s4, 0x10700
	s_addc_u32 s23, s5, 0
	v_mfma_f32_16x16x32_bf16 v[6:9], v[188:191], v[168:171], v[6:9]
	ds_read_b128 v[140:143], v224 offset:2048
	s_add_u32 s24, s6, 0x80700
	s_addc_u32 s25, s7, 0
	v_mfma_f32_16x16x32_bf16 v[10:13], v[192:195], v[168:171], v[10:13]
	ds_read_b128 v[144:147], v224 offset:4096
	s_add_u32 s52, s6, 0x88700
	s_addc_u32 s53, s7, 0
	v_mfma_f32_16x16x32_bf16 v[14:17], v[196:199], v[168:171], v[14:17]
	ds_read_b128 v[148:151], v224 offset:6144
	s_add_u32 m0, s8, 0xc000
	v_mfma_f32_16x16x32_bf16 v[18:21], v[184:187], v[172:175], v[18:21]
	global_load_lds_dwordx4 v200, s[14:15]
	ds_read_b128 v[152:155], v232 offset:0
	s_add_u32 m0, s8, 0xc400
	v_mfma_f32_16x16x32_bf16 v[22:25], v[188:191], v[172:175], v[22:25]
	global_load_lds_dwordx4 v201, s[14:15]
	ds_read_b128 v[156:159], v232 offset:2048
	s_add_u32 m0, s8, 0xc800
	v_mfma_f32_16x16x32_bf16 v[26:29], v[192:195], v[172:175], v[26:29]
	global_load_lds_dwordx4 v202, s[14:15]
	ds_read_b128 v[160:163], v232 offset:4096
	s_add_u32 m0, s8, 0xcc00
	v_mfma_f32_16x16x32_bf16 v[30:33], v[196:199], v[172:175], v[30:33]
	global_load_lds_dwordx4 v203, s[14:15]
	ds_read_b128 v[164:167], v232 offset:6144
	s_add_u32 m0, s8, 0xd000
	v_mfma_f32_16x16x32_bf16 v[34:37], v[184:187], v[176:179], v[34:37]
	global_load_lds_dwordx4 v200, s[22:23]
	s_add_u32 m0, s8, 0xd400
	v_mfma_f32_16x16x32_bf16 v[38:41], v[188:191], v[176:179], v[38:41]
	global_load_lds_dwordx4 v201, s[22:23]
	s_add_u32 m0, s8, 0xd800
	v_mfma_f32_16x16x32_bf16 v[42:45], v[192:195], v[176:179], v[42:45]
	global_load_lds_dwordx4 v202, s[22:23]
	s_add_u32 m0, s8, 0xdc00
	v_mfma_f32_16x16x32_bf16 v[46:49], v[196:199], v[176:179], v[46:49]
	global_load_lds_dwordx4 v203, s[22:23]
	s_add_u32 m0, s9, 0xc000
	v_mfma_f32_16x16x32_bf16 v[50:53], v[184:187], v[180:183], v[50:53]
	global_load_lds_dwordx4 v204, s[24:25]
	s_add_u32 m0, s9, 0xc400
	v_mfma_f32_16x16x32_bf16 v[54:57], v[188:191], v[180:183], v[54:57]
	global_load_lds_dwordx4 v205, s[24:25]
	s_add_u32 m0, s9, 0xc800
	v_mfma_f32_16x16x32_bf16 v[58:61], v[192:195], v[180:183], v[58:61]
	global_load_lds_dwordx4 v204, s[52:53]
	s_add_u32 m0, s9, 0xcc00
	v_mfma_f32_16x16x32_bf16 v[62:65], v[196:199], v[180:183], v[62:65]
	global_load_lds_dwordx4 v205, s[52:53]
	s_waitcnt lgkmcnt(0)
	v_mfma_f32_16x16x32_bf16 v[2:5], v[152:155], v[136:139], v[2:5]
	ds_read_b128 v[168:171], v229 offset:0
	v_mfma_f32_16x16x32_bf16 v[6:9], v[156:159], v[136:139], v[6:9]
	ds_read_b128 v[172:175], v229 offset:2048
	v_mfma_f32_16x16x32_bf16 v[10:13], v[160:163], v[136:139], v[10:13]
	ds_read_b128 v[176:179], v229 offset:4096
	v_mfma_f32_16x16x32_bf16 v[14:17], v[164:167], v[136:139], v[14:17]
	ds_read_b128 v[180:183], v229 offset:6144
	v_mfma_f32_16x16x32_bf16 v[18:21], v[152:155], v[140:143], v[18:21]
	ds_read_b128 v[184:187], v235 offset:0
	v_mfma_f32_16x16x32_bf16 v[22:25], v[156:159], v[140:143], v[22:25]
	ds_read_b128 v[188:191], v235 offset:2048
	v_mfma_f32_16x16x32_bf16 v[26:29], v[160:163], v[140:143], v[26:29]
	ds_read_b128 v[192:195], v235 offset:4096
	v_mfma_f32_16x16x32_bf16 v[30:33], v[164:167], v[140:143], v[30:33]
	ds_read_b128 v[196:199], v235 offset:6144
	v_mfma_f32_16x16x32_bf16 v[34:37], v[152:155], v[144:147], v[34:37]
	v_mfma_f32_16x16x32_bf16 v[38:41], v[156:159], v[144:147], v[38:41]
	v_mfma_f32_16x16x32_bf16 v[42:45], v[160:163], v[144:147], v[42:45]
	v_mfma_f32_16x16x32_bf16 v[46:49], v[164:167], v[144:147], v[46:49]
	v_mfma_f32_16x16x32_bf16 v[50:53], v[152:155], v[148:151], v[50:53]
	v_mfma_f32_16x16x32_bf16 v[54:57], v[156:159], v[148:151], v[54:57]
	v_mfma_f32_16x16x32_bf16 v[58:61], v[160:163], v[148:151], v[58:61]
	v_mfma_f32_16x16x32_bf16 v[62:65], v[164:167], v[148:151], v[62:65]
	s_waitcnt vmcnt(12) lgkmcnt(0)
	s_barrier
	s_add_u32 s14, s4, 0x780
	s_addc_u32 s15, s5, 0
	v_mfma_f32_16x16x32_bf16 v[2:5], v[184:187], v[168:171], v[2:5]
	ds_read_b128 v[136:139], v218 offset:0
	s_add_u32 s22, s4, 0x10780
	s_addc_u32 s23, s5, 0
	v_mfma_f32_16x16x32_bf16 v[6:9], v[188:191], v[168:171], v[6:9]
	ds_read_b128 v[140:143], v218 offset:2048
	s_add_u32 s24, s6, 0x80780
	s_addc_u32 s25, s7, 0
	v_mfma_f32_16x16x32_bf16 v[10:13], v[192:195], v[168:171], v[10:13]
	ds_read_b128 v[144:147], v218 offset:4096
	s_add_u32 s52, s6, 0x88780
	s_addc_u32 s53, s7, 0
	v_mfma_f32_16x16x32_bf16 v[14:17], v[196:199], v[168:171], v[14:17]
	ds_read_b128 v[148:151], v218 offset:6144
	s_add_u32 m0, s8, 0x18000
	v_mfma_f32_16x16x32_bf16 v[18:21], v[184:187], v[172:175], v[18:21]
	global_load_lds_dwordx4 v200, s[14:15]
	ds_read_b128 v[152:155], v230 offset:0
	s_add_u32 m0, s8, 0x18400
	v_mfma_f32_16x16x32_bf16 v[22:25], v[188:191], v[172:175], v[22:25]
	global_load_lds_dwordx4 v201, s[14:15]
	ds_read_b128 v[156:159], v230 offset:2048
	s_add_u32 m0, s8, 0x18800
	v_mfma_f32_16x16x32_bf16 v[26:29], v[192:195], v[172:175], v[26:29]
	global_load_lds_dwordx4 v202, s[14:15]
	ds_read_b128 v[160:163], v230 offset:4096
	s_add_u32 m0, s8, 0x18c00
	v_mfma_f32_16x16x32_bf16 v[30:33], v[196:199], v[172:175], v[30:33]
	global_load_lds_dwordx4 v203, s[14:15]
	ds_read_b128 v[164:167], v230 offset:6144
	s_add_u32 m0, s8, 0x19000
	v_mfma_f32_16x16x32_bf16 v[34:37], v[184:187], v[176:179], v[34:37]
	global_load_lds_dwordx4 v200, s[22:23]
	s_add_u32 m0, s8, 0x19400
	v_mfma_f32_16x16x32_bf16 v[38:41], v[188:191], v[176:179], v[38:41]
	global_load_lds_dwordx4 v201, s[22:23]
	s_add_u32 m0, s8, 0x19800
	v_mfma_f32_16x16x32_bf16 v[42:45], v[192:195], v[176:179], v[42:45]
	global_load_lds_dwordx4 v202, s[22:23]
	s_add_u32 m0, s8, 0x19c00
	v_mfma_f32_16x16x32_bf16 v[46:49], v[196:199], v[176:179], v[46:49]
	global_load_lds_dwordx4 v203, s[22:23]
	s_add_u32 m0, s9, 0x18000
	v_mfma_f32_16x16x32_bf16 v[50:53], v[184:187], v[180:183], v[50:53]
	global_load_lds_dwordx4 v204, s[24:25]
	s_add_u32 m0, s9, 0x18400
	v_mfma_f32_16x16x32_bf16 v[54:57], v[188:191], v[180:183], v[54:57]
	global_load_lds_dwordx4 v205, s[24:25]
	s_add_u32 m0, s9, 0x18800
	v_mfma_f32_16x16x32_bf16 v[58:61], v[192:195], v[180:183], v[58:61]
	global_load_lds_dwordx4 v204, s[52:53]
	s_add_u32 m0, s9, 0x18c00
	v_mfma_f32_16x16x32_bf16 v[62:65], v[196:199], v[180:183], v[62:65]
	global_load_lds_dwordx4 v205, s[52:53]
	s_waitcnt lgkmcnt(0)
	v_mfma_f32_16x16x32_bf16 v[2:5], v[152:155], v[136:139], v[2:5]
	ds_read_b128 v[168:171], v225 offset:0
	v_mfma_f32_16x16x32_bf16 v[6:9], v[156:159], v[136:139], v[6:9]
	ds_read_b128 v[172:175], v225 offset:2048
	v_mfma_f32_16x16x32_bf16 v[10:13], v[160:163], v[136:139], v[10:13]
	ds_read_b128 v[176:179], v225 offset:4096
	v_mfma_f32_16x16x32_bf16 v[14:17], v[164:167], v[136:139], v[14:17]
	ds_read_b128 v[180:183], v225 offset:6144
	v_mfma_f32_16x16x32_bf16 v[18:21], v[152:155], v[140:143], v[18:21]
	ds_read_b128 v[184:187], v233 offset:0
	v_mfma_f32_16x16x32_bf16 v[22:25], v[156:159], v[140:143], v[22:25]
	ds_read_b128 v[188:191], v233 offset:2048
	v_mfma_f32_16x16x32_bf16 v[26:29], v[160:163], v[140:143], v[26:29]
	ds_read_b128 v[192:195], v233 offset:4096
	v_mfma_f32_16x16x32_bf16 v[30:33], v[164:167], v[140:143], v[30:33]
	ds_read_b128 v[196:199], v233 offset:6144
	v_mfma_f32_16x16x32_bf16 v[34:37], v[152:155], v[144:147], v[34:37]
	v_mfma_f32_16x16x32_bf16 v[38:41], v[156:159], v[144:147], v[38:41]
	v_mfma_f32_16x16x32_bf16 v[42:45], v[160:163], v[144:147], v[42:45]
	v_mfma_f32_16x16x32_bf16 v[46:49], v[164:167], v[144:147], v[46:49]
	v_mfma_f32_16x16x32_bf16 v[50:53], v[152:155], v[148:151], v[50:53]
	v_mfma_f32_16x16x32_bf16 v[54:57], v[156:159], v[148:151], v[54:57]
	v_mfma_f32_16x16x32_bf16 v[58:61], v[160:163], v[148:151], v[58:61]
	v_mfma_f32_16x16x32_bf16 v[62:65], v[164:167], v[148:151], v[62:65]
	s_waitcnt vmcnt(12) lgkmcnt(0)
	s_barrier
	s_add_u32 s14, s4, 0x0
	s_addc_u32 s15, s5, 0
	v_mfma_f32_16x16x32_bf16 v[2:5], v[184:187], v[168:171], v[2:5]
	ds_read_b128 v[136:139], v219 offset:0
	s_add_u32 s22, s4, 0x10000
	s_addc_u32 s23, s5, 0
	v_mfma_f32_16x16x32_bf16 v[6:9], v[188:191], v[168:171], v[6:9]
	ds_read_b128 v[140:143], v219 offset:2048
	s_add_u32 s24, s6, 0xc0000
	s_addc_u32 s25, s7, 0
	v_mfma_f32_16x16x32_bf16 v[10:13], v[192:195], v[168:171], v[10:13]
	ds_read_b128 v[144:147], v219 offset:4096
	s_add_u32 s52, s6, 0xc8000
	s_addc_u32 s53, s7, 0
	v_mfma_f32_16x16x32_bf16 v[14:17], v[196:199], v[168:171], v[14:17]
	ds_read_b128 v[148:151], v219 offset:6144
	s_mov_b32 m0, s8
	v_mfma_f32_16x16x32_bf16 v[18:21], v[184:187], v[172:175], v[18:21]
	global_load_lds_dwordx4 v200, s[14:15]
	ds_read_b128 v[152:155], v231 offset:0
	s_add_u32 m0, s8, 0x400
	v_mfma_f32_16x16x32_bf16 v[22:25], v[188:191], v[172:175], v[22:25]
	global_load_lds_dwordx4 v201, s[14:15]
	ds_read_b128 v[156:159], v231 offset:2048
	s_add_u32 m0, s8, 0x800
	v_mfma_f32_16x16x32_bf16 v[26:29], v[192:195], v[172:175], v[26:29]
	global_load_lds_dwordx4 v202, s[14:15]
	ds_read_b128 v[160:163], v231 offset:4096
	s_add_u32 m0, s8, 0xc00
	v_mfma_f32_16x16x32_bf16 v[30:33], v[196:199], v[172:175], v[30:33]
	global_load_lds_dwordx4 v203, s[14:15]
	ds_read_b128 v[164:167], v231 offset:6144
	s_add_u32 m0, s8, 0x1000
	v_mfma_f32_16x16x32_bf16 v[34:37], v[184:187], v[176:179], v[34:37]
	global_load_lds_dwordx4 v200, s[22:23]
	s_add_u32 m0, s8, 0x1400
	v_mfma_f32_16x16x32_bf16 v[38:41], v[188:191], v[176:179], v[38:41]
	global_load_lds_dwordx4 v201, s[22:23]
	s_add_u32 m0, s8, 0x1800
	v_mfma_f32_16x16x32_bf16 v[42:45], v[192:195], v[176:179], v[42:45]
	global_load_lds_dwordx4 v202, s[22:23]
	s_add_u32 m0, s8, 0x1c00
	v_mfma_f32_16x16x32_bf16 v[46:49], v[196:199], v[176:179], v[46:49]
	global_load_lds_dwordx4 v203, s[22:23]
	s_mov_b32 m0, s9
	v_mfma_f32_16x16x32_bf16 v[50:53], v[184:187], v[180:183], v[50:53]
	global_load_lds_dwordx4 v204, s[24:25]
	s_add_u32 m0, s9, 0x400
	v_mfma_f32_16x16x32_bf16 v[54:57], v[188:191], v[180:183], v[54:57]
	global_load_lds_dwordx4 v205, s[24:25]
	s_add_u32 m0, s9, 0x800
	v_mfma_f32_16x16x32_bf16 v[58:61], v[192:195], v[180:183], v[58:61]
	global_load_lds_dwordx4 v204, s[52:53]
	s_add_u32 m0, s9, 0xc00
	v_mfma_f32_16x16x32_bf16 v[62:65], v[196:199], v[180:183], v[62:65]
	global_load_lds_dwordx4 v205, s[52:53]
	s_waitcnt lgkmcnt(0)
	v_mfma_f32_16x16x32_bf16 v[2:5], v[152:155], v[136:139], v[2:5]
	ds_read_b128 v[168:171], v228 offset:0
	v_mfma_f32_16x16x32_bf16 v[6:9], v[156:159], v[136:139], v[6:9]
	ds_read_b128 v[172:175], v228 offset:2048
	v_mfma_f32_16x16x32_bf16 v[10:13], v[160:163], v[136:139], v[10:13]
	ds_read_b128 v[176:179], v228 offset:4096
	v_mfma_f32_16x16x32_bf16 v[14:17], v[164:167], v[136:139], v[14:17]
	ds_read_b128 v[180:183], v228 offset:6144
	v_mfma_f32_16x16x32_bf16 v[18:21], v[152:155], v[140:143], v[18:21]
	ds_read_b128 v[184:187], v234 offset:0
	v_mfma_f32_16x16x32_bf16 v[22:25], v[156:159], v[140:143], v[22:25]
	ds_read_b128 v[188:191], v234 offset:2048
	v_mfma_f32_16x16x32_bf16 v[26:29], v[160:163], v[140:143], v[26:29]
	ds_read_b128 v[192:195], v234 offset:4096
	v_mfma_f32_16x16x32_bf16 v[30:33], v[164:167], v[140:143], v[30:33]
	ds_read_b128 v[196:199], v234 offset:6144
	v_mfma_f32_16x16x32_bf16 v[34:37], v[152:155], v[144:147], v[34:37]
	v_mfma_f32_16x16x32_bf16 v[38:41], v[156:159], v[144:147], v[38:41]
	v_mfma_f32_16x16x32_bf16 v[42:45], v[160:163], v[144:147], v[42:45]
	v_mfma_f32_16x16x32_bf16 v[46:49], v[164:167], v[144:147], v[46:49]
	v_mfma_f32_16x16x32_bf16 v[50:53], v[152:155], v[148:151], v[50:53]
	v_mfma_f32_16x16x32_bf16 v[54:57], v[156:159], v[148:151], v[54:57]
	v_mfma_f32_16x16x32_bf16 v[58:61], v[160:163], v[148:151], v[58:61]
	v_mfma_f32_16x16x32_bf16 v[62:65], v[164:167], v[148:151], v[62:65]
	s_waitcnt vmcnt(12) lgkmcnt(0)
	s_barrier
	s_add_u32 s14, s4, 0x80
	s_addc_u32 s15, s5, 0
	v_mfma_f32_16x16x32_bf16 v[2:5], v[184:187], v[168:171], v[2:5]
	ds_read_b128 v[136:139], v224 offset:0
	s_add_u32 s22, s4, 0x10080
	s_addc_u32 s23, s5, 0
	v_mfma_f32_16x16x32_bf16 v[6:9], v[188:191], v[168:171], v[6:9]
	ds_read_b128 v[140:143], v224 offset:2048
	s_add_u32 s24, s6, 0xc0080
	s_addc_u32 s25, s7, 0
	v_mfma_f32_16x16x32_bf16 v[10:13], v[192:195], v[168:171], v[10:13]
	ds_read_b128 v[144:147], v224 offset:4096
	s_add_u32 s52, s6, 0xc8080
	s_addc_u32 s53, s7, 0
	v_mfma_f32_16x16x32_bf16 v[14:17], v[196:199], v[168:171], v[14:17]
	ds_read_b128 v[148:151], v224 offset:6144
	s_add_u32 m0, s8, 0xc000
	v_mfma_f32_16x16x32_bf16 v[18:21], v[184:187], v[172:175], v[18:21]
	global_load_lds_dwordx4 v200, s[14:15]
	ds_read_b128 v[152:155], v232 offset:0
	s_add_u32 m0, s8, 0xc400
	v_mfma_f32_16x16x32_bf16 v[22:25], v[188:191], v[172:175], v[22:25]
	global_load_lds_dwordx4 v201, s[14:15]
	ds_read_b128 v[156:159], v232 offset:2048
	s_add_u32 m0, s8, 0xc800
	v_mfma_f32_16x16x32_bf16 v[26:29], v[192:195], v[172:175], v[26:29]
	global_load_lds_dwordx4 v202, s[14:15]
	ds_read_b128 v[160:163], v232 offset:4096
	s_add_u32 m0, s8, 0xcc00
	v_mfma_f32_16x16x32_bf16 v[30:33], v[196:199], v[172:175], v[30:33]
	global_load_lds_dwordx4 v203, s[14:15]
	ds_read_b128 v[164:167], v232 offset:6144
	s_add_u32 m0, s8, 0xd000
	v_mfma_f32_16x16x32_bf16 v[34:37], v[184:187], v[176:179], v[34:37]
	global_load_lds_dwordx4 v200, s[22:23]
	s_add_u32 m0, s8, 0xd400
	v_mfma_f32_16x16x32_bf16 v[38:41], v[188:191], v[176:179], v[38:41]
	global_load_lds_dwordx4 v201, s[22:23]
	s_add_u32 m0, s8, 0xd800
	v_mfma_f32_16x16x32_bf16 v[42:45], v[192:195], v[176:179], v[42:45]
	global_load_lds_dwordx4 v202, s[22:23]
	s_add_u32 m0, s8, 0xdc00
	v_mfma_f32_16x16x32_bf16 v[46:49], v[196:199], v[176:179], v[46:49]
	global_load_lds_dwordx4 v203, s[22:23]
	s_add_u32 m0, s9, 0xc000
	v_mfma_f32_16x16x32_bf16 v[50:53], v[184:187], v[180:183], v[50:53]
	global_load_lds_dwordx4 v204, s[24:25]
	s_add_u32 m0, s9, 0xc400
	v_mfma_f32_16x16x32_bf16 v[54:57], v[188:191], v[180:183], v[54:57]
	global_load_lds_dwordx4 v205, s[24:25]
	s_add_u32 m0, s9, 0xc800
	v_mfma_f32_16x16x32_bf16 v[58:61], v[192:195], v[180:183], v[58:61]
	global_load_lds_dwordx4 v204, s[52:53]
	s_add_u32 m0, s9, 0xcc00
	v_mfma_f32_16x16x32_bf16 v[62:65], v[196:199], v[180:183], v[62:65]
	global_load_lds_dwordx4 v205, s[52:53]
	s_waitcnt lgkmcnt(0)
	v_mfma_f32_16x16x32_bf16 v[2:5], v[152:155], v[136:139], v[2:5]
	ds_read_b128 v[168:171], v229 offset:0
	v_mfma_f32_16x16x32_bf16 v[6:9], v[156:159], v[136:139], v[6:9]
	ds_read_b128 v[172:175], v229 offset:2048
	v_mfma_f32_16x16x32_bf16 v[10:13], v[160:163], v[136:139], v[10:13]
	ds_read_b128 v[176:179], v229 offset:4096
	v_mfma_f32_16x16x32_bf16 v[14:17], v[164:167], v[136:139], v[14:17]
	ds_read_b128 v[180:183], v229 offset:6144
	v_mfma_f32_16x16x32_bf16 v[18:21], v[152:155], v[140:143], v[18:21]
	ds_read_b128 v[184:187], v235 offset:0
	v_mfma_f32_16x16x32_bf16 v[22:25], v[156:159], v[140:143], v[22:25]
	ds_read_b128 v[188:191], v235 offset:2048
	v_mfma_f32_16x16x32_bf16 v[26:29], v[160:163], v[140:143], v[26:29]
	ds_read_b128 v[192:195], v235 offset:4096
	v_mfma_f32_16x16x32_bf16 v[30:33], v[164:167], v[140:143], v[30:33]
	ds_read_b128 v[196:199], v235 offset:6144
	v_mfma_f32_16x16x32_bf16 v[34:37], v[152:155], v[144:147], v[34:37]
	v_mfma_f32_16x16x32_bf16 v[38:41], v[156:159], v[144:147], v[38:41]
	v_mfma_f32_16x16x32_bf16 v[42:45], v[160:163], v[144:147], v[42:45]
	v_mfma_f32_16x16x32_bf16 v[46:49], v[164:167], v[144:147], v[46:49]
	v_mfma_f32_16x16x32_bf16 v[50:53], v[152:155], v[148:151], v[50:53]
	v_mfma_f32_16x16x32_bf16 v[54:57], v[156:159], v[148:151], v[54:57]
	v_mfma_f32_16x16x32_bf16 v[58:61], v[160:163], v[148:151], v[58:61]
	v_mfma_f32_16x16x32_bf16 v[62:65], v[164:167], v[148:151], v[62:65]
	s_waitcnt vmcnt(12) lgkmcnt(0)
	s_barrier
	s_add_u32 s14, s4, 0x100
	s_addc_u32 s15, s5, 0
	v_mfma_f32_16x16x32_bf16 v[2:5], v[184:187], v[168:171], v[2:5]
	ds_read_b128 v[136:139], v218 offset:0
	s_add_u32 s22, s4, 0x10100
	s_addc_u32 s23, s5, 0
	v_mfma_f32_16x16x32_bf16 v[6:9], v[188:191], v[168:171], v[6:9]
	ds_read_b128 v[140:143], v218 offset:2048
	s_add_u32 s24, s6, 0xc0100
	s_addc_u32 s25, s7, 0
	v_mfma_f32_16x16x32_bf16 v[10:13], v[192:195], v[168:171], v[10:13]
	ds_read_b128 v[144:147], v218 offset:4096
	s_add_u32 s52, s6, 0xc8100
	s_addc_u32 s53, s7, 0
	v_mfma_f32_16x16x32_bf16 v[14:17], v[196:199], v[168:171], v[14:17]
	ds_read_b128 v[148:151], v218 offset:6144
	s_add_u32 m0, s8, 0x18000
	v_mfma_f32_16x16x32_bf16 v[18:21], v[184:187], v[172:175], v[18:21]
	global_load_lds_dwordx4 v200, s[14:15]
	ds_read_b128 v[152:155], v230 offset:0
	s_add_u32 m0, s8, 0x18400
	v_mfma_f32_16x16x32_bf16 v[22:25], v[188:191], v[172:175], v[22:25]
	global_load_lds_dwordx4 v201, s[14:15]
	ds_read_b128 v[156:159], v230 offset:2048
	s_add_u32 m0, s8, 0x18800
	v_mfma_f32_16x16x32_bf16 v[26:29], v[192:195], v[172:175], v[26:29]
	global_load_lds_dwordx4 v202, s[14:15]
	ds_read_b128 v[160:163], v230 offset:4096
	s_add_u32 m0, s8, 0x18c00
	v_mfma_f32_16x16x32_bf16 v[30:33], v[196:199], v[172:175], v[30:33]
	global_load_lds_dwordx4 v203, s[14:15]
	ds_read_b128 v[164:167], v230 offset:6144
	s_add_u32 m0, s8, 0x19000
	v_mfma_f32_16x16x32_bf16 v[34:37], v[184:187], v[176:179], v[34:37]
	global_load_lds_dwordx4 v200, s[22:23]
	s_add_u32 m0, s8, 0x19400
	v_mfma_f32_16x16x32_bf16 v[38:41], v[188:191], v[176:179], v[38:41]
	global_load_lds_dwordx4 v201, s[22:23]
	s_add_u32 m0, s8, 0x19800
	v_mfma_f32_16x16x32_bf16 v[42:45], v[192:195], v[176:179], v[42:45]
	global_load_lds_dwordx4 v202, s[22:23]
	s_add_u32 m0, s8, 0x19c00
	v_mfma_f32_16x16x32_bf16 v[46:49], v[196:199], v[176:179], v[46:49]
	global_load_lds_dwordx4 v203, s[22:23]
	s_add_u32 m0, s9, 0x18000
	v_mfma_f32_16x16x32_bf16 v[50:53], v[184:187], v[180:183], v[50:53]
	global_load_lds_dwordx4 v204, s[24:25]
	s_add_u32 m0, s9, 0x18400
	v_mfma_f32_16x16x32_bf16 v[54:57], v[188:191], v[180:183], v[54:57]
	global_load_lds_dwordx4 v205, s[24:25]
	s_add_u32 m0, s9, 0x18800
	v_mfma_f32_16x16x32_bf16 v[58:61], v[192:195], v[180:183], v[58:61]
	global_load_lds_dwordx4 v204, s[52:53]
	s_add_u32 m0, s9, 0x18c00
	v_mfma_f32_16x16x32_bf16 v[62:65], v[196:199], v[180:183], v[62:65]
	global_load_lds_dwordx4 v205, s[52:53]
	s_waitcnt lgkmcnt(0)
	v_mfma_f32_16x16x32_bf16 v[66:69], v[152:155], v[136:139], 0
	ds_read_b128 v[168:171], v225 offset:0
	s_add_u32 s10, s28, s13
	s_addc_u32 s11, s29, 0
	s_add_u32 s13, s13, 0x10000
	v_mfma_f32_16x16x32_bf16 v[70:73], v[156:159], v[136:139], 0
	ds_read_b128 v[172:175], v225 offset:2048
	v_mul_f32_e32 v2, s12, v2
	v_mul_f32_e32 v3, s12, v3
	v_mfma_f32_16x16x32_bf16 v[74:77], v[160:163], v[136:139], 0
	ds_read_b128 v[176:179], v225 offset:4096
	v_mul_f32_e32 v4, s12, v4
	v_mul_f32_e32 v5, s12, v5
	v_mul_f32_e32 v6, s12, v6
	v_mfma_f32_16x16x32_bf16 v[78:81], v[164:167], v[136:139], 0
	ds_read_b128 v[180:183], v225 offset:6144
	v_mul_f32_e32 v7, s12, v7
	v_mul_f32_e32 v8, s12, v8
	v_mfma_f32_16x16x32_bf16 v[82:85], v[152:155], v[140:143], 0
	ds_read_b128 v[184:187], v233 offset:0
	v_mul_f32_e32 v9, s12, v9
	v_exp_f32_e32 v2, v2
	v_mfma_f32_16x16x32_bf16 v[86:89], v[156:159], v[140:143], 0
	ds_read_b128 v[188:191], v233 offset:2048
	v_exp_f32_e32 v3, v3
	v_exp_f32_e32 v4, v4
	v_exp_f32_e32 v5, v5
	v_mfma_f32_16x16x32_bf16 v[90:93], v[160:163], v[140:143], 0
	ds_read_b128 v[192:195], v233 offset:4096
	v_exp_f32_e32 v6, v6
	v_exp_f32_e32 v7, v7
	v_mfma_f32_16x16x32_bf16 v[94:97], v[164:167], v[140:143], 0
	ds_read_b128 v[196:199], v233 offset:6144
	v_exp_f32_e32 v8, v8
	v_exp_f32_e32 v9, v9
	v_add_f32_e32 v2, 1.0, v2
	v_mfma_f32_16x16x32_bf16 v[98:101], v[152:155], v[144:147], 0
	v_add_f32_e32 v3, 1.0, v3
	v_add_f32_e32 v4, 1.0, v4
	v_mfma_f32_16x16x32_bf16 v[102:105], v[156:159], v[144:147], 0
	v_add_f32_e32 v5, 1.0, v5
	v_add_f32_e32 v6, 1.0, v6
	v_mfma_f32_16x16x32_bf16 v[106:109], v[160:163], v[144:147], 0
	v_add_f32_e32 v7, 1.0, v7
	v_add_f32_e32 v8, 1.0, v8
	v_add_f32_e32 v9, 1.0, v9
	v_mfma_f32_16x16x32_bf16 v[110:113], v[164:167], v[144:147], 0
	v_rcp_f32_e32 v2, v2
	v_rcp_f32_e32 v3, v3
	v_mfma_f32_16x16x32_bf16 v[114:117], v[152:155], v[148:151], 0
	v_rcp_f32_e32 v4, v4
	v_rcp_f32_e32 v5, v5
	v_mfma_f32_16x16x32_bf16 v[118:121], v[156:159], v[148:151], 0
	v_rcp_f32_e32 v6, v6
	v_rcp_f32_e32 v7, v7
	v_rcp_f32_e32 v8, v8
	v_mfma_f32_16x16x32_bf16 v[122:125], v[160:163], v[148:151], 0
	v_rcp_f32_e32 v9, v9
	v_cvt_pk_bf16_f32 v2, v2, v3
	v_mfma_f32_16x16x32_bf16 v[126:129], v[164:167], v[148:151], 0
	v_cvt_pk_bf16_f32 v3, v4, v5
	v_cvt_pk_bf16_f32 v4, v6, v7
	v_cvt_pk_bf16_f32 v5, v8, v9
	s_waitcnt vmcnt(12) lgkmcnt(0)
	s_barrier
	v_mfma_f32_16x16x32_bf16 v[66:69], v[184:187], v[168:171], v[66:69]
	ds_read_b128 v[136:139], v219 offset:0
	global_store_dwordx4 v240, v[2:5], s[10:11] offset:0
	v_mul_f32_e32 v10, s12, v10
	v_mfma_f32_16x16x32_bf16 v[70:73], v[188:191], v[168:171], v[70:73]
	ds_read_b128 v[140:143], v219 offset:2048
	v_mul_f32_e32 v11, s12, v11
	v_mul_f32_e32 v12, s12, v12
	v_mfma_f32_16x16x32_bf16 v[74:77], v[192:195], v[168:171], v[74:77]
	ds_read_b128 v[144:147], v219 offset:4096
	v_mul_f32_e32 v13, s12, v13
	v_mul_f32_e32 v14, s12, v14
	v_mfma_f32_16x16x32_bf16 v[78:81], v[196:199], v[168:171], v[78:81]
	ds_read_b128 v[148:151], v219 offset:6144
	v_mul_f32_e32 v15, s12, v15
	v_mul_f32_e32 v16, s12, v16
	v_mul_f32_e32 v17, s12, v17
	v_mfma_f32_16x16x32_bf16 v[82:85], v[184:187], v[172:175], v[82:85]
	ds_read_b128 v[152:155], v231 offset:0
	v_exp_f32_e32 v10, v10
	v_exp_f32_e32 v11, v11
	v_mfma_f32_16x16x32_bf16 v[86:89], v[188:191], v[172:175], v[86:89]
	ds_read_b128 v[156:159], v231 offset:2048
	v_exp_f32_e32 v12, v12
	v_exp_f32_e32 v13, v13
	v_mfma_f32_16x16x32_bf16 v[90:93], v[192:195], v[172:175], v[90:93]
	ds_read_b128 v[160:163], v231 offset:4096
	v_exp_f32_e32 v14, v14
	v_exp_f32_e32 v15, v15
	v_exp_f32_e32 v16, v16
	v_mfma_f32_16x16x32_bf16 v[94:97], v[196:199], v[172:175], v[94:97]
	ds_read_b128 v[164:167], v231 offset:6144
	v_exp_f32_e32 v17, v17
	v_add_f32_e32 v10, 1.0, v10
	v_mfma_f32_16x16x32_bf16 v[98:101], v[184:187], v[176:179], v[98:101]
	v_add_f32_e32 v11, 1.0, v11
	v_add_f32_e32 v12, 1.0, v12
	v_mfma_f32_16x16x32_bf16 v[102:105], v[188:191], v[176:179], v[102:105]
	v_add_f32_e32 v13, 1.0, v13
	v_add_f32_e32 v14, 1.0, v14
	v_add_f32_e32 v15, 1.0, v15
	v_mfma_f32_16x16x32_bf16 v[106:109], v[192:195], v[176:179], v[106:109]
	v_add_f32_e32 v16, 1.0, v16
	v_add_f32_e32 v17, 1.0, v17
	v_mfma_f32_16x16x32_bf16 v[110:113], v[196:199], v[176:179], v[110:113]
	v_rcp_f32_e32 v10, v10
	v_rcp_f32_e32 v11, v11
	v_mfma_f32_16x16x32_bf16 v[114:117], v[184:187], v[180:183], v[114:117]
	v_rcp_f32_e32 v12, v12
	v_rcp_f32_e32 v13, v13
	v_rcp_f32_e32 v14, v14
	v_mfma_f32_16x16x32_bf16 v[118:121], v[188:191], v[180:183], v[118:121]
	v_rcp_f32_e32 v15, v15
	v_rcp_f32_e32 v16, v16
	v_mfma_f32_16x16x32_bf16 v[122:125], v[192:195], v[180:183], v[122:125]
	v_rcp_f32_e32 v17, v17
	v_cvt_pk_bf16_f32 v10, v10, v11
	v_mfma_f32_16x16x32_bf16 v[126:129], v[196:199], v[180:183], v[126:129]
	v_cvt_pk_bf16_f32 v11, v12, v13
	v_cvt_pk_bf16_f32 v12, v14, v15
	v_cvt_pk_bf16_f32 v13, v16, v17
	s_waitcnt lgkmcnt(0)
	v_mfma_f32_16x16x32_bf16 v[66:69], v[152:155], v[136:139], v[66:69]
	ds_read_b128 v[168:171], v228 offset:0
	global_store_dwordx4 v240, v[10:13], s[10:11] offset:16
	v_mul_f32_e32 v18, s12, v18
	v_mfma_f32_16x16x32_bf16 v[70:73], v[156:159], v[136:139], v[70:73]
	ds_read_b128 v[172:175], v228 offset:2048
	v_mul_f32_e32 v19, s12, v19
	v_mul_f32_e32 v20, s12, v20
	v_mfma_f32_16x16x32_bf16 v[74:77], v[160:163], v[136:139], v[74:77]
	ds_read_b128 v[176:179], v228 offset:4096
	v_mul_f32_e32 v21, s12, v21
	v_mul_f32_e32 v22, s12, v22
	v_mul_f32_e32 v23, s12, v23
	v_mfma_f32_16x16x32_bf16 v[78:81], v[164:167], v[136:139], v[78:81]
	ds_read_b128 v[180:183], v228 offset:6144
	v_mul_f32_e32 v24, s12, v24
	v_mul_f32_e32 v25, s12, v25
	v_mfma_f32_16x16x32_bf16 v[82:85], v[152:155], v[140:143], v[82:85]
	ds_read_b128 v[184:187], v234 offset:0
	v_exp_f32_e32 v18, v18
	v_exp_f32_e32 v19, v19
	v_mfma_f32_16x16x32_bf16 v[86:89], v[156:159], v[140:143], v[86:89]
	ds_read_b128 v[188:191], v234 offset:2048
	v_exp_f32_e32 v20, v20
	v_exp_f32_e32 v21, v21
	v_exp_f32_e32 v22, v22
	v_mfma_f32_16x16x32_bf16 v[90:93], v[160:163], v[140:143], v[90:93]
	ds_read_b128 v[192:195], v234 offset:4096
	v_exp_f32_e32 v23, v23
	v_exp_f32_e32 v24, v24
	v_mfma_f32_16x16x32_bf16 v[94:97], v[164:167], v[140:143], v[94:97]
	ds_read_b128 v[196:199], v234 offset:6144
	v_exp_f32_e32 v25, v25
	v_add_f32_e32 v18, 1.0, v18
	v_add_f32_e32 v19, 1.0, v19
	v_mfma_f32_16x16x32_bf16 v[98:101], v[152:155], v[144:147], v[98:101]
	v_add_f32_e32 v20, 1.0, v20
	v_add_f32_e32 v21, 1.0, v21
	v_mfma_f32_16x16x32_bf16 v[102:105], v[156:159], v[144:147], v[102:105]
	v_add_f32_e32 v22, 1.0, v22
	v_add_f32_e32 v23, 1.0, v23
	v_mfma_f32_16x16x32_bf16 v[106:109], v[160:163], v[144:147], v[106:109]
	v_add_f32_e32 v24, 1.0, v24
	v_add_f32_e32 v25, 1.0, v25
	v_rcp_f32_e32 v18, v18
	v_mfma_f32_16x16x32_bf16 v[110:113], v[164:167], v[144:147], v[110:113]
	v_rcp_f32_e32 v19, v19
	v_rcp_f32_e32 v20, v20
	v_mfma_f32_16x16x32_bf16 v[114:117], v[152:155], v[148:151], v[114:117]
	v_rcp_f32_e32 v21, v21
	v_rcp_f32_e32 v22, v22
	v_mfma_f32_16x16x32_bf16 v[118:121], v[156:159], v[148:151], v[118:121]
	v_rcp_f32_e32 v23, v23
	v_rcp_f32_e32 v24, v24
	v_rcp_f32_e32 v25, v25
	v_mfma_f32_16x16x32_bf16 v[122:125], v[160:163], v[148:151], v[122:125]
	v_cvt_pk_bf16_f32 v18, v18, v19
	v_cvt_pk_bf16_f32 v19, v20, v21
	v_mfma_f32_16x16x32_bf16 v[126:129], v[164:167], v[148:151], v[126:129]
	v_cvt_pk_bf16_f32 v20, v22, v23
	v_cvt_pk_bf16_f32 v21, v24, v25
	global_store_dwordx4 v240, v[18:21], s[10:11] offset:2048
	s_waitcnt vmcnt(3) lgkmcnt(0)
	s_barrier
	v_mfma_f32_16x16x32_bf16 v[66:69], v[184:187], v[168:171], v[66:69]
	ds_read_b128 v[136:139], v224 offset:0
	v_mul_f32_e32 v26, s12, v26
	v_mul_f32_e32 v27, s12, v27
	v_mfma_f32_16x16x32_bf16 v[70:73], v[188:191], v[168:171], v[70:73]
	ds_read_b128 v[140:143], v224 offset:2048
	v_mul_f32_e32 v28, s12, v28
	v_mul_f32_e32 v29, s12, v29
	v_mfma_f32_16x16x32_bf16 v[74:77], v[192:195], v[168:171], v[74:77]
	ds_read_b128 v[144:147], v224 offset:4096
	v_mul_f32_e32 v30, s12, v30
	v_mul_f32_e32 v31, s12, v31
	v_mfma_f32_16x16x32_bf16 v[78:81], v[196:199], v[168:171], v[78:81]
	ds_read_b128 v[148:151], v224 offset:6144
	v_mul_f32_e32 v32, s12, v32
	v_mul_f32_e32 v33, s12, v33
	v_exp_f32_e32 v26, v26
	v_mfma_f32_16x16x32_bf16 v[82:85], v[184:187], v[172:175], v[82:85]
	ds_read_b128 v[152:155], v232 offset:0
	v_exp_f32_e32 v27, v27
	v_exp_f32_e32 v28, v28
	v_mfma_f32_16x16x32_bf16 v[86:89], v[188:191], v[172:175], v[86:89]
	ds_read_b128 v[156:159], v232 offset:2048
	v_exp_f32_e32 v29, v29
	v_exp_f32_e32 v30, v30
	v_mfma_f32_16x16x32_bf16 v[90:93], v[192:195], v[172:175], v[90:93]
	ds_read_b128 v[160:163], v232 offset:4096
	v_exp_f32_e32 v31, v31
	v_exp_f32_e32 v32, v32
	v_exp_f32_e32 v33, v33
	v_mfma_f32_16x16x32_bf16 v[94:97], v[196:199], v[172:175], v[94:97]
	ds_read_b128 v[164:167], v232 offset:6144
	v_add_f32_e32 v26, 1.0, v26
	v_add_f32_e32 v27, 1.0, v27
	v_mfma_f32_16x16x32_bf16 v[98:101], v[184:187], v[176:179], v[98:101]
	v_add_f32_e32 v28, 1.0, v28
	v_add_f32_e32 v29, 1.0, v29
	v_mfma_f32_16x16x32_bf16 v[102:105], v[188:191], v[176:179], v[102:105]
	v_add_f32_e32 v30, 1.0, v30
	v_add_f32_e32 v31, 1.0, v31
	v_add_f32_e32 v32, 1.0, v32
	v_mfma_f32_16x16x32_bf16 v[106:109], v[192:195], v[176:179], v[106:109]
	v_add_f32_e32 v33, 1.0, v33
	v_rcp_f32_e32 v26, v26
	v_mfma_f32_16x16x32_bf16 v[110:113], v[196:199], v[176:179], v[110:113]
	v_rcp_f32_e32 v27, v27
	v_rcp_f32_e32 v28, v28
	v_mfma_f32_16x16x32_bf16 v[114:117], v[184:187], v[180:183], v[114:117]
	v_rcp_f32_e32 v29, v29
	v_rcp_f32_e32 v30, v30
	v_rcp_f32_e32 v31, v31
	v_mfma_f32_16x16x32_bf16 v[118:121], v[188:191], v[180:183], v[118:121]
	v_rcp_f32_e32 v32, v32
	v_rcp_f32_e32 v33, v33
	v_mfma_f32_16x16x32_bf16 v[122:125], v[192:195], v[180:183], v[122:125]
	v_cvt_pk_bf16_f32 v26, v26, v27
	v_cvt_pk_bf16_f32 v27, v28, v29
	v_mfma_f32_16x16x32_bf16 v[126:129], v[196:199], v[180:183], v[126:129]
	v_cvt_pk_bf16_f32 v28, v30, v31
	v_cvt_pk_bf16_f32 v29, v32, v33
	global_store_dwordx4 v240, v[26:29], s[10:11] offset:2064
	s_waitcnt lgkmcnt(0)
	v_mfma_f32_16x16x32_bf16 v[66:69], v[152:155], v[136:139], v[66:69]
	ds_read_b128 v[168:171], v229 offset:0
	v_mul_f32_e32 v34, s12, v34
	v_mul_f32_e32 v35, s12, v35
	v_mfma_f32_16x16x32_bf16 v[70:73], v[156:159], v[136:139], v[70:73]
	ds_read_b128 v[172:175], v229 offset:2048
	v_mul_f32_e32 v36, s12, v36
	v_mul_f32_e32 v37, s12, v37
	v_mfma_f32_16x16x32_bf16 v[74:77], v[160:163], v[136:139], v[74:77]
	ds_read_b128 v[176:179], v229 offset:4096
	v_mul_f32_e32 v38, s12, v38
	v_mul_f32_e32 v39, s12, v39
	v_mfma_f32_16x16x32_bf16 v[78:81], v[164:167], v[136:139], v[78:81]
	ds_read_b128 v[180:183], v229 offset:6144
	v_mul_f32_e32 v40, s12, v40
	v_mul_f32_e32 v41, s12, v41
	v_exp_f32_e32 v34, v34
	v_mfma_f32_16x16x32_bf16 v[82:85], v[152:155], v[140:143], v[82:85]
	ds_read_b128 v[184:187], v235 offset:0
	v_exp_f32_e32 v35, v35
	v_exp_f32_e32 v36, v36
	v_mfma_f32_16x16x32_bf16 v[86:89], v[156:159], v[140:143], v[86:89]
	ds_read_b128 v[188:191], v235 offset:2048
	v_exp_f32_e32 v37, v37
	v_exp_f32_e32 v38, v38
	v_mfma_f32_16x16x32_bf16 v[90:93], v[160:163], v[140:143], v[90:93]
	ds_read_b128 v[192:195], v235 offset:4096
	v_exp_f32_e32 v39, v39
	v_exp_f32_e32 v40, v40
	v_exp_f32_e32 v41, v41
	v_mfma_f32_16x16x32_bf16 v[94:97], v[164:167], v[140:143], v[94:97]
	ds_read_b128 v[196:199], v235 offset:6144
	v_add_f32_e32 v34, 1.0, v34
	v_add_f32_e32 v35, 1.0, v35
	v_mfma_f32_16x16x32_bf16 v[98:101], v[152:155], v[144:147], v[98:101]
	v_add_f32_e32 v36, 1.0, v36
	v_add_f32_e32 v37, 1.0, v37
	v_mfma_f32_16x16x32_bf16 v[102:105], v[156:159], v[144:147], v[102:105]
	v_add_f32_e32 v38, 1.0, v38
	v_add_f32_e32 v39, 1.0, v39
	v_add_f32_e32 v40, 1.0, v40
	v_mfma_f32_16x16x32_bf16 v[106:109], v[160:163], v[144:147], v[106:109]
	v_add_f32_e32 v41, 1.0, v41
	v_rcp_f32_e32 v34, v34
	v_mfma_f32_16x16x32_bf16 v[110:113], v[164:167], v[144:147], v[110:113]
	v_rcp_f32_e32 v35, v35
	v_rcp_f32_e32 v36, v36
	v_mfma_f32_16x16x32_bf16 v[114:117], v[152:155], v[148:151], v[114:117]
	v_rcp_f32_e32 v37, v37
	v_rcp_f32_e32 v38, v38
	v_rcp_f32_e32 v39, v39
	v_mfma_f32_16x16x32_bf16 v[118:121], v[156:159], v[148:151], v[118:121]
	v_rcp_f32_e32 v40, v40
	v_rcp_f32_e32 v41, v41
	v_mfma_f32_16x16x32_bf16 v[122:125], v[160:163], v[148:151], v[122:125]
	v_cvt_pk_bf16_f32 v34, v34, v35
	v_cvt_pk_bf16_f32 v35, v36, v37
	v_mfma_f32_16x16x32_bf16 v[126:129], v[164:167], v[148:151], v[126:129]
	v_cvt_pk_bf16_f32 v36, v38, v39
	v_cvt_pk_bf16_f32 v37, v40, v41
	global_store_dwordx4 v241, v[34:37], s[10:11] offset:0
	s_waitcnt lgkmcnt(0)
	s_barrier
	v_mfma_f32_16x16x32_bf16 v[66:69], v[184:187], v[168:171], v[66:69]
	ds_read_b128 v[136:139], v218 offset:0
	v_mul_f32_e32 v42, s12, v42
	v_mul_f32_e32 v43, s12, v43
	v_mfma_f32_16x16x32_bf16 v[70:73], v[188:191], v[168:171], v[70:73]
	ds_read_b128 v[140:143], v218 offset:2048
	v_mul_f32_e32 v44, s12, v44
	v_mul_f32_e32 v45, s12, v45
	v_mfma_f32_16x16x32_bf16 v[74:77], v[192:195], v[168:171], v[74:77]
	ds_read_b128 v[144:147], v218 offset:4096
	v_mul_f32_e32 v46, s12, v46
	v_mul_f32_e32 v47, s12, v47
	v_mfma_f32_16x16x32_bf16 v[78:81], v[196:199], v[168:171], v[78:81]
	ds_read_b128 v[148:151], v218 offset:6144
	v_mul_f32_e32 v48, s12, v48
	v_mul_f32_e32 v49, s12, v49
	v_exp_f32_e32 v42, v42
	v_mfma_f32_16x16x32_bf16 v[82:85], v[184:187], v[172:175], v[82:85]
	ds_read_b128 v[152:155], v230 offset:0
	v_exp_f32_e32 v43, v43
	v_exp_f32_e32 v44, v44
	v_mfma_f32_16x16x32_bf16 v[86:89], v[188:191], v[172:175], v[86:89]
	ds_read_b128 v[156:159], v230 offset:2048
	v_exp_f32_e32 v45, v45
	v_exp_f32_e32 v46, v46
	v_mfma_f32_16x16x32_bf16 v[90:93], v[192:195], v[172:175], v[90:93]
	ds_read_b128 v[160:163], v230 offset:4096
	v_exp_f32_e32 v47, v47
	v_exp_f32_e32 v48, v48
	v_exp_f32_e32 v49, v49
	v_mfma_f32_16x16x32_bf16 v[94:97], v[196:199], v[172:175], v[94:97]
	ds_read_b128 v[164:167], v230 offset:6144
	v_add_f32_e32 v42, 1.0, v42
	v_add_f32_e32 v43, 1.0, v43
	v_mfma_f32_16x16x32_bf16 v[98:101], v[184:187], v[176:179], v[98:101]
	v_add_f32_e32 v44, 1.0, v44
	v_add_f32_e32 v45, 1.0, v45
	v_mfma_f32_16x16x32_bf16 v[102:105], v[188:191], v[176:179], v[102:105]
	v_add_f32_e32 v46, 1.0, v46
	v_add_f32_e32 v47, 1.0, v47
	v_add_f32_e32 v48, 1.0, v48
	v_mfma_f32_16x16x32_bf16 v[106:109], v[192:195], v[176:179], v[106:109]
	v_add_f32_e32 v49, 1.0, v49
	v_rcp_f32_e32 v42, v42
	v_mfma_f32_16x16x32_bf16 v[110:113], v[196:199], v[176:179], v[110:113]
	v_rcp_f32_e32 v43, v43
	v_rcp_f32_e32 v44, v44
	v_mfma_f32_16x16x32_bf16 v[114:117], v[184:187], v[180:183], v[114:117]
	v_rcp_f32_e32 v45, v45
	v_rcp_f32_e32 v46, v46
	v_rcp_f32_e32 v47, v47
	v_mfma_f32_16x16x32_bf16 v[118:121], v[188:191], v[180:183], v[118:121]
	v_rcp_f32_e32 v48, v48
	v_rcp_f32_e32 v49, v49
	v_mfma_f32_16x16x32_bf16 v[122:125], v[192:195], v[180:183], v[122:125]
	v_cvt_pk_bf16_f32 v42, v42, v43
	v_cvt_pk_bf16_f32 v43, v44, v45
	v_mfma_f32_16x16x32_bf16 v[126:129], v[196:199], v[180:183], v[126:129]
	v_cvt_pk_bf16_f32 v44, v46, v47
	v_cvt_pk_bf16_f32 v45, v48, v49
	global_store_dwordx4 v241, v[42:45], s[10:11] offset:16
	s_waitcnt lgkmcnt(0)
	v_mfma_f32_16x16x32_bf16 v[66:69], v[152:155], v[136:139], v[66:69]
	ds_read_b128 v[168:171], v225 offset:0
	v_mul_f32_e32 v50, s12, v50
	v_mul_f32_e32 v51, s12, v51
	v_mfma_f32_16x16x32_bf16 v[70:73], v[156:159], v[136:139], v[70:73]
	ds_read_b128 v[172:175], v225 offset:2048
	v_mul_f32_e32 v52, s12, v52
	v_mul_f32_e32 v53, s12, v53
	v_mfma_f32_16x16x32_bf16 v[74:77], v[160:163], v[136:139], v[74:77]
	ds_read_b128 v[176:179], v225 offset:4096
	v_mul_f32_e32 v54, s12, v54
	v_mul_f32_e32 v55, s12, v55
	v_mfma_f32_16x16x32_bf16 v[78:81], v[164:167], v[136:139], v[78:81]
	ds_read_b128 v[180:183], v225 offset:6144
	v_mul_f32_e32 v56, s12, v56
	v_mul_f32_e32 v57, s12, v57
	v_exp_f32_e32 v50, v50
	v_mfma_f32_16x16x32_bf16 v[82:85], v[152:155], v[140:143], v[82:85]
	ds_read_b128 v[184:187], v233 offset:0
	v_exp_f32_e32 v51, v51
	v_exp_f32_e32 v52, v52
	v_mfma_f32_16x16x32_bf16 v[86:89], v[156:159], v[140:143], v[86:89]
	ds_read_b128 v[188:191], v233 offset:2048
	v_exp_f32_e32 v53, v53
	v_exp_f32_e32 v54, v54
	v_mfma_f32_16x16x32_bf16 v[90:93], v[160:163], v[140:143], v[90:93]
	ds_read_b128 v[192:195], v233 offset:4096
	v_exp_f32_e32 v55, v55
	v_exp_f32_e32 v56, v56
	v_exp_f32_e32 v57, v57
	v_mfma_f32_16x16x32_bf16 v[94:97], v[164:167], v[140:143], v[94:97]
	ds_read_b128 v[196:199], v233 offset:6144
	v_add_f32_e32 v50, 1.0, v50
	v_add_f32_e32 v51, 1.0, v51
	v_mfma_f32_16x16x32_bf16 v[98:101], v[152:155], v[144:147], v[98:101]
	v_add_f32_e32 v52, 1.0, v52
	v_add_f32_e32 v53, 1.0, v53
	v_mfma_f32_16x16x32_bf16 v[102:105], v[156:159], v[144:147], v[102:105]
	v_add_f32_e32 v54, 1.0, v54
	v_add_f32_e32 v55, 1.0, v55
	v_add_f32_e32 v56, 1.0, v56
	v_mfma_f32_16x16x32_bf16 v[106:109], v[160:163], v[144:147], v[106:109]
	v_add_f32_e32 v57, 1.0, v57
	v_rcp_f32_e32 v50, v50
	v_mfma_f32_16x16x32_bf16 v[110:113], v[164:167], v[144:147], v[110:113]
	v_rcp_f32_e32 v51, v51
	v_rcp_f32_e32 v52, v52
	v_mfma_f32_16x16x32_bf16 v[114:117], v[152:155], v[148:151], v[114:117]
	v_rcp_f32_e32 v53, v53
	v_rcp_f32_e32 v54, v54
	v_rcp_f32_e32 v55, v55
	v_mfma_f32_16x16x32_bf16 v[118:121], v[156:159], v[148:151], v[118:121]
	v_rcp_f32_e32 v56, v56
	v_rcp_f32_e32 v57, v57
	v_mfma_f32_16x16x32_bf16 v[122:125], v[160:163], v[148:151], v[122:125]
	v_cvt_pk_bf16_f32 v50, v50, v51
	v_cvt_pk_bf16_f32 v51, v52, v53
	v_mfma_f32_16x16x32_bf16 v[126:129], v[164:167], v[148:151], v[126:129]
	v_cvt_pk_bf16_f32 v52, v54, v55
	v_cvt_pk_bf16_f32 v53, v56, v57
	global_store_dwordx4 v241, v[50:53], s[10:11] offset:2048
	s_waitcnt lgkmcnt(0)
	s_barrier
	v_mfma_f32_16x16x32_bf16 v[66:69], v[184:187], v[168:171], v[66:69]
	ds_read_b128 v[136:139], v219 offset:0
	v_mul_f32_e32 v58, s12, v58
	v_mul_f32_e32 v59, s12, v59
	v_mfma_f32_16x16x32_bf16 v[70:73], v[188:191], v[168:171], v[70:73]
	ds_read_b128 v[140:143], v219 offset:2048
	v_mul_f32_e32 v60, s12, v60
	v_mul_f32_e32 v61, s12, v61
	v_mfma_f32_16x16x32_bf16 v[74:77], v[192:195], v[168:171], v[74:77]
	ds_read_b128 v[144:147], v219 offset:4096
	v_mul_f32_e32 v62, s12, v62
	v_mul_f32_e32 v63, s12, v63
	v_mfma_f32_16x16x32_bf16 v[78:81], v[196:199], v[168:171], v[78:81]
	ds_read_b128 v[148:151], v219 offset:6144
	v_mul_f32_e32 v64, s12, v64
	v_mul_f32_e32 v65, s12, v65
	v_exp_f32_e32 v58, v58
	v_mfma_f32_16x16x32_bf16 v[82:85], v[184:187], v[172:175], v[82:85]
	ds_read_b128 v[152:155], v231 offset:0
	v_exp_f32_e32 v59, v59
	v_exp_f32_e32 v60, v60
	v_mfma_f32_16x16x32_bf16 v[86:89], v[188:191], v[172:175], v[86:89]
	ds_read_b128 v[156:159], v231 offset:2048
	v_exp_f32_e32 v61, v61
	v_exp_f32_e32 v62, v62
	v_mfma_f32_16x16x32_bf16 v[90:93], v[192:195], v[172:175], v[90:93]
	ds_read_b128 v[160:163], v231 offset:4096
	v_exp_f32_e32 v63, v63
	v_exp_f32_e32 v64, v64
	v_exp_f32_e32 v65, v65
	v_mfma_f32_16x16x32_bf16 v[94:97], v[196:199], v[172:175], v[94:97]
	ds_read_b128 v[164:167], v231 offset:6144
	v_add_f32_e32 v58, 1.0, v58
	v_add_f32_e32 v59, 1.0, v59
	v_mfma_f32_16x16x32_bf16 v[98:101], v[184:187], v[176:179], v[98:101]
	v_add_f32_e32 v60, 1.0, v60
	v_add_f32_e32 v61, 1.0, v61
	v_mfma_f32_16x16x32_bf16 v[102:105], v[188:191], v[176:179], v[102:105]
	v_add_f32_e32 v62, 1.0, v62
	v_add_f32_e32 v63, 1.0, v63
	v_add_f32_e32 v64, 1.0, v64
	v_mfma_f32_16x16x32_bf16 v[106:109], v[192:195], v[176:179], v[106:109]
	v_add_f32_e32 v65, 1.0, v65
	v_rcp_f32_e32 v58, v58
	v_mfma_f32_16x16x32_bf16 v[110:113], v[196:199], v[176:179], v[110:113]
	v_rcp_f32_e32 v59, v59
	v_rcp_f32_e32 v60, v60
	v_mfma_f32_16x16x32_bf16 v[114:117], v[184:187], v[180:183], v[114:117]
	v_rcp_f32_e32 v61, v61
	v_rcp_f32_e32 v62, v62
	v_rcp_f32_e32 v63, v63
	v_mfma_f32_16x16x32_bf16 v[118:121], v[188:191], v[180:183], v[118:121]
	v_rcp_f32_e32 v64, v64
	v_rcp_f32_e32 v65, v65
	v_mfma_f32_16x16x32_bf16 v[122:125], v[192:195], v[180:183], v[122:125]
	v_cvt_pk_bf16_f32 v58, v58, v59
	v_cvt_pk_bf16_f32 v59, v60, v61
	v_mfma_f32_16x16x32_bf16 v[126:129], v[196:199], v[180:183], v[126:129]
	v_cvt_pk_bf16_f32 v60, v62, v63
	v_cvt_pk_bf16_f32 v61, v64, v65
	global_store_dwordx4 v241, v[58:61], s[10:11] offset:2064
	s_waitcnt lgkmcnt(0)
	v_mfma_f32_16x16x32_bf16 v[66:69], v[152:155], v[136:139], v[66:69]
	ds_read_b128 v[168:171], v228 offset:0
	v_mfma_f32_16x16x32_bf16 v[70:73], v[156:159], v[136:139], v[70:73]
	ds_read_b128 v[172:175], v228 offset:2048
	v_mfma_f32_16x16x32_bf16 v[74:77], v[160:163], v[136:139], v[74:77]
	ds_read_b128 v[176:179], v228 offset:4096
	v_mfma_f32_16x16x32_bf16 v[78:81], v[164:167], v[136:139], v[78:81]
	ds_read_b128 v[180:183], v228 offset:6144
	v_mfma_f32_16x16x32_bf16 v[82:85], v[152:155], v[140:143], v[82:85]
	ds_read_b128 v[184:187], v234 offset:0
	v_mfma_f32_16x16x32_bf16 v[86:89], v[156:159], v[140:143], v[86:89]
	ds_read_b128 v[188:191], v234 offset:2048
	v_mfma_f32_16x16x32_bf16 v[90:93], v[160:163], v[140:143], v[90:93]
	ds_read_b128 v[192:195], v234 offset:4096
	v_mfma_f32_16x16x32_bf16 v[94:97], v[164:167], v[140:143], v[94:97]
	ds_read_b128 v[196:199], v234 offset:6144
	v_mfma_f32_16x16x32_bf16 v[98:101], v[152:155], v[144:147], v[98:101]
	v_mfma_f32_16x16x32_bf16 v[102:105], v[156:159], v[144:147], v[102:105]
	v_mfma_f32_16x16x32_bf16 v[106:109], v[160:163], v[144:147], v[106:109]
	v_mfma_f32_16x16x32_bf16 v[110:113], v[164:167], v[144:147], v[110:113]
	v_mfma_f32_16x16x32_bf16 v[114:117], v[152:155], v[148:151], v[114:117]
	v_mfma_f32_16x16x32_bf16 v[118:121], v[156:159], v[148:151], v[118:121]
	v_mfma_f32_16x16x32_bf16 v[122:125], v[160:163], v[148:151], v[122:125]
	v_mfma_f32_16x16x32_bf16 v[126:129], v[164:167], v[148:151], v[126:129]
	s_waitcnt lgkmcnt(0)
	s_barrier
	v_mfma_f32_16x16x32_bf16 v[66:69], v[184:187], v[168:171], v[66:69]
	ds_read_b128 v[136:139], v224 offset:0
	v_mfma_f32_16x16x32_bf16 v[70:73], v[188:191], v[168:171], v[70:73]
	ds_read_b128 v[140:143], v224 offset:2048
	v_mfma_f32_16x16x32_bf16 v[74:77], v[192:195], v[168:171], v[74:77]
	ds_read_b128 v[144:147], v224 offset:4096
	v_mfma_f32_16x16x32_bf16 v[78:81], v[196:199], v[168:171], v[78:81]
	ds_read_b128 v[148:151], v224 offset:6144
	v_mfma_f32_16x16x32_bf16 v[82:85], v[184:187], v[172:175], v[82:85]
	ds_read_b128 v[152:155], v232 offset:0
	v_mfma_f32_16x16x32_bf16 v[86:89], v[188:191], v[172:175], v[86:89]
	ds_read_b128 v[156:159], v232 offset:2048
	v_mfma_f32_16x16x32_bf16 v[90:93], v[192:195], v[172:175], v[90:93]
	ds_read_b128 v[160:163], v232 offset:4096
	v_mfma_f32_16x16x32_bf16 v[94:97], v[196:199], v[172:175], v[94:97]
	ds_read_b128 v[164:167], v232 offset:6144
	v_mfma_f32_16x16x32_bf16 v[98:101], v[184:187], v[176:179], v[98:101]
	v_mfma_f32_16x16x32_bf16 v[102:105], v[188:191], v[176:179], v[102:105]
	v_mfma_f32_16x16x32_bf16 v[106:109], v[192:195], v[176:179], v[106:109]
	v_mfma_f32_16x16x32_bf16 v[110:113], v[196:199], v[176:179], v[110:113]
	v_mfma_f32_16x16x32_bf16 v[114:117], v[184:187], v[180:183], v[114:117]
	v_mfma_f32_16x16x32_bf16 v[118:121], v[188:191], v[180:183], v[118:121]
	v_mfma_f32_16x16x32_bf16 v[122:125], v[192:195], v[180:183], v[122:125]
	v_mfma_f32_16x16x32_bf16 v[126:129], v[196:199], v[180:183], v[126:129]
	s_waitcnt lgkmcnt(0)
	v_mfma_f32_16x16x32_bf16 v[66:69], v[152:155], v[136:139], v[66:69]
	ds_read_b128 v[168:171], v229 offset:0
	v_mfma_f32_16x16x32_bf16 v[70:73], v[156:159], v[136:139], v[70:73]
	ds_read_b128 v[172:175], v229 offset:2048
	v_mfma_f32_16x16x32_bf16 v[74:77], v[160:163], v[136:139], v[74:77]
	ds_read_b128 v[176:179], v229 offset:4096
	v_mfma_f32_16x16x32_bf16 v[78:81], v[164:167], v[136:139], v[78:81]
	ds_read_b128 v[180:183], v229 offset:6144
	v_mfma_f32_16x16x32_bf16 v[82:85], v[152:155], v[140:143], v[82:85]
	ds_read_b128 v[184:187], v235 offset:0
	v_mfma_f32_16x16x32_bf16 v[86:89], v[156:159], v[140:143], v[86:89]
	ds_read_b128 v[188:191], v235 offset:2048
	v_mfma_f32_16x16x32_bf16 v[90:93], v[160:163], v[140:143], v[90:93]
	ds_read_b128 v[192:195], v235 offset:4096
	v_mfma_f32_16x16x32_bf16 v[94:97], v[164:167], v[140:143], v[94:97]
	ds_read_b128 v[196:199], v235 offset:6144
	v_mfma_f32_16x16x32_bf16 v[98:101], v[152:155], v[144:147], v[98:101]
	v_mfma_f32_16x16x32_bf16 v[102:105], v[156:159], v[144:147], v[102:105]
	v_mfma_f32_16x16x32_bf16 v[106:109], v[160:163], v[144:147], v[106:109]
	v_mfma_f32_16x16x32_bf16 v[110:113], v[164:167], v[144:147], v[110:113]
	v_mfma_f32_16x16x32_bf16 v[114:117], v[152:155], v[148:151], v[114:117]
	v_mfma_f32_16x16x32_bf16 v[118:121], v[156:159], v[148:151], v[118:121]
	v_mfma_f32_16x16x32_bf16 v[122:125], v[160:163], v[148:151], v[122:125]
	v_mfma_f32_16x16x32_bf16 v[126:129], v[164:167], v[148:151], v[126:129]
	s_waitcnt lgkmcnt(0)
	s_barrier
	v_mfma_f32_16x16x32_bf16 v[66:69], v[184:187], v[168:171], v[66:69]
	ds_read_b128 v[136:139], v218 offset:0
	v_mfma_f32_16x16x32_bf16 v[70:73], v[188:191], v[168:171], v[70:73]
	ds_read_b128 v[140:143], v218 offset:2048
	v_mfma_f32_16x16x32_bf16 v[74:77], v[192:195], v[168:171], v[74:77]
	ds_read_b128 v[144:147], v218 offset:4096
	v_mfma_f32_16x16x32_bf16 v[78:81], v[196:199], v[168:171], v[78:81]
	ds_read_b128 v[148:151], v218 offset:6144
	v_mfma_f32_16x16x32_bf16 v[82:85], v[184:187], v[172:175], v[82:85]
	ds_read_b128 v[152:155], v230 offset:0
	v_mfma_f32_16x16x32_bf16 v[86:89], v[188:191], v[172:175], v[86:89]
	ds_read_b128 v[156:159], v230 offset:2048
	v_mfma_f32_16x16x32_bf16 v[90:93], v[192:195], v[172:175], v[90:93]
	ds_read_b128 v[160:163], v230 offset:4096
	v_mfma_f32_16x16x32_bf16 v[94:97], v[196:199], v[172:175], v[94:97]
	ds_read_b128 v[164:167], v230 offset:6144
	v_mfma_f32_16x16x32_bf16 v[98:101], v[184:187], v[176:179], v[98:101]
	v_mfma_f32_16x16x32_bf16 v[102:105], v[188:191], v[176:179], v[102:105]
	v_mfma_f32_16x16x32_bf16 v[106:109], v[192:195], v[176:179], v[106:109]
	v_mfma_f32_16x16x32_bf16 v[110:113], v[196:199], v[176:179], v[110:113]
	v_mfma_f32_16x16x32_bf16 v[114:117], v[184:187], v[180:183], v[114:117]
	v_mfma_f32_16x16x32_bf16 v[118:121], v[188:191], v[180:183], v[118:121]
	v_mfma_f32_16x16x32_bf16 v[122:125], v[192:195], v[180:183], v[122:125]
	v_mfma_f32_16x16x32_bf16 v[126:129], v[196:199], v[180:183], v[126:129]
	s_waitcnt lgkmcnt(0)
	v_mfma_f32_16x16x32_bf16 v[66:69], v[152:155], v[136:139], v[66:69]
	ds_read_b128 v[168:171], v225 offset:0
	v_mfma_f32_16x16x32_bf16 v[70:73], v[156:159], v[136:139], v[70:73]
	ds_read_b128 v[172:175], v225 offset:2048
	v_mfma_f32_16x16x32_bf16 v[74:77], v[160:163], v[136:139], v[74:77]
	ds_read_b128 v[176:179], v225 offset:4096
	v_mfma_f32_16x16x32_bf16 v[78:81], v[164:167], v[136:139], v[78:81]
	ds_read_b128 v[180:183], v225 offset:6144
	v_mfma_f32_16x16x32_bf16 v[82:85], v[152:155], v[140:143], v[82:85]
	ds_read_b128 v[184:187], v233 offset:0
	v_mfma_f32_16x16x32_bf16 v[86:89], v[156:159], v[140:143], v[86:89]
	ds_read_b128 v[188:191], v233 offset:2048
	v_mfma_f32_16x16x32_bf16 v[90:93], v[160:163], v[140:143], v[90:93]
	ds_read_b128 v[192:195], v233 offset:4096
	v_mfma_f32_16x16x32_bf16 v[94:97], v[164:167], v[140:143], v[94:97]
	ds_read_b128 v[196:199], v233 offset:6144
	v_mfma_f32_16x16x32_bf16 v[98:101], v[152:155], v[144:147], v[98:101]
	v_mfma_f32_16x16x32_bf16 v[102:105], v[156:159], v[144:147], v[102:105]
	v_mfma_f32_16x16x32_bf16 v[106:109], v[160:163], v[144:147], v[106:109]
	v_mfma_f32_16x16x32_bf16 v[110:113], v[164:167], v[144:147], v[110:113]
	v_mfma_f32_16x16x32_bf16 v[114:117], v[152:155], v[148:151], v[114:117]
	v_mfma_f32_16x16x32_bf16 v[118:121], v[156:159], v[148:151], v[118:121]
	v_mfma_f32_16x16x32_bf16 v[122:125], v[160:163], v[148:151], v[122:125]
	v_mfma_f32_16x16x32_bf16 v[126:129], v[164:167], v[148:151], v[126:129]
	s_waitcnt lgkmcnt(0)
	s_barrier
	v_mfma_f32_16x16x32_bf16 v[66:69], v[184:187], v[168:171], v[66:69]
	ds_read_b128 v[136:139], v219 offset:0
	v_mfma_f32_16x16x32_bf16 v[70:73], v[188:191], v[168:171], v[70:73]
	ds_read_b128 v[140:143], v219 offset:2048
	v_mfma_f32_16x16x32_bf16 v[74:77], v[192:195], v[168:171], v[74:77]
	ds_read_b128 v[144:147], v219 offset:4096
	v_mfma_f32_16x16x32_bf16 v[78:81], v[196:199], v[168:171], v[78:81]
	ds_read_b128 v[148:151], v219 offset:6144
	v_mfma_f32_16x16x32_bf16 v[82:85], v[184:187], v[172:175], v[82:85]
	ds_read_b128 v[152:155], v231 offset:0
	v_mfma_f32_16x16x32_bf16 v[86:89], v[188:191], v[172:175], v[86:89]
	ds_read_b128 v[156:159], v231 offset:2048
	v_mfma_f32_16x16x32_bf16 v[90:93], v[192:195], v[172:175], v[90:93]
	ds_read_b128 v[160:163], v231 offset:4096
	v_mfma_f32_16x16x32_bf16 v[94:97], v[196:199], v[172:175], v[94:97]
	ds_read_b128 v[164:167], v231 offset:6144
	v_mfma_f32_16x16x32_bf16 v[98:101], v[184:187], v[176:179], v[98:101]
	v_mfma_f32_16x16x32_bf16 v[102:105], v[188:191], v[176:179], v[102:105]
	v_mfma_f32_16x16x32_bf16 v[106:109], v[192:195], v[176:179], v[106:109]
	v_mfma_f32_16x16x32_bf16 v[110:113], v[196:199], v[176:179], v[110:113]
	v_mfma_f32_16x16x32_bf16 v[114:117], v[184:187], v[180:183], v[114:117]
	v_mfma_f32_16x16x32_bf16 v[118:121], v[188:191], v[180:183], v[118:121]
	v_mfma_f32_16x16x32_bf16 v[122:125], v[192:195], v[180:183], v[122:125]
	v_mfma_f32_16x16x32_bf16 v[126:129], v[196:199], v[180:183], v[126:129]
	s_waitcnt lgkmcnt(0)
	v_mfma_f32_16x16x32_bf16 v[66:69], v[152:155], v[136:139], v[66:69]
	ds_read_b128 v[168:171], v228 offset:0
	v_mfma_f32_16x16x32_bf16 v[70:73], v[156:159], v[136:139], v[70:73]
	ds_read_b128 v[172:175], v228 offset:2048
	v_mfma_f32_16x16x32_bf16 v[74:77], v[160:163], v[136:139], v[74:77]
	ds_read_b128 v[176:179], v228 offset:4096
	v_mfma_f32_16x16x32_bf16 v[78:81], v[164:167], v[136:139], v[78:81]
	ds_read_b128 v[180:183], v228 offset:6144
	v_mfma_f32_16x16x32_bf16 v[82:85], v[152:155], v[140:143], v[82:85]
	ds_read_b128 v[184:187], v234 offset:0
	v_mfma_f32_16x16x32_bf16 v[86:89], v[156:159], v[140:143], v[86:89]
	ds_read_b128 v[188:191], v234 offset:2048
	v_mfma_f32_16x16x32_bf16 v[90:93], v[160:163], v[140:143], v[90:93]
	ds_read_b128 v[192:195], v234 offset:4096
	v_mfma_f32_16x16x32_bf16 v[94:97], v[164:167], v[140:143], v[94:97]
	ds_read_b128 v[196:199], v234 offset:6144
	v_mfma_f32_16x16x32_bf16 v[98:101], v[152:155], v[144:147], v[98:101]
	v_mfma_f32_16x16x32_bf16 v[102:105], v[156:159], v[144:147], v[102:105]
	v_mfma_f32_16x16x32_bf16 v[106:109], v[160:163], v[144:147], v[106:109]
	v_mfma_f32_16x16x32_bf16 v[110:113], v[164:167], v[144:147], v[110:113]
	v_mfma_f32_16x16x32_bf16 v[114:117], v[152:155], v[148:151], v[114:117]
	v_mfma_f32_16x16x32_bf16 v[118:121], v[156:159], v[148:151], v[118:121]
	v_mfma_f32_16x16x32_bf16 v[122:125], v[160:163], v[148:151], v[122:125]
	v_mfma_f32_16x16x32_bf16 v[126:129], v[164:167], v[148:151], v[126:129]
	s_waitcnt lgkmcnt(0)
	s_barrier
	v_mfma_f32_16x16x32_bf16 v[66:69], v[184:187], v[168:171], v[66:69]
	ds_read_b128 v[136:139], v224 offset:0
	v_mfma_f32_16x16x32_bf16 v[70:73], v[188:191], v[168:171], v[70:73]
	ds_read_b128 v[140:143], v224 offset:2048
	v_mfma_f32_16x16x32_bf16 v[74:77], v[192:195], v[168:171], v[74:77]
	ds_read_b128 v[144:147], v224 offset:4096
	v_mfma_f32_16x16x32_bf16 v[78:81], v[196:199], v[168:171], v[78:81]
	ds_read_b128 v[148:151], v224 offset:6144
	v_mfma_f32_16x16x32_bf16 v[82:85], v[184:187], v[172:175], v[82:85]
	ds_read_b128 v[152:155], v232 offset:0
	v_mfma_f32_16x16x32_bf16 v[86:89], v[188:191], v[172:175], v[86:89]
	ds_read_b128 v[156:159], v232 offset:2048
	v_mfma_f32_16x16x32_bf16 v[90:93], v[192:195], v[172:175], v[90:93]
	ds_read_b128 v[160:163], v232 offset:4096
	v_mfma_f32_16x16x32_bf16 v[94:97], v[196:199], v[172:175], v[94:97]
	ds_read_b128 v[164:167], v232 offset:6144
	v_mfma_f32_16x16x32_bf16 v[98:101], v[184:187], v[176:179], v[98:101]
	v_mfma_f32_16x16x32_bf16 v[102:105], v[188:191], v[176:179], v[102:105]
	v_mfma_f32_16x16x32_bf16 v[106:109], v[192:195], v[176:179], v[106:109]
	v_mfma_f32_16x16x32_bf16 v[110:113], v[196:199], v[176:179], v[110:113]
	v_mfma_f32_16x16x32_bf16 v[114:117], v[184:187], v[180:183], v[114:117]
	v_mfma_f32_16x16x32_bf16 v[118:121], v[188:191], v[180:183], v[118:121]
	v_mfma_f32_16x16x32_bf16 v[122:125], v[192:195], v[180:183], v[122:125]
	v_mfma_f32_16x16x32_bf16 v[126:129], v[196:199], v[180:183], v[126:129]
	s_waitcnt lgkmcnt(0)
	v_mfma_f32_16x16x32_bf16 v[66:69], v[152:155], v[136:139], v[66:69]
	ds_read_b128 v[168:171], v229 offset:0
	v_mfma_f32_16x16x32_bf16 v[70:73], v[156:159], v[136:139], v[70:73]
	ds_read_b128 v[172:175], v229 offset:2048
	v_mfma_f32_16x16x32_bf16 v[74:77], v[160:163], v[136:139], v[74:77]
	ds_read_b128 v[176:179], v229 offset:4096
	v_mfma_f32_16x16x32_bf16 v[78:81], v[164:167], v[136:139], v[78:81]
	ds_read_b128 v[180:183], v229 offset:6144
	v_mfma_f32_16x16x32_bf16 v[82:85], v[152:155], v[140:143], v[82:85]
	ds_read_b128 v[184:187], v235 offset:0
	v_mfma_f32_16x16x32_bf16 v[86:89], v[156:159], v[140:143], v[86:89]
	ds_read_b128 v[188:191], v235 offset:2048
	v_mfma_f32_16x16x32_bf16 v[90:93], v[160:163], v[140:143], v[90:93]
	ds_read_b128 v[192:195], v235 offset:4096
	v_mfma_f32_16x16x32_bf16 v[94:97], v[164:167], v[140:143], v[94:97]
	ds_read_b128 v[196:199], v235 offset:6144
	v_mfma_f32_16x16x32_bf16 v[98:101], v[152:155], v[144:147], v[98:101]
	v_mfma_f32_16x16x32_bf16 v[102:105], v[156:159], v[144:147], v[102:105]
	v_mfma_f32_16x16x32_bf16 v[106:109], v[160:163], v[144:147], v[106:109]
	v_mfma_f32_16x16x32_bf16 v[110:113], v[164:167], v[144:147], v[110:113]
	v_mfma_f32_16x16x32_bf16 v[114:117], v[152:155], v[148:151], v[114:117]
	v_mfma_f32_16x16x32_bf16 v[118:121], v[156:159], v[148:151], v[118:121]
	v_mfma_f32_16x16x32_bf16 v[122:125], v[160:163], v[148:151], v[122:125]
	v_mfma_f32_16x16x32_bf16 v[126:129], v[164:167], v[148:151], v[126:129]
	s_waitcnt lgkmcnt(0)
	s_barrier
	s_add_u32 s14, s4, 0x580
	s_addc_u32 s15, s5, 0
	v_mfma_f32_16x16x32_bf16 v[66:69], v[184:187], v[168:171], v[66:69]
	ds_read_b128 v[136:139], v218 offset:0
	s_add_u32 s22, s4, 0x10580
	s_addc_u32 s23, s5, 0
	v_mfma_f32_16x16x32_bf16 v[70:73], v[188:191], v[168:171], v[70:73]
	ds_read_b128 v[140:143], v218 offset:2048
	s_add_u32 s24, s6, 0xc0580
	s_addc_u32 s25, s7, 0
	v_mfma_f32_16x16x32_bf16 v[74:77], v[192:195], v[168:171], v[74:77]
	ds_read_b128 v[144:147], v218 offset:4096
	s_add_u32 s52, s6, 0xc8580
	s_addc_u32 s53, s7, 0
	v_mfma_f32_16x16x32_bf16 v[78:81], v[196:199], v[168:171], v[78:81]
	ds_read_b128 v[148:151], v218 offset:6144
	s_add_u32 m0, s8, 0x18000
	v_mfma_f32_16x16x32_bf16 v[82:85], v[184:187], v[172:175], v[82:85]
	global_load_lds_dwordx4 v200, s[14:15]
	ds_read_b128 v[152:155], v230 offset:0
	s_add_u32 m0, s8, 0x18400
	v_mfma_f32_16x16x32_bf16 v[86:89], v[188:191], v[172:175], v[86:89]
	global_load_lds_dwordx4 v201, s[14:15]
	ds_read_b128 v[156:159], v230 offset:2048
	s_add_u32 m0, s8, 0x18800
	v_mfma_f32_16x16x32_bf16 v[90:93], v[192:195], v[172:175], v[90:93]
	global_load_lds_dwordx4 v202, s[14:15]
	ds_read_b128 v[160:163], v230 offset:4096
	s_add_u32 m0, s8, 0x18c00
	v_mfma_f32_16x16x32_bf16 v[94:97], v[196:199], v[172:175], v[94:97]
	global_load_lds_dwordx4 v203, s[14:15]
	ds_read_b128 v[164:167], v230 offset:6144
	s_add_u32 m0, s8, 0x19000
	v_mfma_f32_16x16x32_bf16 v[98:101], v[184:187], v[176:179], v[98:101]
	global_load_lds_dwordx4 v200, s[22:23]
	s_add_u32 m0, s8, 0x19400
	v_mfma_f32_16x16x32_bf16 v[102:105], v[188:191], v[176:179], v[102:105]
	global_load_lds_dwordx4 v201, s[22:23]
	s_add_u32 m0, s8, 0x19800
	v_mfma_f32_16x16x32_bf16 v[106:109], v[192:195], v[176:179], v[106:109]
	global_load_lds_dwordx4 v202, s[22:23]
	s_add_u32 m0, s8, 0x19c00
	v_mfma_f32_16x16x32_bf16 v[110:113], v[196:199], v[176:179], v[110:113]
	global_load_lds_dwordx4 v203, s[22:23]
	s_add_u32 m0, s9, 0x18000
	v_mfma_f32_16x16x32_bf16 v[114:117], v[184:187], v[180:183], v[114:117]
	global_load_lds_dwordx4 v204, s[24:25]
	s_add_u32 m0, s9, 0x18400
	v_mfma_f32_16x16x32_bf16 v[118:121], v[188:191], v[180:183], v[118:121]
	global_load_lds_dwordx4 v205, s[24:25]
	s_add_u32 m0, s9, 0x18800
	v_mfma_f32_16x16x32_bf16 v[122:125], v[192:195], v[180:183], v[122:125]
	global_load_lds_dwordx4 v204, s[52:53]
	s_add_u32 m0, s9, 0x18c00
	v_mfma_f32_16x16x32_bf16 v[126:129], v[196:199], v[180:183], v[126:129]
	global_load_lds_dwordx4 v205, s[52:53]
	s_waitcnt lgkmcnt(0)
	v_mfma_f32_16x16x32_bf16 v[66:69], v[152:155], v[136:139], v[66:69]
	ds_read_b128 v[168:171], v225 offset:0
	v_mfma_f32_16x16x32_bf16 v[70:73], v[156:159], v[136:139], v[70:73]
	ds_read_b128 v[172:175], v225 offset:2048
	v_mfma_f32_16x16x32_bf16 v[74:77], v[160:163], v[136:139], v[74:77]
	ds_read_b128 v[176:179], v225 offset:4096
	v_mfma_f32_16x16x32_bf16 v[78:81], v[164:167], v[136:139], v[78:81]
	ds_read_b128 v[180:183], v225 offset:6144
	v_mfma_f32_16x16x32_bf16 v[82:85], v[152:155], v[140:143], v[82:85]
	ds_read_b128 v[184:187], v233 offset:0
	v_mfma_f32_16x16x32_bf16 v[86:89], v[156:159], v[140:143], v[86:89]
	ds_read_b128 v[188:191], v233 offset:2048
	v_mfma_f32_16x16x32_bf16 v[90:93], v[160:163], v[140:143], v[90:93]
	ds_read_b128 v[192:195], v233 offset:4096
	v_mfma_f32_16x16x32_bf16 v[94:97], v[164:167], v[140:143], v[94:97]
	ds_read_b128 v[196:199], v233 offset:6144
	v_mfma_f32_16x16x32_bf16 v[98:101], v[152:155], v[144:147], v[98:101]
	v_mfma_f32_16x16x32_bf16 v[102:105], v[156:159], v[144:147], v[102:105]
	v_mfma_f32_16x16x32_bf16 v[106:109], v[160:163], v[144:147], v[106:109]
	v_mfma_f32_16x16x32_bf16 v[110:113], v[164:167], v[144:147], v[110:113]
	v_mfma_f32_16x16x32_bf16 v[114:117], v[152:155], v[148:151], v[114:117]
	v_mfma_f32_16x16x32_bf16 v[118:121], v[156:159], v[148:151], v[118:121]
	v_mfma_f32_16x16x32_bf16 v[122:125], v[160:163], v[148:151], v[122:125]
	v_mfma_f32_16x16x32_bf16 v[126:129], v[164:167], v[148:151], v[126:129]
	s_waitcnt lgkmcnt(0)
	s_barrier
	s_add_u32 s14, s4, 0x600
	s_addc_u32 s15, s5, 0
	v_mfma_f32_16x16x32_bf16 v[66:69], v[184:187], v[168:171], v[66:69]
	ds_read_b128 v[136:139], v219 offset:0
	s_add_u32 s22, s4, 0x10600
	s_addc_u32 s23, s5, 0
	v_mfma_f32_16x16x32_bf16 v[70:73], v[188:191], v[168:171], v[70:73]
	ds_read_b128 v[140:143], v219 offset:2048
	s_add_u32 s24, s6, 0xc0600
	s_addc_u32 s25, s7, 0
	v_mfma_f32_16x16x32_bf16 v[74:77], v[192:195], v[168:171], v[74:77]
	ds_read_b128 v[144:147], v219 offset:4096
	s_add_u32 s52, s6, 0xc8600
	s_addc_u32 s53, s7, 0
	v_mfma_f32_16x16x32_bf16 v[78:81], v[196:199], v[168:171], v[78:81]
	ds_read_b128 v[148:151], v219 offset:6144
	s_mov_b32 m0, s8
	v_mfma_f32_16x16x32_bf16 v[82:85], v[184:187], v[172:175], v[82:85]
	global_load_lds_dwordx4 v200, s[14:15]
	ds_read_b128 v[152:155], v231 offset:0
	s_add_u32 m0, s8, 0x400
	v_mfma_f32_16x16x32_bf16 v[86:89], v[188:191], v[172:175], v[86:89]
	global_load_lds_dwordx4 v201, s[14:15]
	ds_read_b128 v[156:159], v231 offset:2048
	s_add_u32 m0, s8, 0x800
	v_mfma_f32_16x16x32_bf16 v[90:93], v[192:195], v[172:175], v[90:93]
	global_load_lds_dwordx4 v202, s[14:15]
	ds_read_b128 v[160:163], v231 offset:4096
	s_add_u32 m0, s8, 0xc00
	v_mfma_f32_16x16x32_bf16 v[94:97], v[196:199], v[172:175], v[94:97]
	global_load_lds_dwordx4 v203, s[14:15]
	ds_read_b128 v[164:167], v231 offset:6144
	s_add_u32 m0, s8, 0x1000
	v_mfma_f32_16x16x32_bf16 v[98:101], v[184:187], v[176:179], v[98:101]
	global_load_lds_dwordx4 v200, s[22:23]
	s_add_u32 m0, s8, 0x1400
	v_mfma_f32_16x16x32_bf16 v[102:105], v[188:191], v[176:179], v[102:105]
	global_load_lds_dwordx4 v201, s[22:23]
	s_add_u32 m0, s8, 0x1800
	v_mfma_f32_16x16x32_bf16 v[106:109], v[192:195], v[176:179], v[106:109]
	global_load_lds_dwordx4 v202, s[22:23]
	s_add_u32 m0, s8, 0x1c00
	v_mfma_f32_16x16x32_bf16 v[110:113], v[196:199], v[176:179], v[110:113]
	global_load_lds_dwordx4 v203, s[22:23]
	s_mov_b32 m0, s9
	v_mfma_f32_16x16x32_bf16 v[114:117], v[184:187], v[180:183], v[114:117]
	global_load_lds_dwordx4 v204, s[24:25]
	s_add_u32 m0, s9, 0x400
	v_mfma_f32_16x16x32_bf16 v[118:121], v[188:191], v[180:183], v[118:121]
	global_load_lds_dwordx4 v205, s[24:25]
	s_add_u32 m0, s9, 0x800
	v_mfma_f32_16x16x32_bf16 v[122:125], v[192:195], v[180:183], v[122:125]
	global_load_lds_dwordx4 v204, s[52:53]
	s_add_u32 m0, s9, 0xc00
	v_mfma_f32_16x16x32_bf16 v[126:129], v[196:199], v[180:183], v[126:129]
	global_load_lds_dwordx4 v205, s[52:53]
	s_waitcnt lgkmcnt(0)
	v_mfma_f32_16x16x32_bf16 v[66:69], v[152:155], v[136:139], v[66:69]
	ds_read_b128 v[168:171], v228 offset:0
	v_mfma_f32_16x16x32_bf16 v[70:73], v[156:159], v[136:139], v[70:73]
	ds_read_b128 v[172:175], v228 offset:2048
	v_mfma_f32_16x16x32_bf16 v[74:77], v[160:163], v[136:139], v[74:77]
	ds_read_b128 v[176:179], v228 offset:4096
	v_mfma_f32_16x16x32_bf16 v[78:81], v[164:167], v[136:139], v[78:81]
	ds_read_b128 v[180:183], v228 offset:6144
	v_mfma_f32_16x16x32_bf16 v[82:85], v[152:155], v[140:143], v[82:85]
	ds_read_b128 v[184:187], v234 offset:0
	v_mfma_f32_16x16x32_bf16 v[86:89], v[156:159], v[140:143], v[86:89]
	ds_read_b128 v[188:191], v234 offset:2048
	v_mfma_f32_16x16x32_bf16 v[90:93], v[160:163], v[140:143], v[90:93]
	ds_read_b128 v[192:195], v234 offset:4096
	v_mfma_f32_16x16x32_bf16 v[94:97], v[164:167], v[140:143], v[94:97]
	ds_read_b128 v[196:199], v234 offset:6144
	v_mfma_f32_16x16x32_bf16 v[98:101], v[152:155], v[144:147], v[98:101]
	v_mfma_f32_16x16x32_bf16 v[102:105], v[156:159], v[144:147], v[102:105]
	v_mfma_f32_16x16x32_bf16 v[106:109], v[160:163], v[144:147], v[106:109]
	v_mfma_f32_16x16x32_bf16 v[110:113], v[164:167], v[144:147], v[110:113]
	v_mfma_f32_16x16x32_bf16 v[114:117], v[152:155], v[148:151], v[114:117]
	v_mfma_f32_16x16x32_bf16 v[118:121], v[156:159], v[148:151], v[118:121]
	v_mfma_f32_16x16x32_bf16 v[122:125], v[160:163], v[148:151], v[122:125]
	v_mfma_f32_16x16x32_bf16 v[126:129], v[164:167], v[148:151], v[126:129]
	s_waitcnt vmcnt(12) lgkmcnt(0)
	s_barrier
	s_add_u32 s14, s4, 0x680
	s_addc_u32 s15, s5, 0
	v_mfma_f32_16x16x32_bf16 v[66:69], v[184:187], v[168:171], v[66:69]
	ds_read_b128 v[136:139], v224 offset:0
	s_add_u32 s22, s4, 0x10680
	s_addc_u32 s23, s5, 0
	v_mfma_f32_16x16x32_bf16 v[70:73], v[188:191], v[168:171], v[70:73]
	ds_read_b128 v[140:143], v224 offset:2048
	s_add_u32 s24, s6, 0xc0680
	s_addc_u32 s25, s7, 0
	v_mfma_f32_16x16x32_bf16 v[74:77], v[192:195], v[168:171], v[74:77]
	ds_read_b128 v[144:147], v224 offset:4096
	s_add_u32 s52, s6, 0xc8680
	s_addc_u32 s53, s7, 0
	v_mfma_f32_16x16x32_bf16 v[78:81], v[196:199], v[168:171], v[78:81]
	ds_read_b128 v[148:151], v224 offset:6144
	s_add_u32 m0, s8, 0xc000
	v_mfma_f32_16x16x32_bf16 v[82:85], v[184:187], v[172:175], v[82:85]
	global_load_lds_dwordx4 v200, s[14:15]
	ds_read_b128 v[152:155], v232 offset:0
	s_add_u32 m0, s8, 0xc400
	v_mfma_f32_16x16x32_bf16 v[86:89], v[188:191], v[172:175], v[86:89]
	global_load_lds_dwordx4 v201, s[14:15]
	ds_read_b128 v[156:159], v232 offset:2048
	s_add_u32 m0, s8, 0xc800
	v_mfma_f32_16x16x32_bf16 v[90:93], v[192:195], v[172:175], v[90:93]
	global_load_lds_dwordx4 v202, s[14:15]
	ds_read_b128 v[160:163], v232 offset:4096
	s_add_u32 m0, s8, 0xcc00
	v_mfma_f32_16x16x32_bf16 v[94:97], v[196:199], v[172:175], v[94:97]
	global_load_lds_dwordx4 v203, s[14:15]
	ds_read_b128 v[164:167], v232 offset:6144
	s_add_u32 m0, s8, 0xd000
	v_mfma_f32_16x16x32_bf16 v[98:101], v[184:187], v[176:179], v[98:101]
	global_load_lds_dwordx4 v200, s[22:23]
	s_add_u32 m0, s8, 0xd400
	v_mfma_f32_16x16x32_bf16 v[102:105], v[188:191], v[176:179], v[102:105]
	global_load_lds_dwordx4 v201, s[22:23]
	s_add_u32 m0, s8, 0xd800
	v_mfma_f32_16x16x32_bf16 v[106:109], v[192:195], v[176:179], v[106:109]
	global_load_lds_dwordx4 v202, s[22:23]
	s_add_u32 m0, s8, 0xdc00
	v_mfma_f32_16x16x32_bf16 v[110:113], v[196:199], v[176:179], v[110:113]
	global_load_lds_dwordx4 v203, s[22:23]
	s_add_u32 m0, s9, 0xc000
	v_mfma_f32_16x16x32_bf16 v[114:117], v[184:187], v[180:183], v[114:117]
	global_load_lds_dwordx4 v204, s[24:25]
	s_add_u32 m0, s9, 0xc400
	v_mfma_f32_16x16x32_bf16 v[118:121], v[188:191], v[180:183], v[118:121]
	global_load_lds_dwordx4 v205, s[24:25]
	s_add_u32 m0, s9, 0xc800
	v_mfma_f32_16x16x32_bf16 v[122:125], v[192:195], v[180:183], v[122:125]
	global_load_lds_dwordx4 v204, s[52:53]
	s_add_u32 m0, s9, 0xcc00
	v_mfma_f32_16x16x32_bf16 v[126:129], v[196:199], v[180:183], v[126:129]
	global_load_lds_dwordx4 v205, s[52:53]
	s_waitcnt lgkmcnt(0)
	v_mfma_f32_16x16x32_bf16 v[66:69], v[152:155], v[136:139], v[66:69]
	ds_read_b128 v[168:171], v229 offset:0
	v_mfma_f32_16x16x32_bf16 v[70:73], v[156:159], v[136:139], v[70:73]
	ds_read_b128 v[172:175], v229 offset:2048
	v_mfma_f32_16x16x32_bf16 v[74:77], v[160:163], v[136:139], v[74:77]
	ds_read_b128 v[176:179], v229 offset:4096
	v_mfma_f32_16x16x32_bf16 v[78:81], v[164:167], v[136:139], v[78:81]
	ds_read_b128 v[180:183], v229 offset:6144
	v_mfma_f32_16x16x32_bf16 v[82:85], v[152:155], v[140:143], v[82:85]
	ds_read_b128 v[184:187], v235 offset:0
	v_mfma_f32_16x16x32_bf16 v[86:89], v[156:159], v[140:143], v[86:89]
	ds_read_b128 v[188:191], v235 offset:2048
	v_mfma_f32_16x16x32_bf16 v[90:93], v[160:163], v[140:143], v[90:93]
	ds_read_b128 v[192:195], v235 offset:4096
	v_mfma_f32_16x16x32_bf16 v[94:97], v[164:167], v[140:143], v[94:97]
	ds_read_b128 v[196:199], v235 offset:6144
	v_mfma_f32_16x16x32_bf16 v[98:101], v[152:155], v[144:147], v[98:101]
	v_mfma_f32_16x16x32_bf16 v[102:105], v[156:159], v[144:147], v[102:105]
	v_mfma_f32_16x16x32_bf16 v[106:109], v[160:163], v[144:147], v[106:109]
	v_mfma_f32_16x16x32_bf16 v[110:113], v[164:167], v[144:147], v[110:113]
	v_mfma_f32_16x16x32_bf16 v[114:117], v[152:155], v[148:151], v[114:117]
	v_mfma_f32_16x16x32_bf16 v[118:121], v[156:159], v[148:151], v[118:121]
	v_mfma_f32_16x16x32_bf16 v[122:125], v[160:163], v[148:151], v[122:125]
	v_mfma_f32_16x16x32_bf16 v[126:129], v[164:167], v[148:151], v[126:129]
	s_waitcnt vmcnt(12) lgkmcnt(0)
	s_barrier
	s_add_u32 s14, s4, 0x700
	s_addc_u32 s15, s5, 0
	v_mfma_f32_16x16x32_bf16 v[66:69], v[184:187], v[168:171], v[66:69]
	ds_read_b128 v[136:139], v218 offset:0
	s_add_u32 s22, s4, 0x10700
	s_addc_u32 s23, s5, 0
	v_mfma_f32_16x16x32_bf16 v[70:73], v[188:191], v[168:171], v[70:73]
	ds_read_b128 v[140:143], v218 offset:2048
	s_add_u32 s24, s6, 0xc0700
	s_addc_u32 s25, s7, 0
	v_mfma_f32_16x16x32_bf16 v[74:77], v[192:195], v[168:171], v[74:77]
	ds_read_b128 v[144:147], v218 offset:4096
	s_add_u32 s52, s6, 0xc8700
	s_addc_u32 s53, s7, 0
	v_mfma_f32_16x16x32_bf16 v[78:81], v[196:199], v[168:171], v[78:81]
	ds_read_b128 v[148:151], v218 offset:6144
	s_add_u32 m0, s8, 0x18000
	v_mfma_f32_16x16x32_bf16 v[82:85], v[184:187], v[172:175], v[82:85]
	global_load_lds_dwordx4 v200, s[14:15]
	ds_read_b128 v[152:155], v230 offset:0
	s_add_u32 m0, s8, 0x18400
	v_mfma_f32_16x16x32_bf16 v[86:89], v[188:191], v[172:175], v[86:89]
	global_load_lds_dwordx4 v201, s[14:15]
	ds_read_b128 v[156:159], v230 offset:2048
	s_add_u32 m0, s8, 0x18800
	v_mfma_f32_16x16x32_bf16 v[90:93], v[192:195], v[172:175], v[90:93]
	global_load_lds_dwordx4 v202, s[14:15]
	ds_read_b128 v[160:163], v230 offset:4096
	s_add_u32 m0, s8, 0x18c00
	v_mfma_f32_16x16x32_bf16 v[94:97], v[196:199], v[172:175], v[94:97]
	global_load_lds_dwordx4 v203, s[14:15]
	ds_read_b128 v[164:167], v230 offset:6144
	s_add_u32 m0, s8, 0x19000
	v_mfma_f32_16x16x32_bf16 v[98:101], v[184:187], v[176:179], v[98:101]
	global_load_lds_dwordx4 v200, s[22:23]
	s_add_u32 m0, s8, 0x19400
	v_mfma_f32_16x16x32_bf16 v[102:105], v[188:191], v[176:179], v[102:105]
	global_load_lds_dwordx4 v201, s[22:23]
	s_add_u32 m0, s8, 0x19800
	v_mfma_f32_16x16x32_bf16 v[106:109], v[192:195], v[176:179], v[106:109]
	global_load_lds_dwordx4 v202, s[22:23]
	s_add_u32 m0, s8, 0x19c00
	v_mfma_f32_16x16x32_bf16 v[110:113], v[196:199], v[176:179], v[110:113]
	global_load_lds_dwordx4 v203, s[22:23]
	s_add_u32 m0, s9, 0x18000
	v_mfma_f32_16x16x32_bf16 v[114:117], v[184:187], v[180:183], v[114:117]
	global_load_lds_dwordx4 v204, s[24:25]
	s_add_u32 m0, s9, 0x18400
	v_mfma_f32_16x16x32_bf16 v[118:121], v[188:191], v[180:183], v[118:121]
	global_load_lds_dwordx4 v205, s[24:25]
	s_add_u32 m0, s9, 0x18800
	v_mfma_f32_16x16x32_bf16 v[122:125], v[192:195], v[180:183], v[122:125]
	global_load_lds_dwordx4 v204, s[52:53]
	s_add_u32 m0, s9, 0x18c00
	v_mfma_f32_16x16x32_bf16 v[126:129], v[196:199], v[180:183], v[126:129]
	global_load_lds_dwordx4 v205, s[52:53]
	s_waitcnt lgkmcnt(0)
	v_mfma_f32_16x16x32_bf16 v[66:69], v[152:155], v[136:139], v[66:69]
	ds_read_b128 v[168:171], v225 offset:0
	v_mfma_f32_16x16x32_bf16 v[70:73], v[156:159], v[136:139], v[70:73]
	ds_read_b128 v[172:175], v225 offset:2048
	v_mfma_f32_16x16x32_bf16 v[74:77], v[160:163], v[136:139], v[74:77]
	ds_read_b128 v[176:179], v225 offset:4096
	v_mfma_f32_16x16x32_bf16 v[78:81], v[164:167], v[136:139], v[78:81]
	ds_read_b128 v[180:183], v225 offset:6144
	v_mfma_f32_16x16x32_bf16 v[82:85], v[152:155], v[140:143], v[82:85]
	ds_read_b128 v[184:187], v233 offset:0
	v_mfma_f32_16x16x32_bf16 v[86:89], v[156:159], v[140:143], v[86:89]
	ds_read_b128 v[188:191], v233 offset:2048
	v_mfma_f32_16x16x32_bf16 v[90:93], v[160:163], v[140:143], v[90:93]
	ds_read_b128 v[192:195], v233 offset:4096
	v_mfma_f32_16x16x32_bf16 v[94:97], v[164:167], v[140:143], v[94:97]
	ds_read_b128 v[196:199], v233 offset:6144
	v_mfma_f32_16x16x32_bf16 v[98:101], v[152:155], v[144:147], v[98:101]
	v_mfma_f32_16x16x32_bf16 v[102:105], v[156:159], v[144:147], v[102:105]
	v_mfma_f32_16x16x32_bf16 v[106:109], v[160:163], v[144:147], v[106:109]
	v_mfma_f32_16x16x32_bf16 v[110:113], v[164:167], v[144:147], v[110:113]
	v_mfma_f32_16x16x32_bf16 v[114:117], v[152:155], v[148:151], v[114:117]
	v_mfma_f32_16x16x32_bf16 v[118:121], v[156:159], v[148:151], v[118:121]
	v_mfma_f32_16x16x32_bf16 v[122:125], v[160:163], v[148:151], v[122:125]
	v_mfma_f32_16x16x32_bf16 v[126:129], v[164:167], v[148:151], v[126:129]
	s_waitcnt vmcnt(12) lgkmcnt(0)
	s_barrier
	s_add_u32 s14, s4, 0x780
	s_addc_u32 s15, s5, 0
	v_mfma_f32_16x16x32_bf16 v[66:69], v[184:187], v[168:171], v[66:69]
	ds_read_b128 v[136:139], v219 offset:0
	s_add_u32 s22, s4, 0x10780
	s_addc_u32 s23, s5, 0
	v_mfma_f32_16x16x32_bf16 v[70:73], v[188:191], v[168:171], v[70:73]
	ds_read_b128 v[140:143], v219 offset:2048
	s_add_u32 s24, s6, 0xc0780
	s_addc_u32 s25, s7, 0
	v_mfma_f32_16x16x32_bf16 v[74:77], v[192:195], v[168:171], v[74:77]
	ds_read_b128 v[144:147], v219 offset:4096
	s_add_u32 s52, s6, 0xc8780
	s_addc_u32 s53, s7, 0
	v_mfma_f32_16x16x32_bf16 v[78:81], v[196:199], v[168:171], v[78:81]
	ds_read_b128 v[148:151], v219 offset:6144
	s_mov_b32 m0, s8
	v_mfma_f32_16x16x32_bf16 v[82:85], v[184:187], v[172:175], v[82:85]
	global_load_lds_dwordx4 v200, s[14:15]
	ds_read_b128 v[152:155], v231 offset:0
	s_add_u32 m0, s8, 0x400
	v_mfma_f32_16x16x32_bf16 v[86:89], v[188:191], v[172:175], v[86:89]
	global_load_lds_dwordx4 v201, s[14:15]
	ds_read_b128 v[156:159], v231 offset:2048
	s_add_u32 m0, s8, 0x800
	v_mfma_f32_16x16x32_bf16 v[90:93], v[192:195], v[172:175], v[90:93]
	global_load_lds_dwordx4 v202, s[14:15]
	ds_read_b128 v[160:163], v231 offset:4096
	s_add_u32 m0, s8, 0xc00
	v_mfma_f32_16x16x32_bf16 v[94:97], v[196:199], v[172:175], v[94:97]
	global_load_lds_dwordx4 v203, s[14:15]
	ds_read_b128 v[164:167], v231 offset:6144
	s_add_u32 m0, s8, 0x1000
	v_mfma_f32_16x16x32_bf16 v[98:101], v[184:187], v[176:179], v[98:101]
	global_load_lds_dwordx4 v200, s[22:23]
	s_add_u32 m0, s8, 0x1400
	v_mfma_f32_16x16x32_bf16 v[102:105], v[188:191], v[176:179], v[102:105]
	global_load_lds_dwordx4 v201, s[22:23]
	s_add_u32 m0, s8, 0x1800
	v_mfma_f32_16x16x32_bf16 v[106:109], v[192:195], v[176:179], v[106:109]
	global_load_lds_dwordx4 v202, s[22:23]
	s_add_u32 m0, s8, 0x1c00
	v_mfma_f32_16x16x32_bf16 v[110:113], v[196:199], v[176:179], v[110:113]
	global_load_lds_dwordx4 v203, s[22:23]
	s_mov_b32 m0, s9
	v_mfma_f32_16x16x32_bf16 v[114:117], v[184:187], v[180:183], v[114:117]
	global_load_lds_dwordx4 v204, s[24:25]
	s_add_u32 m0, s9, 0x400
	v_mfma_f32_16x16x32_bf16 v[118:121], v[188:191], v[180:183], v[118:121]
	global_load_lds_dwordx4 v205, s[24:25]
	s_add_u32 m0, s9, 0x800
	v_mfma_f32_16x16x32_bf16 v[122:125], v[192:195], v[180:183], v[122:125]
	global_load_lds_dwordx4 v204, s[52:53]
	s_add_u32 m0, s9, 0xc00
	v_mfma_f32_16x16x32_bf16 v[126:129], v[196:199], v[180:183], v[126:129]
	global_load_lds_dwordx4 v205, s[52:53]
	s_waitcnt lgkmcnt(0)
	v_mfma_f32_16x16x32_bf16 v[66:69], v[152:155], v[136:139], v[66:69]
	ds_read_b128 v[168:171], v228 offset:0
	v_mfma_f32_16x16x32_bf16 v[70:73], v[156:159], v[136:139], v[70:73]
	ds_read_b128 v[172:175], v228 offset:2048
	v_mfma_f32_16x16x32_bf16 v[74:77], v[160:163], v[136:139], v[74:77]
	ds_read_b128 v[176:179], v228 offset:4096
	v_mfma_f32_16x16x32_bf16 v[78:81], v[164:167], v[136:139], v[78:81]
	ds_read_b128 v[180:183], v228 offset:6144
	v_mfma_f32_16x16x32_bf16 v[82:85], v[152:155], v[140:143], v[82:85]
	ds_read_b128 v[184:187], v234 offset:0
	v_mfma_f32_16x16x32_bf16 v[86:89], v[156:159], v[140:143], v[86:89]
	ds_read_b128 v[188:191], v234 offset:2048
	v_mfma_f32_16x16x32_bf16 v[90:93], v[160:163], v[140:143], v[90:93]
	ds_read_b128 v[192:195], v234 offset:4096
	v_mfma_f32_16x16x32_bf16 v[94:97], v[164:167], v[140:143], v[94:97]
	ds_read_b128 v[196:199], v234 offset:6144
	v_mfma_f32_16x16x32_bf16 v[98:101], v[152:155], v[144:147], v[98:101]
	v_mfma_f32_16x16x32_bf16 v[102:105], v[156:159], v[144:147], v[102:105]
	v_mfma_f32_16x16x32_bf16 v[106:109], v[160:163], v[144:147], v[106:109]
	v_mfma_f32_16x16x32_bf16 v[110:113], v[164:167], v[144:147], v[110:113]
	v_mfma_f32_16x16x32_bf16 v[114:117], v[152:155], v[148:151], v[114:117]
	v_mfma_f32_16x16x32_bf16 v[118:121], v[156:159], v[148:151], v[118:121]
	v_mfma_f32_16x16x32_bf16 v[122:125], v[160:163], v[148:151], v[122:125]
	v_mfma_f32_16x16x32_bf16 v[126:129], v[164:167], v[148:151], v[126:129]
	s_waitcnt vmcnt(12) lgkmcnt(0)
	s_barrier
	v_mfma_f32_16x16x32_bf16 v[66:69], v[184:187], v[168:171], v[66:69]
	ds_read_b128 v[136:139], v224 offset:0
	v_mfma_f32_16x16x32_bf16 v[70:73], v[188:191], v[168:171], v[70:73]
	ds_read_b128 v[140:143], v224 offset:2048
	v_mfma_f32_16x16x32_bf16 v[74:77], v[192:195], v[168:171], v[74:77]
	ds_read_b128 v[144:147], v224 offset:4096
	v_mfma_f32_16x16x32_bf16 v[78:81], v[196:199], v[168:171], v[78:81]
	ds_read_b128 v[148:151], v224 offset:6144
	v_mfma_f32_16x16x32_bf16 v[82:85], v[184:187], v[172:175], v[82:85]
	ds_read_b128 v[152:155], v232 offset:0
	v_mfma_f32_16x16x32_bf16 v[86:89], v[188:191], v[172:175], v[86:89]
	ds_read_b128 v[156:159], v232 offset:2048
	v_mfma_f32_16x16x32_bf16 v[90:93], v[192:195], v[172:175], v[90:93]
	ds_read_b128 v[160:163], v232 offset:4096
	v_mfma_f32_16x16x32_bf16 v[94:97], v[196:199], v[172:175], v[94:97]
	ds_read_b128 v[164:167], v232 offset:6144
	v_mfma_f32_16x16x32_bf16 v[98:101], v[184:187], v[176:179], v[98:101]
	v_mfma_f32_16x16x32_bf16 v[102:105], v[188:191], v[176:179], v[102:105]
	v_mfma_f32_16x16x32_bf16 v[106:109], v[192:195], v[176:179], v[106:109]
	v_mfma_f32_16x16x32_bf16 v[110:113], v[196:199], v[176:179], v[110:113]
	v_mfma_f32_16x16x32_bf16 v[114:117], v[184:187], v[180:183], v[114:117]
	v_mfma_f32_16x16x32_bf16 v[118:121], v[188:191], v[180:183], v[118:121]
	v_mfma_f32_16x16x32_bf16 v[122:125], v[192:195], v[180:183], v[122:125]
	v_mfma_f32_16x16x32_bf16 v[126:129], v[196:199], v[180:183], v[126:129]
	s_waitcnt lgkmcnt(0)
	v_mfma_f32_16x16x32_bf16 v[66:69], v[152:155], v[136:139], v[66:69]
	ds_read_b128 v[168:171], v229 offset:0
	v_mfma_f32_16x16x32_bf16 v[70:73], v[156:159], v[136:139], v[70:73]
	ds_read_b128 v[172:175], v229 offset:2048
	v_mfma_f32_16x16x32_bf16 v[74:77], v[160:163], v[136:139], v[74:77]
	ds_read_b128 v[176:179], v229 offset:4096
	v_mfma_f32_16x16x32_bf16 v[78:81], v[164:167], v[136:139], v[78:81]
	ds_read_b128 v[180:183], v229 offset:6144
	v_mfma_f32_16x16x32_bf16 v[82:85], v[152:155], v[140:143], v[82:85]
	ds_read_b128 v[184:187], v235 offset:0
	v_mfma_f32_16x16x32_bf16 v[86:89], v[156:159], v[140:143], v[86:89]
	ds_read_b128 v[188:191], v235 offset:2048
	v_mfma_f32_16x16x32_bf16 v[90:93], v[160:163], v[140:143], v[90:93]
	ds_read_b128 v[192:195], v235 offset:4096
	v_mfma_f32_16x16x32_bf16 v[94:97], v[164:167], v[140:143], v[94:97]
	ds_read_b128 v[196:199], v235 offset:6144
	v_mfma_f32_16x16x32_bf16 v[98:101], v[152:155], v[144:147], v[98:101]
	v_mfma_f32_16x16x32_bf16 v[102:105], v[156:159], v[144:147], v[102:105]
	v_mfma_f32_16x16x32_bf16 v[106:109], v[160:163], v[144:147], v[106:109]
	v_mfma_f32_16x16x32_bf16 v[110:113], v[164:167], v[144:147], v[110:113]
	v_mfma_f32_16x16x32_bf16 v[114:117], v[152:155], v[148:151], v[114:117]
	v_mfma_f32_16x16x32_bf16 v[118:121], v[156:159], v[148:151], v[118:121]
	v_mfma_f32_16x16x32_bf16 v[122:125], v[160:163], v[148:151], v[122:125]
	v_mfma_f32_16x16x32_bf16 v[126:129], v[164:167], v[148:151], v[126:129]
	s_waitcnt vmcnt(0) lgkmcnt(0)
	s_barrier
	v_mfma_f32_16x16x32_bf16 v[66:69], v[184:187], v[168:171], v[66:69]
	ds_read_b128 v[136:139], v218 offset:0
	v_mfma_f32_16x16x32_bf16 v[70:73], v[188:191], v[168:171], v[70:73]
	ds_read_b128 v[140:143], v218 offset:2048
	v_mfma_f32_16x16x32_bf16 v[74:77], v[192:195], v[168:171], v[74:77]
	ds_read_b128 v[144:147], v218 offset:4096
	v_mfma_f32_16x16x32_bf16 v[78:81], v[196:199], v[168:171], v[78:81]
	ds_read_b128 v[148:151], v218 offset:6144
	v_mfma_f32_16x16x32_bf16 v[82:85], v[184:187], v[172:175], v[82:85]
	ds_read_b128 v[152:155], v230 offset:0
	v_mfma_f32_16x16x32_bf16 v[86:89], v[188:191], v[172:175], v[86:89]
	ds_read_b128 v[156:159], v230 offset:2048
	v_mfma_f32_16x16x32_bf16 v[90:93], v[192:195], v[172:175], v[90:93]
	ds_read_b128 v[160:163], v230 offset:4096
	v_mfma_f32_16x16x32_bf16 v[94:97], v[196:199], v[172:175], v[94:97]
	ds_read_b128 v[164:167], v230 offset:6144
	v_mfma_f32_16x16x32_bf16 v[98:101], v[184:187], v[176:179], v[98:101]
	v_mfma_f32_16x16x32_bf16 v[102:105], v[188:191], v[176:179], v[102:105]
	v_mfma_f32_16x16x32_bf16 v[106:109], v[192:195], v[176:179], v[106:109]
	v_mfma_f32_16x16x32_bf16 v[110:113], v[196:199], v[176:179], v[110:113]
	v_mfma_f32_16x16x32_bf16 v[114:117], v[184:187], v[180:183], v[114:117]
	v_mfma_f32_16x16x32_bf16 v[118:121], v[188:191], v[180:183], v[118:121]
	v_mfma_f32_16x16x32_bf16 v[122:125], v[192:195], v[180:183], v[122:125]
	v_mfma_f32_16x16x32_bf16 v[126:129], v[196:199], v[180:183], v[126:129]
	s_waitcnt lgkmcnt(0)
	v_mfma_f32_16x16x32_bf16 v[66:69], v[152:155], v[136:139], v[66:69]
	ds_read_b128 v[168:171], v225 offset:0
	v_mfma_f32_16x16x32_bf16 v[70:73], v[156:159], v[136:139], v[70:73]
	ds_read_b128 v[172:175], v225 offset:2048
	v_mfma_f32_16x16x32_bf16 v[74:77], v[160:163], v[136:139], v[74:77]
	ds_read_b128 v[176:179], v225 offset:4096
	v_mfma_f32_16x16x32_bf16 v[78:81], v[164:167], v[136:139], v[78:81]
	ds_read_b128 v[180:183], v225 offset:6144
	v_mfma_f32_16x16x32_bf16 v[82:85], v[152:155], v[140:143], v[82:85]
	ds_read_b128 v[184:187], v233 offset:0
	v_mfma_f32_16x16x32_bf16 v[86:89], v[156:159], v[140:143], v[86:89]
	ds_read_b128 v[188:191], v233 offset:2048
	v_mfma_f32_16x16x32_bf16 v[90:93], v[160:163], v[140:143], v[90:93]
	ds_read_b128 v[192:195], v233 offset:4096
	v_mfma_f32_16x16x32_bf16 v[94:97], v[164:167], v[140:143], v[94:97]
	ds_read_b128 v[196:199], v233 offset:6144
	v_mfma_f32_16x16x32_bf16 v[98:101], v[152:155], v[144:147], v[98:101]
	v_mfma_f32_16x16x32_bf16 v[102:105], v[156:159], v[144:147], v[102:105]
	v_mfma_f32_16x16x32_bf16 v[106:109], v[160:163], v[144:147], v[106:109]
	v_mfma_f32_16x16x32_bf16 v[110:113], v[164:167], v[144:147], v[110:113]
	v_mfma_f32_16x16x32_bf16 v[114:117], v[152:155], v[148:151], v[114:117]
	v_mfma_f32_16x16x32_bf16 v[118:121], v[156:159], v[148:151], v[118:121]
	v_mfma_f32_16x16x32_bf16 v[122:125], v[160:163], v[148:151], v[122:125]
	v_mfma_f32_16x16x32_bf16 v[126:129], v[164:167], v[148:151], v[126:129]
	s_waitcnt lgkmcnt(0)
	v_mfma_f32_16x16x32_bf16 v[66:69], v[184:187], v[168:171], v[66:69]
	v_mfma_f32_16x16x32_bf16 v[70:73], v[188:191], v[168:171], v[70:73]
	v_mfma_f32_16x16x32_bf16 v[74:77], v[192:195], v[168:171], v[74:77]
	v_mfma_f32_16x16x32_bf16 v[78:81], v[196:199], v[168:171], v[78:81]
	v_mfma_f32_16x16x32_bf16 v[82:85], v[184:187], v[172:175], v[82:85]
	v_mfma_f32_16x16x32_bf16 v[86:89], v[188:191], v[172:175], v[86:89]
	v_mfma_f32_16x16x32_bf16 v[90:93], v[192:195], v[172:175], v[90:93]
	v_mfma_f32_16x16x32_bf16 v[94:97], v[196:199], v[172:175], v[94:97]
	v_mfma_f32_16x16x32_bf16 v[98:101], v[184:187], v[176:179], v[98:101]
	v_mfma_f32_16x16x32_bf16 v[102:105], v[188:191], v[176:179], v[102:105]
	v_mfma_f32_16x16x32_bf16 v[106:109], v[192:195], v[176:179], v[106:109]
	v_mfma_f32_16x16x32_bf16 v[110:113], v[196:199], v[176:179], v[110:113]
	v_mfma_f32_16x16x32_bf16 v[114:117], v[184:187], v[180:183], v[114:117]
	v_mfma_f32_16x16x32_bf16 v[118:121], v[188:191], v[180:183], v[118:121]
	v_mfma_f32_16x16x32_bf16 v[122:125], v[192:195], v[180:183], v[122:125]
	v_mfma_f32_16x16x32_bf16 v[126:129], v[196:199], v[180:183], v[126:129]
	s_add_u32 s10, s28, s13
	s_addc_u32 s11, s29, 0
	s_add_u32 s13, s13, 0x10000
	v_mul_f32_e32 v66, s12, v66
	v_mul_f32_e32 v67, s12, v67
	v_mul_f32_e32 v68, s12, v68
	v_mul_f32_e32 v69, s12, v69
	v_mul_f32_e32 v70, s12, v70
	v_mul_f32_e32 v71, s12, v71
	v_mul_f32_e32 v72, s12, v72
	v_mul_f32_e32 v73, s12, v73
	v_exp_f32_e32 v66, v66
	v_exp_f32_e32 v67, v67
	v_exp_f32_e32 v68, v68
	v_exp_f32_e32 v69, v69
	v_exp_f32_e32 v70, v70
	v_exp_f32_e32 v71, v71
	v_exp_f32_e32 v72, v72
	v_exp_f32_e32 v73, v73
	v_add_f32_e32 v66, 1.0, v66
	v_add_f32_e32 v67, 1.0, v67
	v_add_f32_e32 v68, 1.0, v68
	v_add_f32_e32 v69, 1.0, v69
	v_add_f32_e32 v70, 1.0, v70
	v_add_f32_e32 v71, 1.0, v71
	v_add_f32_e32 v72, 1.0, v72
	v_add_f32_e32 v73, 1.0, v73
	v_rcp_f32_e32 v66, v66
	v_rcp_f32_e32 v67, v67
	v_rcp_f32_e32 v68, v68
	v_rcp_f32_e32 v69, v69
	v_rcp_f32_e32 v70, v70
	v_rcp_f32_e32 v71, v71
	v_rcp_f32_e32 v72, v72
	v_rcp_f32_e32 v73, v73
	v_cvt_pk_bf16_f32 v66, v66, v67
	v_cvt_pk_bf16_f32 v67, v68, v69
	v_cvt_pk_bf16_f32 v68, v70, v71
	v_cvt_pk_bf16_f32 v69, v72, v73
	global_store_dwordx4 v240, v[66:69], s[10:11] offset:0
	v_mul_f32_e32 v74, s12, v74
	v_mul_f32_e32 v75, s12, v75
	v_mul_f32_e32 v76, s12, v76
	v_mul_f32_e32 v77, s12, v77
	v_mul_f32_e32 v78, s12, v78
	v_mul_f32_e32 v79, s12, v79
	v_mul_f32_e32 v80, s12, v80
	v_mul_f32_e32 v81, s12, v81
	v_exp_f32_e32 v74, v74
	v_exp_f32_e32 v75, v75
	v_exp_f32_e32 v76, v76
	v_exp_f32_e32 v77, v77
	v_exp_f32_e32 v78, v78
	v_exp_f32_e32 v79, v79
	v_exp_f32_e32 v80, v80
	v_exp_f32_e32 v81, v81
	v_add_f32_e32 v74, 1.0, v74
	v_add_f32_e32 v75, 1.0, v75
	v_add_f32_e32 v76, 1.0, v76
	v_add_f32_e32 v77, 1.0, v77
	v_add_f32_e32 v78, 1.0, v78
	v_add_f32_e32 v79, 1.0, v79
	v_add_f32_e32 v80, 1.0, v80
	v_add_f32_e32 v81, 1.0, v81
	v_rcp_f32_e32 v74, v74
	v_rcp_f32_e32 v75, v75
	v_rcp_f32_e32 v76, v76
	v_rcp_f32_e32 v77, v77
	v_rcp_f32_e32 v78, v78
	v_rcp_f32_e32 v79, v79
	v_rcp_f32_e32 v80, v80
	v_rcp_f32_e32 v81, v81
	v_cvt_pk_bf16_f32 v74, v74, v75
	v_cvt_pk_bf16_f32 v75, v76, v77
	v_cvt_pk_bf16_f32 v76, v78, v79
	v_cvt_pk_bf16_f32 v77, v80, v81
	global_store_dwordx4 v240, v[74:77], s[10:11] offset:16
	v_mul_f32_e32 v82, s12, v82
	v_mul_f32_e32 v83, s12, v83
	v_mul_f32_e32 v84, s12, v84
	v_mul_f32_e32 v85, s12, v85
	v_mul_f32_e32 v86, s12, v86
	v_mul_f32_e32 v87, s12, v87
	v_mul_f32_e32 v88, s12, v88
	v_mul_f32_e32 v89, s12, v89
	v_exp_f32_e32 v82, v82
	v_exp_f32_e32 v83, v83
	v_exp_f32_e32 v84, v84
	v_exp_f32_e32 v85, v85
	v_exp_f32_e32 v86, v86
	v_exp_f32_e32 v87, v87
	v_exp_f32_e32 v88, v88
	v_exp_f32_e32 v89, v89
	v_add_f32_e32 v82, 1.0, v82
	v_add_f32_e32 v83, 1.0, v83
	v_add_f32_e32 v84, 1.0, v84
	v_add_f32_e32 v85, 1.0, v85
	v_add_f32_e32 v86, 1.0, v86
	v_add_f32_e32 v87, 1.0, v87
	v_add_f32_e32 v88, 1.0, v88
	v_add_f32_e32 v89, 1.0, v89
	v_rcp_f32_e32 v82, v82
	v_rcp_f32_e32 v83, v83
	v_rcp_f32_e32 v84, v84
	v_rcp_f32_e32 v85, v85
	v_rcp_f32_e32 v86, v86
	v_rcp_f32_e32 v87, v87
	v_rcp_f32_e32 v88, v88
	v_rcp_f32_e32 v89, v89
	v_cvt_pk_bf16_f32 v82, v82, v83
	v_cvt_pk_bf16_f32 v83, v84, v85
	v_cvt_pk_bf16_f32 v84, v86, v87
	v_cvt_pk_bf16_f32 v85, v88, v89
	global_store_dwordx4 v240, v[82:85], s[10:11] offset:2048
	v_mul_f32_e32 v90, s12, v90
	v_mul_f32_e32 v91, s12, v91
	v_mul_f32_e32 v92, s12, v92
	v_mul_f32_e32 v93, s12, v93
	v_mul_f32_e32 v94, s12, v94
	v_mul_f32_e32 v95, s12, v95
	v_mul_f32_e32 v96, s12, v96
	v_mul_f32_e32 v97, s12, v97
	v_exp_f32_e32 v90, v90
	v_exp_f32_e32 v91, v91
	v_exp_f32_e32 v92, v92
	v_exp_f32_e32 v93, v93
	v_exp_f32_e32 v94, v94
	v_exp_f32_e32 v95, v95
	v_exp_f32_e32 v96, v96
	v_exp_f32_e32 v97, v97
	v_add_f32_e32 v90, 1.0, v90
	v_add_f32_e32 v91, 1.0, v91
	v_add_f32_e32 v92, 1.0, v92
	v_add_f32_e32 v93, 1.0, v93
	v_add_f32_e32 v94, 1.0, v94
	v_add_f32_e32 v95, 1.0, v95
	v_add_f32_e32 v96, 1.0, v96
	v_add_f32_e32 v97, 1.0, v97
	v_rcp_f32_e32 v90, v90
	v_rcp_f32_e32 v91, v91
	v_rcp_f32_e32 v92, v92
	v_rcp_f32_e32 v93, v93
	v_rcp_f32_e32 v94, v94
	v_rcp_f32_e32 v95, v95
	v_rcp_f32_e32 v96, v96
	v_rcp_f32_e32 v97, v97
	v_cvt_pk_bf16_f32 v90, v90, v91
	v_cvt_pk_bf16_f32 v91, v92, v93
	v_cvt_pk_bf16_f32 v92, v94, v95
	v_cvt_pk_bf16_f32 v93, v96, v97
	global_store_dwordx4 v240, v[90:93], s[10:11] offset:2064
	v_mul_f32_e32 v98, s12, v98
	v_mul_f32_e32 v99, s12, v99
	v_mul_f32_e32 v100, s12, v100
	v_mul_f32_e32 v101, s12, v101
	v_mul_f32_e32 v102, s12, v102
	v_mul_f32_e32 v103, s12, v103
	v_mul_f32_e32 v104, s12, v104
	v_mul_f32_e32 v105, s12, v105
	v_exp_f32_e32 v98, v98
	v_exp_f32_e32 v99, v99
	v_exp_f32_e32 v100, v100
	v_exp_f32_e32 v101, v101
	v_exp_f32_e32 v102, v102
	v_exp_f32_e32 v103, v103
	v_exp_f32_e32 v104, v104
	v_exp_f32_e32 v105, v105
	v_add_f32_e32 v98, 1.0, v98
	v_add_f32_e32 v99, 1.0, v99
	v_add_f32_e32 v100, 1.0, v100
	v_add_f32_e32 v101, 1.0, v101
	v_add_f32_e32 v102, 1.0, v102
	v_add_f32_e32 v103, 1.0, v103
	v_add_f32_e32 v104, 1.0, v104
	v_add_f32_e32 v105, 1.0, v105
	v_rcp_f32_e32 v98, v98
	v_rcp_f32_e32 v99, v99
	v_rcp_f32_e32 v100, v100
	v_rcp_f32_e32 v101, v101
	v_rcp_f32_e32 v102, v102
	v_rcp_f32_e32 v103, v103
	v_rcp_f32_e32 v104, v104
	v_rcp_f32_e32 v105, v105
	v_cvt_pk_bf16_f32 v98, v98, v99
	v_cvt_pk_bf16_f32 v99, v100, v101
	v_cvt_pk_bf16_f32 v100, v102, v103
	v_cvt_pk_bf16_f32 v101, v104, v105
	global_store_dwordx4 v241, v[98:101], s[10:11] offset:0
	v_mul_f32_e32 v106, s12, v106
	v_mul_f32_e32 v107, s12, v107
	v_mul_f32_e32 v108, s12, v108
	v_mul_f32_e32 v109, s12, v109
	v_mul_f32_e32 v110, s12, v110
	v_mul_f32_e32 v111, s12, v111
	v_mul_f32_e32 v112, s12, v112
	v_mul_f32_e32 v113, s12, v113
	v_exp_f32_e32 v106, v106
	v_exp_f32_e32 v107, v107
	v_exp_f32_e32 v108, v108
	v_exp_f32_e32 v109, v109
	v_exp_f32_e32 v110, v110
	v_exp_f32_e32 v111, v111
	v_exp_f32_e32 v112, v112
	v_exp_f32_e32 v113, v113
	v_add_f32_e32 v106, 1.0, v106
	v_add_f32_e32 v107, 1.0, v107
	v_add_f32_e32 v108, 1.0, v108
	v_add_f32_e32 v109, 1.0, v109
	v_add_f32_e32 v110, 1.0, v110
	v_add_f32_e32 v111, 1.0, v111
	v_add_f32_e32 v112, 1.0, v112
	v_add_f32_e32 v113, 1.0, v113
	v_rcp_f32_e32 v106, v106
	v_rcp_f32_e32 v107, v107
	v_rcp_f32_e32 v108, v108
	v_rcp_f32_e32 v109, v109
	v_rcp_f32_e32 v110, v110
	v_rcp_f32_e32 v111, v111
	v_rcp_f32_e32 v112, v112
	v_rcp_f32_e32 v113, v113
	v_cvt_pk_bf16_f32 v106, v106, v107
	v_cvt_pk_bf16_f32 v107, v108, v109
	v_cvt_pk_bf16_f32 v108, v110, v111
	v_cvt_pk_bf16_f32 v109, v112, v113
	global_store_dwordx4 v241, v[106:109], s[10:11] offset:16
	v_mul_f32_e32 v114, s12, v114
	v_mul_f32_e32 v115, s12, v115
	v_mul_f32_e32 v116, s12, v116
	v_mul_f32_e32 v117, s12, v117
	v_mul_f32_e32 v118, s12, v118
	v_mul_f32_e32 v119, s12, v119
	v_mul_f32_e32 v120, s12, v120
	v_mul_f32_e32 v121, s12, v121
	v_exp_f32_e32 v114, v114
	v_exp_f32_e32 v115, v115
	v_exp_f32_e32 v116, v116
	v_exp_f32_e32 v117, v117
	v_exp_f32_e32 v118, v118
	v_exp_f32_e32 v119, v119
	v_exp_f32_e32 v120, v120
	v_exp_f32_e32 v121, v121
	v_add_f32_e32 v114, 1.0, v114
	v_add_f32_e32 v115, 1.0, v115
	v_add_f32_e32 v116, 1.0, v116
	v_add_f32_e32 v117, 1.0, v117
	v_add_f32_e32 v118, 1.0, v118
	v_add_f32_e32 v119, 1.0, v119
	v_add_f32_e32 v120, 1.0, v120
	v_add_f32_e32 v121, 1.0, v121
	v_rcp_f32_e32 v114, v114
	v_rcp_f32_e32 v115, v115
	v_rcp_f32_e32 v116, v116
	v_rcp_f32_e32 v117, v117
	v_rcp_f32_e32 v118, v118
	v_rcp_f32_e32 v119, v119
	v_rcp_f32_e32 v120, v120
	v_rcp_f32_e32 v121, v121
	v_cvt_pk_bf16_f32 v114, v114, v115
	v_cvt_pk_bf16_f32 v115, v116, v117
	v_cvt_pk_bf16_f32 v116, v118, v119
	v_cvt_pk_bf16_f32 v117, v120, v121
	global_store_dwordx4 v241, v[114:117], s[10:11] offset:2048
	v_mul_f32_e32 v122, s12, v122
	v_mul_f32_e32 v123, s12, v123
	v_mul_f32_e32 v124, s12, v124
	v_mul_f32_e32 v125, s12, v125
	v_mul_f32_e32 v126, s12, v126
	v_mul_f32_e32 v127, s12, v127
	v_mul_f32_e32 v128, s12, v128
	v_mul_f32_e32 v129, s12, v129
	v_exp_f32_e32 v122, v122
	v_exp_f32_e32 v123, v123
	v_exp_f32_e32 v124, v124
	v_exp_f32_e32 v125, v125
	v_exp_f32_e32 v126, v126
	v_exp_f32_e32 v127, v127
	v_exp_f32_e32 v128, v128
	v_exp_f32_e32 v129, v129
	v_add_f32_e32 v122, 1.0, v122
	v_add_f32_e32 v123, 1.0, v123
	v_add_f32_e32 v124, 1.0, v124
	v_add_f32_e32 v125, 1.0, v125
	v_add_f32_e32 v126, 1.0, v126
	v_add_f32_e32 v127, 1.0, v127
	v_add_f32_e32 v128, 1.0, v128
	v_add_f32_e32 v129, 1.0, v129
	v_rcp_f32_e32 v122, v122
	v_rcp_f32_e32 v123, v123
	v_rcp_f32_e32 v124, v124
	v_rcp_f32_e32 v125, v125
	v_rcp_f32_e32 v126, v126
	v_rcp_f32_e32 v127, v127
	v_rcp_f32_e32 v128, v128
	v_rcp_f32_e32 v129, v129
	v_cvt_pk_bf16_f32 v122, v122, v123
	v_cvt_pk_bf16_f32 v123, v124, v125
	v_cvt_pk_bf16_f32 v124, v126, v127
	v_cvt_pk_bf16_f32 v125, v128, v129
	global_store_dwordx4 v241, v[122:125], s[10:11] offset:2064
	s_branch .Lc1_join0
.Lc1_grpB0:
	s_and_b32 s1, s2, 7
	s_lshr_b32 s22, s2, 3
	s_and_b32 s23, s22, 3
	s_lshl_b32 s1, s1, 2
	s_add_u32 s1, s1, s23
	s_lshr_b32 s22, s22, 2
	s_lshl_b32 s23, s1, 19
	s_add_u32 s4, s26, s23
	s_addc_u32 s5, s27, 0
	v_readlane_b32 s6, v254, 57
	v_readlane_b32 s7, v254, 58
	s_lshl_b32 s23, s22, 20
	s_add_u32 s23, s23, 0x640000
	s_nop 0
	s_add_u32 s6, s6, s23
	s_addc_u32 s7, s7, 0
	s_lshr_b32 s23, s22, 1
	s_lshl_b32 s23, s23, 5
	s_add_u32 s23, s23, s1
	s_lshl_b32 s23, s23, 3
	s_and_b32 s24, s22, 1
	s_lshl_b32 s24, s24, 2
	s_add_u32 s23, s23, s24
	s_lshl_b32 s13, s23, 16
	s_mov_b32 s12, 0xbfb8aa3b
	s_add_u32 s14, s4, 0x0
	s_addc_u32 s15, s5, 0
	s_add_u32 s22, s4, 0x10000
	s_addc_u32 s23, s5, 0
	s_add_u32 s24, s6, 0x0
	s_addc_u32 s25, s7, 0
	s_add_u32 s52, s6, 0x8000
	s_addc_u32 s53, s7, 0
	s_mov_b32 m0, s8
	s_nop 0
	global_load_lds_dwordx4 v200, s[14:15]
	s_add_u32 m0, s8, 0x400
	s_nop 0
	global_load_lds_dwordx4 v201, s[14:15]
	s_add_u32 m0, s8, 0x800
	s_nop 0
	global_load_lds_dwordx4 v202, s[14:15]
	s_add_u32 m0, s8, 0xc00
	s_nop 0
	global_load_lds_dwordx4 v203, s[14:15]
	s_add_u32 m0, s8, 0x1000
	s_nop 0
	global_load_lds_dwordx4 v200, s[22:23]
	s_add_u32 m0, s8, 0x1400
	s_nop 0
	global_load_lds_dwordx4 v201, s[22:23]
	s_add_u32 m0, s8, 0x1800
	s_nop 0
	global_load_lds_dwordx4 v202, s[22:23]
	s_add_u32 m0, s8, 0x1c00
	s_nop 0
	global_load_lds_dwordx4 v203, s[22:23]
	s_mov_b32 m0, s9
	s_nop 0
	global_load_lds_dwordx4 v204, s[24:25]
	s_add_u32 m0, s9, 0x400
	s_nop 0
	global_load_lds_dwordx4 v205, s[24:25]
	s_add_u32 m0, s9, 0x800
	s_nop 0
	global_load_lds_dwordx4 v204, s[52:53]
	s_add_u32 m0, s9, 0xc00
	s_nop 0
	global_load_lds_dwordx4 v205, s[52:53]
	s_add_u32 s14, s4, 0x80
	s_addc_u32 s15, s5, 0
	s_add_u32 s22, s4, 0x10080
	s_addc_u32 s23, s5, 0
	s_add_u32 s24, s6, 0x80
	s_addc_u32 s25, s7, 0
	s_add_u32 s52, s6, 0x8080
	s_addc_u32 s53, s7, 0
	s_add_u32 m0, s8, 0xc000
	s_nop 0
	global_load_lds_dwordx4 v200, s[14:15]
	s_add_u32 m0, s8, 0xc400
	s_nop 0
	global_load_lds_dwordx4 v201, s[14:15]
	s_add_u32 m0, s8, 0xc800
	s_nop 0
	global_load_lds_dwordx4 v202, s[14:15]
	s_add_u32 m0, s8, 0xcc00
	s_nop 0
	global_load_lds_dwordx4 v203, s[14:15]
	s_add_u32 m0, s8, 0xd000
	s_nop 0
	global_load_lds_dwordx4 v200, s[22:23]
	s_add_u32 m0, s8, 0xd400
	s_nop 0
	global_load_lds_dwordx4 v201, s[22:23]
	s_add_u32 m0, s8, 0xd800
	s_nop 0
	global_load_lds_dwordx4 v202, s[22:23]
	s_add_u32 m0, s8, 0xdc00
	s_nop 0
	global_load_lds_dwordx4 v203, s[22:23]
	s_add_u32 m0, s9, 0xc000
	s_nop 0
	global_load_lds_dwordx4 v204, s[24:25]
	s_add_u32 m0, s9, 0xc400
	s_nop 0
	global_load_lds_dwordx4 v205, s[24:25]
	s_add_u32 m0, s9, 0xc800
	s_nop 0
	global_load_lds_dwordx4 v204, s[52:53]
	s_add_u32 m0, s9, 0xcc00
	s_nop 0
	global_load_lds_dwordx4 v205, s[52:53]
	s_add_u32 s14, s4, 0x100
	s_addc_u32 s15, s5, 0
	s_add_u32 s22, s4, 0x10100
	s_addc_u32 s23, s5, 0
	s_add_u32 s24, s6, 0x100
	s_addc_u32 s25, s7, 0
	s_add_u32 s52, s6, 0x8100
	s_addc_u32 s53, s7, 0
	s_add_u32 m0, s8, 0x18000
	s_nop 0
	global_load_lds_dwordx4 v200, s[14:15]
	s_add_u32 m0, s8, 0x18400
	s_nop 0
	global_load_lds_dwordx4 v201, s[14:15]
	s_add_u32 m0, s8, 0x18800
	s_nop 0
	global_load_lds_dwordx4 v202, s[14:15]
	s_add_u32 m0, s8, 0x18c00
	s_nop 0
	global_load_lds_dwordx4 v203, s[14:15]
	s_add_u32 m0, s8, 0x19000
	s_nop 0
	global_load_lds_dwordx4 v200, s[22:23]
	s_add_u32 m0, s8, 0x19400
	s_nop 0
	global_load_lds_dwordx4 v201, s[22:23]
	s_add_u32 m0, s8, 0x19800
	s_nop 0
	global_load_lds_dwordx4 v202, s[22:23]
	s_add_u32 m0, s8, 0x19c00
	s_nop 0
	global_load_lds_dwordx4 v203, s[22:23]
	s_add_u32 m0, s9, 0x18000
	s_nop 0
	global_load_lds_dwordx4 v204, s[24:25]
	s_add_u32 m0, s9, 0x18400
	s_nop 0
	global_load_lds_dwordx4 v205, s[24:25]
	s_add_u32 m0, s9, 0x18800
	s_nop 0
	global_load_lds_dwordx4 v204, s[52:53]
	s_add_u32 m0, s9, 0x18c00
	s_nop 0
	global_load_lds_dwordx4 v205, s[52:53]
	s_waitcnt vmcnt(24)
	s_barrier
	ds_read_b128 v[136:139], v218 offset:0
	ds_read_b128 v[140:143], v218 offset:2048
	ds_read_b128 v[144:147], v218 offset:4096
	ds_read_b128 v[148:151], v218 offset:6144
	ds_read_b128 v[152:155], v230 offset:0
	ds_read_b128 v[156:159], v230 offset:2048
	ds_read_b128 v[160:163], v230 offset:4096
	ds_read_b128 v[164:167], v230 offset:6144
	s_waitcnt lgkmcnt(0)
	v_mfma_f32_16x16x32_bf16 v[2:5], v[152:155], v[136:139], 0
	ds_read_b128 v[168:171], v225 offset:0
	v_mfma_f32_16x16x32_bf16 v[6:9], v[156:159], v[136:139], 0
	ds_read_b128 v[172:175], v225 offset:2048
	v_mfma_f32_16x16x32_bf16 v[10:13], v[160:163], v[136:139], 0
	ds_read_b128 v[176:179], v225 offset:4096
	v_mfma_f32_16x16x32_bf16 v[14:17], v[164:167], v[136:139], 0
	ds_read_b128 v[180:183], v225 offset:6144
	v_mfma_f32_16x16x32_bf16 v[18:21], v[152:155], v[140:143], 0
	ds_read_b128 v[184:187], v233 offset:0
	v_mfma_f32_16x16x32_bf16 v[22:25], v[156:159], v[140:143], 0
	ds_read_b128 v[188:191], v233 offset:2048
	v_mfma_f32_16x16x32_bf16 v[26:29], v[160:163], v[140:143], 0
	ds_read_b128 v[192:195], v233 offset:4096
	v_mfma_f32_16x16x32_bf16 v[30:33], v[164:167], v[140:143], 0
	ds_read_b128 v[196:199], v233 offset:6144
	v_mfma_f32_16x16x32_bf16 v[34:37], v[152:155], v[144:147], 0
	v_mfma_f32_16x16x32_bf16 v[38:41], v[156:159], v[144:147], 0
	v_mfma_f32_16x16x32_bf16 v[42:45], v[160:163], v[144:147], 0
	v_mfma_f32_16x16x32_bf16 v[46:49], v[164:167], v[144:147], 0
	v_mfma_f32_16x16x32_bf16 v[50:53], v[152:155], v[148:151], 0
	v_mfma_f32_16x16x32_bf16 v[54:57], v[156:159], v[148:151], 0
	v_mfma_f32_16x16x32_bf16 v[58:61], v[160:163], v[148:151], 0
	v_mfma_f32_16x16x32_bf16 v[62:65], v[164:167], v[148:151], 0
	s_waitcnt vmcnt(12) lgkmcnt(0)
	s_barrier
	s_add_u32 s14, s4, 0x180
	s_addc_u32 s15, s5, 0
	v_mfma_f32_16x16x32_bf16 v[2:5], v[184:187], v[168:171], v[2:5]
	ds_read_b128 v[136:139], v219 offset:0
	s_add_u32 s22, s4, 0x10180
	s_addc_u32 s23, s5, 0
	v_mfma_f32_16x16x32_bf16 v[6:9], v[188:191], v[168:171], v[6:9]
	ds_read_b128 v[140:143], v219 offset:2048
	s_add_u32 s24, s6, 0x180
	s_addc_u32 s25, s7, 0
	v_mfma_f32_16x16x32_bf16 v[10:13], v[192:195], v[168:171], v[10:13]
	ds_read_b128 v[144:147], v219 offset:4096
	s_add_u32 s52, s6, 0x8180
	s_addc_u32 s53, s7, 0
	v_mfma_f32_16x16x32_bf16 v[14:17], v[196:199], v[168:171], v[14:17]
	ds_read_b128 v[148:151], v219 offset:6144
	s_mov_b32 m0, s8
	v_mfma_f32_16x16x32_bf16 v[18:21], v[184:187], v[172:175], v[18:21]
	global_load_lds_dwordx4 v200, s[14:15]
	ds_read_b128 v[152:155], v231 offset:0
	s_add_u32 m0, s8, 0x400
	v_mfma_f32_16x16x32_bf16 v[22:25], v[188:191], v[172:175], v[22:25]
	global_load_lds_dwordx4 v201, s[14:15]
	ds_read_b128 v[156:159], v231 offset:2048
	s_add_u32 m0, s8, 0x800
	v_mfma_f32_16x16x32_bf16 v[26:29], v[192:195], v[172:175], v[26:29]
	global_load_lds_dwordx4 v202, s[14:15]
	ds_read_b128 v[160:163], v231 offset:4096
	s_add_u32 m0, s8, 0xc00
	v_mfma_f32_16x16x32_bf16 v[30:33], v[196:199], v[172:175], v[30:33]
	global_load_lds_dwordx4 v203, s[14:15]
	ds_read_b128 v[164:167], v231 offset:6144
	s_add_u32 m0, s8, 0x1000
	v_mfma_f32_16x16x32_bf16 v[34:37], v[184:187], v[176:179], v[34:37]
	global_load_lds_dwordx4 v200, s[22:23]
	s_add_u32 m0, s8, 0x1400
	v_mfma_f32_16x16x32_bf16 v[38:41], v[188:191], v[176:179], v[38:41]
	global_load_lds_dwordx4 v201, s[22:23]
	s_add_u32 m0, s8, 0x1800
	v_mfma_f32_16x16x32_bf16 v[42:45], v[192:195], v[176:179], v[42:45]
	global_load_lds_dwordx4 v202, s[22:23]
	s_add_u32 m0, s8, 0x1c00
	v_mfma_f32_16x16x32_bf16 v[46:49], v[196:199], v[176:179], v[46:49]
	global_load_lds_dwordx4 v203, s[22:23]
	s_mov_b32 m0, s9
	v_mfma_f32_16x16x32_bf16 v[50:53], v[184:187], v[180:183], v[50:53]
	global_load_lds_dwordx4 v204, s[24:25]
	s_add_u32 m0, s9, 0x400
	v_mfma_f32_16x16x32_bf16 v[54:57], v[188:191], v[180:183], v[54:57]
	global_load_lds_dwordx4 v205, s[24:25]
	s_add_u32 m0, s9, 0x800
	v_mfma_f32_16x16x32_bf16 v[58:61], v[192:195], v[180:183], v[58:61]
	global_load_lds_dwordx4 v204, s[52:53]
	s_add_u32 m0, s9, 0xc00
	v_mfma_f32_16x16x32_bf16 v[62:65], v[196:199], v[180:183], v[62:65]
	global_load_lds_dwordx4 v205, s[52:53]
	s_waitcnt lgkmcnt(0)
	v_mfma_f32_16x16x32_bf16 v[2:5], v[152:155], v[136:139], v[2:5]
	ds_read_b128 v[168:171], v228 offset:0
	v_mfma_f32_16x16x32_bf16 v[6:9], v[156:159], v[136:139], v[6:9]
	ds_read_b128 v[172:175], v228 offset:2048
	v_mfma_f32_16x16x32_bf16 v[10:13], v[160:163], v[136:139], v[10:13]
	ds_read_b128 v[176:179], v228 offset:4096
	v_mfma_f32_16x16x32_bf16 v[14:17], v[164:167], v[136:139], v[14:17]
	ds_read_b128 v[180:183], v228 offset:6144
	v_mfma_f32_16x16x32_bf16 v[18:21], v[152:155], v[140:143], v[18:21]
	ds_read_b128 v[184:187], v234 offset:0
	v_mfma_f32_16x16x32_bf16 v[22:25], v[156:159], v[140:143], v[22:25]
	ds_read_b128 v[188:191], v234 offset:2048
	v_mfma_f32_16x16x32_bf16 v[26:29], v[160:163], v[140:143], v[26:29]
	ds_read_b128 v[192:195], v234 offset:4096
	v_mfma_f32_16x16x32_bf16 v[30:33], v[164:167], v[140:143], v[30:33]
	ds_read_b128 v[196:199], v234 offset:6144
	v_mfma_f32_16x16x32_bf16 v[34:37], v[152:155], v[144:147], v[34:37]
	v_mfma_f32_16x16x32_bf16 v[38:41], v[156:159], v[144:147], v[38:41]
	v_mfma_f32_16x16x32_bf16 v[42:45], v[160:163], v[144:147], v[42:45]
	v_mfma_f32_16x16x32_bf16 v[46:49], v[164:167], v[144:147], v[46:49]
	v_mfma_f32_16x16x32_bf16 v[50:53], v[152:155], v[148:151], v[50:53]
	v_mfma_f32_16x16x32_bf16 v[54:57], v[156:159], v[148:151], v[54:57]
	v_mfma_f32_16x16x32_bf16 v[58:61], v[160:163], v[148:151], v[58:61]
	v_mfma_f32_16x16x32_bf16 v[62:65], v[164:167], v[148:151], v[62:65]
	s_waitcnt vmcnt(12) lgkmcnt(0)
	s_barrier
	s_add_u32 s14, s4, 0x200
	s_addc_u32 s15, s5, 0
	v_mfma_f32_16x16x32_bf16 v[2:5], v[184:187], v[168:171], v[2:5]
	ds_read_b128 v[136:139], v224 offset:0
	s_add_u32 s22, s4, 0x10200
	s_addc_u32 s23, s5, 0
	v_mfma_f32_16x16x32_bf16 v[6:9], v[188:191], v[168:171], v[6:9]
	ds_read_b128 v[140:143], v224 offset:2048
	s_add_u32 s24, s6, 0x200
	s_addc_u32 s25, s7, 0
	v_mfma_f32_16x16x32_bf16 v[10:13], v[192:195], v[168:171], v[10:13]
	ds_read_b128 v[144:147], v224 offset:4096
	s_add_u32 s52, s6, 0x8200
	s_addc_u32 s53, s7, 0
	v_mfma_f32_16x16x32_bf16 v[14:17], v[196:199], v[168:171], v[14:17]
	ds_read_b128 v[148:151], v224 offset:6144
	s_add_u32 m0, s8, 0xc000
	v_mfma_f32_16x16x32_bf16 v[18:21], v[184:187], v[172:175], v[18:21]
	global_load_lds_dwordx4 v200, s[14:15]
	ds_read_b128 v[152:155], v232 offset:0
	s_add_u32 m0, s8, 0xc400
	v_mfma_f32_16x16x32_bf16 v[22:25], v[188:191], v[172:175], v[22:25]
	global_load_lds_dwordx4 v201, s[14:15]
	ds_read_b128 v[156:159], v232 offset:2048
	s_add_u32 m0, s8, 0xc800
	v_mfma_f32_16x16x32_bf16 v[26:29], v[192:195], v[172:175], v[26:29]
	global_load_lds_dwordx4 v202, s[14:15]
	ds_read_b128 v[160:163], v232 offset:4096
	s_add_u32 m0, s8, 0xcc00
	v_mfma_f32_16x16x32_bf16 v[30:33], v[196:199], v[172:175], v[30:33]
	global_load_lds_dwordx4 v203, s[14:15]
	ds_read_b128 v[164:167], v232 offset:6144
	s_add_u32 m0, s8, 0xd000
	v_mfma_f32_16x16x32_bf16 v[34:37], v[184:187], v[176:179], v[34:37]
	global_load_lds_dwordx4 v200, s[22:23]
	s_add_u32 m0, s8, 0xd400
	v_mfma_f32_16x16x32_bf16 v[38:41], v[188:191], v[176:179], v[38:41]
	global_load_lds_dwordx4 v201, s[22:23]
	s_add_u32 m0, s8, 0xd800
	v_mfma_f32_16x16x32_bf16 v[42:45], v[192:195], v[176:179], v[42:45]
	global_load_lds_dwordx4 v202, s[22:23]
	s_add_u32 m0, s8, 0xdc00
	v_mfma_f32_16x16x32_bf16 v[46:49], v[196:199], v[176:179], v[46:49]
	global_load_lds_dwordx4 v203, s[22:23]
	s_add_u32 m0, s9, 0xc000
	v_mfma_f32_16x16x32_bf16 v[50:53], v[184:187], v[180:183], v[50:53]
	global_load_lds_dwordx4 v204, s[24:25]
	s_add_u32 m0, s9, 0xc400
	v_mfma_f32_16x16x32_bf16 v[54:57], v[188:191], v[180:183], v[54:57]
	global_load_lds_dwordx4 v205, s[24:25]
	s_add_u32 m0, s9, 0xc800
	v_mfma_f32_16x16x32_bf16 v[58:61], v[192:195], v[180:183], v[58:61]
	global_load_lds_dwordx4 v204, s[52:53]
	s_add_u32 m0, s9, 0xcc00
	v_mfma_f32_16x16x32_bf16 v[62:65], v[196:199], v[180:183], v[62:65]
	global_load_lds_dwordx4 v205, s[52:53]
	s_waitcnt lgkmcnt(0)
	v_mfma_f32_16x16x32_bf16 v[2:5], v[152:155], v[136:139], v[2:5]
	ds_read_b128 v[168:171], v229 offset:0
	v_mfma_f32_16x16x32_bf16 v[6:9], v[156:159], v[136:139], v[6:9]
	ds_read_b128 v[172:175], v229 offset:2048
	v_mfma_f32_16x16x32_bf16 v[10:13], v[160:163], v[136:139], v[10:13]
	ds_read_b128 v[176:179], v229 offset:4096
	v_mfma_f32_16x16x32_bf16 v[14:17], v[164:167], v[136:139], v[14:17]
	ds_read_b128 v[180:183], v229 offset:6144
	v_mfma_f32_16x16x32_bf16 v[18:21], v[152:155], v[140:143], v[18:21]
	ds_read_b128 v[184:187], v235 offset:0
	v_mfma_f32_16x16x32_bf16 v[22:25], v[156:159], v[140:143], v[22:25]
	ds_read_b128 v[188:191], v235 offset:2048
	v_mfma_f32_16x16x32_bf16 v[26:29], v[160:163], v[140:143], v[26:29]
	ds_read_b128 v[192:195], v235 offset:4096
	v_mfma_f32_16x16x32_bf16 v[30:33], v[164:167], v[140:143], v[30:33]
	ds_read_b128 v[196:199], v235 offset:6144
	v_mfma_f32_16x16x32_bf16 v[34:37], v[152:155], v[144:147], v[34:37]
	v_mfma_f32_16x16x32_bf16 v[38:41], v[156:159], v[144:147], v[38:41]
	v_mfma_f32_16x16x32_bf16 v[42:45], v[160:163], v[144:147], v[42:45]
	v_mfma_f32_16x16x32_bf16 v[46:49], v[164:167], v[144:147], v[46:49]
	v_mfma_f32_16x16x32_bf16 v[50:53], v[152:155], v[148:151], v[50:53]
	v_mfma_f32_16x16x32_bf16 v[54:57], v[156:159], v[148:151], v[54:57]
	v_mfma_f32_16x16x32_bf16 v[58:61], v[160:163], v[148:151], v[58:61]
	v_mfma_f32_16x16x32_bf16 v[62:65], v[164:167], v[148:151], v[62:65]
	s_waitcnt vmcnt(12) lgkmcnt(0)
	s_barrier
	s_add_u32 s14, s4, 0x280
	s_addc_u32 s15, s5, 0
	v_mfma_f32_16x16x32_bf16 v[2:5], v[184:187], v[168:171], v[2:5]
	ds_read_b128 v[136:139], v218 offset:0
	s_add_u32 s22, s4, 0x10280
	s_addc_u32 s23, s5, 0
	v_mfma_f32_16x16x32_bf16 v[6:9], v[188:191], v[168:171], v[6:9]
	ds_read_b128 v[140:143], v218 offset:2048
	s_add_u32 s24, s6, 0x280
	s_addc_u32 s25, s7, 0
	v_mfma_f32_16x16x32_bf16 v[10:13], v[192:195], v[168:171], v[10:13]
	ds_read_b128 v[144:147], v218 offset:4096
	s_add_u32 s52, s6, 0x8280
	s_addc_u32 s53, s7, 0
	v_mfma_f32_16x16x32_bf16 v[14:17], v[196:199], v[168:171], v[14:17]
	ds_read_b128 v[148:151], v218 offset:6144
	s_add_u32 m0, s8, 0x18000
	v_mfma_f32_16x16x32_bf16 v[18:21], v[184:187], v[172:175], v[18:21]
	global_load_lds_dwordx4 v200, s[14:15]
	ds_read_b128 v[152:155], v230 offset:0
	s_add_u32 m0, s8, 0x18400
	v_mfma_f32_16x16x32_bf16 v[22:25], v[188:191], v[172:175], v[22:25]
	global_load_lds_dwordx4 v201, s[14:15]
	ds_read_b128 v[156:159], v230 offset:2048
	s_add_u32 m0, s8, 0x18800
	v_mfma_f32_16x16x32_bf16 v[26:29], v[192:195], v[172:175], v[26:29]
	global_load_lds_dwordx4 v202, s[14:15]
	ds_read_b128 v[160:163], v230 offset:4096
	s_add_u32 m0, s8, 0x18c00
	v_mfma_f32_16x16x32_bf16 v[30:33], v[196:199], v[172:175], v[30:33]
	global_load_lds_dwordx4 v203, s[14:15]
	ds_read_b128 v[164:167], v230 offset:6144
	s_add_u32 m0, s8, 0x19000
	v_mfma_f32_16x16x32_bf16 v[34:37], v[184:187], v[176:179], v[34:37]
	global_load_lds_dwordx4 v200, s[22:23]
	s_add_u32 m0, s8, 0x19400
	v_mfma_f32_16x16x32_bf16 v[38:41], v[188:191], v[176:179], v[38:41]
	global_load_lds_dwordx4 v201, s[22:23]
	s_add_u32 m0, s8, 0x19800
	v_mfma_f32_16x16x32_bf16 v[42:45], v[192:195], v[176:179], v[42:45]
	global_load_lds_dwordx4 v202, s[22:23]
	s_add_u32 m0, s8, 0x19c00
	v_mfma_f32_16x16x32_bf16 v[46:49], v[196:199], v[176:179], v[46:49]
	global_load_lds_dwordx4 v203, s[22:23]
	s_add_u32 m0, s9, 0x18000
	v_mfma_f32_16x16x32_bf16 v[50:53], v[184:187], v[180:183], v[50:53]
	global_load_lds_dwordx4 v204, s[24:25]
	s_add_u32 m0, s9, 0x18400
	v_mfma_f32_16x16x32_bf16 v[54:57], v[188:191], v[180:183], v[54:57]
	global_load_lds_dwordx4 v205, s[24:25]
	s_add_u32 m0, s9, 0x18800
	v_mfma_f32_16x16x32_bf16 v[58:61], v[192:195], v[180:183], v[58:61]
	global_load_lds_dwordx4 v204, s[52:53]
	s_add_u32 m0, s9, 0x18c00
	v_mfma_f32_16x16x32_bf16 v[62:65], v[196:199], v[180:183], v[62:65]
	global_load_lds_dwordx4 v205, s[52:53]
	s_waitcnt lgkmcnt(0)
	v_mfma_f32_16x16x32_bf16 v[2:5], v[152:155], v[136:139], v[2:5]
	ds_read_b128 v[168:171], v225 offset:0
	v_mfma_f32_16x16x32_bf16 v[6:9], v[156:159], v[136:139], v[6:9]
	ds_read_b128 v[172:175], v225 offset:2048
	v_mfma_f32_16x16x32_bf16 v[10:13], v[160:163], v[136:139], v[10:13]
	ds_read_b128 v[176:179], v225 offset:4096
	v_mfma_f32_16x16x32_bf16 v[14:17], v[164:167], v[136:139], v[14:17]
	ds_read_b128 v[180:183], v225 offset:6144
	v_mfma_f32_16x16x32_bf16 v[18:21], v[152:155], v[140:143], v[18:21]
	ds_read_b128 v[184:187], v233 offset:0
	v_mfma_f32_16x16x32_bf16 v[22:25], v[156:159], v[140:143], v[22:25]
	ds_read_b128 v[188:191], v233 offset:2048
	v_mfma_f32_16x16x32_bf16 v[26:29], v[160:163], v[140:143], v[26:29]
	ds_read_b128 v[192:195], v233 offset:4096
	v_mfma_f32_16x16x32_bf16 v[30:33], v[164:167], v[140:143], v[30:33]
	ds_read_b128 v[196:199], v233 offset:6144
	v_mfma_f32_16x16x32_bf16 v[34:37], v[152:155], v[144:147], v[34:37]
	v_mfma_f32_16x16x32_bf16 v[38:41], v[156:159], v[144:147], v[38:41]
	v_mfma_f32_16x16x32_bf16 v[42:45], v[160:163], v[144:147], v[42:45]
	v_mfma_f32_16x16x32_bf16 v[46:49], v[164:167], v[144:147], v[46:49]
	v_mfma_f32_16x16x32_bf16 v[50:53], v[152:155], v[148:151], v[50:53]
	v_mfma_f32_16x16x32_bf16 v[54:57], v[156:159], v[148:151], v[54:57]
	v_mfma_f32_16x16x32_bf16 v[58:61], v[160:163], v[148:151], v[58:61]
	v_mfma_f32_16x16x32_bf16 v[62:65], v[164:167], v[148:151], v[62:65]
	s_waitcnt vmcnt(12) lgkmcnt(0)
	s_barrier
	s_add_u32 s14, s4, 0x300
	s_addc_u32 s15, s5, 0
	v_mfma_f32_16x16x32_bf16 v[2:5], v[184:187], v[168:171], v[2:5]
	ds_read_b128 v[136:139], v219 offset:0
	s_add_u32 s22, s4, 0x10300
	s_addc_u32 s23, s5, 0
	v_mfma_f32_16x16x32_bf16 v[6:9], v[188:191], v[168:171], v[6:9]
	ds_read_b128 v[140:143], v219 offset:2048
	s_add_u32 s24, s6, 0x300
	s_addc_u32 s25, s7, 0
	v_mfma_f32_16x16x32_bf16 v[10:13], v[192:195], v[168:171], v[10:13]
	ds_read_b128 v[144:147], v219 offset:4096
	s_add_u32 s52, s6, 0x8300
	s_addc_u32 s53, s7, 0
	v_mfma_f32_16x16x32_bf16 v[14:17], v[196:199], v[168:171], v[14:17]
	ds_read_b128 v[148:151], v219 offset:6144
	s_mov_b32 m0, s8
	v_mfma_f32_16x16x32_bf16 v[18:21], v[184:187], v[172:175], v[18:21]
	global_load_lds_dwordx4 v200, s[14:15]
	ds_read_b128 v[152:155], v231 offset:0
	s_add_u32 m0, s8, 0x400
	v_mfma_f32_16x16x32_bf16 v[22:25], v[188:191], v[172:175], v[22:25]
	global_load_lds_dwordx4 v201, s[14:15]
	ds_read_b128 v[156:159], v231 offset:2048
	s_add_u32 m0, s8, 0x800
	v_mfma_f32_16x16x32_bf16 v[26:29], v[192:195], v[172:175], v[26:29]
	global_load_lds_dwordx4 v202, s[14:15]
	ds_read_b128 v[160:163], v231 offset:4096
	s_add_u32 m0, s8, 0xc00
	v_mfma_f32_16x16x32_bf16 v[30:33], v[196:199], v[172:175], v[30:33]
	global_load_lds_dwordx4 v203, s[14:15]
	ds_read_b128 v[164:167], v231 offset:6144
	s_add_u32 m0, s8, 0x1000
	v_mfma_f32_16x16x32_bf16 v[34:37], v[184:187], v[176:179], v[34:37]
	global_load_lds_dwordx4 v200, s[22:23]
	s_add_u32 m0, s8, 0x1400
	v_mfma_f32_16x16x32_bf16 v[38:41], v[188:191], v[176:179], v[38:41]
	global_load_lds_dwordx4 v201, s[22:23]
	s_add_u32 m0, s8, 0x1800
	v_mfma_f32_16x16x32_bf16 v[42:45], v[192:195], v[176:179], v[42:45]
	global_load_lds_dwordx4 v202, s[22:23]
	s_add_u32 m0, s8, 0x1c00
	v_mfma_f32_16x16x32_bf16 v[46:49], v[196:199], v[176:179], v[46:49]
	global_load_lds_dwordx4 v203, s[22:23]
	s_mov_b32 m0, s9
	v_mfma_f32_16x16x32_bf16 v[50:53], v[184:187], v[180:183], v[50:53]
	global_load_lds_dwordx4 v204, s[24:25]
	s_add_u32 m0, s9, 0x400
	v_mfma_f32_16x16x32_bf16 v[54:57], v[188:191], v[180:183], v[54:57]
	global_load_lds_dwordx4 v205, s[24:25]
	s_add_u32 m0, s9, 0x800
	v_mfma_f32_16x16x32_bf16 v[58:61], v[192:195], v[180:183], v[58:61]
	global_load_lds_dwordx4 v204, s[52:53]
	s_add_u32 m0, s9, 0xc00
	v_mfma_f32_16x16x32_bf16 v[62:65], v[196:199], v[180:183], v[62:65]
	global_load_lds_dwordx4 v205, s[52:53]
	s_waitcnt lgkmcnt(0)
	v_mfma_f32_16x16x32_bf16 v[2:5], v[152:155], v[136:139], v[2:5]
	ds_read_b128 v[168:171], v228 offset:0
	v_mfma_f32_16x16x32_bf16 v[6:9], v[156:159], v[136:139], v[6:9]
	ds_read_b128 v[172:175], v228 offset:2048
	v_mfma_f32_16x16x32_bf16 v[10:13], v[160:163], v[136:139], v[10:13]
	ds_read_b128 v[176:179], v228 offset:4096
	v_mfma_f32_16x16x32_bf16 v[14:17], v[164:167], v[136:139], v[14:17]
	ds_read_b128 v[180:183], v228 offset:6144
	v_mfma_f32_16x16x32_bf16 v[18:21], v[152:155], v[140:143], v[18:21]
	ds_read_b128 v[184:187], v234 offset:0
	v_mfma_f32_16x16x32_bf16 v[22:25], v[156:159], v[140:143], v[22:25]
	ds_read_b128 v[188:191], v234 offset:2048
	v_mfma_f32_16x16x32_bf16 v[26:29], v[160:163], v[140:143], v[26:29]
	ds_read_b128 v[192:195], v234 offset:4096
	v_mfma_f32_16x16x32_bf16 v[30:33], v[164:167], v[140:143], v[30:33]
	ds_read_b128 v[196:199], v234 offset:6144
	v_mfma_f32_16x16x32_bf16 v[34:37], v[152:155], v[144:147], v[34:37]
	v_mfma_f32_16x16x32_bf16 v[38:41], v[156:159], v[144:147], v[38:41]
	v_mfma_f32_16x16x32_bf16 v[42:45], v[160:163], v[144:147], v[42:45]
	v_mfma_f32_16x16x32_bf16 v[46:49], v[164:167], v[144:147], v[46:49]
	v_mfma_f32_16x16x32_bf16 v[50:53], v[152:155], v[148:151], v[50:53]
	v_mfma_f32_16x16x32_bf16 v[54:57], v[156:159], v[148:151], v[54:57]
	v_mfma_f32_16x16x32_bf16 v[58:61], v[160:163], v[148:151], v[58:61]
	v_mfma_f32_16x16x32_bf16 v[62:65], v[164:167], v[148:151], v[62:65]
	s_waitcnt vmcnt(12) lgkmcnt(0)
	s_barrier
	s_add_u32 s14, s4, 0x380
	s_addc_u32 s15, s5, 0
	v_mfma_f32_16x16x32_bf16 v[2:5], v[184:187], v[168:171], v[2:5]
	ds_read_b128 v[136:139], v224 offset:0
	s_add_u32 s22, s4, 0x10380
	s_addc_u32 s23, s5, 0
	v_mfma_f32_16x16x32_bf16 v[6:9], v[188:191], v[168:171], v[6:9]
	ds_read_b128 v[140:143], v224 offset:2048
	s_add_u32 s24, s6, 0x380
	s_addc_u32 s25, s7, 0
	v_mfma_f32_16x16x32_bf16 v[10:13], v[192:195], v[168:171], v[10:13]
	ds_read_b128 v[144:147], v224 offset:4096
	s_add_u32 s52, s6, 0x8380
	s_addc_u32 s53, s7, 0
	v_mfma_f32_16x16x32_bf16 v[14:17], v[196:199], v[168:171], v[14:17]
	ds_read_b128 v[148:151], v224 offset:6144
	s_add_u32 m0, s8, 0xc000
	v_mfma_f32_16x16x32_bf16 v[18:21], v[184:187], v[172:175], v[18:21]
	global_load_lds_dwordx4 v200, s[14:15]
	ds_read_b128 v[152:155], v232 offset:0
	s_add_u32 m0, s8, 0xc400
	v_mfma_f32_16x16x32_bf16 v[22:25], v[188:191], v[172:175], v[22:25]
	global_load_lds_dwordx4 v201, s[14:15]
	ds_read_b128 v[156:159], v232 offset:2048
	s_add_u32 m0, s8, 0xc800
	v_mfma_f32_16x16x32_bf16 v[26:29], v[192:195], v[172:175], v[26:29]
	global_load_lds_dwordx4 v202, s[14:15]
	ds_read_b128 v[160:163], v232 offset:4096
	s_add_u32 m0, s8, 0xcc00
	v_mfma_f32_16x16x32_bf16 v[30:33], v[196:199], v[172:175], v[30:33]
	global_load_lds_dwordx4 v203, s[14:15]
	ds_read_b128 v[164:167], v232 offset:6144
	s_add_u32 m0, s8, 0xd000
	v_mfma_f32_16x16x32_bf16 v[34:37], v[184:187], v[176:179], v[34:37]
	global_load_lds_dwordx4 v200, s[22:23]
	s_add_u32 m0, s8, 0xd400
	v_mfma_f32_16x16x32_bf16 v[38:41], v[188:191], v[176:179], v[38:41]
	global_load_lds_dwordx4 v201, s[22:23]
	s_add_u32 m0, s8, 0xd800
	v_mfma_f32_16x16x32_bf16 v[42:45], v[192:195], v[176:179], v[42:45]
	global_load_lds_dwordx4 v202, s[22:23]
	s_add_u32 m0, s8, 0xdc00
	v_mfma_f32_16x16x32_bf16 v[46:49], v[196:199], v[176:179], v[46:49]
	global_load_lds_dwordx4 v203, s[22:23]
	s_add_u32 m0, s9, 0xc000
	v_mfma_f32_16x16x32_bf16 v[50:53], v[184:187], v[180:183], v[50:53]
	global_load_lds_dwordx4 v204, s[24:25]
	s_add_u32 m0, s9, 0xc400
	v_mfma_f32_16x16x32_bf16 v[54:57], v[188:191], v[180:183], v[54:57]
	global_load_lds_dwordx4 v205, s[24:25]
	s_add_u32 m0, s9, 0xc800
	v_mfma_f32_16x16x32_bf16 v[58:61], v[192:195], v[180:183], v[58:61]
	global_load_lds_dwordx4 v204, s[52:53]
	s_add_u32 m0, s9, 0xcc00
	v_mfma_f32_16x16x32_bf16 v[62:65], v[196:199], v[180:183], v[62:65]
	global_load_lds_dwordx4 v205, s[52:53]
	s_waitcnt lgkmcnt(0)
	v_mfma_f32_16x16x32_bf16 v[2:5], v[152:155], v[136:139], v[2:5]
	ds_read_b128 v[168:171], v229 offset:0
	v_mfma_f32_16x16x32_bf16 v[6:9], v[156:159], v[136:139], v[6:9]
	ds_read_b128 v[172:175], v229 offset:2048
	v_mfma_f32_16x16x32_bf16 v[10:13], v[160:163], v[136:139], v[10:13]
	ds_read_b128 v[176:179], v229 offset:4096
	v_mfma_f32_16x16x32_bf16 v[14:17], v[164:167], v[136:139], v[14:17]
	ds_read_b128 v[180:183], v229 offset:6144
	v_mfma_f32_16x16x32_bf16 v[18:21], v[152:155], v[140:143], v[18:21]
	ds_read_b128 v[184:187], v235 offset:0
	v_mfma_f32_16x16x32_bf16 v[22:25], v[156:159], v[140:143], v[22:25]
	ds_read_b128 v[188:191], v235 offset:2048
	v_mfma_f32_16x16x32_bf16 v[26:29], v[160:163], v[140:143], v[26:29]
	ds_read_b128 v[192:195], v235 offset:4096
	v_mfma_f32_16x16x32_bf16 v[30:33], v[164:167], v[140:143], v[30:33]
	ds_read_b128 v[196:199], v235 offset:6144
	v_mfma_f32_16x16x32_bf16 v[34:37], v[152:155], v[144:147], v[34:37]
	v_mfma_f32_16x16x32_bf16 v[38:41], v[156:159], v[144:147], v[38:41]
	v_mfma_f32_16x16x32_bf16 v[42:45], v[160:163], v[144:147], v[42:45]
	v_mfma_f32_16x16x32_bf16 v[46:49], v[164:167], v[144:147], v[46:49]
	v_mfma_f32_16x16x32_bf16 v[50:53], v[152:155], v[148:151], v[50:53]
	v_mfma_f32_16x16x32_bf16 v[54:57], v[156:159], v[148:151], v[54:57]
	v_mfma_f32_16x16x32_bf16 v[58:61], v[160:163], v[148:151], v[58:61]
	v_mfma_f32_16x16x32_bf16 v[62:65], v[164:167], v[148:151], v[62:65]
	s_waitcnt vmcnt(12) lgkmcnt(0)
	s_barrier
	s_add_u32 s14, s4, 0x400
	s_addc_u32 s15, s5, 0
	v_mfma_f32_16x16x32_bf16 v[2:5], v[184:187], v[168:171], v[2:5]
	ds_read_b128 v[136:139], v218 offset:0
	s_add_u32 s22, s4, 0x10400
	s_addc_u32 s23, s5, 0
	v_mfma_f32_16x16x32_bf16 v[6:9], v[188:191], v[168:171], v[6:9]
	ds_read_b128 v[140:143], v218 offset:2048
	s_add_u32 s24, s6, 0x400
	s_addc_u32 s25, s7, 0
	v_mfma_f32_16x16x32_bf16 v[10:13], v[192:195], v[168:171], v[10:13]
	ds_read_b128 v[144:147], v218 offset:4096
	s_add_u32 s52, s6, 0x8400
	s_addc_u32 s53, s7, 0
	v_mfma_f32_16x16x32_bf16 v[14:17], v[196:199], v[168:171], v[14:17]
	ds_read_b128 v[148:151], v218 offset:6144
	s_add_u32 m0, s8, 0x18000
	v_mfma_f32_16x16x32_bf16 v[18:21], v[184:187], v[172:175], v[18:21]
	global_load_lds_dwordx4 v200, s[14:15]
	ds_read_b128 v[152:155], v230 offset:0
	s_add_u32 m0, s8, 0x18400
	v_mfma_f32_16x16x32_bf16 v[22:25], v[188:191], v[172:175], v[22:25]
	global_load_lds_dwordx4 v201, s[14:15]
	ds_read_b128 v[156:159], v230 offset:2048
	s_add_u32 m0, s8, 0x18800
	v_mfma_f32_16x16x32_bf16 v[26:29], v[192:195], v[172:175], v[26:29]
	global_load_lds_dwordx4 v202, s[14:15]
	ds_read_b128 v[160:163], v230 offset:4096
	s_add_u32 m0, s8, 0x18c00
	v_mfma_f32_16x16x32_bf16 v[30:33], v[196:199], v[172:175], v[30:33]
	global_load_lds_dwordx4 v203, s[14:15]
	ds_read_b128 v[164:167], v230 offset:6144
	s_add_u32 m0, s8, 0x19000
	v_mfma_f32_16x16x32_bf16 v[34:37], v[184:187], v[176:179], v[34:37]
	global_load_lds_dwordx4 v200, s[22:23]
	s_add_u32 m0, s8, 0x19400
	v_mfma_f32_16x16x32_bf16 v[38:41], v[188:191], v[176:179], v[38:41]
	global_load_lds_dwordx4 v201, s[22:23]
	s_add_u32 m0, s8, 0x19800
	v_mfma_f32_16x16x32_bf16 v[42:45], v[192:195], v[176:179], v[42:45]
	global_load_lds_dwordx4 v202, s[22:23]
	s_add_u32 m0, s8, 0x19c00
	v_mfma_f32_16x16x32_bf16 v[46:49], v[196:199], v[176:179], v[46:49]
	global_load_lds_dwordx4 v203, s[22:23]
	s_add_u32 m0, s9, 0x18000
	v_mfma_f32_16x16x32_bf16 v[50:53], v[184:187], v[180:183], v[50:53]
	global_load_lds_dwordx4 v204, s[24:25]
	s_add_u32 m0, s9, 0x18400
	v_mfma_f32_16x16x32_bf16 v[54:57], v[188:191], v[180:183], v[54:57]
	global_load_lds_dwordx4 v205, s[24:25]
	s_add_u32 m0, s9, 0x18800
	v_mfma_f32_16x16x32_bf16 v[58:61], v[192:195], v[180:183], v[58:61]
	global_load_lds_dwordx4 v204, s[52:53]
	s_add_u32 m0, s9, 0x18c00
	v_mfma_f32_16x16x32_bf16 v[62:65], v[196:199], v[180:183], v[62:65]
	global_load_lds_dwordx4 v205, s[52:53]
	s_waitcnt lgkmcnt(0)
	v_mfma_f32_16x16x32_bf16 v[2:5], v[152:155], v[136:139], v[2:5]
	ds_read_b128 v[168:171], v225 offset:0
	v_mfma_f32_16x16x32_bf16 v[6:9], v[156:159], v[136:139], v[6:9]
	ds_read_b128 v[172:175], v225 offset:2048
	v_mfma_f32_16x16x32_bf16 v[10:13], v[160:163], v[136:139], v[10:13]
	ds_read_b128 v[176:179], v225 offset:4096
	v_mfma_f32_16x16x32_bf16 v[14:17], v[164:167], v[136:139], v[14:17]
	ds_read_b128 v[180:183], v225 offset:6144
	v_mfma_f32_16x16x32_bf16 v[18:21], v[152:155], v[140:143], v[18:21]
	ds_read_b128 v[184:187], v233 offset:0
	v_mfma_f32_16x16x32_bf16 v[22:25], v[156:159], v[140:143], v[22:25]
	ds_read_b128 v[188:191], v233 offset:2048
	v_mfma_f32_16x16x32_bf16 v[26:29], v[160:163], v[140:143], v[26:29]
	ds_read_b128 v[192:195], v233 offset:4096
	v_mfma_f32_16x16x32_bf16 v[30:33], v[164:167], v[140:143], v[30:33]
	ds_read_b128 v[196:199], v233 offset:6144
	v_mfma_f32_16x16x32_bf16 v[34:37], v[152:155], v[144:147], v[34:37]
	v_mfma_f32_16x16x32_bf16 v[38:41], v[156:159], v[144:147], v[38:41]
	v_mfma_f32_16x16x32_bf16 v[42:45], v[160:163], v[144:147], v[42:45]
	v_mfma_f32_16x16x32_bf16 v[46:49], v[164:167], v[144:147], v[46:49]
	v_mfma_f32_16x16x32_bf16 v[50:53], v[152:155], v[148:151], v[50:53]
	v_mfma_f32_16x16x32_bf16 v[54:57], v[156:159], v[148:151], v[54:57]
	v_mfma_f32_16x16x32_bf16 v[58:61], v[160:163], v[148:151], v[58:61]
	v_mfma_f32_16x16x32_bf16 v[62:65], v[164:167], v[148:151], v[62:65]
	s_waitcnt vmcnt(12) lgkmcnt(0)
	s_barrier
	s_add_u32 s14, s4, 0x480
	s_addc_u32 s15, s5, 0
	v_mfma_f32_16x16x32_bf16 v[2:5], v[184:187], v[168:171], v[2:5]
	ds_read_b128 v[136:139], v219 offset:0
	s_add_u32 s22, s4, 0x10480
	s_addc_u32 s23, s5, 0
	v_mfma_f32_16x16x32_bf16 v[6:9], v[188:191], v[168:171], v[6:9]
	ds_read_b128 v[140:143], v219 offset:2048
	s_add_u32 s24, s6, 0x480
	s_addc_u32 s25, s7, 0
	v_mfma_f32_16x16x32_bf16 v[10:13], v[192:195], v[168:171], v[10:13]
	ds_read_b128 v[144:147], v219 offset:4096
	s_add_u32 s52, s6, 0x8480
	s_addc_u32 s53, s7, 0
	v_mfma_f32_16x16x32_bf16 v[14:17], v[196:199], v[168:171], v[14:17]
	ds_read_b128 v[148:151], v219 offset:6144
	s_mov_b32 m0, s8
	v_mfma_f32_16x16x32_bf16 v[18:21], v[184:187], v[172:175], v[18:21]
	global_load_lds_dwordx4 v200, s[14:15]
	ds_read_b128 v[152:155], v231 offset:0
	s_add_u32 m0, s8, 0x400
	v_mfma_f32_16x16x32_bf16 v[22:25], v[188:191], v[172:175], v[22:25]
	global_load_lds_dwordx4 v201, s[14:15]
	ds_read_b128 v[156:159], v231 offset:2048
	s_add_u32 m0, s8, 0x800
	v_mfma_f32_16x16x32_bf16 v[26:29], v[192:195], v[172:175], v[26:29]
	global_load_lds_dwordx4 v202, s[14:15]
	ds_read_b128 v[160:163], v231 offset:4096
	s_add_u32 m0, s8, 0xc00
	v_mfma_f32_16x16x32_bf16 v[30:33], v[196:199], v[172:175], v[30:33]
	global_load_lds_dwordx4 v203, s[14:15]
	ds_read_b128 v[164:167], v231 offset:6144
	s_add_u32 m0, s8, 0x1000
	v_mfma_f32_16x16x32_bf16 v[34:37], v[184:187], v[176:179], v[34:37]
	global_load_lds_dwordx4 v200, s[22:23]
	s_add_u32 m0, s8, 0x1400
	v_mfma_f32_16x16x32_bf16 v[38:41], v[188:191], v[176:179], v[38:41]
	global_load_lds_dwordx4 v201, s[22:23]
	s_add_u32 m0, s8, 0x1800
	v_mfma_f32_16x16x32_bf16 v[42:45], v[192:195], v[176:179], v[42:45]
	global_load_lds_dwordx4 v202, s[22:23]
	s_add_u32 m0, s8, 0x1c00
	v_mfma_f32_16x16x32_bf16 v[46:49], v[196:199], v[176:179], v[46:49]
	global_load_lds_dwordx4 v203, s[22:23]
	s_mov_b32 m0, s9
	v_mfma_f32_16x16x32_bf16 v[50:53], v[184:187], v[180:183], v[50:53]
	global_load_lds_dwordx4 v204, s[24:25]
	s_add_u32 m0, s9, 0x400
	v_mfma_f32_16x16x32_bf16 v[54:57], v[188:191], v[180:183], v[54:57]
	global_load_lds_dwordx4 v205, s[24:25]
	s_add_u32 m0, s9, 0x800
	v_mfma_f32_16x16x32_bf16 v[58:61], v[192:195], v[180:183], v[58:61]
	global_load_lds_dwordx4 v204, s[52:53]
	s_add_u32 m0, s9, 0xc00
	v_mfma_f32_16x16x32_bf16 v[62:65], v[196:199], v[180:183], v[62:65]
	global_load_lds_dwordx4 v205, s[52:53]
	s_waitcnt lgkmcnt(0)
	v_mfma_f32_16x16x32_bf16 v[2:5], v[152:155], v[136:139], v[2:5]
	ds_read_b128 v[168:171], v228 offset:0
	v_mfma_f32_16x16x32_bf16 v[6:9], v[156:159], v[136:139], v[6:9]
	ds_read_b128 v[172:175], v228 offset:2048
	v_mfma_f32_16x16x32_bf16 v[10:13], v[160:163], v[136:139], v[10:13]
	ds_read_b128 v[176:179], v228 offset:4096
	v_mfma_f32_16x16x32_bf16 v[14:17], v[164:167], v[136:139], v[14:17]
	ds_read_b128 v[180:183], v228 offset:6144
	v_mfma_f32_16x16x32_bf16 v[18:21], v[152:155], v[140:143], v[18:21]
	ds_read_b128 v[184:187], v234 offset:0
	v_mfma_f32_16x16x32_bf16 v[22:25], v[156:159], v[140:143], v[22:25]
	ds_read_b128 v[188:191], v234 offset:2048
	v_mfma_f32_16x16x32_bf16 v[26:29], v[160:163], v[140:143], v[26:29]
	ds_read_b128 v[192:195], v234 offset:4096
	v_mfma_f32_16x16x32_bf16 v[30:33], v[164:167], v[140:143], v[30:33]
	ds_read_b128 v[196:199], v234 offset:6144
	v_mfma_f32_16x16x32_bf16 v[34:37], v[152:155], v[144:147], v[34:37]
	v_mfma_f32_16x16x32_bf16 v[38:41], v[156:159], v[144:147], v[38:41]
	v_mfma_f32_16x16x32_bf16 v[42:45], v[160:163], v[144:147], v[42:45]
	v_mfma_f32_16x16x32_bf16 v[46:49], v[164:167], v[144:147], v[46:49]
	v_mfma_f32_16x16x32_bf16 v[50:53], v[152:155], v[148:151], v[50:53]
	v_mfma_f32_16x16x32_bf16 v[54:57], v[156:159], v[148:151], v[54:57]
	v_mfma_f32_16x16x32_bf16 v[58:61], v[160:163], v[148:151], v[58:61]
	v_mfma_f32_16x16x32_bf16 v[62:65], v[164:167], v[148:151], v[62:65]
	s_waitcnt vmcnt(12) lgkmcnt(0)
	s_barrier
	s_add_u32 s14, s4, 0x500
	s_addc_u32 s15, s5, 0
	v_mfma_f32_16x16x32_bf16 v[2:5], v[184:187], v[168:171], v[2:5]
	ds_read_b128 v[136:139], v224 offset:0
	s_add_u32 s22, s4, 0x10500
	s_addc_u32 s23, s5, 0
	v_mfma_f32_16x16x32_bf16 v[6:9], v[188:191], v[168:171], v[6:9]
	ds_read_b128 v[140:143], v224 offset:2048
	s_add_u32 s24, s6, 0x500
	s_addc_u32 s25, s7, 0
	v_mfma_f32_16x16x32_bf16 v[10:13], v[192:195], v[168:171], v[10:13]
	ds_read_b128 v[144:147], v224 offset:4096
	s_add_u32 s52, s6, 0x8500
	s_addc_u32 s53, s7, 0
	v_mfma_f32_16x16x32_bf16 v[14:17], v[196:199], v[168:171], v[14:17]
	ds_read_b128 v[148:151], v224 offset:6144
	s_add_u32 m0, s8, 0xc000
	v_mfma_f32_16x16x32_bf16 v[18:21], v[184:187], v[172:175], v[18:21]
	global_load_lds_dwordx4 v200, s[14:15]
	ds_read_b128 v[152:155], v232 offset:0
	s_add_u32 m0, s8, 0xc400
	v_mfma_f32_16x16x32_bf16 v[22:25], v[188:191], v[172:175], v[22:25]
	global_load_lds_dwordx4 v201, s[14:15]
	ds_read_b128 v[156:159], v232 offset:2048
	s_add_u32 m0, s8, 0xc800
	v_mfma_f32_16x16x32_bf16 v[26:29], v[192:195], v[172:175], v[26:29]
	global_load_lds_dwordx4 v202, s[14:15]
	ds_read_b128 v[160:163], v232 offset:4096
	s_add_u32 m0, s8, 0xcc00
	v_mfma_f32_16x16x32_bf16 v[30:33], v[196:199], v[172:175], v[30:33]
	global_load_lds_dwordx4 v203, s[14:15]
	ds_read_b128 v[164:167], v232 offset:6144
	s_add_u32 m0, s8, 0xd000
	v_mfma_f32_16x16x32_bf16 v[34:37], v[184:187], v[176:179], v[34:37]
	global_load_lds_dwordx4 v200, s[22:23]
	s_add_u32 m0, s8, 0xd400
	v_mfma_f32_16x16x32_bf16 v[38:41], v[188:191], v[176:179], v[38:41]
	global_load_lds_dwordx4 v201, s[22:23]
	s_add_u32 m0, s8, 0xd800
	v_mfma_f32_16x16x32_bf16 v[42:45], v[192:195], v[176:179], v[42:45]
	global_load_lds_dwordx4 v202, s[22:23]
	s_add_u32 m0, s8, 0xdc00
	v_mfma_f32_16x16x32_bf16 v[46:49], v[196:199], v[176:179], v[46:49]
	global_load_lds_dwordx4 v203, s[22:23]
	s_add_u32 m0, s9, 0xc000
	v_mfma_f32_16x16x32_bf16 v[50:53], v[184:187], v[180:183], v[50:53]
	global_load_lds_dwordx4 v204, s[24:25]
	s_add_u32 m0, s9, 0xc400
	v_mfma_f32_16x16x32_bf16 v[54:57], v[188:191], v[180:183], v[54:57]
	global_load_lds_dwordx4 v205, s[24:25]
	s_add_u32 m0, s9, 0xc800
	v_mfma_f32_16x16x32_bf16 v[58:61], v[192:195], v[180:183], v[58:61]
	global_load_lds_dwordx4 v204, s[52:53]
	s_add_u32 m0, s9, 0xcc00
	v_mfma_f32_16x16x32_bf16 v[62:65], v[196:199], v[180:183], v[62:65]
	global_load_lds_dwordx4 v205, s[52:53]
	s_waitcnt lgkmcnt(0)
	v_mfma_f32_16x16x32_bf16 v[2:5], v[152:155], v[136:139], v[2:5]
	ds_read_b128 v[168:171], v229 offset:0
	v_mfma_f32_16x16x32_bf16 v[6:9], v[156:159], v[136:139], v[6:9]
	ds_read_b128 v[172:175], v229 offset:2048
	v_mfma_f32_16x16x32_bf16 v[10:13], v[160:163], v[136:139], v[10:13]
	ds_read_b128 v[176:179], v229 offset:4096
	v_mfma_f32_16x16x32_bf16 v[14:17], v[164:167], v[136:139], v[14:17]
	ds_read_b128 v[180:183], v229 offset:6144
	v_mfma_f32_16x16x32_bf16 v[18:21], v[152:155], v[140:143], v[18:21]
	ds_read_b128 v[184:187], v235 offset:0
	v_mfma_f32_16x16x32_bf16 v[22:25], v[156:159], v[140:143], v[22:25]
	ds_read_b128 v[188:191], v235 offset:2048
	v_mfma_f32_16x16x32_bf16 v[26:29], v[160:163], v[140:143], v[26:29]
	ds_read_b128 v[192:195], v235 offset:4096
	v_mfma_f32_16x16x32_bf16 v[30:33], v[164:167], v[140:143], v[30:33]
	ds_read_b128 v[196:199], v235 offset:6144
	v_mfma_f32_16x16x32_bf16 v[34:37], v[152:155], v[144:147], v[34:37]
	v_mfma_f32_16x16x32_bf16 v[38:41], v[156:159], v[144:147], v[38:41]
	v_mfma_f32_16x16x32_bf16 v[42:45], v[160:163], v[144:147], v[42:45]
	v_mfma_f32_16x16x32_bf16 v[46:49], v[164:167], v[144:147], v[46:49]
	v_mfma_f32_16x16x32_bf16 v[50:53], v[152:155], v[148:151], v[50:53]
	v_mfma_f32_16x16x32_bf16 v[54:57], v[156:159], v[148:151], v[54:57]
	v_mfma_f32_16x16x32_bf16 v[58:61], v[160:163], v[148:151], v[58:61]
	v_mfma_f32_16x16x32_bf16 v[62:65], v[164:167], v[148:151], v[62:65]
	s_waitcnt vmcnt(12) lgkmcnt(0)
	s_barrier
	v_mfma_f32_16x16x32_bf16 v[2:5], v[184:187], v[168:171], v[2:5]
	ds_read_b128 v[136:139], v218 offset:0
	v_mfma_f32_16x16x32_bf16 v[6:9], v[188:191], v[168:171], v[6:9]
	ds_read_b128 v[140:143], v218 offset:2048
	v_mfma_f32_16x16x32_bf16 v[10:13], v[192:195], v[168:171], v[10:13]
	ds_read_b128 v[144:147], v218 offset:4096
	v_mfma_f32_16x16x32_bf16 v[14:17], v[196:199], v[168:171], v[14:17]
	ds_read_b128 v[148:151], v218 offset:6144
	v_mfma_f32_16x16x32_bf16 v[18:21], v[184:187], v[172:175], v[18:21]
	ds_read_b128 v[152:155], v230 offset:0
	v_mfma_f32_16x16x32_bf16 v[22:25], v[188:191], v[172:175], v[22:25]
	ds_read_b128 v[156:159], v230 offset:2048
	v_mfma_f32_16x16x32_bf16 v[26:29], v[192:195], v[172:175], v[26:29]
	ds_read_b128 v[160:163], v230 offset:4096
	v_mfma_f32_16x16x32_bf16 v[30:33], v[196:199], v[172:175], v[30:33]
	ds_read_b128 v[164:167], v230 offset:6144
	v_mfma_f32_16x16x32_bf16 v[34:37], v[184:187], v[176:179], v[34:37]
	v_mfma_f32_16x16x32_bf16 v[38:41], v[188:191], v[176:179], v[38:41]
	v_mfma_f32_16x16x32_bf16 v[42:45], v[192:195], v[176:179], v[42:45]
	v_mfma_f32_16x16x32_bf16 v[46:49], v[196:199], v[176:179], v[46:49]
	v_mfma_f32_16x16x32_bf16 v[50:53], v[184:187], v[180:183], v[50:53]
	v_mfma_f32_16x16x32_bf16 v[54:57], v[188:191], v[180:183], v[54:57]
	v_mfma_f32_16x16x32_bf16 v[58:61], v[192:195], v[180:183], v[58:61]
	v_mfma_f32_16x16x32_bf16 v[62:65], v[196:199], v[180:183], v[62:65]
	s_waitcnt lgkmcnt(0)
	v_mfma_f32_16x16x32_bf16 v[2:5], v[152:155], v[136:139], v[2:5]
	ds_read_b128 v[168:171], v225 offset:0
	v_mfma_f32_16x16x32_bf16 v[6:9], v[156:159], v[136:139], v[6:9]
	ds_read_b128 v[172:175], v225 offset:2048
	v_mfma_f32_16x16x32_bf16 v[10:13], v[160:163], v[136:139], v[10:13]
	ds_read_b128 v[176:179], v225 offset:4096
	v_mfma_f32_16x16x32_bf16 v[14:17], v[164:167], v[136:139], v[14:17]
	ds_read_b128 v[180:183], v225 offset:6144
	v_mfma_f32_16x16x32_bf16 v[18:21], v[152:155], v[140:143], v[18:21]
	ds_read_b128 v[184:187], v233 offset:0
	v_mfma_f32_16x16x32_bf16 v[22:25], v[156:159], v[140:143], v[22:25]
	ds_read_b128 v[188:191], v233 offset:2048
	v_mfma_f32_16x16x32_bf16 v[26:29], v[160:163], v[140:143], v[26:29]
	ds_read_b128 v[192:195], v233 offset:4096
	v_mfma_f32_16x16x32_bf16 v[30:33], v[164:167], v[140:143], v[30:33]
	ds_read_b128 v[196:199], v233 offset:6144
	v_mfma_f32_16x16x32_bf16 v[34:37], v[152:155], v[144:147], v[34:37]
	v_mfma_f32_16x16x32_bf16 v[38:41], v[156:159], v[144:147], v[38:41]
	v_mfma_f32_16x16x32_bf16 v[42:45], v[160:163], v[144:147], v[42:45]
	v_mfma_f32_16x16x32_bf16 v[46:49], v[164:167], v[144:147], v[46:49]
	v_mfma_f32_16x16x32_bf16 v[50:53], v[152:155], v[148:151], v[50:53]
	v_mfma_f32_16x16x32_bf16 v[54:57], v[156:159], v[148:151], v[54:57]
	v_mfma_f32_16x16x32_bf16 v[58:61], v[160:163], v[148:151], v[58:61]
	v_mfma_f32_16x16x32_bf16 v[62:65], v[164:167], v[148:151], v[62:65]
	s_waitcnt vmcnt(0) lgkmcnt(0)
	s_barrier
	v_mfma_f32_16x16x32_bf16 v[2:5], v[184:187], v[168:171], v[2:5]
	ds_read_b128 v[136:139], v219 offset:0
	v_mfma_f32_16x16x32_bf16 v[6:9], v[188:191], v[168:171], v[6:9]
	ds_read_b128 v[140:143], v219 offset:2048
	v_mfma_f32_16x16x32_bf16 v[10:13], v[192:195], v[168:171], v[10:13]
	ds_read_b128 v[144:147], v219 offset:4096
	v_mfma_f32_16x16x32_bf16 v[14:17], v[196:199], v[168:171], v[14:17]
	ds_read_b128 v[148:151], v219 offset:6144
	v_mfma_f32_16x16x32_bf16 v[18:21], v[184:187], v[172:175], v[18:21]
	ds_read_b128 v[152:155], v231 offset:0
	v_mfma_f32_16x16x32_bf16 v[22:25], v[188:191], v[172:175], v[22:25]
	ds_read_b128 v[156:159], v231 offset:2048
	v_mfma_f32_16x16x32_bf16 v[26:29], v[192:195], v[172:175], v[26:29]
	ds_read_b128 v[160:163], v231 offset:4096
	v_mfma_f32_16x16x32_bf16 v[30:33], v[196:199], v[172:175], v[30:33]
	ds_read_b128 v[164:167], v231 offset:6144
	v_mfma_f32_16x16x32_bf16 v[34:37], v[184:187], v[176:179], v[34:37]
	v_mfma_f32_16x16x32_bf16 v[38:41], v[188:191], v[176:179], v[38:41]
	v_mfma_f32_16x16x32_bf16 v[42:45], v[192:195], v[176:179], v[42:45]
	v_mfma_f32_16x16x32_bf16 v[46:49], v[196:199], v[176:179], v[46:49]
	v_mfma_f32_16x16x32_bf16 v[50:53], v[184:187], v[180:183], v[50:53]
	v_mfma_f32_16x16x32_bf16 v[54:57], v[188:191], v[180:183], v[54:57]
	v_mfma_f32_16x16x32_bf16 v[58:61], v[192:195], v[180:183], v[58:61]
	v_mfma_f32_16x16x32_bf16 v[62:65], v[196:199], v[180:183], v[62:65]
	s_waitcnt lgkmcnt(0)
	v_mfma_f32_16x16x32_bf16 v[2:5], v[152:155], v[136:139], v[2:5]
	ds_read_b128 v[168:171], v228 offset:0
	v_mfma_f32_16x16x32_bf16 v[6:9], v[156:159], v[136:139], v[6:9]
	ds_read_b128 v[172:175], v228 offset:2048
	v_mfma_f32_16x16x32_bf16 v[10:13], v[160:163], v[136:139], v[10:13]
	ds_read_b128 v[176:179], v228 offset:4096
	v_mfma_f32_16x16x32_bf16 v[14:17], v[164:167], v[136:139], v[14:17]
	ds_read_b128 v[180:183], v228 offset:6144
	v_mfma_f32_16x16x32_bf16 v[18:21], v[152:155], v[140:143], v[18:21]
	ds_read_b128 v[184:187], v234 offset:0
	v_mfma_f32_16x16x32_bf16 v[22:25], v[156:159], v[140:143], v[22:25]
	ds_read_b128 v[188:191], v234 offset:2048
	v_mfma_f32_16x16x32_bf16 v[26:29], v[160:163], v[140:143], v[26:29]
	ds_read_b128 v[192:195], v234 offset:4096
	v_mfma_f32_16x16x32_bf16 v[30:33], v[164:167], v[140:143], v[30:33]
	ds_read_b128 v[196:199], v234 offset:6144
	v_mfma_f32_16x16x32_bf16 v[34:37], v[152:155], v[144:147], v[34:37]
	v_mfma_f32_16x16x32_bf16 v[38:41], v[156:159], v[144:147], v[38:41]
	v_mfma_f32_16x16x32_bf16 v[42:45], v[160:163], v[144:147], v[42:45]
	v_mfma_f32_16x16x32_bf16 v[46:49], v[164:167], v[144:147], v[46:49]
	v_mfma_f32_16x16x32_bf16 v[50:53], v[152:155], v[148:151], v[50:53]
	v_mfma_f32_16x16x32_bf16 v[54:57], v[156:159], v[148:151], v[54:57]
	v_mfma_f32_16x16x32_bf16 v[58:61], v[160:163], v[148:151], v[58:61]
	v_mfma_f32_16x16x32_bf16 v[62:65], v[164:167], v[148:151], v[62:65]
	s_waitcnt lgkmcnt(0)
	s_barrier
	v_mfma_f32_16x16x32_bf16 v[2:5], v[184:187], v[168:171], v[2:5]
	ds_read_b128 v[136:139], v224 offset:0
	v_mfma_f32_16x16x32_bf16 v[6:9], v[188:191], v[168:171], v[6:9]
	ds_read_b128 v[140:143], v224 offset:2048
	v_mfma_f32_16x16x32_bf16 v[10:13], v[192:195], v[168:171], v[10:13]
	ds_read_b128 v[144:147], v224 offset:4096
	v_mfma_f32_16x16x32_bf16 v[14:17], v[196:199], v[168:171], v[14:17]
	ds_read_b128 v[148:151], v224 offset:6144
	v_mfma_f32_16x16x32_bf16 v[18:21], v[184:187], v[172:175], v[18:21]
	ds_read_b128 v[152:155], v232 offset:0
	v_mfma_f32_16x16x32_bf16 v[22:25], v[188:191], v[172:175], v[22:25]
	ds_read_b128 v[156:159], v232 offset:2048
	v_mfma_f32_16x16x32_bf16 v[26:29], v[192:195], v[172:175], v[26:29]
	ds_read_b128 v[160:163], v232 offset:4096
	v_mfma_f32_16x16x32_bf16 v[30:33], v[196:199], v[172:175], v[30:33]
	ds_read_b128 v[164:167], v232 offset:6144
	v_mfma_f32_16x16x32_bf16 v[34:37], v[184:187], v[176:179], v[34:37]
	v_mfma_f32_16x16x32_bf16 v[38:41], v[188:191], v[176:179], v[38:41]
	v_mfma_f32_16x16x32_bf16 v[42:45], v[192:195], v[176:179], v[42:45]
	v_mfma_f32_16x16x32_bf16 v[46:49], v[196:199], v[176:179], v[46:49]
	v_mfma_f32_16x16x32_bf16 v[50:53], v[184:187], v[180:183], v[50:53]
	v_mfma_f32_16x16x32_bf16 v[54:57], v[188:191], v[180:183], v[54:57]
	v_mfma_f32_16x16x32_bf16 v[58:61], v[192:195], v[180:183], v[58:61]
	v_mfma_f32_16x16x32_bf16 v[62:65], v[196:199], v[180:183], v[62:65]
	s_waitcnt lgkmcnt(0)
	v_mfma_f32_16x16x32_bf16 v[2:5], v[152:155], v[136:139], v[2:5]
	ds_read_b128 v[168:171], v229 offset:0
	v_mfma_f32_16x16x32_bf16 v[6:9], v[156:159], v[136:139], v[6:9]
	ds_read_b128 v[172:175], v229 offset:2048
	v_mfma_f32_16x16x32_bf16 v[10:13], v[160:163], v[136:139], v[10:13]
	ds_read_b128 v[176:179], v229 offset:4096
	v_mfma_f32_16x16x32_bf16 v[14:17], v[164:167], v[136:139], v[14:17]
	ds_read_b128 v[180:183], v229 offset:6144
	v_mfma_f32_16x16x32_bf16 v[18:21], v[152:155], v[140:143], v[18:21]
	ds_read_b128 v[184:187], v235 offset:0
	v_mfma_f32_16x16x32_bf16 v[22:25], v[156:159], v[140:143], v[22:25]
	ds_read_b128 v[188:191], v235 offset:2048
	v_mfma_f32_16x16x32_bf16 v[26:29], v[160:163], v[140:143], v[26:29]
	ds_read_b128 v[192:195], v235 offset:4096
	v_mfma_f32_16x16x32_bf16 v[30:33], v[164:167], v[140:143], v[30:33]
	ds_read_b128 v[196:199], v235 offset:6144
	v_mfma_f32_16x16x32_bf16 v[34:37], v[152:155], v[144:147], v[34:37]
	v_mfma_f32_16x16x32_bf16 v[38:41], v[156:159], v[144:147], v[38:41]
	v_mfma_f32_16x16x32_bf16 v[42:45], v[160:163], v[144:147], v[42:45]
	v_mfma_f32_16x16x32_bf16 v[46:49], v[164:167], v[144:147], v[46:49]
	v_mfma_f32_16x16x32_bf16 v[50:53], v[152:155], v[148:151], v[50:53]
	v_mfma_f32_16x16x32_bf16 v[54:57], v[156:159], v[148:151], v[54:57]
	v_mfma_f32_16x16x32_bf16 v[58:61], v[160:163], v[148:151], v[58:61]
	v_mfma_f32_16x16x32_bf16 v[62:65], v[164:167], v[148:151], v[62:65]
	s_waitcnt lgkmcnt(0)
	s_barrier
	v_mfma_f32_16x16x32_bf16 v[2:5], v[184:187], v[168:171], v[2:5]
	ds_read_b128 v[136:139], v218 offset:0
	v_mfma_f32_16x16x32_bf16 v[6:9], v[188:191], v[168:171], v[6:9]
	ds_read_b128 v[140:143], v218 offset:2048
	v_mfma_f32_16x16x32_bf16 v[10:13], v[192:195], v[168:171], v[10:13]
	ds_read_b128 v[144:147], v218 offset:4096
	v_mfma_f32_16x16x32_bf16 v[14:17], v[196:199], v[168:171], v[14:17]
	ds_read_b128 v[148:151], v218 offset:6144
	v_mfma_f32_16x16x32_bf16 v[18:21], v[184:187], v[172:175], v[18:21]
	ds_read_b128 v[152:155], v230 offset:0
	v_mfma_f32_16x16x32_bf16 v[22:25], v[188:191], v[172:175], v[22:25]
	ds_read_b128 v[156:159], v230 offset:2048
	v_mfma_f32_16x16x32_bf16 v[26:29], v[192:195], v[172:175], v[26:29]
	ds_read_b128 v[160:163], v230 offset:4096
	v_mfma_f32_16x16x32_bf16 v[30:33], v[196:199], v[172:175], v[30:33]
	ds_read_b128 v[164:167], v230 offset:6144
	v_mfma_f32_16x16x32_bf16 v[34:37], v[184:187], v[176:179], v[34:37]
	v_mfma_f32_16x16x32_bf16 v[38:41], v[188:191], v[176:179], v[38:41]
	v_mfma_f32_16x16x32_bf16 v[42:45], v[192:195], v[176:179], v[42:45]
	v_mfma_f32_16x16x32_bf16 v[46:49], v[196:199], v[176:179], v[46:49]
	v_mfma_f32_16x16x32_bf16 v[50:53], v[184:187], v[180:183], v[50:53]
	v_mfma_f32_16x16x32_bf16 v[54:57], v[188:191], v[180:183], v[54:57]
	v_mfma_f32_16x16x32_bf16 v[58:61], v[192:195], v[180:183], v[58:61]
	v_mfma_f32_16x16x32_bf16 v[62:65], v[196:199], v[180:183], v[62:65]
	s_waitcnt lgkmcnt(0)
	v_mfma_f32_16x16x32_bf16 v[2:5], v[152:155], v[136:139], v[2:5]
	ds_read_b128 v[168:171], v225 offset:0
	v_mfma_f32_16x16x32_bf16 v[6:9], v[156:159], v[136:139], v[6:9]
	ds_read_b128 v[172:175], v225 offset:2048
	v_mfma_f32_16x16x32_bf16 v[10:13], v[160:163], v[136:139], v[10:13]
	ds_read_b128 v[176:179], v225 offset:4096
	v_mfma_f32_16x16x32_bf16 v[14:17], v[164:167], v[136:139], v[14:17]
	ds_read_b128 v[180:183], v225 offset:6144
	v_mfma_f32_16x16x32_bf16 v[18:21], v[152:155], v[140:143], v[18:21]
	ds_read_b128 v[184:187], v233 offset:0
	v_mfma_f32_16x16x32_bf16 v[22:25], v[156:159], v[140:143], v[22:25]
	ds_read_b128 v[188:191], v233 offset:2048
	v_mfma_f32_16x16x32_bf16 v[26:29], v[160:163], v[140:143], v[26:29]
	ds_read_b128 v[192:195], v233 offset:4096
	v_mfma_f32_16x16x32_bf16 v[30:33], v[164:167], v[140:143], v[30:33]
	ds_read_b128 v[196:199], v233 offset:6144
	v_mfma_f32_16x16x32_bf16 v[34:37], v[152:155], v[144:147], v[34:37]
	v_mfma_f32_16x16x32_bf16 v[38:41], v[156:159], v[144:147], v[38:41]
	v_mfma_f32_16x16x32_bf16 v[42:45], v[160:163], v[144:147], v[42:45]
	v_mfma_f32_16x16x32_bf16 v[46:49], v[164:167], v[144:147], v[46:49]
	v_mfma_f32_16x16x32_bf16 v[50:53], v[152:155], v[148:151], v[50:53]
	v_mfma_f32_16x16x32_bf16 v[54:57], v[156:159], v[148:151], v[54:57]
	v_mfma_f32_16x16x32_bf16 v[58:61], v[160:163], v[148:151], v[58:61]
	v_mfma_f32_16x16x32_bf16 v[62:65], v[164:167], v[148:151], v[62:65]
	s_waitcnt lgkmcnt(0)
	s_barrier
	v_mfma_f32_16x16x32_bf16 v[2:5], v[184:187], v[168:171], v[2:5]
	ds_read_b128 v[136:139], v219 offset:0
	v_mfma_f32_16x16x32_bf16 v[6:9], v[188:191], v[168:171], v[6:9]
	ds_read_b128 v[140:143], v219 offset:2048
	v_mfma_f32_16x16x32_bf16 v[10:13], v[192:195], v[168:171], v[10:13]
	ds_read_b128 v[144:147], v219 offset:4096
	v_mfma_f32_16x16x32_bf16 v[14:17], v[196:199], v[168:171], v[14:17]
	ds_read_b128 v[148:151], v219 offset:6144
	v_mfma_f32_16x16x32_bf16 v[18:21], v[184:187], v[172:175], v[18:21]
	ds_read_b128 v[152:155], v231 offset:0
	v_mfma_f32_16x16x32_bf16 v[22:25], v[188:191], v[172:175], v[22:25]
	ds_read_b128 v[156:159], v231 offset:2048
	v_mfma_f32_16x16x32_bf16 v[26:29], v[192:195], v[172:175], v[26:29]
	ds_read_b128 v[160:163], v231 offset:4096
	v_mfma_f32_16x16x32_bf16 v[30:33], v[196:199], v[172:175], v[30:33]
	ds_read_b128 v[164:167], v231 offset:6144
	v_mfma_f32_16x16x32_bf16 v[34:37], v[184:187], v[176:179], v[34:37]
	v_mfma_f32_16x16x32_bf16 v[38:41], v[188:191], v[176:179], v[38:41]
	v_mfma_f32_16x16x32_bf16 v[42:45], v[192:195], v[176:179], v[42:45]
	v_mfma_f32_16x16x32_bf16 v[46:49], v[196:199], v[176:179], v[46:49]
	v_mfma_f32_16x16x32_bf16 v[50:53], v[184:187], v[180:183], v[50:53]
	v_mfma_f32_16x16x32_bf16 v[54:57], v[188:191], v[180:183], v[54:57]
	v_mfma_f32_16x16x32_bf16 v[58:61], v[192:195], v[180:183], v[58:61]
	v_mfma_f32_16x16x32_bf16 v[62:65], v[196:199], v[180:183], v[62:65]
	s_waitcnt lgkmcnt(0)
	v_mfma_f32_16x16x32_bf16 v[2:5], v[152:155], v[136:139], v[2:5]
	ds_read_b128 v[168:171], v228 offset:0
	v_mfma_f32_16x16x32_bf16 v[6:9], v[156:159], v[136:139], v[6:9]
	ds_read_b128 v[172:175], v228 offset:2048
	v_mfma_f32_16x16x32_bf16 v[10:13], v[160:163], v[136:139], v[10:13]
	ds_read_b128 v[176:179], v228 offset:4096
	v_mfma_f32_16x16x32_bf16 v[14:17], v[164:167], v[136:139], v[14:17]
	ds_read_b128 v[180:183], v228 offset:6144
	v_mfma_f32_16x16x32_bf16 v[18:21], v[152:155], v[140:143], v[18:21]
	ds_read_b128 v[184:187], v234 offset:0
	v_mfma_f32_16x16x32_bf16 v[22:25], v[156:159], v[140:143], v[22:25]
	ds_read_b128 v[188:191], v234 offset:2048
	v_mfma_f32_16x16x32_bf16 v[26:29], v[160:163], v[140:143], v[26:29]
	ds_read_b128 v[192:195], v234 offset:4096
	v_mfma_f32_16x16x32_bf16 v[30:33], v[164:167], v[140:143], v[30:33]
	ds_read_b128 v[196:199], v234 offset:6144
	v_mfma_f32_16x16x32_bf16 v[34:37], v[152:155], v[144:147], v[34:37]
	v_mfma_f32_16x16x32_bf16 v[38:41], v[156:159], v[144:147], v[38:41]
	v_mfma_f32_16x16x32_bf16 v[42:45], v[160:163], v[144:147], v[42:45]
	v_mfma_f32_16x16x32_bf16 v[46:49], v[164:167], v[144:147], v[46:49]
	v_mfma_f32_16x16x32_bf16 v[50:53], v[152:155], v[148:151], v[50:53]
	v_mfma_f32_16x16x32_bf16 v[54:57], v[156:159], v[148:151], v[54:57]
	v_mfma_f32_16x16x32_bf16 v[58:61], v[160:163], v[148:151], v[58:61]
	v_mfma_f32_16x16x32_bf16 v[62:65], v[164:167], v[148:151], v[62:65]
	s_waitcnt lgkmcnt(0)
	s_barrier
	v_mfma_f32_16x16x32_bf16 v[2:5], v[184:187], v[168:171], v[2:5]
	ds_read_b128 v[136:139], v224 offset:0
	v_mfma_f32_16x16x32_bf16 v[6:9], v[188:191], v[168:171], v[6:9]
	ds_read_b128 v[140:143], v224 offset:2048
	v_mfma_f32_16x16x32_bf16 v[10:13], v[192:195], v[168:171], v[10:13]
	ds_read_b128 v[144:147], v224 offset:4096
	v_mfma_f32_16x16x32_bf16 v[14:17], v[196:199], v[168:171], v[14:17]
	ds_read_b128 v[148:151], v224 offset:6144
	v_mfma_f32_16x16x32_bf16 v[18:21], v[184:187], v[172:175], v[18:21]
	ds_read_b128 v[152:155], v232 offset:0
	v_mfma_f32_16x16x32_bf16 v[22:25], v[188:191], v[172:175], v[22:25]
	ds_read_b128 v[156:159], v232 offset:2048
	v_mfma_f32_16x16x32_bf16 v[26:29], v[192:195], v[172:175], v[26:29]
	ds_read_b128 v[160:163], v232 offset:4096
	v_mfma_f32_16x16x32_bf16 v[30:33], v[196:199], v[172:175], v[30:33]
	ds_read_b128 v[164:167], v232 offset:6144
	v_mfma_f32_16x16x32_bf16 v[34:37], v[184:187], v[176:179], v[34:37]
	v_mfma_f32_16x16x32_bf16 v[38:41], v[188:191], v[176:179], v[38:41]
	v_mfma_f32_16x16x32_bf16 v[42:45], v[192:195], v[176:179], v[42:45]
	v_mfma_f32_16x16x32_bf16 v[46:49], v[196:199], v[176:179], v[46:49]
	v_mfma_f32_16x16x32_bf16 v[50:53], v[184:187], v[180:183], v[50:53]
	v_mfma_f32_16x16x32_bf16 v[54:57], v[188:191], v[180:183], v[54:57]
	v_mfma_f32_16x16x32_bf16 v[58:61], v[192:195], v[180:183], v[58:61]
	v_mfma_f32_16x16x32_bf16 v[62:65], v[196:199], v[180:183], v[62:65]
	s_waitcnt lgkmcnt(0)
	v_mfma_f32_16x16x32_bf16 v[2:5], v[152:155], v[136:139], v[2:5]
	ds_read_b128 v[168:171], v229 offset:0
	v_mfma_f32_16x16x32_bf16 v[6:9], v[156:159], v[136:139], v[6:9]
	ds_read_b128 v[172:175], v229 offset:2048
	v_mfma_f32_16x16x32_bf16 v[10:13], v[160:163], v[136:139], v[10:13]
	ds_read_b128 v[176:179], v229 offset:4096
	v_mfma_f32_16x16x32_bf16 v[14:17], v[164:167], v[136:139], v[14:17]
	ds_read_b128 v[180:183], v229 offset:6144
	v_mfma_f32_16x16x32_bf16 v[18:21], v[152:155], v[140:143], v[18:21]
	ds_read_b128 v[184:187], v235 offset:0
	v_mfma_f32_16x16x32_bf16 v[22:25], v[156:159], v[140:143], v[22:25]
	ds_read_b128 v[188:191], v235 offset:2048
	v_mfma_f32_16x16x32_bf16 v[26:29], v[160:163], v[140:143], v[26:29]
	ds_read_b128 v[192:195], v235 offset:4096
	v_mfma_f32_16x16x32_bf16 v[30:33], v[164:167], v[140:143], v[30:33]
	ds_read_b128 v[196:199], v235 offset:6144
	v_mfma_f32_16x16x32_bf16 v[34:37], v[152:155], v[144:147], v[34:37]
	v_mfma_f32_16x16x32_bf16 v[38:41], v[156:159], v[144:147], v[38:41]
	v_mfma_f32_16x16x32_bf16 v[42:45], v[160:163], v[144:147], v[42:45]
	v_mfma_f32_16x16x32_bf16 v[46:49], v[164:167], v[144:147], v[46:49]
	v_mfma_f32_16x16x32_bf16 v[50:53], v[152:155], v[148:151], v[50:53]
	v_mfma_f32_16x16x32_bf16 v[54:57], v[156:159], v[148:151], v[54:57]
	v_mfma_f32_16x16x32_bf16 v[58:61], v[160:163], v[148:151], v[58:61]
	v_mfma_f32_16x16x32_bf16 v[62:65], v[164:167], v[148:151], v[62:65]
	s_waitcnt lgkmcnt(0)
	s_barrier
	v_mfma_f32_16x16x32_bf16 v[2:5], v[184:187], v[168:171], v[2:5]
	ds_read_b128 v[136:139], v218 offset:0
	v_mfma_f32_16x16x32_bf16 v[6:9], v[188:191], v[168:171], v[6:9]
	ds_read_b128 v[140:143], v218 offset:2048
	v_mfma_f32_16x16x32_bf16 v[10:13], v[192:195], v[168:171], v[10:13]
	ds_read_b128 v[144:147], v218 offset:4096
	v_mfma_f32_16x16x32_bf16 v[14:17], v[196:199], v[168:171], v[14:17]
	ds_read_b128 v[148:151], v218 offset:6144
	v_mfma_f32_16x16x32_bf16 v[18:21], v[184:187], v[172:175], v[18:21]
	ds_read_b128 v[152:155], v230 offset:0
	v_mfma_f32_16x16x32_bf16 v[22:25], v[188:191], v[172:175], v[22:25]
	ds_read_b128 v[156:159], v230 offset:2048
	v_mfma_f32_16x16x32_bf16 v[26:29], v[192:195], v[172:175], v[26:29]
	ds_read_b128 v[160:163], v230 offset:4096
	v_mfma_f32_16x16x32_bf16 v[30:33], v[196:199], v[172:175], v[30:33]
	ds_read_b128 v[164:167], v230 offset:6144
	v_mfma_f32_16x16x32_bf16 v[34:37], v[184:187], v[176:179], v[34:37]
	v_mfma_f32_16x16x32_bf16 v[38:41], v[188:191], v[176:179], v[38:41]
	v_mfma_f32_16x16x32_bf16 v[42:45], v[192:195], v[176:179], v[42:45]
	v_mfma_f32_16x16x32_bf16 v[46:49], v[196:199], v[176:179], v[46:49]
	v_mfma_f32_16x16x32_bf16 v[50:53], v[184:187], v[180:183], v[50:53]
	v_mfma_f32_16x16x32_bf16 v[54:57], v[188:191], v[180:183], v[54:57]
	v_mfma_f32_16x16x32_bf16 v[58:61], v[192:195], v[180:183], v[58:61]
	v_mfma_f32_16x16x32_bf16 v[62:65], v[196:199], v[180:183], v[62:65]
	s_waitcnt lgkmcnt(0)
	v_mfma_f32_16x16x32_bf16 v[2:5], v[152:155], v[136:139], v[2:5]
	ds_read_b128 v[168:171], v225 offset:0
	v_mfma_f32_16x16x32_bf16 v[6:9], v[156:159], v[136:139], v[6:9]
	ds_read_b128 v[172:175], v225 offset:2048
	v_mfma_f32_16x16x32_bf16 v[10:13], v[160:163], v[136:139], v[10:13]
	ds_read_b128 v[176:179], v225 offset:4096
	v_mfma_f32_16x16x32_bf16 v[14:17], v[164:167], v[136:139], v[14:17]
	ds_read_b128 v[180:183], v225 offset:6144
	v_mfma_f32_16x16x32_bf16 v[18:21], v[152:155], v[140:143], v[18:21]
	ds_read_b128 v[184:187], v233 offset:0
	v_mfma_f32_16x16x32_bf16 v[22:25], v[156:159], v[140:143], v[22:25]
	ds_read_b128 v[188:191], v233 offset:2048
	v_mfma_f32_16x16x32_bf16 v[26:29], v[160:163], v[140:143], v[26:29]
	ds_read_b128 v[192:195], v233 offset:4096
	v_mfma_f32_16x16x32_bf16 v[30:33], v[164:167], v[140:143], v[30:33]
	ds_read_b128 v[196:199], v233 offset:6144
	v_mfma_f32_16x16x32_bf16 v[34:37], v[152:155], v[144:147], v[34:37]
	v_mfma_f32_16x16x32_bf16 v[38:41], v[156:159], v[144:147], v[38:41]
	v_mfma_f32_16x16x32_bf16 v[42:45], v[160:163], v[144:147], v[42:45]
	v_mfma_f32_16x16x32_bf16 v[46:49], v[164:167], v[144:147], v[46:49]
	v_mfma_f32_16x16x32_bf16 v[50:53], v[152:155], v[148:151], v[50:53]
	v_mfma_f32_16x16x32_bf16 v[54:57], v[156:159], v[148:151], v[54:57]
	v_mfma_f32_16x16x32_bf16 v[58:61], v[160:163], v[148:151], v[58:61]
	v_mfma_f32_16x16x32_bf16 v[62:65], v[164:167], v[148:151], v[62:65]
	s_waitcnt lgkmcnt(0)
	s_barrier
	v_mfma_f32_16x16x32_bf16 v[2:5], v[184:187], v[168:171], v[2:5]
	ds_read_b128 v[136:139], v219 offset:0
	v_mfma_f32_16x16x32_bf16 v[6:9], v[188:191], v[168:171], v[6:9]
	ds_read_b128 v[140:143], v219 offset:2048
	v_mfma_f32_16x16x32_bf16 v[10:13], v[192:195], v[168:171], v[10:13]
	ds_read_b128 v[144:147], v219 offset:4096
	v_mfma_f32_16x16x32_bf16 v[14:17], v[196:199], v[168:171], v[14:17]
	ds_read_b128 v[148:151], v219 offset:6144
	v_mfma_f32_16x16x32_bf16 v[18:21], v[184:187], v[172:175], v[18:21]
	ds_read_b128 v[152:155], v231 offset:0
	v_mfma_f32_16x16x32_bf16 v[22:25], v[188:191], v[172:175], v[22:25]
	ds_read_b128 v[156:159], v231 offset:2048
	v_mfma_f32_16x16x32_bf16 v[26:29], v[192:195], v[172:175], v[26:29]
	ds_read_b128 v[160:163], v231 offset:4096
	v_mfma_f32_16x16x32_bf16 v[30:33], v[196:199], v[172:175], v[30:33]
	ds_read_b128 v[164:167], v231 offset:6144
	v_mfma_f32_16x16x32_bf16 v[34:37], v[184:187], v[176:179], v[34:37]
	v_mfma_f32_16x16x32_bf16 v[38:41], v[188:191], v[176:179], v[38:41]
	v_mfma_f32_16x16x32_bf16 v[42:45], v[192:195], v[176:179], v[42:45]
	v_mfma_f32_16x16x32_bf16 v[46:49], v[196:199], v[176:179], v[46:49]
	v_mfma_f32_16x16x32_bf16 v[50:53], v[184:187], v[180:183], v[50:53]
	v_mfma_f32_16x16x32_bf16 v[54:57], v[188:191], v[180:183], v[54:57]
	v_mfma_f32_16x16x32_bf16 v[58:61], v[192:195], v[180:183], v[58:61]
	v_mfma_f32_16x16x32_bf16 v[62:65], v[196:199], v[180:183], v[62:65]
	s_waitcnt lgkmcnt(0)
	v_mfma_f32_16x16x32_bf16 v[66:69], v[152:155], v[136:139], 0
	ds_read_b128 v[168:171], v228 offset:0
	v_mfma_f32_16x16x32_bf16 v[70:73], v[156:159], v[136:139], 0
	ds_read_b128 v[172:175], v228 offset:2048
	v_mfma_f32_16x16x32_bf16 v[74:77], v[160:163], v[136:139], 0
	ds_read_b128 v[176:179], v228 offset:4096
	v_mfma_f32_16x16x32_bf16 v[78:81], v[164:167], v[136:139], 0
	ds_read_b128 v[180:183], v228 offset:6144
	v_mfma_f32_16x16x32_bf16 v[82:85], v[152:155], v[140:143], 0
	ds_read_b128 v[184:187], v234 offset:0
	v_mfma_f32_16x16x32_bf16 v[86:89], v[156:159], v[140:143], 0
	ds_read_b128 v[188:191], v234 offset:2048
	v_mfma_f32_16x16x32_bf16 v[90:93], v[160:163], v[140:143], 0
	ds_read_b128 v[192:195], v234 offset:4096
	v_mfma_f32_16x16x32_bf16 v[94:97], v[164:167], v[140:143], 0
	ds_read_b128 v[196:199], v234 offset:6144
	v_mfma_f32_16x16x32_bf16 v[98:101], v[152:155], v[144:147], 0
	v_mfma_f32_16x16x32_bf16 v[102:105], v[156:159], v[144:147], 0
	v_mfma_f32_16x16x32_bf16 v[106:109], v[160:163], v[144:147], 0
	v_mfma_f32_16x16x32_bf16 v[110:113], v[164:167], v[144:147], 0
	v_mfma_f32_16x16x32_bf16 v[114:117], v[152:155], v[148:151], 0
	v_mfma_f32_16x16x32_bf16 v[118:121], v[156:159], v[148:151], 0
	v_mfma_f32_16x16x32_bf16 v[122:125], v[160:163], v[148:151], 0
	v_mfma_f32_16x16x32_bf16 v[126:129], v[164:167], v[148:151], 0
	s_waitcnt lgkmcnt(0)
	s_barrier
	s_add_u32 s14, s4, 0x180
	s_addc_u32 s15, s5, 0
	v_mfma_f32_16x16x32_bf16 v[66:69], v[184:187], v[168:171], v[66:69]
	ds_read_b128 v[136:139], v224 offset:0
	s_add_u32 s22, s4, 0x10180
	s_addc_u32 s23, s5, 0
	v_mfma_f32_16x16x32_bf16 v[70:73], v[188:191], v[168:171], v[70:73]
	ds_read_b128 v[140:143], v224 offset:2048
	s_add_u32 s24, s6, 0x40180
	s_addc_u32 s25, s7, 0
	v_mfma_f32_16x16x32_bf16 v[74:77], v[192:195], v[168:171], v[74:77]
	ds_read_b128 v[144:147], v224 offset:4096
	s_add_u32 s52, s6, 0x48180
	s_addc_u32 s53, s7, 0
	v_mfma_f32_16x16x32_bf16 v[78:81], v[196:199], v[168:171], v[78:81]
	ds_read_b128 v[148:151], v224 offset:6144
	s_add_u32 m0, s8, 0xc000
	v_mfma_f32_16x16x32_bf16 v[82:85], v[184:187], v[172:175], v[82:85]
	global_load_lds_dwordx4 v200, s[14:15]
	ds_read_b128 v[152:155], v232 offset:0
	s_add_u32 m0, s8, 0xc400
	v_mfma_f32_16x16x32_bf16 v[86:89], v[188:191], v[172:175], v[86:89]
	global_load_lds_dwordx4 v201, s[14:15]
	ds_read_b128 v[156:159], v232 offset:2048
	s_add_u32 m0, s8, 0xc800
	v_mfma_f32_16x16x32_bf16 v[90:93], v[192:195], v[172:175], v[90:93]
	global_load_lds_dwordx4 v202, s[14:15]
	ds_read_b128 v[160:163], v232 offset:4096
	s_add_u32 m0, s8, 0xcc00
	v_mfma_f32_16x16x32_bf16 v[94:97], v[196:199], v[172:175], v[94:97]
	global_load_lds_dwordx4 v203, s[14:15]
	ds_read_b128 v[164:167], v232 offset:6144
	s_add_u32 m0, s8, 0xd000
	v_mfma_f32_16x16x32_bf16 v[98:101], v[184:187], v[176:179], v[98:101]
	global_load_lds_dwordx4 v200, s[22:23]
	s_add_u32 m0, s8, 0xd400
	v_mfma_f32_16x16x32_bf16 v[102:105], v[188:191], v[176:179], v[102:105]
	global_load_lds_dwordx4 v201, s[22:23]
	s_add_u32 m0, s8, 0xd800
	v_mfma_f32_16x16x32_bf16 v[106:109], v[192:195], v[176:179], v[106:109]
	global_load_lds_dwordx4 v202, s[22:23]
	s_add_u32 m0, s8, 0xdc00
	v_mfma_f32_16x16x32_bf16 v[110:113], v[196:199], v[176:179], v[110:113]
	global_load_lds_dwordx4 v203, s[22:23]
	s_add_u32 m0, s9, 0xc000
	v_mfma_f32_16x16x32_bf16 v[114:117], v[184:187], v[180:183], v[114:117]
	global_load_lds_dwordx4 v204, s[24:25]
	s_add_u32 m0, s9, 0xc400
	v_mfma_f32_16x16x32_bf16 v[118:121], v[188:191], v[180:183], v[118:121]
	global_load_lds_dwordx4 v205, s[24:25]
	s_add_u32 m0, s9, 0xc800
	v_mfma_f32_16x16x32_bf16 v[122:125], v[192:195], v[180:183], v[122:125]
	global_load_lds_dwordx4 v204, s[52:53]
	s_add_u32 m0, s9, 0xcc00
	v_mfma_f32_16x16x32_bf16 v[126:129], v[196:199], v[180:183], v[126:129]
	global_load_lds_dwordx4 v205, s[52:53]
	s_waitcnt lgkmcnt(0)
	v_mfma_f32_16x16x32_bf16 v[66:69], v[152:155], v[136:139], v[66:69]
	ds_read_b128 v[168:171], v229 offset:0
	v_mfma_f32_16x16x32_bf16 v[70:73], v[156:159], v[136:139], v[70:73]
	ds_read_b128 v[172:175], v229 offset:2048
	v_mfma_f32_16x16x32_bf16 v[74:77], v[160:163], v[136:139], v[74:77]
	ds_read_b128 v[176:179], v229 offset:4096
	v_mfma_f32_16x16x32_bf16 v[78:81], v[164:167], v[136:139], v[78:81]
	ds_read_b128 v[180:183], v229 offset:6144
	v_mfma_f32_16x16x32_bf16 v[82:85], v[152:155], v[140:143], v[82:85]
	ds_read_b128 v[184:187], v235 offset:0
	v_mfma_f32_16x16x32_bf16 v[86:89], v[156:159], v[140:143], v[86:89]
	ds_read_b128 v[188:191], v235 offset:2048
	v_mfma_f32_16x16x32_bf16 v[90:93], v[160:163], v[140:143], v[90:93]
	ds_read_b128 v[192:195], v235 offset:4096
	v_mfma_f32_16x16x32_bf16 v[94:97], v[164:167], v[140:143], v[94:97]
	ds_read_b128 v[196:199], v235 offset:6144
	v_mfma_f32_16x16x32_bf16 v[98:101], v[152:155], v[144:147], v[98:101]
	v_mfma_f32_16x16x32_bf16 v[102:105], v[156:159], v[144:147], v[102:105]
	v_mfma_f32_16x16x32_bf16 v[106:109], v[160:163], v[144:147], v[106:109]
	v_mfma_f32_16x16x32_bf16 v[110:113], v[164:167], v[144:147], v[110:113]
	v_mfma_f32_16x16x32_bf16 v[114:117], v[152:155], v[148:151], v[114:117]
	v_mfma_f32_16x16x32_bf16 v[118:121], v[156:159], v[148:151], v[118:121]
	v_mfma_f32_16x16x32_bf16 v[122:125], v[160:163], v[148:151], v[122:125]
	v_mfma_f32_16x16x32_bf16 v[126:129], v[164:167], v[148:151], v[126:129]
	s_waitcnt lgkmcnt(0)
	s_barrier
	s_add_u32 s14, s4, 0x200
	s_addc_u32 s15, s5, 0
	v_mfma_f32_16x16x32_bf16 v[66:69], v[184:187], v[168:171], v[66:69]
	ds_read_b128 v[136:139], v218 offset:0
	s_add_u32 s22, s4, 0x10200
	s_addc_u32 s23, s5, 0
	v_mfma_f32_16x16x32_bf16 v[70:73], v[188:191], v[168:171], v[70:73]
	ds_read_b128 v[140:143], v218 offset:2048
	s_add_u32 s24, s6, 0x40200
	s_addc_u32 s25, s7, 0
	v_mfma_f32_16x16x32_bf16 v[74:77], v[192:195], v[168:171], v[74:77]
	ds_read_b128 v[144:147], v218 offset:4096
	s_add_u32 s52, s6, 0x48200
	s_addc_u32 s53, s7, 0
	v_mfma_f32_16x16x32_bf16 v[78:81], v[196:199], v[168:171], v[78:81]
	ds_read_b128 v[148:151], v218 offset:6144
	s_add_u32 m0, s8, 0x18000
	v_mfma_f32_16x16x32_bf16 v[82:85], v[184:187], v[172:175], v[82:85]
	global_load_lds_dwordx4 v200, s[14:15]
	ds_read_b128 v[152:155], v230 offset:0
	s_add_u32 m0, s8, 0x18400
	v_mfma_f32_16x16x32_bf16 v[86:89], v[188:191], v[172:175], v[86:89]
	global_load_lds_dwordx4 v201, s[14:15]
	ds_read_b128 v[156:159], v230 offset:2048
	s_add_u32 m0, s8, 0x18800
	v_mfma_f32_16x16x32_bf16 v[90:93], v[192:195], v[172:175], v[90:93]
	global_load_lds_dwordx4 v202, s[14:15]
	ds_read_b128 v[160:163], v230 offset:4096
	s_add_u32 m0, s8, 0x18c00
	v_mfma_f32_16x16x32_bf16 v[94:97], v[196:199], v[172:175], v[94:97]
	global_load_lds_dwordx4 v203, s[14:15]
	ds_read_b128 v[164:167], v230 offset:6144
	s_add_u32 m0, s8, 0x19000
	v_mfma_f32_16x16x32_bf16 v[98:101], v[184:187], v[176:179], v[98:101]
	global_load_lds_dwordx4 v200, s[22:23]
	s_add_u32 m0, s8, 0x19400
	v_mfma_f32_16x16x32_bf16 v[102:105], v[188:191], v[176:179], v[102:105]
	global_load_lds_dwordx4 v201, s[22:23]
	s_add_u32 m0, s8, 0x19800
	v_mfma_f32_16x16x32_bf16 v[106:109], v[192:195], v[176:179], v[106:109]
	global_load_lds_dwordx4 v202, s[22:23]
	s_add_u32 m0, s8, 0x19c00
	v_mfma_f32_16x16x32_bf16 v[110:113], v[196:199], v[176:179], v[110:113]
	global_load_lds_dwordx4 v203, s[22:23]
	s_add_u32 m0, s9, 0x18000
	v_mfma_f32_16x16x32_bf16 v[114:117], v[184:187], v[180:183], v[114:117]
	global_load_lds_dwordx4 v204, s[24:25]
	s_add_u32 m0, s9, 0x18400
	v_mfma_f32_16x16x32_bf16 v[118:121], v[188:191], v[180:183], v[118:121]
	global_load_lds_dwordx4 v205, s[24:25]
	s_add_u32 m0, s9, 0x18800
	v_mfma_f32_16x16x32_bf16 v[122:125], v[192:195], v[180:183], v[122:125]
	global_load_lds_dwordx4 v204, s[52:53]
	s_add_u32 m0, s9, 0x18c00
	v_mfma_f32_16x16x32_bf16 v[126:129], v[196:199], v[180:183], v[126:129]
	global_load_lds_dwordx4 v205, s[52:53]
	s_waitcnt lgkmcnt(0)
	v_mfma_f32_16x16x32_bf16 v[66:69], v[152:155], v[136:139], v[66:69]
	ds_read_b128 v[168:171], v225 offset:0
	v_mfma_f32_16x16x32_bf16 v[70:73], v[156:159], v[136:139], v[70:73]
	ds_read_b128 v[172:175], v225 offset:2048
	v_mfma_f32_16x16x32_bf16 v[74:77], v[160:163], v[136:139], v[74:77]
	ds_read_b128 v[176:179], v225 offset:4096
	v_mfma_f32_16x16x32_bf16 v[78:81], v[164:167], v[136:139], v[78:81]
	ds_read_b128 v[180:183], v225 offset:6144
	v_mfma_f32_16x16x32_bf16 v[82:85], v[152:155], v[140:143], v[82:85]
	ds_read_b128 v[184:187], v233 offset:0
	v_mfma_f32_16x16x32_bf16 v[86:89], v[156:159], v[140:143], v[86:89]
	ds_read_b128 v[188:191], v233 offset:2048
	v_mfma_f32_16x16x32_bf16 v[90:93], v[160:163], v[140:143], v[90:93]
	ds_read_b128 v[192:195], v233 offset:4096
	v_mfma_f32_16x16x32_bf16 v[94:97], v[164:167], v[140:143], v[94:97]
	ds_read_b128 v[196:199], v233 offset:6144
	v_mfma_f32_16x16x32_bf16 v[98:101], v[152:155], v[144:147], v[98:101]
	v_mfma_f32_16x16x32_bf16 v[102:105], v[156:159], v[144:147], v[102:105]
	v_mfma_f32_16x16x32_bf16 v[106:109], v[160:163], v[144:147], v[106:109]
	v_mfma_f32_16x16x32_bf16 v[110:113], v[164:167], v[144:147], v[110:113]
	v_mfma_f32_16x16x32_bf16 v[114:117], v[152:155], v[148:151], v[114:117]
	v_mfma_f32_16x16x32_bf16 v[118:121], v[156:159], v[148:151], v[118:121]
	v_mfma_f32_16x16x32_bf16 v[122:125], v[160:163], v[148:151], v[122:125]
	v_mfma_f32_16x16x32_bf16 v[126:129], v[164:167], v[148:151], v[126:129]
	s_waitcnt vmcnt(12) lgkmcnt(0)
	s_barrier
	s_add_u32 s14, s4, 0x280
	s_addc_u32 s15, s5, 0
	v_mfma_f32_16x16x32_bf16 v[66:69], v[184:187], v[168:171], v[66:69]
	ds_read_b128 v[136:139], v219 offset:0
	s_add_u32 s22, s4, 0x10280
	s_addc_u32 s23, s5, 0
	v_mfma_f32_16x16x32_bf16 v[70:73], v[188:191], v[168:171], v[70:73]
	ds_read_b128 v[140:143], v219 offset:2048
	s_add_u32 s24, s6, 0x40280
	s_addc_u32 s25, s7, 0
	v_mfma_f32_16x16x32_bf16 v[74:77], v[192:195], v[168:171], v[74:77]
	ds_read_b128 v[144:147], v219 offset:4096
	s_add_u32 s52, s6, 0x48280
	s_addc_u32 s53, s7, 0
	v_mfma_f32_16x16x32_bf16 v[78:81], v[196:199], v[168:171], v[78:81]
	ds_read_b128 v[148:151], v219 offset:6144
	s_mov_b32 m0, s8
	v_mfma_f32_16x16x32_bf16 v[82:85], v[184:187], v[172:175], v[82:85]
	global_load_lds_dwordx4 v200, s[14:15]
	ds_read_b128 v[152:155], v231 offset:0
	s_add_u32 m0, s8, 0x400
	v_mfma_f32_16x16x32_bf16 v[86:89], v[188:191], v[172:175], v[86:89]
	global_load_lds_dwordx4 v201, s[14:15]
	ds_read_b128 v[156:159], v231 offset:2048
	s_add_u32 m0, s8, 0x800
	v_mfma_f32_16x16x32_bf16 v[90:93], v[192:195], v[172:175], v[90:93]
	global_load_lds_dwordx4 v202, s[14:15]
	ds_read_b128 v[160:163], v231 offset:4096
	s_add_u32 m0, s8, 0xc00
	v_mfma_f32_16x16x32_bf16 v[94:97], v[196:199], v[172:175], v[94:97]
	global_load_lds_dwordx4 v203, s[14:15]
	ds_read_b128 v[164:167], v231 offset:6144
	s_add_u32 m0, s8, 0x1000
	v_mfma_f32_16x16x32_bf16 v[98:101], v[184:187], v[176:179], v[98:101]
	global_load_lds_dwordx4 v200, s[22:23]
	s_add_u32 m0, s8, 0x1400
	v_mfma_f32_16x16x32_bf16 v[102:105], v[188:191], v[176:179], v[102:105]
	global_load_lds_dwordx4 v201, s[22:23]
	s_add_u32 m0, s8, 0x1800
	v_mfma_f32_16x16x32_bf16 v[106:109], v[192:195], v[176:179], v[106:109]
	global_load_lds_dwordx4 v202, s[22:23]
	s_add_u32 m0, s8, 0x1c00
	v_mfma_f32_16x16x32_bf16 v[110:113], v[196:199], v[176:179], v[110:113]
	global_load_lds_dwordx4 v203, s[22:23]
	s_mov_b32 m0, s9
	v_mfma_f32_16x16x32_bf16 v[114:117], v[184:187], v[180:183], v[114:117]
	global_load_lds_dwordx4 v204, s[24:25]
	s_add_u32 m0, s9, 0x400
	v_mfma_f32_16x16x32_bf16 v[118:121], v[188:191], v[180:183], v[118:121]
	global_load_lds_dwordx4 v205, s[24:25]
	s_add_u32 m0, s9, 0x800
	v_mfma_f32_16x16x32_bf16 v[122:125], v[192:195], v[180:183], v[122:125]
	global_load_lds_dwordx4 v204, s[52:53]
	s_add_u32 m0, s9, 0xc00
	v_mfma_f32_16x16x32_bf16 v[126:129], v[196:199], v[180:183], v[126:129]
	global_load_lds_dwordx4 v205, s[52:53]
	s_waitcnt lgkmcnt(0)
	v_mfma_f32_16x16x32_bf16 v[66:69], v[152:155], v[136:139], v[66:69]
	ds_read_b128 v[168:171], v228 offset:0
	v_mfma_f32_16x16x32_bf16 v[70:73], v[156:159], v[136:139], v[70:73]
	ds_read_b128 v[172:175], v228 offset:2048
	v_mfma_f32_16x16x32_bf16 v[74:77], v[160:163], v[136:139], v[74:77]
	ds_read_b128 v[176:179], v228 offset:4096
	v_mfma_f32_16x16x32_bf16 v[78:81], v[164:167], v[136:139], v[78:81]
	ds_read_b128 v[180:183], v228 offset:6144
	v_mfma_f32_16x16x32_bf16 v[82:85], v[152:155], v[140:143], v[82:85]
	ds_read_b128 v[184:187], v234 offset:0
	v_mfma_f32_16x16x32_bf16 v[86:89], v[156:159], v[140:143], v[86:89]
	ds_read_b128 v[188:191], v234 offset:2048
	v_mfma_f32_16x16x32_bf16 v[90:93], v[160:163], v[140:143], v[90:93]
	ds_read_b128 v[192:195], v234 offset:4096
	v_mfma_f32_16x16x32_bf16 v[94:97], v[164:167], v[140:143], v[94:97]
	ds_read_b128 v[196:199], v234 offset:6144
	v_mfma_f32_16x16x32_bf16 v[98:101], v[152:155], v[144:147], v[98:101]
	v_mfma_f32_16x16x32_bf16 v[102:105], v[156:159], v[144:147], v[102:105]
	v_mfma_f32_16x16x32_bf16 v[106:109], v[160:163], v[144:147], v[106:109]
	v_mfma_f32_16x16x32_bf16 v[110:113], v[164:167], v[144:147], v[110:113]
	v_mfma_f32_16x16x32_bf16 v[114:117], v[152:155], v[148:151], v[114:117]
	v_mfma_f32_16x16x32_bf16 v[118:121], v[156:159], v[148:151], v[118:121]
	v_mfma_f32_16x16x32_bf16 v[122:125], v[160:163], v[148:151], v[122:125]
	v_mfma_f32_16x16x32_bf16 v[126:129], v[164:167], v[148:151], v[126:129]
	s_waitcnt vmcnt(12) lgkmcnt(0)
	s_barrier
	s_add_u32 s14, s4, 0x300
	s_addc_u32 s15, s5, 0
	v_mfma_f32_16x16x32_bf16 v[66:69], v[184:187], v[168:171], v[66:69]
	ds_read_b128 v[136:139], v224 offset:0
	s_add_u32 s22, s4, 0x10300
	s_addc_u32 s23, s5, 0
	v_mfma_f32_16x16x32_bf16 v[70:73], v[188:191], v[168:171], v[70:73]
	ds_read_b128 v[140:143], v224 offset:2048
	s_add_u32 s24, s6, 0x40300
	s_addc_u32 s25, s7, 0
	v_mfma_f32_16x16x32_bf16 v[74:77], v[192:195], v[168:171], v[74:77]
	ds_read_b128 v[144:147], v224 offset:4096
	s_add_u32 s52, s6, 0x48300
	s_addc_u32 s53, s7, 0
	v_mfma_f32_16x16x32_bf16 v[78:81], v[196:199], v[168:171], v[78:81]
	ds_read_b128 v[148:151], v224 offset:6144
	s_add_u32 m0, s8, 0xc000
	v_mfma_f32_16x16x32_bf16 v[82:85], v[184:187], v[172:175], v[82:85]
	global_load_lds_dwordx4 v200, s[14:15]
	ds_read_b128 v[152:155], v232 offset:0
	s_add_u32 m0, s8, 0xc400
	v_mfma_f32_16x16x32_bf16 v[86:89], v[188:191], v[172:175], v[86:89]
	global_load_lds_dwordx4 v201, s[14:15]
	ds_read_b128 v[156:159], v232 offset:2048
	s_add_u32 m0, s8, 0xc800
	v_mfma_f32_16x16x32_bf16 v[90:93], v[192:195], v[172:175], v[90:93]
	global_load_lds_dwordx4 v202, s[14:15]
	ds_read_b128 v[160:163], v232 offset:4096
	s_add_u32 m0, s8, 0xcc00
	v_mfma_f32_16x16x32_bf16 v[94:97], v[196:199], v[172:175], v[94:97]
	global_load_lds_dwordx4 v203, s[14:15]
	ds_read_b128 v[164:167], v232 offset:6144
	s_add_u32 m0, s8, 0xd000
	v_mfma_f32_16x16x32_bf16 v[98:101], v[184:187], v[176:179], v[98:101]
	global_load_lds_dwordx4 v200, s[22:23]
	s_add_u32 m0, s8, 0xd400
	v_mfma_f32_16x16x32_bf16 v[102:105], v[188:191], v[176:179], v[102:105]
	global_load_lds_dwordx4 v201, s[22:23]
	s_add_u32 m0, s8, 0xd800
	v_mfma_f32_16x16x32_bf16 v[106:109], v[192:195], v[176:179], v[106:109]
	global_load_lds_dwordx4 v202, s[22:23]
	s_add_u32 m0, s8, 0xdc00
	v_mfma_f32_16x16x32_bf16 v[110:113], v[196:199], v[176:179], v[110:113]
	global_load_lds_dwordx4 v203, s[22:23]
	s_add_u32 m0, s9, 0xc000
	v_mfma_f32_16x16x32_bf16 v[114:117], v[184:187], v[180:183], v[114:117]
	global_load_lds_dwordx4 v204, s[24:25]
	s_add_u32 m0, s9, 0xc400
	v_mfma_f32_16x16x32_bf16 v[118:121], v[188:191], v[180:183], v[118:121]
	global_load_lds_dwordx4 v205, s[24:25]
	s_add_u32 m0, s9, 0xc800
	v_mfma_f32_16x16x32_bf16 v[122:125], v[192:195], v[180:183], v[122:125]
	global_load_lds_dwordx4 v204, s[52:53]
	s_add_u32 m0, s9, 0xcc00
	v_mfma_f32_16x16x32_bf16 v[126:129], v[196:199], v[180:183], v[126:129]
	global_load_lds_dwordx4 v205, s[52:53]
	s_waitcnt lgkmcnt(0)
	v_mfma_f32_16x16x32_bf16 v[66:69], v[152:155], v[136:139], v[66:69]
	ds_read_b128 v[168:171], v229 offset:0
	v_mfma_f32_16x16x32_bf16 v[70:73], v[156:159], v[136:139], v[70:73]
	ds_read_b128 v[172:175], v229 offset:2048
	v_mfma_f32_16x16x32_bf16 v[74:77], v[160:163], v[136:139], v[74:77]
	ds_read_b128 v[176:179], v229 offset:4096
	v_mfma_f32_16x16x32_bf16 v[78:81], v[164:167], v[136:139], v[78:81]
	ds_read_b128 v[180:183], v229 offset:6144
	v_mfma_f32_16x16x32_bf16 v[82:85], v[152:155], v[140:143], v[82:85]
	ds_read_b128 v[184:187], v235 offset:0
	v_mfma_f32_16x16x32_bf16 v[86:89], v[156:159], v[140:143], v[86:89]
	ds_read_b128 v[188:191], v235 offset:2048
	v_mfma_f32_16x16x32_bf16 v[90:93], v[160:163], v[140:143], v[90:93]
	ds_read_b128 v[192:195], v235 offset:4096
	v_mfma_f32_16x16x32_bf16 v[94:97], v[164:167], v[140:143], v[94:97]
	ds_read_b128 v[196:199], v235 offset:6144
	v_mfma_f32_16x16x32_bf16 v[98:101], v[152:155], v[144:147], v[98:101]
	v_mfma_f32_16x16x32_bf16 v[102:105], v[156:159], v[144:147], v[102:105]
	v_mfma_f32_16x16x32_bf16 v[106:109], v[160:163], v[144:147], v[106:109]
	v_mfma_f32_16x16x32_bf16 v[110:113], v[164:167], v[144:147], v[110:113]
	v_mfma_f32_16x16x32_bf16 v[114:117], v[152:155], v[148:151], v[114:117]
	v_mfma_f32_16x16x32_bf16 v[118:121], v[156:159], v[148:151], v[118:121]
	v_mfma_f32_16x16x32_bf16 v[122:125], v[160:163], v[148:151], v[122:125]
	v_mfma_f32_16x16x32_bf16 v[126:129], v[164:167], v[148:151], v[126:129]
	s_waitcnt vmcnt(12) lgkmcnt(0)
	s_barrier
	s_add_u32 s14, s4, 0x380
	s_addc_u32 s15, s5, 0
	v_mfma_f32_16x16x32_bf16 v[66:69], v[184:187], v[168:171], v[66:69]
	ds_read_b128 v[136:139], v218 offset:0
	s_add_u32 s22, s4, 0x10380
	s_addc_u32 s23, s5, 0
	v_mfma_f32_16x16x32_bf16 v[70:73], v[188:191], v[168:171], v[70:73]
	ds_read_b128 v[140:143], v218 offset:2048
	s_add_u32 s24, s6, 0x40380
	s_addc_u32 s25, s7, 0
	v_mfma_f32_16x16x32_bf16 v[74:77], v[192:195], v[168:171], v[74:77]
	ds_read_b128 v[144:147], v218 offset:4096
	s_add_u32 s52, s6, 0x48380
	s_addc_u32 s53, s7, 0
	v_mfma_f32_16x16x32_bf16 v[78:81], v[196:199], v[168:171], v[78:81]
	ds_read_b128 v[148:151], v218 offset:6144
	s_add_u32 m0, s8, 0x18000
	v_mfma_f32_16x16x32_bf16 v[82:85], v[184:187], v[172:175], v[82:85]
	global_load_lds_dwordx4 v200, s[14:15]
	ds_read_b128 v[152:155], v230 offset:0
	s_add_u32 m0, s8, 0x18400
	v_mfma_f32_16x16x32_bf16 v[86:89], v[188:191], v[172:175], v[86:89]
	global_load_lds_dwordx4 v201, s[14:15]
	ds_read_b128 v[156:159], v230 offset:2048
	s_add_u32 m0, s8, 0x18800
	v_mfma_f32_16x16x32_bf16 v[90:93], v[192:195], v[172:175], v[90:93]
	global_load_lds_dwordx4 v202, s[14:15]
	ds_read_b128 v[160:163], v230 offset:4096
	s_add_u32 m0, s8, 0x18c00
	v_mfma_f32_16x16x32_bf16 v[94:97], v[196:199], v[172:175], v[94:97]
	global_load_lds_dwordx4 v203, s[14:15]
	ds_read_b128 v[164:167], v230 offset:6144
	s_add_u32 m0, s8, 0x19000
	v_mfma_f32_16x16x32_bf16 v[98:101], v[184:187], v[176:179], v[98:101]
	global_load_lds_dwordx4 v200, s[22:23]
	s_add_u32 m0, s8, 0x19400
	v_mfma_f32_16x16x32_bf16 v[102:105], v[188:191], v[176:179], v[102:105]
	global_load_lds_dwordx4 v201, s[22:23]
	s_add_u32 m0, s8, 0x19800
	v_mfma_f32_16x16x32_bf16 v[106:109], v[192:195], v[176:179], v[106:109]
	global_load_lds_dwordx4 v202, s[22:23]
	s_add_u32 m0, s8, 0x19c00
	v_mfma_f32_16x16x32_bf16 v[110:113], v[196:199], v[176:179], v[110:113]
	global_load_lds_dwordx4 v203, s[22:23]
	s_add_u32 m0, s9, 0x18000
	v_mfma_f32_16x16x32_bf16 v[114:117], v[184:187], v[180:183], v[114:117]
	global_load_lds_dwordx4 v204, s[24:25]
	s_add_u32 m0, s9, 0x18400
	v_mfma_f32_16x16x32_bf16 v[118:121], v[188:191], v[180:183], v[118:121]
	global_load_lds_dwordx4 v205, s[24:25]
	s_add_u32 m0, s9, 0x18800
	v_mfma_f32_16x16x32_bf16 v[122:125], v[192:195], v[180:183], v[122:125]
	global_load_lds_dwordx4 v204, s[52:53]
	s_add_u32 m0, s9, 0x18c00
	v_mfma_f32_16x16x32_bf16 v[126:129], v[196:199], v[180:183], v[126:129]
	global_load_lds_dwordx4 v205, s[52:53]
	s_waitcnt lgkmcnt(0)
	v_mfma_f32_16x16x32_bf16 v[66:69], v[152:155], v[136:139], v[66:69]
	ds_read_b128 v[168:171], v225 offset:0
	v_mfma_f32_16x16x32_bf16 v[70:73], v[156:159], v[136:139], v[70:73]
	ds_read_b128 v[172:175], v225 offset:2048
	v_mfma_f32_16x16x32_bf16 v[74:77], v[160:163], v[136:139], v[74:77]
	ds_read_b128 v[176:179], v225 offset:4096
	v_mfma_f32_16x16x32_bf16 v[78:81], v[164:167], v[136:139], v[78:81]
	ds_read_b128 v[180:183], v225 offset:6144
	v_mfma_f32_16x16x32_bf16 v[82:85], v[152:155], v[140:143], v[82:85]
	ds_read_b128 v[184:187], v233 offset:0
	v_mfma_f32_16x16x32_bf16 v[86:89], v[156:159], v[140:143], v[86:89]
	ds_read_b128 v[188:191], v233 offset:2048
	v_mfma_f32_16x16x32_bf16 v[90:93], v[160:163], v[140:143], v[90:93]
	ds_read_b128 v[192:195], v233 offset:4096
	v_mfma_f32_16x16x32_bf16 v[94:97], v[164:167], v[140:143], v[94:97]
	ds_read_b128 v[196:199], v233 offset:6144
	v_mfma_f32_16x16x32_bf16 v[98:101], v[152:155], v[144:147], v[98:101]
	v_mfma_f32_16x16x32_bf16 v[102:105], v[156:159], v[144:147], v[102:105]
	v_mfma_f32_16x16x32_bf16 v[106:109], v[160:163], v[144:147], v[106:109]
	v_mfma_f32_16x16x32_bf16 v[110:113], v[164:167], v[144:147], v[110:113]
	v_mfma_f32_16x16x32_bf16 v[114:117], v[152:155], v[148:151], v[114:117]
	v_mfma_f32_16x16x32_bf16 v[118:121], v[156:159], v[148:151], v[118:121]
	v_mfma_f32_16x16x32_bf16 v[122:125], v[160:163], v[148:151], v[122:125]
	v_mfma_f32_16x16x32_bf16 v[126:129], v[164:167], v[148:151], v[126:129]
	s_waitcnt vmcnt(12) lgkmcnt(0)
	s_barrier
	s_add_u32 s14, s4, 0x400
	s_addc_u32 s15, s5, 0
	v_mfma_f32_16x16x32_bf16 v[66:69], v[184:187], v[168:171], v[66:69]
	ds_read_b128 v[136:139], v219 offset:0
	s_add_u32 s22, s4, 0x10400
	s_addc_u32 s23, s5, 0
	v_mfma_f32_16x16x32_bf16 v[70:73], v[188:191], v[168:171], v[70:73]
	ds_read_b128 v[140:143], v219 offset:2048
	s_add_u32 s24, s6, 0x40400
	s_addc_u32 s25, s7, 0
	v_mfma_f32_16x16x32_bf16 v[74:77], v[192:195], v[168:171], v[74:77]
	ds_read_b128 v[144:147], v219 offset:4096
	s_add_u32 s52, s6, 0x48400
	s_addc_u32 s53, s7, 0
	v_mfma_f32_16x16x32_bf16 v[78:81], v[196:199], v[168:171], v[78:81]
	ds_read_b128 v[148:151], v219 offset:6144
	s_mov_b32 m0, s8
	v_mfma_f32_16x16x32_bf16 v[82:85], v[184:187], v[172:175], v[82:85]
	global_load_lds_dwordx4 v200, s[14:15]
	ds_read_b128 v[152:155], v231 offset:0
	s_add_u32 m0, s8, 0x400
	v_mfma_f32_16x16x32_bf16 v[86:89], v[188:191], v[172:175], v[86:89]
	global_load_lds_dwordx4 v201, s[14:15]
	ds_read_b128 v[156:159], v231 offset:2048
	s_add_u32 m0, s8, 0x800
	v_mfma_f32_16x16x32_bf16 v[90:93], v[192:195], v[172:175], v[90:93]
	global_load_lds_dwordx4 v202, s[14:15]
	ds_read_b128 v[160:163], v231 offset:4096
	s_add_u32 m0, s8, 0xc00
	v_mfma_f32_16x16x32_bf16 v[94:97], v[196:199], v[172:175], v[94:97]
	global_load_lds_dwordx4 v203, s[14:15]
	ds_read_b128 v[164:167], v231 offset:6144
	s_add_u32 m0, s8, 0x1000
	v_mfma_f32_16x16x32_bf16 v[98:101], v[184:187], v[176:179], v[98:101]
	global_load_lds_dwordx4 v200, s[22:23]
	s_add_u32 m0, s8, 0x1400
	v_mfma_f32_16x16x32_bf16 v[102:105], v[188:191], v[176:179], v[102:105]
	global_load_lds_dwordx4 v201, s[22:23]
	s_add_u32 m0, s8, 0x1800
	v_mfma_f32_16x16x32_bf16 v[106:109], v[192:195], v[176:179], v[106:109]
	global_load_lds_dwordx4 v202, s[22:23]
	s_add_u32 m0, s8, 0x1c00
	v_mfma_f32_16x16x32_bf16 v[110:113], v[196:199], v[176:179], v[110:113]
	global_load_lds_dwordx4 v203, s[22:23]
	s_mov_b32 m0, s9
	v_mfma_f32_16x16x32_bf16 v[114:117], v[184:187], v[180:183], v[114:117]
	global_load_lds_dwordx4 v204, s[24:25]
	s_add_u32 m0, s9, 0x400
	v_mfma_f32_16x16x32_bf16 v[118:121], v[188:191], v[180:183], v[118:121]
	global_load_lds_dwordx4 v205, s[24:25]
	s_add_u32 m0, s9, 0x800
	v_mfma_f32_16x16x32_bf16 v[122:125], v[192:195], v[180:183], v[122:125]
	global_load_lds_dwordx4 v204, s[52:53]
	s_add_u32 m0, s9, 0xc00
	v_mfma_f32_16x16x32_bf16 v[126:129], v[196:199], v[180:183], v[126:129]
	global_load_lds_dwordx4 v205, s[52:53]
	s_waitcnt lgkmcnt(0)
	v_mfma_f32_16x16x32_bf16 v[66:69], v[152:155], v[136:139], v[66:69]
	ds_read_b128 v[168:171], v228 offset:0
	v_mfma_f32_16x16x32_bf16 v[70:73], v[156:159], v[136:139], v[70:73]
	ds_read_b128 v[172:175], v228 offset:2048
	v_mfma_f32_16x16x32_bf16 v[74:77], v[160:163], v[136:139], v[74:77]
	ds_read_b128 v[176:179], v228 offset:4096
	v_mfma_f32_16x16x32_bf16 v[78:81], v[164:167], v[136:139], v[78:81]
	ds_read_b128 v[180:183], v228 offset:6144
	v_mfma_f32_16x16x32_bf16 v[82:85], v[152:155], v[140:143], v[82:85]
	ds_read_b128 v[184:187], v234 offset:0
	v_mfma_f32_16x16x32_bf16 v[86:89], v[156:159], v[140:143], v[86:89]
	ds_read_b128 v[188:191], v234 offset:2048
	v_mfma_f32_16x16x32_bf16 v[90:93], v[160:163], v[140:143], v[90:93]
	ds_read_b128 v[192:195], v234 offset:4096
	v_mfma_f32_16x16x32_bf16 v[94:97], v[164:167], v[140:143], v[94:97]
	ds_read_b128 v[196:199], v234 offset:6144
	v_mfma_f32_16x16x32_bf16 v[98:101], v[152:155], v[144:147], v[98:101]
	v_mfma_f32_16x16x32_bf16 v[102:105], v[156:159], v[144:147], v[102:105]
	v_mfma_f32_16x16x32_bf16 v[106:109], v[160:163], v[144:147], v[106:109]
	v_mfma_f32_16x16x32_bf16 v[110:113], v[164:167], v[144:147], v[110:113]
	v_mfma_f32_16x16x32_bf16 v[114:117], v[152:155], v[148:151], v[114:117]
	v_mfma_f32_16x16x32_bf16 v[118:121], v[156:159], v[148:151], v[118:121]
	v_mfma_f32_16x16x32_bf16 v[122:125], v[160:163], v[148:151], v[122:125]
	v_mfma_f32_16x16x32_bf16 v[126:129], v[164:167], v[148:151], v[126:129]
	s_waitcnt vmcnt(12) lgkmcnt(0)
	s_barrier
	s_add_u32 s14, s4, 0x480
	s_addc_u32 s15, s5, 0
	v_mfma_f32_16x16x32_bf16 v[66:69], v[184:187], v[168:171], v[66:69]
	ds_read_b128 v[136:139], v224 offset:0
	s_add_u32 s22, s4, 0x10480
	s_addc_u32 s23, s5, 0
	v_mfma_f32_16x16x32_bf16 v[70:73], v[188:191], v[168:171], v[70:73]
	ds_read_b128 v[140:143], v224 offset:2048
	s_add_u32 s24, s6, 0x40480
	s_addc_u32 s25, s7, 0
	v_mfma_f32_16x16x32_bf16 v[74:77], v[192:195], v[168:171], v[74:77]
	ds_read_b128 v[144:147], v224 offset:4096
	s_add_u32 s52, s6, 0x48480
	s_addc_u32 s53, s7, 0
	v_mfma_f32_16x16x32_bf16 v[78:81], v[196:199], v[168:171], v[78:81]
	ds_read_b128 v[148:151], v224 offset:6144
	s_add_u32 m0, s8, 0xc000
	v_mfma_f32_16x16x32_bf16 v[82:85], v[184:187], v[172:175], v[82:85]
	global_load_lds_dwordx4 v200, s[14:15]
	ds_read_b128 v[152:155], v232 offset:0
	s_add_u32 m0, s8, 0xc400
	v_mfma_f32_16x16x32_bf16 v[86:89], v[188:191], v[172:175], v[86:89]
	global_load_lds_dwordx4 v201, s[14:15]
	ds_read_b128 v[156:159], v232 offset:2048
	s_add_u32 m0, s8, 0xc800
	v_mfma_f32_16x16x32_bf16 v[90:93], v[192:195], v[172:175], v[90:93]
	global_load_lds_dwordx4 v202, s[14:15]
	ds_read_b128 v[160:163], v232 offset:4096
	s_add_u32 m0, s8, 0xcc00
	v_mfma_f32_16x16x32_bf16 v[94:97], v[196:199], v[172:175], v[94:97]
	global_load_lds_dwordx4 v203, s[14:15]
	ds_read_b128 v[164:167], v232 offset:6144
	s_add_u32 m0, s8, 0xd000
	v_mfma_f32_16x16x32_bf16 v[98:101], v[184:187], v[176:179], v[98:101]
	global_load_lds_dwordx4 v200, s[22:23]
	s_add_u32 m0, s8, 0xd400
	v_mfma_f32_16x16x32_bf16 v[102:105], v[188:191], v[176:179], v[102:105]
	global_load_lds_dwordx4 v201, s[22:23]
	s_add_u32 m0, s8, 0xd800
	v_mfma_f32_16x16x32_bf16 v[106:109], v[192:195], v[176:179], v[106:109]
	global_load_lds_dwordx4 v202, s[22:23]
	s_add_u32 m0, s8, 0xdc00
	v_mfma_f32_16x16x32_bf16 v[110:113], v[196:199], v[176:179], v[110:113]
	global_load_lds_dwordx4 v203, s[22:23]
	s_add_u32 m0, s9, 0xc000
	v_mfma_f32_16x16x32_bf16 v[114:117], v[184:187], v[180:183], v[114:117]
	global_load_lds_dwordx4 v204, s[24:25]
	s_add_u32 m0, s9, 0xc400
	v_mfma_f32_16x16x32_bf16 v[118:121], v[188:191], v[180:183], v[118:121]
	global_load_lds_dwordx4 v205, s[24:25]
	s_add_u32 m0, s9, 0xc800
	v_mfma_f32_16x16x32_bf16 v[122:125], v[192:195], v[180:183], v[122:125]
	global_load_lds_dwordx4 v204, s[52:53]
	s_add_u32 m0, s9, 0xcc00
	v_mfma_f32_16x16x32_bf16 v[126:129], v[196:199], v[180:183], v[126:129]
	global_load_lds_dwordx4 v205, s[52:53]
	s_waitcnt lgkmcnt(0)
	v_mfma_f32_16x16x32_bf16 v[66:69], v[152:155], v[136:139], v[66:69]
	ds_read_b128 v[168:171], v229 offset:0
	v_mfma_f32_16x16x32_bf16 v[70:73], v[156:159], v[136:139], v[70:73]
	ds_read_b128 v[172:175], v229 offset:2048
	v_mfma_f32_16x16x32_bf16 v[74:77], v[160:163], v[136:139], v[74:77]
	ds_read_b128 v[176:179], v229 offset:4096
	v_mfma_f32_16x16x32_bf16 v[78:81], v[164:167], v[136:139], v[78:81]
	ds_read_b128 v[180:183], v229 offset:6144
	v_mfma_f32_16x16x32_bf16 v[82:85], v[152:155], v[140:143], v[82:85]
	ds_read_b128 v[184:187], v235 offset:0
	v_mfma_f32_16x16x32_bf16 v[86:89], v[156:159], v[140:143], v[86:89]
	ds_read_b128 v[188:191], v235 offset:2048
	v_mfma_f32_16x16x32_bf16 v[90:93], v[160:163], v[140:143], v[90:93]
	ds_read_b128 v[192:195], v235 offset:4096
	v_mfma_f32_16x16x32_bf16 v[94:97], v[164:167], v[140:143], v[94:97]
	ds_read_b128 v[196:199], v235 offset:6144
	v_mfma_f32_16x16x32_bf16 v[98:101], v[152:155], v[144:147], v[98:101]
	v_mfma_f32_16x16x32_bf16 v[102:105], v[156:159], v[144:147], v[102:105]
	v_mfma_f32_16x16x32_bf16 v[106:109], v[160:163], v[144:147], v[106:109]
	v_mfma_f32_16x16x32_bf16 v[110:113], v[164:167], v[144:147], v[110:113]
	v_mfma_f32_16x16x32_bf16 v[114:117], v[152:155], v[148:151], v[114:117]
	v_mfma_f32_16x16x32_bf16 v[118:121], v[156:159], v[148:151], v[118:121]
	v_mfma_f32_16x16x32_bf16 v[122:125], v[160:163], v[148:151], v[122:125]
	v_mfma_f32_16x16x32_bf16 v[126:129], v[164:167], v[148:151], v[126:129]
	s_waitcnt vmcnt(12) lgkmcnt(0)
	s_barrier
	s_add_u32 s14, s4, 0x500
	s_addc_u32 s15, s5, 0
	v_mfma_f32_16x16x32_bf16 v[66:69], v[184:187], v[168:171], v[66:69]
	ds_read_b128 v[136:139], v218 offset:0
	s_add_u32 s22, s4, 0x10500
	s_addc_u32 s23, s5, 0
	v_mfma_f32_16x16x32_bf16 v[70:73], v[188:191], v[168:171], v[70:73]
	ds_read_b128 v[140:143], v218 offset:2048
	s_add_u32 s24, s6, 0x40500
	s_addc_u32 s25, s7, 0
	v_mfma_f32_16x16x32_bf16 v[74:77], v[192:195], v[168:171], v[74:77]
	ds_read_b128 v[144:147], v218 offset:4096
	s_add_u32 s52, s6, 0x48500
	s_addc_u32 s53, s7, 0
	v_mfma_f32_16x16x32_bf16 v[78:81], v[196:199], v[168:171], v[78:81]
	ds_read_b128 v[148:151], v218 offset:6144
	s_add_u32 m0, s8, 0x18000
	v_mfma_f32_16x16x32_bf16 v[82:85], v[184:187], v[172:175], v[82:85]
	global_load_lds_dwordx4 v200, s[14:15]
	ds_read_b128 v[152:155], v230 offset:0
	s_add_u32 m0, s8, 0x18400
	v_mfma_f32_16x16x32_bf16 v[86:89], v[188:191], v[172:175], v[86:89]
	global_load_lds_dwordx4 v201, s[14:15]
	ds_read_b128 v[156:159], v230 offset:2048
	s_add_u32 m0, s8, 0x18800
	v_mfma_f32_16x16x32_bf16 v[90:93], v[192:195], v[172:175], v[90:93]
	global_load_lds_dwordx4 v202, s[14:15]
	ds_read_b128 v[160:163], v230 offset:4096
	s_add_u32 m0, s8, 0x18c00
	v_mfma_f32_16x16x32_bf16 v[94:97], v[196:199], v[172:175], v[94:97]
	global_load_lds_dwordx4 v203, s[14:15]
	ds_read_b128 v[164:167], v230 offset:6144
	s_add_u32 m0, s8, 0x19000
	v_mfma_f32_16x16x32_bf16 v[98:101], v[184:187], v[176:179], v[98:101]
	global_load_lds_dwordx4 v200, s[22:23]
	s_add_u32 m0, s8, 0x19400
	v_mfma_f32_16x16x32_bf16 v[102:105], v[188:191], v[176:179], v[102:105]
	global_load_lds_dwordx4 v201, s[22:23]
	s_add_u32 m0, s8, 0x19800
	v_mfma_f32_16x16x32_bf16 v[106:109], v[192:195], v[176:179], v[106:109]
	global_load_lds_dwordx4 v202, s[22:23]
	s_add_u32 m0, s8, 0x19c00
	v_mfma_f32_16x16x32_bf16 v[110:113], v[196:199], v[176:179], v[110:113]
	global_load_lds_dwordx4 v203, s[22:23]
	s_add_u32 m0, s9, 0x18000
	v_mfma_f32_16x16x32_bf16 v[114:117], v[184:187], v[180:183], v[114:117]
	global_load_lds_dwordx4 v204, s[24:25]
	s_add_u32 m0, s9, 0x18400
	v_mfma_f32_16x16x32_bf16 v[118:121], v[188:191], v[180:183], v[118:121]
	global_load_lds_dwordx4 v205, s[24:25]
	s_add_u32 m0, s9, 0x18800
	v_mfma_f32_16x16x32_bf16 v[122:125], v[192:195], v[180:183], v[122:125]
	global_load_lds_dwordx4 v204, s[52:53]
	s_add_u32 m0, s9, 0x18c00
	v_mfma_f32_16x16x32_bf16 v[126:129], v[196:199], v[180:183], v[126:129]
	global_load_lds_dwordx4 v205, s[52:53]
	s_waitcnt lgkmcnt(0)
	v_mfma_f32_16x16x32_bf16 v[66:69], v[152:155], v[136:139], v[66:69]
	ds_read_b128 v[168:171], v225 offset:0
	s_add_u32 s10, s28, s13
	s_addc_u32 s11, s29, 0
	s_add_u32 s13, s13, 0x10000
	v_mfma_f32_16x16x32_bf16 v[70:73], v[156:159], v[136:139], v[70:73]
	ds_read_b128 v[172:175], v225 offset:2048
	v_mul_f32_e32 v2, s12, v2
	v_mul_f32_e32 v3, s12, v3
	v_mfma_f32_16x16x32_bf16 v[74:77], v[160:163], v[136:139], v[74:77]
	ds_read_b128 v[176:179], v225 offset:4096
	v_mul_f32_e32 v4, s12, v4
	v_mul_f32_e32 v5, s12, v5
	v_mul_f32_e32 v6, s12, v6
	v_mfma_f32_16x16x32_bf16 v[78:81], v[164:167], v[136:139], v[78:81]
	ds_read_b128 v[180:183], v225 offset:6144
	v_mul_f32_e32 v7, s12, v7
	v_mul_f32_e32 v8, s12, v8
	v_mfma_f32_16x16x32_bf16 v[82:85], v[152:155], v[140:143], v[82:85]
	ds_read_b128 v[184:187], v233 offset:0
	v_mul_f32_e32 v9, s12, v9
	v_exp_f32_e32 v2, v2
	v_mfma_f32_16x16x32_bf16 v[86:89], v[156:159], v[140:143], v[86:89]
	ds_read_b128 v[188:191], v233 offset:2048
	v_exp_f32_e32 v3, v3
	v_exp_f32_e32 v4, v4
	v_exp_f32_e32 v5, v5
	v_mfma_f32_16x16x32_bf16 v[90:93], v[160:163], v[140:143], v[90:93]
	ds_read_b128 v[192:195], v233 offset:4096
	v_exp_f32_e32 v6, v6
	v_exp_f32_e32 v7, v7
	v_mfma_f32_16x16x32_bf16 v[94:97], v[164:167], v[140:143], v[94:97]
	ds_read_b128 v[196:199], v233 offset:6144
	v_exp_f32_e32 v8, v8
	v_exp_f32_e32 v9, v9
	v_add_f32_e32 v2, 1.0, v2
	v_mfma_f32_16x16x32_bf16 v[98:101], v[152:155], v[144:147], v[98:101]
	v_add_f32_e32 v3, 1.0, v3
	v_add_f32_e32 v4, 1.0, v4
	v_mfma_f32_16x16x32_bf16 v[102:105], v[156:159], v[144:147], v[102:105]
	v_add_f32_e32 v5, 1.0, v5
	v_add_f32_e32 v6, 1.0, v6
	v_mfma_f32_16x16x32_bf16 v[106:109], v[160:163], v[144:147], v[106:109]
	v_add_f32_e32 v7, 1.0, v7
	v_add_f32_e32 v8, 1.0, v8
	v_add_f32_e32 v9, 1.0, v9
	v_mfma_f32_16x16x32_bf16 v[110:113], v[164:167], v[144:147], v[110:113]
	v_rcp_f32_e32 v2, v2
	v_rcp_f32_e32 v3, v3
	v_mfma_f32_16x16x32_bf16 v[114:117], v[152:155], v[148:151], v[114:117]
	v_rcp_f32_e32 v4, v4
	v_rcp_f32_e32 v5, v5
	v_mfma_f32_16x16x32_bf16 v[118:121], v[156:159], v[148:151], v[118:121]
	v_rcp_f32_e32 v6, v6
	v_rcp_f32_e32 v7, v7
	v_rcp_f32_e32 v8, v8
	v_mfma_f32_16x16x32_bf16 v[122:125], v[160:163], v[148:151], v[122:125]
	v_rcp_f32_e32 v9, v9
	v_cvt_pk_bf16_f32 v2, v2, v3
	v_mfma_f32_16x16x32_bf16 v[126:129], v[164:167], v[148:151], v[126:129]
	v_cvt_pk_bf16_f32 v3, v4, v5
	v_cvt_pk_bf16_f32 v4, v6, v7
	v_cvt_pk_bf16_f32 v5, v8, v9
	s_waitcnt vmcnt(12) lgkmcnt(0)
	s_barrier
	v_mfma_f32_16x16x32_bf16 v[66:69], v[184:187], v[168:171], v[66:69]
	ds_read_b128 v[136:139], v219 offset:0
	global_store_dwordx4 v240, v[2:5], s[10:11] offset:0
	v_mul_f32_e32 v10, s12, v10
	v_mfma_f32_16x16x32_bf16 v[70:73], v[188:191], v[168:171], v[70:73]
	ds_read_b128 v[140:143], v219 offset:2048
	v_mul_f32_e32 v11, s12, v11
	v_mul_f32_e32 v12, s12, v12
	v_mfma_f32_16x16x32_bf16 v[74:77], v[192:195], v[168:171], v[74:77]
	ds_read_b128 v[144:147], v219 offset:4096
	v_mul_f32_e32 v13, s12, v13
	v_mul_f32_e32 v14, s12, v14
	v_mfma_f32_16x16x32_bf16 v[78:81], v[196:199], v[168:171], v[78:81]
	ds_read_b128 v[148:151], v219 offset:6144
	v_mul_f32_e32 v15, s12, v15
	v_mul_f32_e32 v16, s12, v16
	v_mul_f32_e32 v17, s12, v17
	v_mfma_f32_16x16x32_bf16 v[82:85], v[184:187], v[172:175], v[82:85]
	ds_read_b128 v[152:155], v231 offset:0
	v_exp_f32_e32 v10, v10
	v_exp_f32_e32 v11, v11
	v_mfma_f32_16x16x32_bf16 v[86:89], v[188:191], v[172:175], v[86:89]
	ds_read_b128 v[156:159], v231 offset:2048
	v_exp_f32_e32 v12, v12
	v_exp_f32_e32 v13, v13
	v_mfma_f32_16x16x32_bf16 v[90:93], v[192:195], v[172:175], v[90:93]
	ds_read_b128 v[160:163], v231 offset:4096
	v_exp_f32_e32 v14, v14
	v_exp_f32_e32 v15, v15
	v_exp_f32_e32 v16, v16
	v_mfma_f32_16x16x32_bf16 v[94:97], v[196:199], v[172:175], v[94:97]
	ds_read_b128 v[164:167], v231 offset:6144
	v_exp_f32_e32 v17, v17
	v_add_f32_e32 v10, 1.0, v10
	v_mfma_f32_16x16x32_bf16 v[98:101], v[184:187], v[176:179], v[98:101]
	v_add_f32_e32 v11, 1.0, v11
	v_add_f32_e32 v12, 1.0, v12
	v_mfma_f32_16x16x32_bf16 v[102:105], v[188:191], v[176:179], v[102:105]
	v_add_f32_e32 v13, 1.0, v13
	v_add_f32_e32 v14, 1.0, v14
	v_add_f32_e32 v15, 1.0, v15
	v_mfma_f32_16x16x32_bf16 v[106:109], v[192:195], v[176:179], v[106:109]
	v_add_f32_e32 v16, 1.0, v16
	v_add_f32_e32 v17, 1.0, v17
	v_mfma_f32_16x16x32_bf16 v[110:113], v[196:199], v[176:179], v[110:113]
	v_rcp_f32_e32 v10, v10
	v_rcp_f32_e32 v11, v11
	v_mfma_f32_16x16x32_bf16 v[114:117], v[184:187], v[180:183], v[114:117]
	v_rcp_f32_e32 v12, v12
	v_rcp_f32_e32 v13, v13
	v_rcp_f32_e32 v14, v14
	v_mfma_f32_16x16x32_bf16 v[118:121], v[188:191], v[180:183], v[118:121]
	v_rcp_f32_e32 v15, v15
	v_rcp_f32_e32 v16, v16
	v_mfma_f32_16x16x32_bf16 v[122:125], v[192:195], v[180:183], v[122:125]
	v_rcp_f32_e32 v17, v17
	v_cvt_pk_bf16_f32 v10, v10, v11
	v_mfma_f32_16x16x32_bf16 v[126:129], v[196:199], v[180:183], v[126:129]
	v_cvt_pk_bf16_f32 v11, v12, v13
	v_cvt_pk_bf16_f32 v12, v14, v15
	v_cvt_pk_bf16_f32 v13, v16, v17
	s_waitcnt lgkmcnt(0)
	v_mfma_f32_16x16x32_bf16 v[66:69], v[152:155], v[136:139], v[66:69]
	ds_read_b128 v[168:171], v228 offset:0
	global_store_dwordx4 v240, v[10:13], s[10:11] offset:16
	v_mul_f32_e32 v18, s12, v18
	v_mfma_f32_16x16x32_bf16 v[70:73], v[156:159], v[136:139], v[70:73]
	ds_read_b128 v[172:175], v228 offset:2048
	v_mul_f32_e32 v19, s12, v19
	v_mul_f32_e32 v20, s12, v20
	v_mfma_f32_16x16x32_bf16 v[74:77], v[160:163], v[136:139], v[74:77]
	ds_read_b128 v[176:179], v228 offset:4096
	v_mul_f32_e32 v21, s12, v21
	v_mul_f32_e32 v22, s12, v22
	v_mul_f32_e32 v23, s12, v23
	v_mfma_f32_16x16x32_bf16 v[78:81], v[164:167], v[136:139], v[78:81]
	ds_read_b128 v[180:183], v228 offset:6144
	v_mul_f32_e32 v24, s12, v24
	v_mul_f32_e32 v25, s12, v25
	v_mfma_f32_16x16x32_bf16 v[82:85], v[152:155], v[140:143], v[82:85]
	ds_read_b128 v[184:187], v234 offset:0
	v_exp_f32_e32 v18, v18
	v_exp_f32_e32 v19, v19
	v_mfma_f32_16x16x32_bf16 v[86:89], v[156:159], v[140:143], v[86:89]
	ds_read_b128 v[188:191], v234 offset:2048
	v_exp_f32_e32 v20, v20
	v_exp_f32_e32 v21, v21
	v_exp_f32_e32 v22, v22
	v_mfma_f32_16x16x32_bf16 v[90:93], v[160:163], v[140:143], v[90:93]
	ds_read_b128 v[192:195], v234 offset:4096
	v_exp_f32_e32 v23, v23
	v_exp_f32_e32 v24, v24
	v_mfma_f32_16x16x32_bf16 v[94:97], v[164:167], v[140:143], v[94:97]
	ds_read_b128 v[196:199], v234 offset:6144
	v_exp_f32_e32 v25, v25
	v_add_f32_e32 v18, 1.0, v18
	v_add_f32_e32 v19, 1.0, v19
	v_mfma_f32_16x16x32_bf16 v[98:101], v[152:155], v[144:147], v[98:101]
	v_add_f32_e32 v20, 1.0, v20
	v_add_f32_e32 v21, 1.0, v21
	v_mfma_f32_16x16x32_bf16 v[102:105], v[156:159], v[144:147], v[102:105]
	v_add_f32_e32 v22, 1.0, v22
	v_add_f32_e32 v23, 1.0, v23
	v_mfma_f32_16x16x32_bf16 v[106:109], v[160:163], v[144:147], v[106:109]
	v_add_f32_e32 v24, 1.0, v24
	v_add_f32_e32 v25, 1.0, v25
	v_rcp_f32_e32 v18, v18
	v_mfma_f32_16x16x32_bf16 v[110:113], v[164:167], v[144:147], v[110:113]
	v_rcp_f32_e32 v19, v19
	v_rcp_f32_e32 v20, v20
	v_mfma_f32_16x16x32_bf16 v[114:117], v[152:155], v[148:151], v[114:117]
	v_rcp_f32_e32 v21, v21
	v_rcp_f32_e32 v22, v22
	v_mfma_f32_16x16x32_bf16 v[118:121], v[156:159], v[148:151], v[118:121]
	v_rcp_f32_e32 v23, v23
	v_rcp_f32_e32 v24, v24
	v_rcp_f32_e32 v25, v25
	v_mfma_f32_16x16x32_bf16 v[122:125], v[160:163], v[148:151], v[122:125]
	v_cvt_pk_bf16_f32 v18, v18, v19
	v_cvt_pk_bf16_f32 v19, v20, v21
	v_mfma_f32_16x16x32_bf16 v[126:129], v[164:167], v[148:151], v[126:129]
	v_cvt_pk_bf16_f32 v20, v22, v23
	v_cvt_pk_bf16_f32 v21, v24, v25
	global_store_dwordx4 v240, v[18:21], s[10:11] offset:2048
	s_waitcnt vmcnt(3) lgkmcnt(0)
	s_barrier
	v_mfma_f32_16x16x32_bf16 v[66:69], v[184:187], v[168:171], v[66:69]
	ds_read_b128 v[136:139], v224 offset:0
	v_mul_f32_e32 v26, s12, v26
	v_mul_f32_e32 v27, s12, v27
	v_mfma_f32_16x16x32_bf16 v[70:73], v[188:191], v[168:171], v[70:73]
	ds_read_b128 v[140:143], v224 offset:2048
	v_mul_f32_e32 v28, s12, v28
	v_mul_f32_e32 v29, s12, v29
	v_mfma_f32_16x16x32_bf16 v[74:77], v[192:195], v[168:171], v[74:77]
	ds_read_b128 v[144:147], v224 offset:4096
	v_mul_f32_e32 v30, s12, v30
	v_mul_f32_e32 v31, s12, v31
	v_mfma_f32_16x16x32_bf16 v[78:81], v[196:199], v[168:171], v[78:81]
	ds_read_b128 v[148:151], v224 offset:6144
	v_mul_f32_e32 v32, s12, v32
	v_mul_f32_e32 v33, s12, v33
	v_exp_f32_e32 v26, v26
	v_mfma_f32_16x16x32_bf16 v[82:85], v[184:187], v[172:175], v[82:85]
	ds_read_b128 v[152:155], v232 offset:0
	v_exp_f32_e32 v27, v27
	v_exp_f32_e32 v28, v28
	v_mfma_f32_16x16x32_bf16 v[86:89], v[188:191], v[172:175], v[86:89]
	ds_read_b128 v[156:159], v232 offset:2048
	v_exp_f32_e32 v29, v29
	v_exp_f32_e32 v30, v30
	v_mfma_f32_16x16x32_bf16 v[90:93], v[192:195], v[172:175], v[90:93]
	ds_read_b128 v[160:163], v232 offset:4096
	v_exp_f32_e32 v31, v31
	v_exp_f32_e32 v32, v32
	v_exp_f32_e32 v33, v33
	v_mfma_f32_16x16x32_bf16 v[94:97], v[196:199], v[172:175], v[94:97]
	ds_read_b128 v[164:167], v232 offset:6144
	v_add_f32_e32 v26, 1.0, v26
	v_add_f32_e32 v27, 1.0, v27
	v_mfma_f32_16x16x32_bf16 v[98:101], v[184:187], v[176:179], v[98:101]
	v_add_f32_e32 v28, 1.0, v28
	v_add_f32_e32 v29, 1.0, v29
	v_mfma_f32_16x16x32_bf16 v[102:105], v[188:191], v[176:179], v[102:105]
	v_add_f32_e32 v30, 1.0, v30
	v_add_f32_e32 v31, 1.0, v31
	v_add_f32_e32 v32, 1.0, v32
	v_mfma_f32_16x16x32_bf16 v[106:109], v[192:195], v[176:179], v[106:109]
	v_add_f32_e32 v33, 1.0, v33
	v_rcp_f32_e32 v26, v26
	v_mfma_f32_16x16x32_bf16 v[110:113], v[196:199], v[176:179], v[110:113]
	v_rcp_f32_e32 v27, v27
	v_rcp_f32_e32 v28, v28
	v_mfma_f32_16x16x32_bf16 v[114:117], v[184:187], v[180:183], v[114:117]
	v_rcp_f32_e32 v29, v29
	v_rcp_f32_e32 v30, v30
	v_rcp_f32_e32 v31, v31
	v_mfma_f32_16x16x32_bf16 v[118:121], v[188:191], v[180:183], v[118:121]
	v_rcp_f32_e32 v32, v32
	v_rcp_f32_e32 v33, v33
	v_mfma_f32_16x16x32_bf16 v[122:125], v[192:195], v[180:183], v[122:125]
	v_cvt_pk_bf16_f32 v26, v26, v27
	v_cvt_pk_bf16_f32 v27, v28, v29
	v_mfma_f32_16x16x32_bf16 v[126:129], v[196:199], v[180:183], v[126:129]
	v_cvt_pk_bf16_f32 v28, v30, v31
	v_cvt_pk_bf16_f32 v29, v32, v33
	global_store_dwordx4 v240, v[26:29], s[10:11] offset:2064
	s_waitcnt lgkmcnt(0)
	v_mfma_f32_16x16x32_bf16 v[66:69], v[152:155], v[136:139], v[66:69]
	ds_read_b128 v[168:171], v229 offset:0
	v_mul_f32_e32 v34, s12, v34
	v_mul_f32_e32 v35, s12, v35
	v_mfma_f32_16x16x32_bf16 v[70:73], v[156:159], v[136:139], v[70:73]
	ds_read_b128 v[172:175], v229 offset:2048
	v_mul_f32_e32 v36, s12, v36
	v_mul_f32_e32 v37, s12, v37
	v_mfma_f32_16x16x32_bf16 v[74:77], v[160:163], v[136:139], v[74:77]
	ds_read_b128 v[176:179], v229 offset:4096
	v_mul_f32_e32 v38, s12, v38
	v_mul_f32_e32 v39, s12, v39
	v_mfma_f32_16x16x32_bf16 v[78:81], v[164:167], v[136:139], v[78:81]
	ds_read_b128 v[180:183], v229 offset:6144
	v_mul_f32_e32 v40, s12, v40
	v_mul_f32_e32 v41, s12, v41
	v_exp_f32_e32 v34, v34
	v_mfma_f32_16x16x32_bf16 v[82:85], v[152:155], v[140:143], v[82:85]
	ds_read_b128 v[184:187], v235 offset:0
	v_exp_f32_e32 v35, v35
	v_exp_f32_e32 v36, v36
	v_mfma_f32_16x16x32_bf16 v[86:89], v[156:159], v[140:143], v[86:89]
	ds_read_b128 v[188:191], v235 offset:2048
	v_exp_f32_e32 v37, v37
	v_exp_f32_e32 v38, v38
	v_mfma_f32_16x16x32_bf16 v[90:93], v[160:163], v[140:143], v[90:93]
	ds_read_b128 v[192:195], v235 offset:4096
	v_exp_f32_e32 v39, v39
	v_exp_f32_e32 v40, v40
	v_exp_f32_e32 v41, v41
	v_mfma_f32_16x16x32_bf16 v[94:97], v[164:167], v[140:143], v[94:97]
	ds_read_b128 v[196:199], v235 offset:6144
	v_add_f32_e32 v34, 1.0, v34
	v_add_f32_e32 v35, 1.0, v35
	v_mfma_f32_16x16x32_bf16 v[98:101], v[152:155], v[144:147], v[98:101]
	v_add_f32_e32 v36, 1.0, v36
	v_add_f32_e32 v37, 1.0, v37
	v_mfma_f32_16x16x32_bf16 v[102:105], v[156:159], v[144:147], v[102:105]
	v_add_f32_e32 v38, 1.0, v38
	v_add_f32_e32 v39, 1.0, v39
	v_add_f32_e32 v40, 1.0, v40
	v_mfma_f32_16x16x32_bf16 v[106:109], v[160:163], v[144:147], v[106:109]
	v_add_f32_e32 v41, 1.0, v41
	v_rcp_f32_e32 v34, v34
	v_mfma_f32_16x16x32_bf16 v[110:113], v[164:167], v[144:147], v[110:113]
	v_rcp_f32_e32 v35, v35
	v_rcp_f32_e32 v36, v36
	v_mfma_f32_16x16x32_bf16 v[114:117], v[152:155], v[148:151], v[114:117]
	v_rcp_f32_e32 v37, v37
	v_rcp_f32_e32 v38, v38
	v_rcp_f32_e32 v39, v39
	v_mfma_f32_16x16x32_bf16 v[118:121], v[156:159], v[148:151], v[118:121]
	v_rcp_f32_e32 v40, v40
	v_rcp_f32_e32 v41, v41
	v_mfma_f32_16x16x32_bf16 v[122:125], v[160:163], v[148:151], v[122:125]
	v_cvt_pk_bf16_f32 v34, v34, v35
	v_cvt_pk_bf16_f32 v35, v36, v37
	v_mfma_f32_16x16x32_bf16 v[126:129], v[164:167], v[148:151], v[126:129]
	v_cvt_pk_bf16_f32 v36, v38, v39
	v_cvt_pk_bf16_f32 v37, v40, v41
	global_store_dwordx4 v241, v[34:37], s[10:11] offset:0
	s_waitcnt lgkmcnt(0)
	s_barrier
	v_mfma_f32_16x16x32_bf16 v[66:69], v[184:187], v[168:171], v[66:69]
	ds_read_b128 v[136:139], v218 offset:0
	v_mul_f32_e32 v42, s12, v42
	v_mul_f32_e32 v43, s12, v43
	v_mfma_f32_16x16x32_bf16 v[70:73], v[188:191], v[168:171], v[70:73]
	ds_read_b128 v[140:143], v218 offset:2048
	v_mul_f32_e32 v44, s12, v44
	v_mul_f32_e32 v45, s12, v45
	v_mfma_f32_16x16x32_bf16 v[74:77], v[192:195], v[168:171], v[74:77]
	ds_read_b128 v[144:147], v218 offset:4096
	v_mul_f32_e32 v46, s12, v46
	v_mul_f32_e32 v47, s12, v47
	v_mfma_f32_16x16x32_bf16 v[78:81], v[196:199], v[168:171], v[78:81]
	ds_read_b128 v[148:151], v218 offset:6144
	v_mul_f32_e32 v48, s12, v48
	v_mul_f32_e32 v49, s12, v49
	v_exp_f32_e32 v42, v42
	v_mfma_f32_16x16x32_bf16 v[82:85], v[184:187], v[172:175], v[82:85]
	ds_read_b128 v[152:155], v230 offset:0
	v_exp_f32_e32 v43, v43
	v_exp_f32_e32 v44, v44
	v_mfma_f32_16x16x32_bf16 v[86:89], v[188:191], v[172:175], v[86:89]
	ds_read_b128 v[156:159], v230 offset:2048
	v_exp_f32_e32 v45, v45
	v_exp_f32_e32 v46, v46
	v_mfma_f32_16x16x32_bf16 v[90:93], v[192:195], v[172:175], v[90:93]
	ds_read_b128 v[160:163], v230 offset:4096
	v_exp_f32_e32 v47, v47
	v_exp_f32_e32 v48, v48
	v_exp_f32_e32 v49, v49
	v_mfma_f32_16x16x32_bf16 v[94:97], v[196:199], v[172:175], v[94:97]
	ds_read_b128 v[164:167], v230 offset:6144
	v_add_f32_e32 v42, 1.0, v42
	v_add_f32_e32 v43, 1.0, v43
	v_mfma_f32_16x16x32_bf16 v[98:101], v[184:187], v[176:179], v[98:101]
	v_add_f32_e32 v44, 1.0, v44
	v_add_f32_e32 v45, 1.0, v45
	v_mfma_f32_16x16x32_bf16 v[102:105], v[188:191], v[176:179], v[102:105]
	v_add_f32_e32 v46, 1.0, v46
	v_add_f32_e32 v47, 1.0, v47
	v_add_f32_e32 v48, 1.0, v48
	v_mfma_f32_16x16x32_bf16 v[106:109], v[192:195], v[176:179], v[106:109]
	v_add_f32_e32 v49, 1.0, v49
	v_rcp_f32_e32 v42, v42
	v_mfma_f32_16x16x32_bf16 v[110:113], v[196:199], v[176:179], v[110:113]
	v_rcp_f32_e32 v43, v43
	v_rcp_f32_e32 v44, v44
	v_mfma_f32_16x16x32_bf16 v[114:117], v[184:187], v[180:183], v[114:117]
	v_rcp_f32_e32 v45, v45
	v_rcp_f32_e32 v46, v46
	v_rcp_f32_e32 v47, v47
	v_mfma_f32_16x16x32_bf16 v[118:121], v[188:191], v[180:183], v[118:121]
	v_rcp_f32_e32 v48, v48
	v_rcp_f32_e32 v49, v49
	v_mfma_f32_16x16x32_bf16 v[122:125], v[192:195], v[180:183], v[122:125]
	v_cvt_pk_bf16_f32 v42, v42, v43
	v_cvt_pk_bf16_f32 v43, v44, v45
	v_mfma_f32_16x16x32_bf16 v[126:129], v[196:199], v[180:183], v[126:129]
	v_cvt_pk_bf16_f32 v44, v46, v47
	v_cvt_pk_bf16_f32 v45, v48, v49
	global_store_dwordx4 v241, v[42:45], s[10:11] offset:16
	s_waitcnt lgkmcnt(0)
	v_mfma_f32_16x16x32_bf16 v[66:69], v[152:155], v[136:139], v[66:69]
	ds_read_b128 v[168:171], v225 offset:0
	v_mul_f32_e32 v50, s12, v50
	v_mul_f32_e32 v51, s12, v51
	v_mfma_f32_16x16x32_bf16 v[70:73], v[156:159], v[136:139], v[70:73]
	ds_read_b128 v[172:175], v225 offset:2048
	v_mul_f32_e32 v52, s12, v52
	v_mul_f32_e32 v53, s12, v53
	v_mfma_f32_16x16x32_bf16 v[74:77], v[160:163], v[136:139], v[74:77]
	ds_read_b128 v[176:179], v225 offset:4096
	v_mul_f32_e32 v54, s12, v54
	v_mul_f32_e32 v55, s12, v55
	v_mfma_f32_16x16x32_bf16 v[78:81], v[164:167], v[136:139], v[78:81]
	ds_read_b128 v[180:183], v225 offset:6144
	v_mul_f32_e32 v56, s12, v56
	v_mul_f32_e32 v57, s12, v57
	v_exp_f32_e32 v50, v50
	v_mfma_f32_16x16x32_bf16 v[82:85], v[152:155], v[140:143], v[82:85]
	ds_read_b128 v[184:187], v233 offset:0
	v_exp_f32_e32 v51, v51
	v_exp_f32_e32 v52, v52
	v_mfma_f32_16x16x32_bf16 v[86:89], v[156:159], v[140:143], v[86:89]
	ds_read_b128 v[188:191], v233 offset:2048
	v_exp_f32_e32 v53, v53
	v_exp_f32_e32 v54, v54
	v_mfma_f32_16x16x32_bf16 v[90:93], v[160:163], v[140:143], v[90:93]
	ds_read_b128 v[192:195], v233 offset:4096
	v_exp_f32_e32 v55, v55
	v_exp_f32_e32 v56, v56
	v_exp_f32_e32 v57, v57
	v_mfma_f32_16x16x32_bf16 v[94:97], v[164:167], v[140:143], v[94:97]
	ds_read_b128 v[196:199], v233 offset:6144
	v_add_f32_e32 v50, 1.0, v50
	v_add_f32_e32 v51, 1.0, v51
	v_mfma_f32_16x16x32_bf16 v[98:101], v[152:155], v[144:147], v[98:101]
	v_add_f32_e32 v52, 1.0, v52
	v_add_f32_e32 v53, 1.0, v53
	v_mfma_f32_16x16x32_bf16 v[102:105], v[156:159], v[144:147], v[102:105]
	v_add_f32_e32 v54, 1.0, v54
	v_add_f32_e32 v55, 1.0, v55
	v_add_f32_e32 v56, 1.0, v56
	v_mfma_f32_16x16x32_bf16 v[106:109], v[160:163], v[144:147], v[106:109]
	v_add_f32_e32 v57, 1.0, v57
	v_rcp_f32_e32 v50, v50
	v_mfma_f32_16x16x32_bf16 v[110:113], v[164:167], v[144:147], v[110:113]
	v_rcp_f32_e32 v51, v51
	v_rcp_f32_e32 v52, v52
	v_mfma_f32_16x16x32_bf16 v[114:117], v[152:155], v[148:151], v[114:117]
	v_rcp_f32_e32 v53, v53
	v_rcp_f32_e32 v54, v54
	v_rcp_f32_e32 v55, v55
	v_mfma_f32_16x16x32_bf16 v[118:121], v[156:159], v[148:151], v[118:121]
	v_rcp_f32_e32 v56, v56
	v_rcp_f32_e32 v57, v57
	v_mfma_f32_16x16x32_bf16 v[122:125], v[160:163], v[148:151], v[122:125]
	v_cvt_pk_bf16_f32 v50, v50, v51
	v_cvt_pk_bf16_f32 v51, v52, v53
	v_mfma_f32_16x16x32_bf16 v[126:129], v[164:167], v[148:151], v[126:129]
	v_cvt_pk_bf16_f32 v52, v54, v55
	v_cvt_pk_bf16_f32 v53, v56, v57
	global_store_dwordx4 v241, v[50:53], s[10:11] offset:2048
	s_waitcnt lgkmcnt(0)
	s_barrier
	v_mfma_f32_16x16x32_bf16 v[66:69], v[184:187], v[168:171], v[66:69]
	ds_read_b128 v[136:139], v219 offset:0
	v_mul_f32_e32 v58, s12, v58
	v_mul_f32_e32 v59, s12, v59
	v_mfma_f32_16x16x32_bf16 v[70:73], v[188:191], v[168:171], v[70:73]
	ds_read_b128 v[140:143], v219 offset:2048
	v_mul_f32_e32 v60, s12, v60
	v_mul_f32_e32 v61, s12, v61
	v_mfma_f32_16x16x32_bf16 v[74:77], v[192:195], v[168:171], v[74:77]
	ds_read_b128 v[144:147], v219 offset:4096
	v_mul_f32_e32 v62, s12, v62
	v_mul_f32_e32 v63, s12, v63
	v_mfma_f32_16x16x32_bf16 v[78:81], v[196:199], v[168:171], v[78:81]
	ds_read_b128 v[148:151], v219 offset:6144
	v_mul_f32_e32 v64, s12, v64
	v_mul_f32_e32 v65, s12, v65
	v_exp_f32_e32 v58, v58
	v_mfma_f32_16x16x32_bf16 v[82:85], v[184:187], v[172:175], v[82:85]
	ds_read_b128 v[152:155], v231 offset:0
	v_exp_f32_e32 v59, v59
	v_exp_f32_e32 v60, v60
	v_mfma_f32_16x16x32_bf16 v[86:89], v[188:191], v[172:175], v[86:89]
	ds_read_b128 v[156:159], v231 offset:2048
	v_exp_f32_e32 v61, v61
	v_exp_f32_e32 v62, v62
	v_mfma_f32_16x16x32_bf16 v[90:93], v[192:195], v[172:175], v[90:93]
	ds_read_b128 v[160:163], v231 offset:4096
	v_exp_f32_e32 v63, v63
	v_exp_f32_e32 v64, v64
	v_exp_f32_e32 v65, v65
	v_mfma_f32_16x16x32_bf16 v[94:97], v[196:199], v[172:175], v[94:97]
	ds_read_b128 v[164:167], v231 offset:6144
	v_add_f32_e32 v58, 1.0, v58
	v_add_f32_e32 v59, 1.0, v59
	v_mfma_f32_16x16x32_bf16 v[98:101], v[184:187], v[176:179], v[98:101]
	v_add_f32_e32 v60, 1.0, v60
	v_add_f32_e32 v61, 1.0, v61
	v_mfma_f32_16x16x32_bf16 v[102:105], v[188:191], v[176:179], v[102:105]
	v_add_f32_e32 v62, 1.0, v62
	v_add_f32_e32 v63, 1.0, v63
	v_add_f32_e32 v64, 1.0, v64
	v_mfma_f32_16x16x32_bf16 v[106:109], v[192:195], v[176:179], v[106:109]
	v_add_f32_e32 v65, 1.0, v65
	v_rcp_f32_e32 v58, v58
	v_mfma_f32_16x16x32_bf16 v[110:113], v[196:199], v[176:179], v[110:113]
	v_rcp_f32_e32 v59, v59
	v_rcp_f32_e32 v60, v60
	v_mfma_f32_16x16x32_bf16 v[114:117], v[184:187], v[180:183], v[114:117]
	v_rcp_f32_e32 v61, v61
	v_rcp_f32_e32 v62, v62
	v_rcp_f32_e32 v63, v63
	v_mfma_f32_16x16x32_bf16 v[118:121], v[188:191], v[180:183], v[118:121]
	v_rcp_f32_e32 v64, v64
	v_rcp_f32_e32 v65, v65
	v_mfma_f32_16x16x32_bf16 v[122:125], v[192:195], v[180:183], v[122:125]
	v_cvt_pk_bf16_f32 v58, v58, v59
	v_cvt_pk_bf16_f32 v59, v60, v61
	v_mfma_f32_16x16x32_bf16 v[126:129], v[196:199], v[180:183], v[126:129]
	v_cvt_pk_bf16_f32 v60, v62, v63
	v_cvt_pk_bf16_f32 v61, v64, v65
	global_store_dwordx4 v241, v[58:61], s[10:11] offset:2064
	s_waitcnt lgkmcnt(0)
	v_mfma_f32_16x16x32_bf16 v[66:69], v[152:155], v[136:139], v[66:69]
	ds_read_b128 v[168:171], v228 offset:0
	v_mfma_f32_16x16x32_bf16 v[70:73], v[156:159], v[136:139], v[70:73]
	ds_read_b128 v[172:175], v228 offset:2048
	v_mfma_f32_16x16x32_bf16 v[74:77], v[160:163], v[136:139], v[74:77]
	ds_read_b128 v[176:179], v228 offset:4096
	v_mfma_f32_16x16x32_bf16 v[78:81], v[164:167], v[136:139], v[78:81]
	ds_read_b128 v[180:183], v228 offset:6144
	v_mfma_f32_16x16x32_bf16 v[82:85], v[152:155], v[140:143], v[82:85]
	ds_read_b128 v[184:187], v234 offset:0
	v_mfma_f32_16x16x32_bf16 v[86:89], v[156:159], v[140:143], v[86:89]
	ds_read_b128 v[188:191], v234 offset:2048
	v_mfma_f32_16x16x32_bf16 v[90:93], v[160:163], v[140:143], v[90:93]
	ds_read_b128 v[192:195], v234 offset:4096
	v_mfma_f32_16x16x32_bf16 v[94:97], v[164:167], v[140:143], v[94:97]
	ds_read_b128 v[196:199], v234 offset:6144
	v_mfma_f32_16x16x32_bf16 v[98:101], v[152:155], v[144:147], v[98:101]
	v_mfma_f32_16x16x32_bf16 v[102:105], v[156:159], v[144:147], v[102:105]
	v_mfma_f32_16x16x32_bf16 v[106:109], v[160:163], v[144:147], v[106:109]
	v_mfma_f32_16x16x32_bf16 v[110:113], v[164:167], v[144:147], v[110:113]
	v_mfma_f32_16x16x32_bf16 v[114:117], v[152:155], v[148:151], v[114:117]
	v_mfma_f32_16x16x32_bf16 v[118:121], v[156:159], v[148:151], v[118:121]
	v_mfma_f32_16x16x32_bf16 v[122:125], v[160:163], v[148:151], v[122:125]
	v_mfma_f32_16x16x32_bf16 v[126:129], v[164:167], v[148:151], v[126:129]
	s_waitcnt lgkmcnt(0)
	s_barrier
	v_mfma_f32_16x16x32_bf16 v[66:69], v[184:187], v[168:171], v[66:69]
	ds_read_b128 v[136:139], v224 offset:0
	v_mfma_f32_16x16x32_bf16 v[70:73], v[188:191], v[168:171], v[70:73]
	ds_read_b128 v[140:143], v224 offset:2048
	v_mfma_f32_16x16x32_bf16 v[74:77], v[192:195], v[168:171], v[74:77]
	ds_read_b128 v[144:147], v224 offset:4096
	v_mfma_f32_16x16x32_bf16 v[78:81], v[196:199], v[168:171], v[78:81]
	ds_read_b128 v[148:151], v224 offset:6144
	v_mfma_f32_16x16x32_bf16 v[82:85], v[184:187], v[172:175], v[82:85]
	ds_read_b128 v[152:155], v232 offset:0
	v_mfma_f32_16x16x32_bf16 v[86:89], v[188:191], v[172:175], v[86:89]
	ds_read_b128 v[156:159], v232 offset:2048
	v_mfma_f32_16x16x32_bf16 v[90:93], v[192:195], v[172:175], v[90:93]
	ds_read_b128 v[160:163], v232 offset:4096
	v_mfma_f32_16x16x32_bf16 v[94:97], v[196:199], v[172:175], v[94:97]
	ds_read_b128 v[164:167], v232 offset:6144
	v_mfma_f32_16x16x32_bf16 v[98:101], v[184:187], v[176:179], v[98:101]
	v_mfma_f32_16x16x32_bf16 v[102:105], v[188:191], v[176:179], v[102:105]
	v_mfma_f32_16x16x32_bf16 v[106:109], v[192:195], v[176:179], v[106:109]
	v_mfma_f32_16x16x32_bf16 v[110:113], v[196:199], v[176:179], v[110:113]
	v_mfma_f32_16x16x32_bf16 v[114:117], v[184:187], v[180:183], v[114:117]
	v_mfma_f32_16x16x32_bf16 v[118:121], v[188:191], v[180:183], v[118:121]
	v_mfma_f32_16x16x32_bf16 v[122:125], v[192:195], v[180:183], v[122:125]
	v_mfma_f32_16x16x32_bf16 v[126:129], v[196:199], v[180:183], v[126:129]
	s_waitcnt lgkmcnt(0)
	v_mfma_f32_16x16x32_bf16 v[66:69], v[152:155], v[136:139], v[66:69]
	ds_read_b128 v[168:171], v229 offset:0
	v_mfma_f32_16x16x32_bf16 v[70:73], v[156:159], v[136:139], v[70:73]
	ds_read_b128 v[172:175], v229 offset:2048
	v_mfma_f32_16x16x32_bf16 v[74:77], v[160:163], v[136:139], v[74:77]
	ds_read_b128 v[176:179], v229 offset:4096
	v_mfma_f32_16x16x32_bf16 v[78:81], v[164:167], v[136:139], v[78:81]
	ds_read_b128 v[180:183], v229 offset:6144
	v_mfma_f32_16x16x32_bf16 v[82:85], v[152:155], v[140:143], v[82:85]
	ds_read_b128 v[184:187], v235 offset:0
	v_mfma_f32_16x16x32_bf16 v[86:89], v[156:159], v[140:143], v[86:89]
	ds_read_b128 v[188:191], v235 offset:2048
	v_mfma_f32_16x16x32_bf16 v[90:93], v[160:163], v[140:143], v[90:93]
	ds_read_b128 v[192:195], v235 offset:4096
	v_mfma_f32_16x16x32_bf16 v[94:97], v[164:167], v[140:143], v[94:97]
	ds_read_b128 v[196:199], v235 offset:6144
	v_mfma_f32_16x16x32_bf16 v[98:101], v[152:155], v[144:147], v[98:101]
	v_mfma_f32_16x16x32_bf16 v[102:105], v[156:159], v[144:147], v[102:105]
	v_mfma_f32_16x16x32_bf16 v[106:109], v[160:163], v[144:147], v[106:109]
	v_mfma_f32_16x16x32_bf16 v[110:113], v[164:167], v[144:147], v[110:113]
	v_mfma_f32_16x16x32_bf16 v[114:117], v[152:155], v[148:151], v[114:117]
	v_mfma_f32_16x16x32_bf16 v[118:121], v[156:159], v[148:151], v[118:121]
	v_mfma_f32_16x16x32_bf16 v[122:125], v[160:163], v[148:151], v[122:125]
	v_mfma_f32_16x16x32_bf16 v[126:129], v[164:167], v[148:151], v[126:129]
	s_waitcnt lgkmcnt(0)
	s_barrier
	v_mfma_f32_16x16x32_bf16 v[66:69], v[184:187], v[168:171], v[66:69]
	ds_read_b128 v[136:139], v218 offset:0
	v_mfma_f32_16x16x32_bf16 v[70:73], v[188:191], v[168:171], v[70:73]
	ds_read_b128 v[140:143], v218 offset:2048
	v_mfma_f32_16x16x32_bf16 v[74:77], v[192:195], v[168:171], v[74:77]
	ds_read_b128 v[144:147], v218 offset:4096
	v_mfma_f32_16x16x32_bf16 v[78:81], v[196:199], v[168:171], v[78:81]
	ds_read_b128 v[148:151], v218 offset:6144
	v_mfma_f32_16x16x32_bf16 v[82:85], v[184:187], v[172:175], v[82:85]
	ds_read_b128 v[152:155], v230 offset:0
	v_mfma_f32_16x16x32_bf16 v[86:89], v[188:191], v[172:175], v[86:89]
	ds_read_b128 v[156:159], v230 offset:2048
	v_mfma_f32_16x16x32_bf16 v[90:93], v[192:195], v[172:175], v[90:93]
	ds_read_b128 v[160:163], v230 offset:4096
	v_mfma_f32_16x16x32_bf16 v[94:97], v[196:199], v[172:175], v[94:97]
	ds_read_b128 v[164:167], v230 offset:6144
	v_mfma_f32_16x16x32_bf16 v[98:101], v[184:187], v[176:179], v[98:101]
	v_mfma_f32_16x16x32_bf16 v[102:105], v[188:191], v[176:179], v[102:105]
	v_mfma_f32_16x16x32_bf16 v[106:109], v[192:195], v[176:179], v[106:109]
	v_mfma_f32_16x16x32_bf16 v[110:113], v[196:199], v[176:179], v[110:113]
	v_mfma_f32_16x16x32_bf16 v[114:117], v[184:187], v[180:183], v[114:117]
	v_mfma_f32_16x16x32_bf16 v[118:121], v[188:191], v[180:183], v[118:121]
	v_mfma_f32_16x16x32_bf16 v[122:125], v[192:195], v[180:183], v[122:125]
	v_mfma_f32_16x16x32_bf16 v[126:129], v[196:199], v[180:183], v[126:129]
	s_waitcnt lgkmcnt(0)
	v_mfma_f32_16x16x32_bf16 v[66:69], v[152:155], v[136:139], v[66:69]
	ds_read_b128 v[168:171], v225 offset:0
	v_mfma_f32_16x16x32_bf16 v[70:73], v[156:159], v[136:139], v[70:73]
	ds_read_b128 v[172:175], v225 offset:2048
	v_mfma_f32_16x16x32_bf16 v[74:77], v[160:163], v[136:139], v[74:77]
	ds_read_b128 v[176:179], v225 offset:4096
	v_mfma_f32_16x16x32_bf16 v[78:81], v[164:167], v[136:139], v[78:81]
	ds_read_b128 v[180:183], v225 offset:6144
	v_mfma_f32_16x16x32_bf16 v[82:85], v[152:155], v[140:143], v[82:85]
	ds_read_b128 v[184:187], v233 offset:0
	v_mfma_f32_16x16x32_bf16 v[86:89], v[156:159], v[140:143], v[86:89]
	ds_read_b128 v[188:191], v233 offset:2048
	v_mfma_f32_16x16x32_bf16 v[90:93], v[160:163], v[140:143], v[90:93]
	ds_read_b128 v[192:195], v233 offset:4096
	v_mfma_f32_16x16x32_bf16 v[94:97], v[164:167], v[140:143], v[94:97]
	ds_read_b128 v[196:199], v233 offset:6144
	v_mfma_f32_16x16x32_bf16 v[98:101], v[152:155], v[144:147], v[98:101]
	v_mfma_f32_16x16x32_bf16 v[102:105], v[156:159], v[144:147], v[102:105]
	v_mfma_f32_16x16x32_bf16 v[106:109], v[160:163], v[144:147], v[106:109]
	v_mfma_f32_16x16x32_bf16 v[110:113], v[164:167], v[144:147], v[110:113]
	v_mfma_f32_16x16x32_bf16 v[114:117], v[152:155], v[148:151], v[114:117]
	v_mfma_f32_16x16x32_bf16 v[118:121], v[156:159], v[148:151], v[118:121]
	v_mfma_f32_16x16x32_bf16 v[122:125], v[160:163], v[148:151], v[122:125]
	v_mfma_f32_16x16x32_bf16 v[126:129], v[164:167], v[148:151], v[126:129]
	s_waitcnt lgkmcnt(0)
	s_barrier
	v_mfma_f32_16x16x32_bf16 v[66:69], v[184:187], v[168:171], v[66:69]
	ds_read_b128 v[136:139], v219 offset:0
	v_mfma_f32_16x16x32_bf16 v[70:73], v[188:191], v[168:171], v[70:73]
	ds_read_b128 v[140:143], v219 offset:2048
	v_mfma_f32_16x16x32_bf16 v[74:77], v[192:195], v[168:171], v[74:77]
	ds_read_b128 v[144:147], v219 offset:4096
	v_mfma_f32_16x16x32_bf16 v[78:81], v[196:199], v[168:171], v[78:81]
	ds_read_b128 v[148:151], v219 offset:6144
	v_mfma_f32_16x16x32_bf16 v[82:85], v[184:187], v[172:175], v[82:85]
	ds_read_b128 v[152:155], v231 offset:0
	v_mfma_f32_16x16x32_bf16 v[86:89], v[188:191], v[172:175], v[86:89]
	ds_read_b128 v[156:159], v231 offset:2048
	v_mfma_f32_16x16x32_bf16 v[90:93], v[192:195], v[172:175], v[90:93]
	ds_read_b128 v[160:163], v231 offset:4096
	v_mfma_f32_16x16x32_bf16 v[94:97], v[196:199], v[172:175], v[94:97]
	ds_read_b128 v[164:167], v231 offset:6144
	v_mfma_f32_16x16x32_bf16 v[98:101], v[184:187], v[176:179], v[98:101]
	v_mfma_f32_16x16x32_bf16 v[102:105], v[188:191], v[176:179], v[102:105]
	v_mfma_f32_16x16x32_bf16 v[106:109], v[192:195], v[176:179], v[106:109]
	v_mfma_f32_16x16x32_bf16 v[110:113], v[196:199], v[176:179], v[110:113]
	v_mfma_f32_16x16x32_bf16 v[114:117], v[184:187], v[180:183], v[114:117]
	v_mfma_f32_16x16x32_bf16 v[118:121], v[188:191], v[180:183], v[118:121]
	v_mfma_f32_16x16x32_bf16 v[122:125], v[192:195], v[180:183], v[122:125]
	v_mfma_f32_16x16x32_bf16 v[126:129], v[196:199], v[180:183], v[126:129]
	s_waitcnt lgkmcnt(0)
	v_mfma_f32_16x16x32_bf16 v[66:69], v[152:155], v[136:139], v[66:69]
	ds_read_b128 v[168:171], v228 offset:0
	v_mfma_f32_16x16x32_bf16 v[70:73], v[156:159], v[136:139], v[70:73]
	ds_read_b128 v[172:175], v228 offset:2048
	v_mfma_f32_16x16x32_bf16 v[74:77], v[160:163], v[136:139], v[74:77]
	ds_read_b128 v[176:179], v228 offset:4096
	v_mfma_f32_16x16x32_bf16 v[78:81], v[164:167], v[136:139], v[78:81]
	ds_read_b128 v[180:183], v228 offset:6144
	v_mfma_f32_16x16x32_bf16 v[82:85], v[152:155], v[140:143], v[82:85]
	ds_read_b128 v[184:187], v234 offset:0
	v_mfma_f32_16x16x32_bf16 v[86:89], v[156:159], v[140:143], v[86:89]
	ds_read_b128 v[188:191], v234 offset:2048
	v_mfma_f32_16x16x32_bf16 v[90:93], v[160:163], v[140:143], v[90:93]
	ds_read_b128 v[192:195], v234 offset:4096
	v_mfma_f32_16x16x32_bf16 v[94:97], v[164:167], v[140:143], v[94:97]
	ds_read_b128 v[196:199], v234 offset:6144
	v_mfma_f32_16x16x32_bf16 v[98:101], v[152:155], v[144:147], v[98:101]
	v_mfma_f32_16x16x32_bf16 v[102:105], v[156:159], v[144:147], v[102:105]
	v_mfma_f32_16x16x32_bf16 v[106:109], v[160:163], v[144:147], v[106:109]
	v_mfma_f32_16x16x32_bf16 v[110:113], v[164:167], v[144:147], v[110:113]
	v_mfma_f32_16x16x32_bf16 v[114:117], v[152:155], v[148:151], v[114:117]
	v_mfma_f32_16x16x32_bf16 v[118:121], v[156:159], v[148:151], v[118:121]
	v_mfma_f32_16x16x32_bf16 v[122:125], v[160:163], v[148:151], v[122:125]
	v_mfma_f32_16x16x32_bf16 v[126:129], v[164:167], v[148:151], v[126:129]
	s_waitcnt lgkmcnt(0)
	s_barrier
	v_mfma_f32_16x16x32_bf16 v[66:69], v[184:187], v[168:171], v[66:69]
	ds_read_b128 v[136:139], v224 offset:0
	v_mfma_f32_16x16x32_bf16 v[70:73], v[188:191], v[168:171], v[70:73]
	ds_read_b128 v[140:143], v224 offset:2048
	v_mfma_f32_16x16x32_bf16 v[74:77], v[192:195], v[168:171], v[74:77]
	ds_read_b128 v[144:147], v224 offset:4096
	v_mfma_f32_16x16x32_bf16 v[78:81], v[196:199], v[168:171], v[78:81]
	ds_read_b128 v[148:151], v224 offset:6144
	v_mfma_f32_16x16x32_bf16 v[82:85], v[184:187], v[172:175], v[82:85]
	ds_read_b128 v[152:155], v232 offset:0
	v_mfma_f32_16x16x32_bf16 v[86:89], v[188:191], v[172:175], v[86:89]
	ds_read_b128 v[156:159], v232 offset:2048
	v_mfma_f32_16x16x32_bf16 v[90:93], v[192:195], v[172:175], v[90:93]
	ds_read_b128 v[160:163], v232 offset:4096
	v_mfma_f32_16x16x32_bf16 v[94:97], v[196:199], v[172:175], v[94:97]
	ds_read_b128 v[164:167], v232 offset:6144
	v_mfma_f32_16x16x32_bf16 v[98:101], v[184:187], v[176:179], v[98:101]
	v_mfma_f32_16x16x32_bf16 v[102:105], v[188:191], v[176:179], v[102:105]
	v_mfma_f32_16x16x32_bf16 v[106:109], v[192:195], v[176:179], v[106:109]
	v_mfma_f32_16x16x32_bf16 v[110:113], v[196:199], v[176:179], v[110:113]
	v_mfma_f32_16x16x32_bf16 v[114:117], v[184:187], v[180:183], v[114:117]
	v_mfma_f32_16x16x32_bf16 v[118:121], v[188:191], v[180:183], v[118:121]
	v_mfma_f32_16x16x32_bf16 v[122:125], v[192:195], v[180:183], v[122:125]
	v_mfma_f32_16x16x32_bf16 v[126:129], v[196:199], v[180:183], v[126:129]
	s_waitcnt lgkmcnt(0)
	v_mfma_f32_16x16x32_bf16 v[2:5], v[152:155], v[136:139], 0
	ds_read_b128 v[168:171], v229 offset:0
	v_mfma_f32_16x16x32_bf16 v[6:9], v[156:159], v[136:139], 0
	ds_read_b128 v[172:175], v229 offset:2048
	v_mfma_f32_16x16x32_bf16 v[10:13], v[160:163], v[136:139], 0
	ds_read_b128 v[176:179], v229 offset:4096
	v_mfma_f32_16x16x32_bf16 v[14:17], v[164:167], v[136:139], 0
	ds_read_b128 v[180:183], v229 offset:6144
	v_mfma_f32_16x16x32_bf16 v[18:21], v[152:155], v[140:143], 0
	ds_read_b128 v[184:187], v235 offset:0
	v_mfma_f32_16x16x32_bf16 v[22:25], v[156:159], v[140:143], 0
	ds_read_b128 v[188:191], v235 offset:2048
	v_mfma_f32_16x16x32_bf16 v[26:29], v[160:163], v[140:143], 0
	ds_read_b128 v[192:195], v235 offset:4096
	v_mfma_f32_16x16x32_bf16 v[30:33], v[164:167], v[140:143], 0
	ds_read_b128 v[196:199], v235 offset:6144
	v_mfma_f32_16x16x32_bf16 v[34:37], v[152:155], v[144:147], 0
	v_mfma_f32_16x16x32_bf16 v[38:41], v[156:159], v[144:147], 0
	v_mfma_f32_16x16x32_bf16 v[42:45], v[160:163], v[144:147], 0
	v_mfma_f32_16x16x32_bf16 v[46:49], v[164:167], v[144:147], 0
	v_mfma_f32_16x16x32_bf16 v[50:53], v[152:155], v[148:151], 0
	v_mfma_f32_16x16x32_bf16 v[54:57], v[156:159], v[148:151], 0
	v_mfma_f32_16x16x32_bf16 v[58:61], v[160:163], v[148:151], 0
	v_mfma_f32_16x16x32_bf16 v[62:65], v[164:167], v[148:151], 0
	s_waitcnt lgkmcnt(0)
	s_barrier
	s_add_u32 s14, s4, 0x180
	s_addc_u32 s15, s5, 0
	v_mfma_f32_16x16x32_bf16 v[2:5], v[184:187], v[168:171], v[2:5]
	ds_read_b128 v[136:139], v218 offset:0
	s_add_u32 s22, s4, 0x10180
	s_addc_u32 s23, s5, 0
	v_mfma_f32_16x16x32_bf16 v[6:9], v[188:191], v[168:171], v[6:9]
	ds_read_b128 v[140:143], v218 offset:2048
	s_add_u32 s24, s6, 0x80180
	s_addc_u32 s25, s7, 0
	v_mfma_f32_16x16x32_bf16 v[10:13], v[192:195], v[168:171], v[10:13]
	ds_read_b128 v[144:147], v218 offset:4096
	s_add_u32 s52, s6, 0x88180
	s_addc_u32 s53, s7, 0
	v_mfma_f32_16x16x32_bf16 v[14:17], v[196:199], v[168:171], v[14:17]
	ds_read_b128 v[148:151], v218 offset:6144
	s_add_u32 m0, s8, 0x18000
	v_mfma_f32_16x16x32_bf16 v[18:21], v[184:187], v[172:175], v[18:21]
	global_load_lds_dwordx4 v200, s[14:15]
	ds_read_b128 v[152:155], v230 offset:0
	s_add_u32 m0, s8, 0x18400
	v_mfma_f32_16x16x32_bf16 v[22:25], v[188:191], v[172:175], v[22:25]
	global_load_lds_dwordx4 v201, s[14:15]
	ds_read_b128 v[156:159], v230 offset:2048
	s_add_u32 m0, s8, 0x18800
	v_mfma_f32_16x16x32_bf16 v[26:29], v[192:195], v[172:175], v[26:29]
	global_load_lds_dwordx4 v202, s[14:15]
	ds_read_b128 v[160:163], v230 offset:4096
	s_add_u32 m0, s8, 0x18c00
	v_mfma_f32_16x16x32_bf16 v[30:33], v[196:199], v[172:175], v[30:33]
	global_load_lds_dwordx4 v203, s[14:15]
	ds_read_b128 v[164:167], v230 offset:6144
	s_add_u32 m0, s8, 0x19000
	v_mfma_f32_16x16x32_bf16 v[34:37], v[184:187], v[176:179], v[34:37]
	global_load_lds_dwordx4 v200, s[22:23]
	s_add_u32 m0, s8, 0x19400
	v_mfma_f32_16x16x32_bf16 v[38:41], v[188:191], v[176:179], v[38:41]
	global_load_lds_dwordx4 v201, s[22:23]
	s_add_u32 m0, s8, 0x19800
	v_mfma_f32_16x16x32_bf16 v[42:45], v[192:195], v[176:179], v[42:45]
	global_load_lds_dwordx4 v202, s[22:23]
	s_add_u32 m0, s8, 0x19c00
	v_mfma_f32_16x16x32_bf16 v[46:49], v[196:199], v[176:179], v[46:49]
	global_load_lds_dwordx4 v203, s[22:23]
	s_add_u32 m0, s9, 0x18000
	v_mfma_f32_16x16x32_bf16 v[50:53], v[184:187], v[180:183], v[50:53]
	global_load_lds_dwordx4 v204, s[24:25]
	s_add_u32 m0, s9, 0x18400
	v_mfma_f32_16x16x32_bf16 v[54:57], v[188:191], v[180:183], v[54:57]
	global_load_lds_dwordx4 v205, s[24:25]
	s_add_u32 m0, s9, 0x18800
	v_mfma_f32_16x16x32_bf16 v[58:61], v[192:195], v[180:183], v[58:61]
	global_load_lds_dwordx4 v204, s[52:53]
	s_add_u32 m0, s9, 0x18c00
	v_mfma_f32_16x16x32_bf16 v[62:65], v[196:199], v[180:183], v[62:65]
	global_load_lds_dwordx4 v205, s[52:53]
	s_waitcnt lgkmcnt(0)
	v_mfma_f32_16x16x32_bf16 v[2:5], v[152:155], v[136:139], v[2:5]
	ds_read_b128 v[168:171], v225 offset:0
	v_mfma_f32_16x16x32_bf16 v[6:9], v[156:159], v[136:139], v[6:9]
	ds_read_b128 v[172:175], v225 offset:2048
	v_mfma_f32_16x16x32_bf16 v[10:13], v[160:163], v[136:139], v[10:13]
	ds_read_b128 v[176:179], v225 offset:4096
	v_mfma_f32_16x16x32_bf16 v[14:17], v[164:167], v[136:139], v[14:17]
	ds_read_b128 v[180:183], v225 offset:6144
	v_mfma_f32_16x16x32_bf16 v[18:21], v[152:155], v[140:143], v[18:21]
	ds_read_b128 v[184:187], v233 offset:0
	v_mfma_f32_16x16x32_bf16 v[22:25], v[156:159], v[140:143], v[22:25]
	ds_read_b128 v[188:191], v233 offset:2048
	v_mfma_f32_16x16x32_bf16 v[26:29], v[160:163], v[140:143], v[26:29]
	ds_read_b128 v[192:195], v233 offset:4096
	v_mfma_f32_16x16x32_bf16 v[30:33], v[164:167], v[140:143], v[30:33]
	ds_read_b128 v[196:199], v233 offset:6144
	v_mfma_f32_16x16x32_bf16 v[34:37], v[152:155], v[144:147], v[34:37]
	v_mfma_f32_16x16x32_bf16 v[38:41], v[156:159], v[144:147], v[38:41]
	v_mfma_f32_16x16x32_bf16 v[42:45], v[160:163], v[144:147], v[42:45]
	v_mfma_f32_16x16x32_bf16 v[46:49], v[164:167], v[144:147], v[46:49]
	v_mfma_f32_16x16x32_bf16 v[50:53], v[152:155], v[148:151], v[50:53]
	v_mfma_f32_16x16x32_bf16 v[54:57], v[156:159], v[148:151], v[54:57]
	v_mfma_f32_16x16x32_bf16 v[58:61], v[160:163], v[148:151], v[58:61]
	v_mfma_f32_16x16x32_bf16 v[62:65], v[164:167], v[148:151], v[62:65]
	s_waitcnt lgkmcnt(0)
	s_barrier
	s_add_u32 s14, s4, 0x200
	s_addc_u32 s15, s5, 0
	v_mfma_f32_16x16x32_bf16 v[2:5], v[184:187], v[168:171], v[2:5]
	ds_read_b128 v[136:139], v219 offset:0
	s_add_u32 s22, s4, 0x10200
	s_addc_u32 s23, s5, 0
	v_mfma_f32_16x16x32_bf16 v[6:9], v[188:191], v[168:171], v[6:9]
	ds_read_b128 v[140:143], v219 offset:2048
	s_add_u32 s24, s6, 0x80200
	s_addc_u32 s25, s7, 0
	v_mfma_f32_16x16x32_bf16 v[10:13], v[192:195], v[168:171], v[10:13]
	ds_read_b128 v[144:147], v219 offset:4096
	s_add_u32 s52, s6, 0x88200
	s_addc_u32 s53, s7, 0
	v_mfma_f32_16x16x32_bf16 v[14:17], v[196:199], v[168:171], v[14:17]
	ds_read_b128 v[148:151], v219 offset:6144
	s_mov_b32 m0, s8
	v_mfma_f32_16x16x32_bf16 v[18:21], v[184:187], v[172:175], v[18:21]
	global_load_lds_dwordx4 v200, s[14:15]
	ds_read_b128 v[152:155], v231 offset:0
	s_add_u32 m0, s8, 0x400
	v_mfma_f32_16x16x32_bf16 v[22:25], v[188:191], v[172:175], v[22:25]
	global_load_lds_dwordx4 v201, s[14:15]
	ds_read_b128 v[156:159], v231 offset:2048
	s_add_u32 m0, s8, 0x800
	v_mfma_f32_16x16x32_bf16 v[26:29], v[192:195], v[172:175], v[26:29]
	global_load_lds_dwordx4 v202, s[14:15]
	ds_read_b128 v[160:163], v231 offset:4096
	s_add_u32 m0, s8, 0xc00
	v_mfma_f32_16x16x32_bf16 v[30:33], v[196:199], v[172:175], v[30:33]
	global_load_lds_dwordx4 v203, s[14:15]
	ds_read_b128 v[164:167], v231 offset:6144
	s_add_u32 m0, s8, 0x1000
	v_mfma_f32_16x16x32_bf16 v[34:37], v[184:187], v[176:179], v[34:37]
	global_load_lds_dwordx4 v200, s[22:23]
	s_add_u32 m0, s8, 0x1400
	v_mfma_f32_16x16x32_bf16 v[38:41], v[188:191], v[176:179], v[38:41]
	global_load_lds_dwordx4 v201, s[22:23]
	s_add_u32 m0, s8, 0x1800
	v_mfma_f32_16x16x32_bf16 v[42:45], v[192:195], v[176:179], v[42:45]
	global_load_lds_dwordx4 v202, s[22:23]
	s_add_u32 m0, s8, 0x1c00
	v_mfma_f32_16x16x32_bf16 v[46:49], v[196:199], v[176:179], v[46:49]
	global_load_lds_dwordx4 v203, s[22:23]
	s_mov_b32 m0, s9
	v_mfma_f32_16x16x32_bf16 v[50:53], v[184:187], v[180:183], v[50:53]
	global_load_lds_dwordx4 v204, s[24:25]
	s_add_u32 m0, s9, 0x400
	v_mfma_f32_16x16x32_bf16 v[54:57], v[188:191], v[180:183], v[54:57]
	global_load_lds_dwordx4 v205, s[24:25]
	s_add_u32 m0, s9, 0x800
	v_mfma_f32_16x16x32_bf16 v[58:61], v[192:195], v[180:183], v[58:61]
	global_load_lds_dwordx4 v204, s[52:53]
	s_add_u32 m0, s9, 0xc00
	v_mfma_f32_16x16x32_bf16 v[62:65], v[196:199], v[180:183], v[62:65]
	global_load_lds_dwordx4 v205, s[52:53]
	s_waitcnt lgkmcnt(0)
	v_mfma_f32_16x16x32_bf16 v[2:5], v[152:155], v[136:139], v[2:5]
	ds_read_b128 v[168:171], v228 offset:0
	v_mfma_f32_16x16x32_bf16 v[6:9], v[156:159], v[136:139], v[6:9]
	ds_read_b128 v[172:175], v228 offset:2048
	v_mfma_f32_16x16x32_bf16 v[10:13], v[160:163], v[136:139], v[10:13]
	ds_read_b128 v[176:179], v228 offset:4096
	v_mfma_f32_16x16x32_bf16 v[14:17], v[164:167], v[136:139], v[14:17]
	ds_read_b128 v[180:183], v228 offset:6144
	v_mfma_f32_16x16x32_bf16 v[18:21], v[152:155], v[140:143], v[18:21]
	ds_read_b128 v[184:187], v234 offset:0
	v_mfma_f32_16x16x32_bf16 v[22:25], v[156:159], v[140:143], v[22:25]
	ds_read_b128 v[188:191], v234 offset:2048
	v_mfma_f32_16x16x32_bf16 v[26:29], v[160:163], v[140:143], v[26:29]
	ds_read_b128 v[192:195], v234 offset:4096
	v_mfma_f32_16x16x32_bf16 v[30:33], v[164:167], v[140:143], v[30:33]
	ds_read_b128 v[196:199], v234 offset:6144
	v_mfma_f32_16x16x32_bf16 v[34:37], v[152:155], v[144:147], v[34:37]
	v_mfma_f32_16x16x32_bf16 v[38:41], v[156:159], v[144:147], v[38:41]
	v_mfma_f32_16x16x32_bf16 v[42:45], v[160:163], v[144:147], v[42:45]
	v_mfma_f32_16x16x32_bf16 v[46:49], v[164:167], v[144:147], v[46:49]
	v_mfma_f32_16x16x32_bf16 v[50:53], v[152:155], v[148:151], v[50:53]
	v_mfma_f32_16x16x32_bf16 v[54:57], v[156:159], v[148:151], v[54:57]
	v_mfma_f32_16x16x32_bf16 v[58:61], v[160:163], v[148:151], v[58:61]
	v_mfma_f32_16x16x32_bf16 v[62:65], v[164:167], v[148:151], v[62:65]
	s_waitcnt vmcnt(12) lgkmcnt(0)
	s_barrier
	s_add_u32 s14, s4, 0x280
	s_addc_u32 s15, s5, 0
	v_mfma_f32_16x16x32_bf16 v[2:5], v[184:187], v[168:171], v[2:5]
	ds_read_b128 v[136:139], v224 offset:0
	s_add_u32 s22, s4, 0x10280
	s_addc_u32 s23, s5, 0
	v_mfma_f32_16x16x32_bf16 v[6:9], v[188:191], v[168:171], v[6:9]
	ds_read_b128 v[140:143], v224 offset:2048
	s_add_u32 s24, s6, 0x80280
	s_addc_u32 s25, s7, 0
	v_mfma_f32_16x16x32_bf16 v[10:13], v[192:195], v[168:171], v[10:13]
	ds_read_b128 v[144:147], v224 offset:4096
	s_add_u32 s52, s6, 0x88280
	s_addc_u32 s53, s7, 0
	v_mfma_f32_16x16x32_bf16 v[14:17], v[196:199], v[168:171], v[14:17]
	ds_read_b128 v[148:151], v224 offset:6144
	s_add_u32 m0, s8, 0xc000
	v_mfma_f32_16x16x32_bf16 v[18:21], v[184:187], v[172:175], v[18:21]
	global_load_lds_dwordx4 v200, s[14:15]
	ds_read_b128 v[152:155], v232 offset:0
	s_add_u32 m0, s8, 0xc400
	v_mfma_f32_16x16x32_bf16 v[22:25], v[188:191], v[172:175], v[22:25]
	global_load_lds_dwordx4 v201, s[14:15]
	ds_read_b128 v[156:159], v232 offset:2048
	s_add_u32 m0, s8, 0xc800
	v_mfma_f32_16x16x32_bf16 v[26:29], v[192:195], v[172:175], v[26:29]
	global_load_lds_dwordx4 v202, s[14:15]
	ds_read_b128 v[160:163], v232 offset:4096
	s_add_u32 m0, s8, 0xcc00
	v_mfma_f32_16x16x32_bf16 v[30:33], v[196:199], v[172:175], v[30:33]
	global_load_lds_dwordx4 v203, s[14:15]
	ds_read_b128 v[164:167], v232 offset:6144
	s_add_u32 m0, s8, 0xd000
	v_mfma_f32_16x16x32_bf16 v[34:37], v[184:187], v[176:179], v[34:37]
	global_load_lds_dwordx4 v200, s[22:23]
	s_add_u32 m0, s8, 0xd400
	v_mfma_f32_16x16x32_bf16 v[38:41], v[188:191], v[176:179], v[38:41]
	global_load_lds_dwordx4 v201, s[22:23]
	s_add_u32 m0, s8, 0xd800
	v_mfma_f32_16x16x32_bf16 v[42:45], v[192:195], v[176:179], v[42:45]
	global_load_lds_dwordx4 v202, s[22:23]
	s_add_u32 m0, s8, 0xdc00
	v_mfma_f32_16x16x32_bf16 v[46:49], v[196:199], v[176:179], v[46:49]
	global_load_lds_dwordx4 v203, s[22:23]
	s_add_u32 m0, s9, 0xc000
	v_mfma_f32_16x16x32_bf16 v[50:53], v[184:187], v[180:183], v[50:53]
	global_load_lds_dwordx4 v204, s[24:25]
	s_add_u32 m0, s9, 0xc400
	v_mfma_f32_16x16x32_bf16 v[54:57], v[188:191], v[180:183], v[54:57]
	global_load_lds_dwordx4 v205, s[24:25]
	s_add_u32 m0, s9, 0xc800
	v_mfma_f32_16x16x32_bf16 v[58:61], v[192:195], v[180:183], v[58:61]
	global_load_lds_dwordx4 v204, s[52:53]
	s_add_u32 m0, s9, 0xcc00
	v_mfma_f32_16x16x32_bf16 v[62:65], v[196:199], v[180:183], v[62:65]
	global_load_lds_dwordx4 v205, s[52:53]
	s_waitcnt lgkmcnt(0)
	v_mfma_f32_16x16x32_bf16 v[2:5], v[152:155], v[136:139], v[2:5]
	ds_read_b128 v[168:171], v229 offset:0
	v_mfma_f32_16x16x32_bf16 v[6:9], v[156:159], v[136:139], v[6:9]
	ds_read_b128 v[172:175], v229 offset:2048
	v_mfma_f32_16x16x32_bf16 v[10:13], v[160:163], v[136:139], v[10:13]
	ds_read_b128 v[176:179], v229 offset:4096
	v_mfma_f32_16x16x32_bf16 v[14:17], v[164:167], v[136:139], v[14:17]
	ds_read_b128 v[180:183], v229 offset:6144
	v_mfma_f32_16x16x32_bf16 v[18:21], v[152:155], v[140:143], v[18:21]
	ds_read_b128 v[184:187], v235 offset:0
	v_mfma_f32_16x16x32_bf16 v[22:25], v[156:159], v[140:143], v[22:25]
	ds_read_b128 v[188:191], v235 offset:2048
	v_mfma_f32_16x16x32_bf16 v[26:29], v[160:163], v[140:143], v[26:29]
	ds_read_b128 v[192:195], v235 offset:4096
	v_mfma_f32_16x16x32_bf16 v[30:33], v[164:167], v[140:143], v[30:33]
	ds_read_b128 v[196:199], v235 offset:6144
	v_mfma_f32_16x16x32_bf16 v[34:37], v[152:155], v[144:147], v[34:37]
	v_mfma_f32_16x16x32_bf16 v[38:41], v[156:159], v[144:147], v[38:41]
	v_mfma_f32_16x16x32_bf16 v[42:45], v[160:163], v[144:147], v[42:45]
	v_mfma_f32_16x16x32_bf16 v[46:49], v[164:167], v[144:147], v[46:49]
	v_mfma_f32_16x16x32_bf16 v[50:53], v[152:155], v[148:151], v[50:53]
	v_mfma_f32_16x16x32_bf16 v[54:57], v[156:159], v[148:151], v[54:57]
	v_mfma_f32_16x16x32_bf16 v[58:61], v[160:163], v[148:151], v[58:61]
	v_mfma_f32_16x16x32_bf16 v[62:65], v[164:167], v[148:151], v[62:65]
	s_waitcnt vmcnt(12) lgkmcnt(0)
	s_barrier
	s_add_u32 s14, s4, 0x300
	s_addc_u32 s15, s5, 0
	v_mfma_f32_16x16x32_bf16 v[2:5], v[184:187], v[168:171], v[2:5]
	ds_read_b128 v[136:139], v218 offset:0
	s_add_u32 s22, s4, 0x10300
	s_addc_u32 s23, s5, 0
	v_mfma_f32_16x16x32_bf16 v[6:9], v[188:191], v[168:171], v[6:9]
	ds_read_b128 v[140:143], v218 offset:2048
	s_add_u32 s24, s6, 0x80300
	s_addc_u32 s25, s7, 0
	v_mfma_f32_16x16x32_bf16 v[10:13], v[192:195], v[168:171], v[10:13]
	ds_read_b128 v[144:147], v218 offset:4096
	s_add_u32 s52, s6, 0x88300
	s_addc_u32 s53, s7, 0
	v_mfma_f32_16x16x32_bf16 v[14:17], v[196:199], v[168:171], v[14:17]
	ds_read_b128 v[148:151], v218 offset:6144
	s_add_u32 m0, s8, 0x18000
	v_mfma_f32_16x16x32_bf16 v[18:21], v[184:187], v[172:175], v[18:21]
	global_load_lds_dwordx4 v200, s[14:15]
	ds_read_b128 v[152:155], v230 offset:0
	s_add_u32 m0, s8, 0x18400
	v_mfma_f32_16x16x32_bf16 v[22:25], v[188:191], v[172:175], v[22:25]
	global_load_lds_dwordx4 v201, s[14:15]
	ds_read_b128 v[156:159], v230 offset:2048
	s_add_u32 m0, s8, 0x18800
	v_mfma_f32_16x16x32_bf16 v[26:29], v[192:195], v[172:175], v[26:29]
	global_load_lds_dwordx4 v202, s[14:15]
	ds_read_b128 v[160:163], v230 offset:4096
	s_add_u32 m0, s8, 0x18c00
	v_mfma_f32_16x16x32_bf16 v[30:33], v[196:199], v[172:175], v[30:33]
	global_load_lds_dwordx4 v203, s[14:15]
	ds_read_b128 v[164:167], v230 offset:6144
	s_add_u32 m0, s8, 0x19000
	v_mfma_f32_16x16x32_bf16 v[34:37], v[184:187], v[176:179], v[34:37]
	global_load_lds_dwordx4 v200, s[22:23]
	s_add_u32 m0, s8, 0x19400
	v_mfma_f32_16x16x32_bf16 v[38:41], v[188:191], v[176:179], v[38:41]
	global_load_lds_dwordx4 v201, s[22:23]
	s_add_u32 m0, s8, 0x19800
	v_mfma_f32_16x16x32_bf16 v[42:45], v[192:195], v[176:179], v[42:45]
	global_load_lds_dwordx4 v202, s[22:23]
	s_add_u32 m0, s8, 0x19c00
	v_mfma_f32_16x16x32_bf16 v[46:49], v[196:199], v[176:179], v[46:49]
	global_load_lds_dwordx4 v203, s[22:23]
	s_add_u32 m0, s9, 0x18000
	v_mfma_f32_16x16x32_bf16 v[50:53], v[184:187], v[180:183], v[50:53]
	global_load_lds_dwordx4 v204, s[24:25]
	s_add_u32 m0, s9, 0x18400
	v_mfma_f32_16x16x32_bf16 v[54:57], v[188:191], v[180:183], v[54:57]
	global_load_lds_dwordx4 v205, s[24:25]
	s_add_u32 m0, s9, 0x18800
	v_mfma_f32_16x16x32_bf16 v[58:61], v[192:195], v[180:183], v[58:61]
	global_load_lds_dwordx4 v204, s[52:53]
	s_add_u32 m0, s9, 0x18c00
	v_mfma_f32_16x16x32_bf16 v[62:65], v[196:199], v[180:183], v[62:65]
	global_load_lds_dwordx4 v205, s[52:53]
	s_waitcnt lgkmcnt(0)
	v_mfma_f32_16x16x32_bf16 v[2:5], v[152:155], v[136:139], v[2:5]
	ds_read_b128 v[168:171], v225 offset:0
	v_mfma_f32_16x16x32_bf16 v[6:9], v[156:159], v[136:139], v[6:9]
	ds_read_b128 v[172:175], v225 offset:2048
	v_mfma_f32_16x16x32_bf16 v[10:13], v[160:163], v[136:139], v[10:13]
	ds_read_b128 v[176:179], v225 offset:4096
	v_mfma_f32_16x16x32_bf16 v[14:17], v[164:167], v[136:139], v[14:17]
	ds_read_b128 v[180:183], v225 offset:6144
	v_mfma_f32_16x16x32_bf16 v[18:21], v[152:155], v[140:143], v[18:21]
	ds_read_b128 v[184:187], v233 offset:0
	v_mfma_f32_16x16x32_bf16 v[22:25], v[156:159], v[140:143], v[22:25]
	ds_read_b128 v[188:191], v233 offset:2048
	v_mfma_f32_16x16x32_bf16 v[26:29], v[160:163], v[140:143], v[26:29]
	ds_read_b128 v[192:195], v233 offset:4096
	v_mfma_f32_16x16x32_bf16 v[30:33], v[164:167], v[140:143], v[30:33]
	ds_read_b128 v[196:199], v233 offset:6144
	v_mfma_f32_16x16x32_bf16 v[34:37], v[152:155], v[144:147], v[34:37]
	v_mfma_f32_16x16x32_bf16 v[38:41], v[156:159], v[144:147], v[38:41]
	v_mfma_f32_16x16x32_bf16 v[42:45], v[160:163], v[144:147], v[42:45]
	v_mfma_f32_16x16x32_bf16 v[46:49], v[164:167], v[144:147], v[46:49]
	v_mfma_f32_16x16x32_bf16 v[50:53], v[152:155], v[148:151], v[50:53]
	v_mfma_f32_16x16x32_bf16 v[54:57], v[156:159], v[148:151], v[54:57]
	v_mfma_f32_16x16x32_bf16 v[58:61], v[160:163], v[148:151], v[58:61]
	v_mfma_f32_16x16x32_bf16 v[62:65], v[164:167], v[148:151], v[62:65]
	s_waitcnt vmcnt(12) lgkmcnt(0)
	s_barrier
	s_add_u32 s14, s4, 0x380
	s_addc_u32 s15, s5, 0
	v_mfma_f32_16x16x32_bf16 v[2:5], v[184:187], v[168:171], v[2:5]
	ds_read_b128 v[136:139], v219 offset:0
	s_add_u32 s22, s4, 0x10380
	s_addc_u32 s23, s5, 0
	v_mfma_f32_16x16x32_bf16 v[6:9], v[188:191], v[168:171], v[6:9]
	ds_read_b128 v[140:143], v219 offset:2048
	s_add_u32 s24, s6, 0x80380
	s_addc_u32 s25, s7, 0
	v_mfma_f32_16x16x32_bf16 v[10:13], v[192:195], v[168:171], v[10:13]
	ds_read_b128 v[144:147], v219 offset:4096
	s_add_u32 s52, s6, 0x88380
	s_addc_u32 s53, s7, 0
	v_mfma_f32_16x16x32_bf16 v[14:17], v[196:199], v[168:171], v[14:17]
	ds_read_b128 v[148:151], v219 offset:6144
	s_mov_b32 m0, s8
	v_mfma_f32_16x16x32_bf16 v[18:21], v[184:187], v[172:175], v[18:21]
	global_load_lds_dwordx4 v200, s[14:15]
	ds_read_b128 v[152:155], v231 offset:0
	s_add_u32 m0, s8, 0x400
	v_mfma_f32_16x16x32_bf16 v[22:25], v[188:191], v[172:175], v[22:25]
	global_load_lds_dwordx4 v201, s[14:15]
	ds_read_b128 v[156:159], v231 offset:2048
	s_add_u32 m0, s8, 0x800
	v_mfma_f32_16x16x32_bf16 v[26:29], v[192:195], v[172:175], v[26:29]
	global_load_lds_dwordx4 v202, s[14:15]
	ds_read_b128 v[160:163], v231 offset:4096
	s_add_u32 m0, s8, 0xc00
	v_mfma_f32_16x16x32_bf16 v[30:33], v[196:199], v[172:175], v[30:33]
	global_load_lds_dwordx4 v203, s[14:15]
	ds_read_b128 v[164:167], v231 offset:6144
	s_add_u32 m0, s8, 0x1000
	v_mfma_f32_16x16x32_bf16 v[34:37], v[184:187], v[176:179], v[34:37]
	global_load_lds_dwordx4 v200, s[22:23]
	s_add_u32 m0, s8, 0x1400
	v_mfma_f32_16x16x32_bf16 v[38:41], v[188:191], v[176:179], v[38:41]
	global_load_lds_dwordx4 v201, s[22:23]
	s_add_u32 m0, s8, 0x1800
	v_mfma_f32_16x16x32_bf16 v[42:45], v[192:195], v[176:179], v[42:45]
	global_load_lds_dwordx4 v202, s[22:23]
	s_add_u32 m0, s8, 0x1c00
	v_mfma_f32_16x16x32_bf16 v[46:49], v[196:199], v[176:179], v[46:49]
	global_load_lds_dwordx4 v203, s[22:23]
	s_mov_b32 m0, s9
	v_mfma_f32_16x16x32_bf16 v[50:53], v[184:187], v[180:183], v[50:53]
	global_load_lds_dwordx4 v204, s[24:25]
	s_add_u32 m0, s9, 0x400
	v_mfma_f32_16x16x32_bf16 v[54:57], v[188:191], v[180:183], v[54:57]
	global_load_lds_dwordx4 v205, s[24:25]
	s_add_u32 m0, s9, 0x800
	v_mfma_f32_16x16x32_bf16 v[58:61], v[192:195], v[180:183], v[58:61]
	global_load_lds_dwordx4 v204, s[52:53]
	s_add_u32 m0, s9, 0xc00
	v_mfma_f32_16x16x32_bf16 v[62:65], v[196:199], v[180:183], v[62:65]
	global_load_lds_dwordx4 v205, s[52:53]
	s_waitcnt lgkmcnt(0)
	v_mfma_f32_16x16x32_bf16 v[2:5], v[152:155], v[136:139], v[2:5]
	ds_read_b128 v[168:171], v228 offset:0
	v_mfma_f32_16x16x32_bf16 v[6:9], v[156:159], v[136:139], v[6:9]
	ds_read_b128 v[172:175], v228 offset:2048
	v_mfma_f32_16x16x32_bf16 v[10:13], v[160:163], v[136:139], v[10:13]
	ds_read_b128 v[176:179], v228 offset:4096
	v_mfma_f32_16x16x32_bf16 v[14:17], v[164:167], v[136:139], v[14:17]
	ds_read_b128 v[180:183], v228 offset:6144
	v_mfma_f32_16x16x32_bf16 v[18:21], v[152:155], v[140:143], v[18:21]
	ds_read_b128 v[184:187], v234 offset:0
	v_mfma_f32_16x16x32_bf16 v[22:25], v[156:159], v[140:143], v[22:25]
	ds_read_b128 v[188:191], v234 offset:2048
	v_mfma_f32_16x16x32_bf16 v[26:29], v[160:163], v[140:143], v[26:29]
	ds_read_b128 v[192:195], v234 offset:4096
	v_mfma_f32_16x16x32_bf16 v[30:33], v[164:167], v[140:143], v[30:33]
	ds_read_b128 v[196:199], v234 offset:6144
	v_mfma_f32_16x16x32_bf16 v[34:37], v[152:155], v[144:147], v[34:37]
	v_mfma_f32_16x16x32_bf16 v[38:41], v[156:159], v[144:147], v[38:41]
	v_mfma_f32_16x16x32_bf16 v[42:45], v[160:163], v[144:147], v[42:45]
	v_mfma_f32_16x16x32_bf16 v[46:49], v[164:167], v[144:147], v[46:49]
	v_mfma_f32_16x16x32_bf16 v[50:53], v[152:155], v[148:151], v[50:53]
	v_mfma_f32_16x16x32_bf16 v[54:57], v[156:159], v[148:151], v[54:57]
	v_mfma_f32_16x16x32_bf16 v[58:61], v[160:163], v[148:151], v[58:61]
	v_mfma_f32_16x16x32_bf16 v[62:65], v[164:167], v[148:151], v[62:65]
	s_waitcnt vmcnt(12) lgkmcnt(0)
	s_barrier
	s_add_u32 s14, s4, 0x400
	s_addc_u32 s15, s5, 0
	v_mfma_f32_16x16x32_bf16 v[2:5], v[184:187], v[168:171], v[2:5]
	ds_read_b128 v[136:139], v224 offset:0
	s_add_u32 s22, s4, 0x10400
	s_addc_u32 s23, s5, 0
	v_mfma_f32_16x16x32_bf16 v[6:9], v[188:191], v[168:171], v[6:9]
	ds_read_b128 v[140:143], v224 offset:2048
	s_add_u32 s24, s6, 0x80400
	s_addc_u32 s25, s7, 0
	v_mfma_f32_16x16x32_bf16 v[10:13], v[192:195], v[168:171], v[10:13]
	ds_read_b128 v[144:147], v224 offset:4096
	s_add_u32 s52, s6, 0x88400
	s_addc_u32 s53, s7, 0
	v_mfma_f32_16x16x32_bf16 v[14:17], v[196:199], v[168:171], v[14:17]
	ds_read_b128 v[148:151], v224 offset:6144
	s_add_u32 m0, s8, 0xc000
	v_mfma_f32_16x16x32_bf16 v[18:21], v[184:187], v[172:175], v[18:21]
	global_load_lds_dwordx4 v200, s[14:15]
	ds_read_b128 v[152:155], v232 offset:0
	s_add_u32 m0, s8, 0xc400
	v_mfma_f32_16x16x32_bf16 v[22:25], v[188:191], v[172:175], v[22:25]
	global_load_lds_dwordx4 v201, s[14:15]
	ds_read_b128 v[156:159], v232 offset:2048
	s_add_u32 m0, s8, 0xc800
	v_mfma_f32_16x16x32_bf16 v[26:29], v[192:195], v[172:175], v[26:29]
	global_load_lds_dwordx4 v202, s[14:15]
	ds_read_b128 v[160:163], v232 offset:4096
	s_add_u32 m0, s8, 0xcc00
	v_mfma_f32_16x16x32_bf16 v[30:33], v[196:199], v[172:175], v[30:33]
	global_load_lds_dwordx4 v203, s[14:15]
	ds_read_b128 v[164:167], v232 offset:6144
	s_add_u32 m0, s8, 0xd000
	v_mfma_f32_16x16x32_bf16 v[34:37], v[184:187], v[176:179], v[34:37]
	global_load_lds_dwordx4 v200, s[22:23]
	s_add_u32 m0, s8, 0xd400
	v_mfma_f32_16x16x32_bf16 v[38:41], v[188:191], v[176:179], v[38:41]
	global_load_lds_dwordx4 v201, s[22:23]
	s_add_u32 m0, s8, 0xd800
	v_mfma_f32_16x16x32_bf16 v[42:45], v[192:195], v[176:179], v[42:45]
	global_load_lds_dwordx4 v202, s[22:23]
	s_add_u32 m0, s8, 0xdc00
	v_mfma_f32_16x16x32_bf16 v[46:49], v[196:199], v[176:179], v[46:49]
	global_load_lds_dwordx4 v203, s[22:23]
	s_add_u32 m0, s9, 0xc000
	v_mfma_f32_16x16x32_bf16 v[50:53], v[184:187], v[180:183], v[50:53]
	global_load_lds_dwordx4 v204, s[24:25]
	s_add_u32 m0, s9, 0xc400
	v_mfma_f32_16x16x32_bf16 v[54:57], v[188:191], v[180:183], v[54:57]
	global_load_lds_dwordx4 v205, s[24:25]
	s_add_u32 m0, s9, 0xc800
	v_mfma_f32_16x16x32_bf16 v[58:61], v[192:195], v[180:183], v[58:61]
	global_load_lds_dwordx4 v204, s[52:53]
	s_add_u32 m0, s9, 0xcc00
	v_mfma_f32_16x16x32_bf16 v[62:65], v[196:199], v[180:183], v[62:65]
	global_load_lds_dwordx4 v205, s[52:53]
	s_waitcnt lgkmcnt(0)
	v_mfma_f32_16x16x32_bf16 v[2:5], v[152:155], v[136:139], v[2:5]
	ds_read_b128 v[168:171], v229 offset:0
	v_mfma_f32_16x16x32_bf16 v[6:9], v[156:159], v[136:139], v[6:9]
	ds_read_b128 v[172:175], v229 offset:2048
	v_mfma_f32_16x16x32_bf16 v[10:13], v[160:163], v[136:139], v[10:13]
	ds_read_b128 v[176:179], v229 offset:4096
	v_mfma_f32_16x16x32_bf16 v[14:17], v[164:167], v[136:139], v[14:17]
	ds_read_b128 v[180:183], v229 offset:6144
	v_mfma_f32_16x16x32_bf16 v[18:21], v[152:155], v[140:143], v[18:21]
	ds_read_b128 v[184:187], v235 offset:0
	v_mfma_f32_16x16x32_bf16 v[22:25], v[156:159], v[140:143], v[22:25]
	ds_read_b128 v[188:191], v235 offset:2048
	v_mfma_f32_16x16x32_bf16 v[26:29], v[160:163], v[140:143], v[26:29]
	ds_read_b128 v[192:195], v235 offset:4096
	v_mfma_f32_16x16x32_bf16 v[30:33], v[164:167], v[140:143], v[30:33]
	ds_read_b128 v[196:199], v235 offset:6144
	v_mfma_f32_16x16x32_bf16 v[34:37], v[152:155], v[144:147], v[34:37]
	v_mfma_f32_16x16x32_bf16 v[38:41], v[156:159], v[144:147], v[38:41]
	v_mfma_f32_16x16x32_bf16 v[42:45], v[160:163], v[144:147], v[42:45]
	v_mfma_f32_16x16x32_bf16 v[46:49], v[164:167], v[144:147], v[46:49]
	v_mfma_f32_16x16x32_bf16 v[50:53], v[152:155], v[148:151], v[50:53]
	v_mfma_f32_16x16x32_bf16 v[54:57], v[156:159], v[148:151], v[54:57]
	v_mfma_f32_16x16x32_bf16 v[58:61], v[160:163], v[148:151], v[58:61]
	v_mfma_f32_16x16x32_bf16 v[62:65], v[164:167], v[148:151], v[62:65]
	s_waitcnt vmcnt(12) lgkmcnt(0)
	s_barrier
	s_add_u32 s14, s4, 0x480
	s_addc_u32 s15, s5, 0
	v_mfma_f32_16x16x32_bf16 v[2:5], v[184:187], v[168:171], v[2:5]
	ds_read_b128 v[136:139], v218 offset:0
	s_add_u32 s22, s4, 0x10480
	s_addc_u32 s23, s5, 0
	v_mfma_f32_16x16x32_bf16 v[6:9], v[188:191], v[168:171], v[6:9]
	ds_read_b128 v[140:143], v218 offset:2048
	s_add_u32 s24, s6, 0x80480
	s_addc_u32 s25, s7, 0
	v_mfma_f32_16x16x32_bf16 v[10:13], v[192:195], v[168:171], v[10:13]
	ds_read_b128 v[144:147], v218 offset:4096
	s_add_u32 s52, s6, 0x88480
	s_addc_u32 s53, s7, 0
	v_mfma_f32_16x16x32_bf16 v[14:17], v[196:199], v[168:171], v[14:17]
	ds_read_b128 v[148:151], v218 offset:6144
	s_add_u32 m0, s8, 0x18000
	v_mfma_f32_16x16x32_bf16 v[18:21], v[184:187], v[172:175], v[18:21]
	global_load_lds_dwordx4 v200, s[14:15]
	ds_read_b128 v[152:155], v230 offset:0
	s_add_u32 m0, s8, 0x18400
	v_mfma_f32_16x16x32_bf16 v[22:25], v[188:191], v[172:175], v[22:25]
	global_load_lds_dwordx4 v201, s[14:15]
	ds_read_b128 v[156:159], v230 offset:2048
	s_add_u32 m0, s8, 0x18800
	v_mfma_f32_16x16x32_bf16 v[26:29], v[192:195], v[172:175], v[26:29]
	global_load_lds_dwordx4 v202, s[14:15]
	ds_read_b128 v[160:163], v230 offset:4096
	s_add_u32 m0, s8, 0x18c00
	v_mfma_f32_16x16x32_bf16 v[30:33], v[196:199], v[172:175], v[30:33]
	global_load_lds_dwordx4 v203, s[14:15]
	ds_read_b128 v[164:167], v230 offset:6144
	s_add_u32 m0, s8, 0x19000
	v_mfma_f32_16x16x32_bf16 v[34:37], v[184:187], v[176:179], v[34:37]
	global_load_lds_dwordx4 v200, s[22:23]
	s_add_u32 m0, s8, 0x19400
	v_mfma_f32_16x16x32_bf16 v[38:41], v[188:191], v[176:179], v[38:41]
	global_load_lds_dwordx4 v201, s[22:23]
	s_add_u32 m0, s8, 0x19800
	v_mfma_f32_16x16x32_bf16 v[42:45], v[192:195], v[176:179], v[42:45]
	global_load_lds_dwordx4 v202, s[22:23]
	s_add_u32 m0, s8, 0x19c00
	v_mfma_f32_16x16x32_bf16 v[46:49], v[196:199], v[176:179], v[46:49]
	global_load_lds_dwordx4 v203, s[22:23]
	s_add_u32 m0, s9, 0x18000
	v_mfma_f32_16x16x32_bf16 v[50:53], v[184:187], v[180:183], v[50:53]
	global_load_lds_dwordx4 v204, s[24:25]
	s_add_u32 m0, s9, 0x18400
	v_mfma_f32_16x16x32_bf16 v[54:57], v[188:191], v[180:183], v[54:57]
	global_load_lds_dwordx4 v205, s[24:25]
	s_add_u32 m0, s9, 0x18800
	v_mfma_f32_16x16x32_bf16 v[58:61], v[192:195], v[180:183], v[58:61]
	global_load_lds_dwordx4 v204, s[52:53]
	s_add_u32 m0, s9, 0x18c00
	v_mfma_f32_16x16x32_bf16 v[62:65], v[196:199], v[180:183], v[62:65]
	global_load_lds_dwordx4 v205, s[52:53]
	s_waitcnt lgkmcnt(0)
	v_mfma_f32_16x16x32_bf16 v[2:5], v[152:155], v[136:139], v[2:5]
	ds_read_b128 v[168:171], v225 offset:0
	v_mfma_f32_16x16x32_bf16 v[6:9], v[156:159], v[136:139], v[6:9]
	ds_read_b128 v[172:175], v225 offset:2048
	v_mfma_f32_16x16x32_bf16 v[10:13], v[160:163], v[136:139], v[10:13]
	ds_read_b128 v[176:179], v225 offset:4096
	v_mfma_f32_16x16x32_bf16 v[14:17], v[164:167], v[136:139], v[14:17]
	ds_read_b128 v[180:183], v225 offset:6144
	v_mfma_f32_16x16x32_bf16 v[18:21], v[152:155], v[140:143], v[18:21]
	ds_read_b128 v[184:187], v233 offset:0
	v_mfma_f32_16x16x32_bf16 v[22:25], v[156:159], v[140:143], v[22:25]
	ds_read_b128 v[188:191], v233 offset:2048
	v_mfma_f32_16x16x32_bf16 v[26:29], v[160:163], v[140:143], v[26:29]
	ds_read_b128 v[192:195], v233 offset:4096
	v_mfma_f32_16x16x32_bf16 v[30:33], v[164:167], v[140:143], v[30:33]
	ds_read_b128 v[196:199], v233 offset:6144
	v_mfma_f32_16x16x32_bf16 v[34:37], v[152:155], v[144:147], v[34:37]
	v_mfma_f32_16x16x32_bf16 v[38:41], v[156:159], v[144:147], v[38:41]
	v_mfma_f32_16x16x32_bf16 v[42:45], v[160:163], v[144:147], v[42:45]
	v_mfma_f32_16x16x32_bf16 v[46:49], v[164:167], v[144:147], v[46:49]
	v_mfma_f32_16x16x32_bf16 v[50:53], v[152:155], v[148:151], v[50:53]
	v_mfma_f32_16x16x32_bf16 v[54:57], v[156:159], v[148:151], v[54:57]
	v_mfma_f32_16x16x32_bf16 v[58:61], v[160:163], v[148:151], v[58:61]
	v_mfma_f32_16x16x32_bf16 v[62:65], v[164:167], v[148:151], v[62:65]
	s_waitcnt vmcnt(12) lgkmcnt(0)
	s_barrier
	s_add_u32 s14, s4, 0x500
	s_addc_u32 s15, s5, 0
	v_mfma_f32_16x16x32_bf16 v[2:5], v[184:187], v[168:171], v[2:5]
	ds_read_b128 v[136:139], v219 offset:0
	s_add_u32 s22, s4, 0x10500
	s_addc_u32 s23, s5, 0
	v_mfma_f32_16x16x32_bf16 v[6:9], v[188:191], v[168:171], v[6:9]
	ds_read_b128 v[140:143], v219 offset:2048
	s_add_u32 s24, s6, 0x80500
	s_addc_u32 s25, s7, 0
	v_mfma_f32_16x16x32_bf16 v[10:13], v[192:195], v[168:171], v[10:13]
	ds_read_b128 v[144:147], v219 offset:4096
	s_add_u32 s52, s6, 0x88500
	s_addc_u32 s53, s7, 0
	v_mfma_f32_16x16x32_bf16 v[14:17], v[196:199], v[168:171], v[14:17]
	ds_read_b128 v[148:151], v219 offset:6144
	s_mov_b32 m0, s8
	v_mfma_f32_16x16x32_bf16 v[18:21], v[184:187], v[172:175], v[18:21]
	global_load_lds_dwordx4 v200, s[14:15]
	ds_read_b128 v[152:155], v231 offset:0
	s_add_u32 m0, s8, 0x400
	v_mfma_f32_16x16x32_bf16 v[22:25], v[188:191], v[172:175], v[22:25]
	global_load_lds_dwordx4 v201, s[14:15]
	ds_read_b128 v[156:159], v231 offset:2048
	s_add_u32 m0, s8, 0x800
	v_mfma_f32_16x16x32_bf16 v[26:29], v[192:195], v[172:175], v[26:29]
	global_load_lds_dwordx4 v202, s[14:15]
	ds_read_b128 v[160:163], v231 offset:4096
	s_add_u32 m0, s8, 0xc00
	v_mfma_f32_16x16x32_bf16 v[30:33], v[196:199], v[172:175], v[30:33]
	global_load_lds_dwordx4 v203, s[14:15]
	ds_read_b128 v[164:167], v231 offset:6144
	s_add_u32 m0, s8, 0x1000
	v_mfma_f32_16x16x32_bf16 v[34:37], v[184:187], v[176:179], v[34:37]
	global_load_lds_dwordx4 v200, s[22:23]
	s_add_u32 m0, s8, 0x1400
	v_mfma_f32_16x16x32_bf16 v[38:41], v[188:191], v[176:179], v[38:41]
	global_load_lds_dwordx4 v201, s[22:23]
	s_add_u32 m0, s8, 0x1800
	v_mfma_f32_16x16x32_bf16 v[42:45], v[192:195], v[176:179], v[42:45]
	global_load_lds_dwordx4 v202, s[22:23]
	s_add_u32 m0, s8, 0x1c00
	v_mfma_f32_16x16x32_bf16 v[46:49], v[196:199], v[176:179], v[46:49]
	global_load_lds_dwordx4 v203, s[22:23]
	s_mov_b32 m0, s9
	v_mfma_f32_16x16x32_bf16 v[50:53], v[184:187], v[180:183], v[50:53]
	global_load_lds_dwordx4 v204, s[24:25]
	s_add_u32 m0, s9, 0x400
	v_mfma_f32_16x16x32_bf16 v[54:57], v[188:191], v[180:183], v[54:57]
	global_load_lds_dwordx4 v205, s[24:25]
	s_add_u32 m0, s9, 0x800
	v_mfma_f32_16x16x32_bf16 v[58:61], v[192:195], v[180:183], v[58:61]
	global_load_lds_dwordx4 v204, s[52:53]
	s_add_u32 m0, s9, 0xc00
	v_mfma_f32_16x16x32_bf16 v[62:65], v[196:199], v[180:183], v[62:65]
	global_load_lds_dwordx4 v205, s[52:53]
	s_waitcnt lgkmcnt(0)
	v_mfma_f32_16x16x32_bf16 v[2:5], v[152:155], v[136:139], v[2:5]
	ds_read_b128 v[168:171], v228 offset:0
	s_add_u32 s10, s28, s13
	s_addc_u32 s11, s29, 0
	s_add_u32 s13, s13, 0x10000
	v_mfma_f32_16x16x32_bf16 v[6:9], v[156:159], v[136:139], v[6:9]
	ds_read_b128 v[172:175], v228 offset:2048
	v_mul_f32_e32 v66, s12, v66
	v_mul_f32_e32 v67, s12, v67
	v_mfma_f32_16x16x32_bf16 v[10:13], v[160:163], v[136:139], v[10:13]
	ds_read_b128 v[176:179], v228 offset:4096
	v_mul_f32_e32 v68, s12, v68
	v_mul_f32_e32 v69, s12, v69
	v_mul_f32_e32 v70, s12, v70
	v_mfma_f32_16x16x32_bf16 v[14:17], v[164:167], v[136:139], v[14:17]
	ds_read_b128 v[180:183], v228 offset:6144
	v_mul_f32_e32 v71, s12, v71
	v_mul_f32_e32 v72, s12, v72
	v_mfma_f32_16x16x32_bf16 v[18:21], v[152:155], v[140:143], v[18:21]
	ds_read_b128 v[184:187], v234 offset:0
	v_mul_f32_e32 v73, s12, v73
	v_exp_f32_e32 v66, v66
	v_mfma_f32_16x16x32_bf16 v[22:25], v[156:159], v[140:143], v[22:25]
	ds_read_b128 v[188:191], v234 offset:2048
	v_exp_f32_e32 v67, v67
	v_exp_f32_e32 v68, v68
	v_exp_f32_e32 v69, v69
	v_mfma_f32_16x16x32_bf16 v[26:29], v[160:163], v[140:143], v[26:29]
	ds_read_b128 v[192:195], v234 offset:4096
	v_exp_f32_e32 v70, v70
	v_exp_f32_e32 v71, v71
	v_mfma_f32_16x16x32_bf16 v[30:33], v[164:167], v[140:143], v[30:33]
	ds_read_b128 v[196:199], v234 offset:6144
	v_exp_f32_e32 v72, v72
	v_exp_f32_e32 v73, v73
	v_add_f32_e32 v66, 1.0, v66
	v_mfma_f32_16x16x32_bf16 v[34:37], v[152:155], v[144:147], v[34:37]
	v_add_f32_e32 v67, 1.0, v67
	v_add_f32_e32 v68, 1.0, v68
	v_mfma_f32_16x16x32_bf16 v[38:41], v[156:159], v[144:147], v[38:41]
	v_add_f32_e32 v69, 1.0, v69
	v_add_f32_e32 v70, 1.0, v70
	v_mfma_f32_16x16x32_bf16 v[42:45], v[160:163], v[144:147], v[42:45]
	v_add_f32_e32 v71, 1.0, v71
	v_add_f32_e32 v72, 1.0, v72
	v_add_f32_e32 v73, 1.0, v73
	v_mfma_f32_16x16x32_bf16 v[46:49], v[164:167], v[144:147], v[46:49]
	v_rcp_f32_e32 v66, v66
	v_rcp_f32_e32 v67, v67
	v_mfma_f32_16x16x32_bf16 v[50:53], v[152:155], v[148:151], v[50:53]
	v_rcp_f32_e32 v68, v68
	v_rcp_f32_e32 v69, v69
	v_mfma_f32_16x16x32_bf16 v[54:57], v[156:159], v[148:151], v[54:57]
	v_rcp_f32_e32 v70, v70
	v_rcp_f32_e32 v71, v71
	v_rcp_f32_e32 v72, v72
	v_mfma_f32_16x16x32_bf16 v[58:61], v[160:163], v[148:151], v[58:61]
	v_rcp_f32_e32 v73, v73
	v_cvt_pk_bf16_f32 v66, v66, v67
	v_mfma_f32_16x16x32_bf16 v[62:65], v[164:167], v[148:151], v[62:65]
	v_cvt_pk_bf16_f32 v67, v68, v69
	v_cvt_pk_bf16_f32 v68, v70, v71
	v_cvt_pk_bf16_f32 v69, v72, v73
	s_waitcnt vmcnt(12) lgkmcnt(0)
	s_barrier
	v_mfma_f32_16x16x32_bf16 v[2:5], v[184:187], v[168:171], v[2:5]
	ds_read_b128 v[136:139], v224 offset:0
	global_store_dwordx4 v240, v[66:69], s[10:11] offset:0
	v_mul_f32_e32 v74, s12, v74
	v_mfma_f32_16x16x32_bf16 v[6:9], v[188:191], v[168:171], v[6:9]
	ds_read_b128 v[140:143], v224 offset:2048
	v_mul_f32_e32 v75, s12, v75
	v_mul_f32_e32 v76, s12, v76
	v_mfma_f32_16x16x32_bf16 v[10:13], v[192:195], v[168:171], v[10:13]
	ds_read_b128 v[144:147], v224 offset:4096
	v_mul_f32_e32 v77, s12, v77
	v_mul_f32_e32 v78, s12, v78
	v_mfma_f32_16x16x32_bf16 v[14:17], v[196:199], v[168:171], v[14:17]
	ds_read_b128 v[148:151], v224 offset:6144
	v_mul_f32_e32 v79, s12, v79
	v_mul_f32_e32 v80, s12, v80
	v_mul_f32_e32 v81, s12, v81
	v_mfma_f32_16x16x32_bf16 v[18:21], v[184:187], v[172:175], v[18:21]
	ds_read_b128 v[152:155], v232 offset:0
	v_exp_f32_e32 v74, v74
	v_exp_f32_e32 v75, v75
	v_mfma_f32_16x16x32_bf16 v[22:25], v[188:191], v[172:175], v[22:25]
	ds_read_b128 v[156:159], v232 offset:2048
	v_exp_f32_e32 v76, v76
	v_exp_f32_e32 v77, v77
	v_mfma_f32_16x16x32_bf16 v[26:29], v[192:195], v[172:175], v[26:29]
	ds_read_b128 v[160:163], v232 offset:4096
	v_exp_f32_e32 v78, v78
	v_exp_f32_e32 v79, v79
	v_exp_f32_e32 v80, v80
	v_mfma_f32_16x16x32_bf16 v[30:33], v[196:199], v[172:175], v[30:33]
	ds_read_b128 v[164:167], v232 offset:6144
	v_exp_f32_e32 v81, v81
	v_add_f32_e32 v74, 1.0, v74
	v_mfma_f32_16x16x32_bf16 v[34:37], v[184:187], v[176:179], v[34:37]
	v_add_f32_e32 v75, 1.0, v75
	v_add_f32_e32 v76, 1.0, v76
	v_mfma_f32_16x16x32_bf16 v[38:41], v[188:191], v[176:179], v[38:41]
	v_add_f32_e32 v77, 1.0, v77
	v_add_f32_e32 v78, 1.0, v78
	v_add_f32_e32 v79, 1.0, v79
	v_mfma_f32_16x16x32_bf16 v[42:45], v[192:195], v[176:179], v[42:45]
	v_add_f32_e32 v80, 1.0, v80
	v_add_f32_e32 v81, 1.0, v81
	v_mfma_f32_16x16x32_bf16 v[46:49], v[196:199], v[176:179], v[46:49]
	v_rcp_f32_e32 v74, v74
	v_rcp_f32_e32 v75, v75
	v_mfma_f32_16x16x32_bf16 v[50:53], v[184:187], v[180:183], v[50:53]
	v_rcp_f32_e32 v76, v76
	v_rcp_f32_e32 v77, v77
	v_rcp_f32_e32 v78, v78
	v_mfma_f32_16x16x32_bf16 v[54:57], v[188:191], v[180:183], v[54:57]
	v_rcp_f32_e32 v79, v79
	v_rcp_f32_e32 v80, v80
	v_mfma_f32_16x16x32_bf16 v[58:61], v[192:195], v[180:183], v[58:61]
	v_rcp_f32_e32 v81, v81
	v_cvt_pk_bf16_f32 v74, v74, v75
	v_mfma_f32_16x16x32_bf16 v[62:65], v[196:199], v[180:183], v[62:65]
	v_cvt_pk_bf16_f32 v75, v76, v77
	v_cvt_pk_bf16_f32 v76, v78, v79
	v_cvt_pk_bf16_f32 v77, v80, v81
	s_waitcnt lgkmcnt(0)
	v_mfma_f32_16x16x32_bf16 v[2:5], v[152:155], v[136:139], v[2:5]
	ds_read_b128 v[168:171], v229 offset:0
	global_store_dwordx4 v240, v[74:77], s[10:11] offset:16
	v_mul_f32_e32 v82, s12, v82
	v_mfma_f32_16x16x32_bf16 v[6:9], v[156:159], v[136:139], v[6:9]
	ds_read_b128 v[172:175], v229 offset:2048
	v_mul_f32_e32 v83, s12, v83
	v_mul_f32_e32 v84, s12, v84
	v_mfma_f32_16x16x32_bf16 v[10:13], v[160:163], v[136:139], v[10:13]
	ds_read_b128 v[176:179], v229 offset:4096
	v_mul_f32_e32 v85, s12, v85
	v_mul_f32_e32 v86, s12, v86
	v_mul_f32_e32 v87, s12, v87
	v_mfma_f32_16x16x32_bf16 v[14:17], v[164:167], v[136:139], v[14:17]
	ds_read_b128 v[180:183], v229 offset:6144
	v_mul_f32_e32 v88, s12, v88
	v_mul_f32_e32 v89, s12, v89
	v_mfma_f32_16x16x32_bf16 v[18:21], v[152:155], v[140:143], v[18:21]
	ds_read_b128 v[184:187], v235 offset:0
	v_exp_f32_e32 v82, v82
	v_exp_f32_e32 v83, v83
	v_mfma_f32_16x16x32_bf16 v[22:25], v[156:159], v[140:143], v[22:25]
	ds_read_b128 v[188:191], v235 offset:2048
	v_exp_f32_e32 v84, v84
	v_exp_f32_e32 v85, v85
	v_exp_f32_e32 v86, v86
	v_mfma_f32_16x16x32_bf16 v[26:29], v[160:163], v[140:143], v[26:29]
	ds_read_b128 v[192:195], v235 offset:4096
	v_exp_f32_e32 v87, v87
	v_exp_f32_e32 v88, v88
	v_mfma_f32_16x16x32_bf16 v[30:33], v[164:167], v[140:143], v[30:33]
	ds_read_b128 v[196:199], v235 offset:6144
	v_exp_f32_e32 v89, v89
	v_add_f32_e32 v82, 1.0, v82
	v_add_f32_e32 v83, 1.0, v83
	v_mfma_f32_16x16x32_bf16 v[34:37], v[152:155], v[144:147], v[34:37]
	v_add_f32_e32 v84, 1.0, v84
	v_add_f32_e32 v85, 1.0, v85
	v_mfma_f32_16x16x32_bf16 v[38:41], v[156:159], v[144:147], v[38:41]
	v_add_f32_e32 v86, 1.0, v86
	v_add_f32_e32 v87, 1.0, v87
	v_mfma_f32_16x16x32_bf16 v[42:45], v[160:163], v[144:147], v[42:45]
	v_add_f32_e32 v88, 1.0, v88
	v_add_f32_e32 v89, 1.0, v89
	v_rcp_f32_e32 v82, v82
	v_mfma_f32_16x16x32_bf16 v[46:49], v[164:167], v[144:147], v[46:49]
	v_rcp_f32_e32 v83, v83
	v_rcp_f32_e32 v84, v84
	v_mfma_f32_16x16x32_bf16 v[50:53], v[152:155], v[148:151], v[50:53]
	v_rcp_f32_e32 v85, v85
	v_rcp_f32_e32 v86, v86
	v_mfma_f32_16x16x32_bf16 v[54:57], v[156:159], v[148:151], v[54:57]
	v_rcp_f32_e32 v87, v87
	v_rcp_f32_e32 v88, v88
	v_rcp_f32_e32 v89, v89
	v_mfma_f32_16x16x32_bf16 v[58:61], v[160:163], v[148:151], v[58:61]
	v_cvt_pk_bf16_f32 v82, v82, v83
	v_cvt_pk_bf16_f32 v83, v84, v85
	v_mfma_f32_16x16x32_bf16 v[62:65], v[164:167], v[148:151], v[62:65]
	v_cvt_pk_bf16_f32 v84, v86, v87
	v_cvt_pk_bf16_f32 v85, v88, v89
	global_store_dwordx4 v240, v[82:85], s[10:11] offset:2048
	s_waitcnt vmcnt(3) lgkmcnt(0)
	s_barrier
	v_mfma_f32_16x16x32_bf16 v[2:5], v[184:187], v[168:171], v[2:5]
	ds_read_b128 v[136:139], v218 offset:0
	v_mul_f32_e32 v90, s12, v90
	v_mul_f32_e32 v91, s12, v91
	v_mfma_f32_16x16x32_bf16 v[6:9], v[188:191], v[168:171], v[6:9]
	ds_read_b128 v[140:143], v218 offset:2048
	v_mul_f32_e32 v92, s12, v92
	v_mul_f32_e32 v93, s12, v93
	v_mfma_f32_16x16x32_bf16 v[10:13], v[192:195], v[168:171], v[10:13]
	ds_read_b128 v[144:147], v218 offset:4096
	v_mul_f32_e32 v94, s12, v94
	v_mul_f32_e32 v95, s12, v95
	v_mfma_f32_16x16x32_bf16 v[14:17], v[196:199], v[168:171], v[14:17]
	ds_read_b128 v[148:151], v218 offset:6144
	v_mul_f32_e32 v96, s12, v96
	v_mul_f32_e32 v97, s12, v97
	v_exp_f32_e32 v90, v90
	v_mfma_f32_16x16x32_bf16 v[18:21], v[184:187], v[172:175], v[18:21]
	ds_read_b128 v[152:155], v230 offset:0
	v_exp_f32_e32 v91, v91
	v_exp_f32_e32 v92, v92
	v_mfma_f32_16x16x32_bf16 v[22:25], v[188:191], v[172:175], v[22:25]
	ds_read_b128 v[156:159], v230 offset:2048
	v_exp_f32_e32 v93, v93
	v_exp_f32_e32 v94, v94
	v_mfma_f32_16x16x32_bf16 v[26:29], v[192:195], v[172:175], v[26:29]
	ds_read_b128 v[160:163], v230 offset:4096
	v_exp_f32_e32 v95, v95
	v_exp_f32_e32 v96, v96
	v_exp_f32_e32 v97, v97
	v_mfma_f32_16x16x32_bf16 v[30:33], v[196:199], v[172:175], v[30:33]
	ds_read_b128 v[164:167], v230 offset:6144
	v_add_f32_e32 v90, 1.0, v90
	v_add_f32_e32 v91, 1.0, v91
	v_mfma_f32_16x16x32_bf16 v[34:37], v[184:187], v[176:179], v[34:37]
	v_add_f32_e32 v92, 1.0, v92
	v_add_f32_e32 v93, 1.0, v93
	v_mfma_f32_16x16x32_bf16 v[38:41], v[188:191], v[176:179], v[38:41]
	v_add_f32_e32 v94, 1.0, v94
	v_add_f32_e32 v95, 1.0, v95
	v_add_f32_e32 v96, 1.0, v96
	v_mfma_f32_16x16x32_bf16 v[42:45], v[192:195], v[176:179], v[42:45]
	v_add_f32_e32 v97, 1.0, v97
	v_rcp_f32_e32 v90, v90
	v_mfma_f32_16x16x32_bf16 v[46:49], v[196:199], v[176:179], v[46:49]
	v_rcp_f32_e32 v91, v91
	v_rcp_f32_e32 v92, v92
	v_mfma_f32_16x16x32_bf16 v[50:53], v[184:187], v[180:183], v[50:53]
	v_rcp_f32_e32 v93, v93
	v_rcp_f32_e32 v94, v94
	v_rcp_f32_e32 v95, v95
	v_mfma_f32_16x16x32_bf16 v[54:57], v[188:191], v[180:183], v[54:57]
	v_rcp_f32_e32 v96, v96
	v_rcp_f32_e32 v97, v97
	v_mfma_f32_16x16x32_bf16 v[58:61], v[192:195], v[180:183], v[58:61]
	v_cvt_pk_bf16_f32 v90, v90, v91
	v_cvt_pk_bf16_f32 v91, v92, v93
	v_mfma_f32_16x16x32_bf16 v[62:65], v[196:199], v[180:183], v[62:65]
	v_cvt_pk_bf16_f32 v92, v94, v95
	v_cvt_pk_bf16_f32 v93, v96, v97
	global_store_dwordx4 v240, v[90:93], s[10:11] offset:2064
	s_waitcnt lgkmcnt(0)
	v_mfma_f32_16x16x32_bf16 v[2:5], v[152:155], v[136:139], v[2:5]
	ds_read_b128 v[168:171], v225 offset:0
	v_mul_f32_e32 v98, s12, v98
	v_mul_f32_e32 v99, s12, v99
	v_mfma_f32_16x16x32_bf16 v[6:9], v[156:159], v[136:139], v[6:9]
	ds_read_b128 v[172:175], v225 offset:2048
	v_mul_f32_e32 v100, s12, v100
	v_mul_f32_e32 v101, s12, v101
	v_mfma_f32_16x16x32_bf16 v[10:13], v[160:163], v[136:139], v[10:13]
	ds_read_b128 v[176:179], v225 offset:4096
	v_mul_f32_e32 v102, s12, v102
	v_mul_f32_e32 v103, s12, v103
	v_mfma_f32_16x16x32_bf16 v[14:17], v[164:167], v[136:139], v[14:17]
	ds_read_b128 v[180:183], v225 offset:6144
	v_mul_f32_e32 v104, s12, v104
	v_mul_f32_e32 v105, s12, v105
	v_exp_f32_e32 v98, v98
	v_mfma_f32_16x16x32_bf16 v[18:21], v[152:155], v[140:143], v[18:21]
	ds_read_b128 v[184:187], v233 offset:0
	v_exp_f32_e32 v99, v99
	v_exp_f32_e32 v100, v100
	v_mfma_f32_16x16x32_bf16 v[22:25], v[156:159], v[140:143], v[22:25]
	ds_read_b128 v[188:191], v233 offset:2048
	v_exp_f32_e32 v101, v101
	v_exp_f32_e32 v102, v102
	v_mfma_f32_16x16x32_bf16 v[26:29], v[160:163], v[140:143], v[26:29]
	ds_read_b128 v[192:195], v233 offset:4096
	v_exp_f32_e32 v103, v103
	v_exp_f32_e32 v104, v104
	v_exp_f32_e32 v105, v105
	v_mfma_f32_16x16x32_bf16 v[30:33], v[164:167], v[140:143], v[30:33]
	ds_read_b128 v[196:199], v233 offset:6144
	v_add_f32_e32 v98, 1.0, v98
	v_add_f32_e32 v99, 1.0, v99
	v_mfma_f32_16x16x32_bf16 v[34:37], v[152:155], v[144:147], v[34:37]
	v_add_f32_e32 v100, 1.0, v100
	v_add_f32_e32 v101, 1.0, v101
	v_mfma_f32_16x16x32_bf16 v[38:41], v[156:159], v[144:147], v[38:41]
	v_add_f32_e32 v102, 1.0, v102
	v_add_f32_e32 v103, 1.0, v103
	v_add_f32_e32 v104, 1.0, v104
	v_mfma_f32_16x16x32_bf16 v[42:45], v[160:163], v[144:147], v[42:45]
	v_add_f32_e32 v105, 1.0, v105
	v_rcp_f32_e32 v98, v98
	v_mfma_f32_16x16x32_bf16 v[46:49], v[164:167], v[144:147], v[46:49]
	v_rcp_f32_e32 v99, v99
	v_rcp_f32_e32 v100, v100
	v_mfma_f32_16x16x32_bf16 v[50:53], v[152:155], v[148:151], v[50:53]
	v_rcp_f32_e32 v101, v101
	v_rcp_f32_e32 v102, v102
	v_rcp_f32_e32 v103, v103
	v_mfma_f32_16x16x32_bf16 v[54:57], v[156:159], v[148:151], v[54:57]
	v_rcp_f32_e32 v104, v104
	v_rcp_f32_e32 v105, v105
	v_mfma_f32_16x16x32_bf16 v[58:61], v[160:163], v[148:151], v[58:61]
	v_cvt_pk_bf16_f32 v98, v98, v99
	v_cvt_pk_bf16_f32 v99, v100, v101
	v_mfma_f32_16x16x32_bf16 v[62:65], v[164:167], v[148:151], v[62:65]
	v_cvt_pk_bf16_f32 v100, v102, v103
	v_cvt_pk_bf16_f32 v101, v104, v105
	global_store_dwordx4 v241, v[98:101], s[10:11] offset:0
	s_waitcnt lgkmcnt(0)
	s_barrier
	v_mfma_f32_16x16x32_bf16 v[2:5], v[184:187], v[168:171], v[2:5]
	ds_read_b128 v[136:139], v219 offset:0
	v_mul_f32_e32 v106, s12, v106
	v_mul_f32_e32 v107, s12, v107
	v_mfma_f32_16x16x32_bf16 v[6:9], v[188:191], v[168:171], v[6:9]
	ds_read_b128 v[140:143], v219 offset:2048
	v_mul_f32_e32 v108, s12, v108
	v_mul_f32_e32 v109, s12, v109
	v_mfma_f32_16x16x32_bf16 v[10:13], v[192:195], v[168:171], v[10:13]
	ds_read_b128 v[144:147], v219 offset:4096
	v_mul_f32_e32 v110, s12, v110
	v_mul_f32_e32 v111, s12, v111
	v_mfma_f32_16x16x32_bf16 v[14:17], v[196:199], v[168:171], v[14:17]
	ds_read_b128 v[148:151], v219 offset:6144
	v_mul_f32_e32 v112, s12, v112
	v_mul_f32_e32 v113, s12, v113
	v_exp_f32_e32 v106, v106
	v_mfma_f32_16x16x32_bf16 v[18:21], v[184:187], v[172:175], v[18:21]
	ds_read_b128 v[152:155], v231 offset:0
	v_exp_f32_e32 v107, v107
	v_exp_f32_e32 v108, v108
	v_mfma_f32_16x16x32_bf16 v[22:25], v[188:191], v[172:175], v[22:25]
	ds_read_b128 v[156:159], v231 offset:2048
	v_exp_f32_e32 v109, v109
	v_exp_f32_e32 v110, v110
	v_mfma_f32_16x16x32_bf16 v[26:29], v[192:195], v[172:175], v[26:29]
	ds_read_b128 v[160:163], v231 offset:4096
	v_exp_f32_e32 v111, v111
	v_exp_f32_e32 v112, v112
	v_exp_f32_e32 v113, v113
	v_mfma_f32_16x16x32_bf16 v[30:33], v[196:199], v[172:175], v[30:33]
	ds_read_b128 v[164:167], v231 offset:6144
	v_add_f32_e32 v106, 1.0, v106
	v_add_f32_e32 v107, 1.0, v107
	v_mfma_f32_16x16x32_bf16 v[34:37], v[184:187], v[176:179], v[34:37]
	v_add_f32_e32 v108, 1.0, v108
	v_add_f32_e32 v109, 1.0, v109
	v_mfma_f32_16x16x32_bf16 v[38:41], v[188:191], v[176:179], v[38:41]
	v_add_f32_e32 v110, 1.0, v110
	v_add_f32_e32 v111, 1.0, v111
	v_add_f32_e32 v112, 1.0, v112
	v_mfma_f32_16x16x32_bf16 v[42:45], v[192:195], v[176:179], v[42:45]
	v_add_f32_e32 v113, 1.0, v113
	v_rcp_f32_e32 v106, v106
	v_mfma_f32_16x16x32_bf16 v[46:49], v[196:199], v[176:179], v[46:49]
	v_rcp_f32_e32 v107, v107
	v_rcp_f32_e32 v108, v108
	v_mfma_f32_16x16x32_bf16 v[50:53], v[184:187], v[180:183], v[50:53]
	v_rcp_f32_e32 v109, v109
	v_rcp_f32_e32 v110, v110
	v_rcp_f32_e32 v111, v111
	v_mfma_f32_16x16x32_bf16 v[54:57], v[188:191], v[180:183], v[54:57]
	v_rcp_f32_e32 v112, v112
	v_rcp_f32_e32 v113, v113
	v_mfma_f32_16x16x32_bf16 v[58:61], v[192:195], v[180:183], v[58:61]
	v_cvt_pk_bf16_f32 v106, v106, v107
	v_cvt_pk_bf16_f32 v107, v108, v109
	v_mfma_f32_16x16x32_bf16 v[62:65], v[196:199], v[180:183], v[62:65]
	v_cvt_pk_bf16_f32 v108, v110, v111
	v_cvt_pk_bf16_f32 v109, v112, v113
	global_store_dwordx4 v241, v[106:109], s[10:11] offset:16
	s_waitcnt lgkmcnt(0)
	v_mfma_f32_16x16x32_bf16 v[2:5], v[152:155], v[136:139], v[2:5]
	ds_read_b128 v[168:171], v228 offset:0
	v_mul_f32_e32 v114, s12, v114
	v_mul_f32_e32 v115, s12, v115
	v_mfma_f32_16x16x32_bf16 v[6:9], v[156:159], v[136:139], v[6:9]
	ds_read_b128 v[172:175], v228 offset:2048
	v_mul_f32_e32 v116, s12, v116
	v_mul_f32_e32 v117, s12, v117
	v_mfma_f32_16x16x32_bf16 v[10:13], v[160:163], v[136:139], v[10:13]
	ds_read_b128 v[176:179], v228 offset:4096
	v_mul_f32_e32 v118, s12, v118
	v_mul_f32_e32 v119, s12, v119
	v_mfma_f32_16x16x32_bf16 v[14:17], v[164:167], v[136:139], v[14:17]
	ds_read_b128 v[180:183], v228 offset:6144
	v_mul_f32_e32 v120, s12, v120
	v_mul_f32_e32 v121, s12, v121
	v_exp_f32_e32 v114, v114
	v_mfma_f32_16x16x32_bf16 v[18:21], v[152:155], v[140:143], v[18:21]
	ds_read_b128 v[184:187], v234 offset:0
	v_exp_f32_e32 v115, v115
	v_exp_f32_e32 v116, v116
	v_mfma_f32_16x16x32_bf16 v[22:25], v[156:159], v[140:143], v[22:25]
	ds_read_b128 v[188:191], v234 offset:2048
	v_exp_f32_e32 v117, v117
	v_exp_f32_e32 v118, v118
	v_mfma_f32_16x16x32_bf16 v[26:29], v[160:163], v[140:143], v[26:29]
	ds_read_b128 v[192:195], v234 offset:4096
	v_exp_f32_e32 v119, v119
	v_exp_f32_e32 v120, v120
	v_exp_f32_e32 v121, v121
	v_mfma_f32_16x16x32_bf16 v[30:33], v[164:167], v[140:143], v[30:33]
	ds_read_b128 v[196:199], v234 offset:6144
	v_add_f32_e32 v114, 1.0, v114
	v_add_f32_e32 v115, 1.0, v115
	v_mfma_f32_16x16x32_bf16 v[34:37], v[152:155], v[144:147], v[34:37]
	v_add_f32_e32 v116, 1.0, v116
	v_add_f32_e32 v117, 1.0, v117
	v_mfma_f32_16x16x32_bf16 v[38:41], v[156:159], v[144:147], v[38:41]
	v_add_f32_e32 v118, 1.0, v118
	v_add_f32_e32 v119, 1.0, v119
	v_add_f32_e32 v120, 1.0, v120
	v_mfma_f32_16x16x32_bf16 v[42:45], v[160:163], v[144:147], v[42:45]
	v_add_f32_e32 v121, 1.0, v121
	v_rcp_f32_e32 v114, v114
	v_mfma_f32_16x16x32_bf16 v[46:49], v[164:167], v[144:147], v[46:49]
	v_rcp_f32_e32 v115, v115
	v_rcp_f32_e32 v116, v116
	v_mfma_f32_16x16x32_bf16 v[50:53], v[152:155], v[148:151], v[50:53]
	v_rcp_f32_e32 v117, v117
	v_rcp_f32_e32 v118, v118
	v_rcp_f32_e32 v119, v119
	v_mfma_f32_16x16x32_bf16 v[54:57], v[156:159], v[148:151], v[54:57]
	v_rcp_f32_e32 v120, v120
	v_rcp_f32_e32 v121, v121
	v_mfma_f32_16x16x32_bf16 v[58:61], v[160:163], v[148:151], v[58:61]
	v_cvt_pk_bf16_f32 v114, v114, v115
	v_cvt_pk_bf16_f32 v115, v116, v117
	v_mfma_f32_16x16x32_bf16 v[62:65], v[164:167], v[148:151], v[62:65]
	v_cvt_pk_bf16_f32 v116, v118, v119
	v_cvt_pk_bf16_f32 v117, v120, v121
	global_store_dwordx4 v241, v[114:117], s[10:11] offset:2048
	s_waitcnt lgkmcnt(0)
	s_barrier
	v_mfma_f32_16x16x32_bf16 v[2:5], v[184:187], v[168:171], v[2:5]
	ds_read_b128 v[136:139], v224 offset:0
	v_mul_f32_e32 v122, s12, v122
	v_mul_f32_e32 v123, s12, v123
	v_mfma_f32_16x16x32_bf16 v[6:9], v[188:191], v[168:171], v[6:9]
	ds_read_b128 v[140:143], v224 offset:2048
	v_mul_f32_e32 v124, s12, v124
	v_mul_f32_e32 v125, s12, v125
	v_mfma_f32_16x16x32_bf16 v[10:13], v[192:195], v[168:171], v[10:13]
	ds_read_b128 v[144:147], v224 offset:4096
	v_mul_f32_e32 v126, s12, v126
	v_mul_f32_e32 v127, s12, v127
	v_mfma_f32_16x16x32_bf16 v[14:17], v[196:199], v[168:171], v[14:17]
	ds_read_b128 v[148:151], v224 offset:6144
	v_mul_f32_e32 v128, s12, v128
	v_mul_f32_e32 v129, s12, v129
	v_exp_f32_e32 v122, v122
	v_mfma_f32_16x16x32_bf16 v[18:21], v[184:187], v[172:175], v[18:21]
	ds_read_b128 v[152:155], v232 offset:0
	v_exp_f32_e32 v123, v123
	v_exp_f32_e32 v124, v124
	v_mfma_f32_16x16x32_bf16 v[22:25], v[188:191], v[172:175], v[22:25]
	ds_read_b128 v[156:159], v232 offset:2048
	v_exp_f32_e32 v125, v125
	v_exp_f32_e32 v126, v126
	v_mfma_f32_16x16x32_bf16 v[26:29], v[192:195], v[172:175], v[26:29]
	ds_read_b128 v[160:163], v232 offset:4096
	v_exp_f32_e32 v127, v127
	v_exp_f32_e32 v128, v128
	v_exp_f32_e32 v129, v129
	v_mfma_f32_16x16x32_bf16 v[30:33], v[196:199], v[172:175], v[30:33]
	ds_read_b128 v[164:167], v232 offset:6144
	v_add_f32_e32 v122, 1.0, v122
	v_add_f32_e32 v123, 1.0, v123
	v_mfma_f32_16x16x32_bf16 v[34:37], v[184:187], v[176:179], v[34:37]
	v_add_f32_e32 v124, 1.0, v124
	v_add_f32_e32 v125, 1.0, v125
	v_mfma_f32_16x16x32_bf16 v[38:41], v[188:191], v[176:179], v[38:41]
	v_add_f32_e32 v126, 1.0, v126
	v_add_f32_e32 v127, 1.0, v127
	v_add_f32_e32 v128, 1.0, v128
	v_mfma_f32_16x16x32_bf16 v[42:45], v[192:195], v[176:179], v[42:45]
	v_add_f32_e32 v129, 1.0, v129
	v_rcp_f32_e32 v122, v122
	v_mfma_f32_16x16x32_bf16 v[46:49], v[196:199], v[176:179], v[46:49]
	v_rcp_f32_e32 v123, v123
	v_rcp_f32_e32 v124, v124
	v_mfma_f32_16x16x32_bf16 v[50:53], v[184:187], v[180:183], v[50:53]
	v_rcp_f32_e32 v125, v125
	v_rcp_f32_e32 v126, v126
	v_rcp_f32_e32 v127, v127
	v_mfma_f32_16x16x32_bf16 v[54:57], v[188:191], v[180:183], v[54:57]
	v_rcp_f32_e32 v128, v128
	v_rcp_f32_e32 v129, v129
	v_mfma_f32_16x16x32_bf16 v[58:61], v[192:195], v[180:183], v[58:61]
	v_cvt_pk_bf16_f32 v122, v122, v123
	v_cvt_pk_bf16_f32 v123, v124, v125
	v_mfma_f32_16x16x32_bf16 v[62:65], v[196:199], v[180:183], v[62:65]
	v_cvt_pk_bf16_f32 v124, v126, v127
	v_cvt_pk_bf16_f32 v125, v128, v129
	global_store_dwordx4 v241, v[122:125], s[10:11] offset:2064
	s_waitcnt lgkmcnt(0)
	v_mfma_f32_16x16x32_bf16 v[2:5], v[152:155], v[136:139], v[2:5]
	ds_read_b128 v[168:171], v229 offset:0
	v_mfma_f32_16x16x32_bf16 v[6:9], v[156:159], v[136:139], v[6:9]
	ds_read_b128 v[172:175], v229 offset:2048
	v_mfma_f32_16x16x32_bf16 v[10:13], v[160:163], v[136:139], v[10:13]
	ds_read_b128 v[176:179], v229 offset:4096
	v_mfma_f32_16x16x32_bf16 v[14:17], v[164:167], v[136:139], v[14:17]
	ds_read_b128 v[180:183], v229 offset:6144
	v_mfma_f32_16x16x32_bf16 v[18:21], v[152:155], v[140:143], v[18:21]
	ds_read_b128 v[184:187], v235 offset:0
	v_mfma_f32_16x16x32_bf16 v[22:25], v[156:159], v[140:143], v[22:25]
	ds_read_b128 v[188:191], v235 offset:2048
	v_mfma_f32_16x16x32_bf16 v[26:29], v[160:163], v[140:143], v[26:29]
	ds_read_b128 v[192:195], v235 offset:4096
	v_mfma_f32_16x16x32_bf16 v[30:33], v[164:167], v[140:143], v[30:33]
	ds_read_b128 v[196:199], v235 offset:6144
	v_mfma_f32_16x16x32_bf16 v[34:37], v[152:155], v[144:147], v[34:37]
	v_mfma_f32_16x16x32_bf16 v[38:41], v[156:159], v[144:147], v[38:41]
	v_mfma_f32_16x16x32_bf16 v[42:45], v[160:163], v[144:147], v[42:45]
	v_mfma_f32_16x16x32_bf16 v[46:49], v[164:167], v[144:147], v[46:49]
	v_mfma_f32_16x16x32_bf16 v[50:53], v[152:155], v[148:151], v[50:53]
	v_mfma_f32_16x16x32_bf16 v[54:57], v[156:159], v[148:151], v[54:57]
	v_mfma_f32_16x16x32_bf16 v[58:61], v[160:163], v[148:151], v[58:61]
	v_mfma_f32_16x16x32_bf16 v[62:65], v[164:167], v[148:151], v[62:65]
	s_waitcnt lgkmcnt(0)
	s_barrier
	v_mfma_f32_16x16x32_bf16 v[2:5], v[184:187], v[168:171], v[2:5]
	ds_read_b128 v[136:139], v218 offset:0
	v_mfma_f32_16x16x32_bf16 v[6:9], v[188:191], v[168:171], v[6:9]
	ds_read_b128 v[140:143], v218 offset:2048
	v_mfma_f32_16x16x32_bf16 v[10:13], v[192:195], v[168:171], v[10:13]
	ds_read_b128 v[144:147], v218 offset:4096
	v_mfma_f32_16x16x32_bf16 v[14:17], v[196:199], v[168:171], v[14:17]
	ds_read_b128 v[148:151], v218 offset:6144
	v_mfma_f32_16x16x32_bf16 v[18:21], v[184:187], v[172:175], v[18:21]
	ds_read_b128 v[152:155], v230 offset:0
	v_mfma_f32_16x16x32_bf16 v[22:25], v[188:191], v[172:175], v[22:25]
	ds_read_b128 v[156:159], v230 offset:2048
	v_mfma_f32_16x16x32_bf16 v[26:29], v[192:195], v[172:175], v[26:29]
	ds_read_b128 v[160:163], v230 offset:4096
	v_mfma_f32_16x16x32_bf16 v[30:33], v[196:199], v[172:175], v[30:33]
	ds_read_b128 v[164:167], v230 offset:6144
	v_mfma_f32_16x16x32_bf16 v[34:37], v[184:187], v[176:179], v[34:37]
	v_mfma_f32_16x16x32_bf16 v[38:41], v[188:191], v[176:179], v[38:41]
	v_mfma_f32_16x16x32_bf16 v[42:45], v[192:195], v[176:179], v[42:45]
	v_mfma_f32_16x16x32_bf16 v[46:49], v[196:199], v[176:179], v[46:49]
	v_mfma_f32_16x16x32_bf16 v[50:53], v[184:187], v[180:183], v[50:53]
	v_mfma_f32_16x16x32_bf16 v[54:57], v[188:191], v[180:183], v[54:57]
	v_mfma_f32_16x16x32_bf16 v[58:61], v[192:195], v[180:183], v[58:61]
	v_mfma_f32_16x16x32_bf16 v[62:65], v[196:199], v[180:183], v[62:65]
	s_waitcnt lgkmcnt(0)
	v_mfma_f32_16x16x32_bf16 v[2:5], v[152:155], v[136:139], v[2:5]
	ds_read_b128 v[168:171], v225 offset:0
	v_mfma_f32_16x16x32_bf16 v[6:9], v[156:159], v[136:139], v[6:9]
	ds_read_b128 v[172:175], v225 offset:2048
	v_mfma_f32_16x16x32_bf16 v[10:13], v[160:163], v[136:139], v[10:13]
	ds_read_b128 v[176:179], v225 offset:4096
	v_mfma_f32_16x16x32_bf16 v[14:17], v[164:167], v[136:139], v[14:17]
	ds_read_b128 v[180:183], v225 offset:6144
	v_mfma_f32_16x16x32_bf16 v[18:21], v[152:155], v[140:143], v[18:21]
	ds_read_b128 v[184:187], v233 offset:0
	v_mfma_f32_16x16x32_bf16 v[22:25], v[156:159], v[140:143], v[22:25]
	ds_read_b128 v[188:191], v233 offset:2048
	v_mfma_f32_16x16x32_bf16 v[26:29], v[160:163], v[140:143], v[26:29]
	ds_read_b128 v[192:195], v233 offset:4096
	v_mfma_f32_16x16x32_bf16 v[30:33], v[164:167], v[140:143], v[30:33]
	ds_read_b128 v[196:199], v233 offset:6144
	v_mfma_f32_16x16x32_bf16 v[34:37], v[152:155], v[144:147], v[34:37]
	v_mfma_f32_16x16x32_bf16 v[38:41], v[156:159], v[144:147], v[38:41]
	v_mfma_f32_16x16x32_bf16 v[42:45], v[160:163], v[144:147], v[42:45]
	v_mfma_f32_16x16x32_bf16 v[46:49], v[164:167], v[144:147], v[46:49]
	v_mfma_f32_16x16x32_bf16 v[50:53], v[152:155], v[148:151], v[50:53]
	v_mfma_f32_16x16x32_bf16 v[54:57], v[156:159], v[148:151], v[54:57]
	v_mfma_f32_16x16x32_bf16 v[58:61], v[160:163], v[148:151], v[58:61]
	v_mfma_f32_16x16x32_bf16 v[62:65], v[164:167], v[148:151], v[62:65]
	s_waitcnt lgkmcnt(0)
	s_barrier
	v_mfma_f32_16x16x32_bf16 v[2:5], v[184:187], v[168:171], v[2:5]
	ds_read_b128 v[136:139], v219 offset:0
	v_mfma_f32_16x16x32_bf16 v[6:9], v[188:191], v[168:171], v[6:9]
	ds_read_b128 v[140:143], v219 offset:2048
	v_mfma_f32_16x16x32_bf16 v[10:13], v[192:195], v[168:171], v[10:13]
	ds_read_b128 v[144:147], v219 offset:4096
	v_mfma_f32_16x16x32_bf16 v[14:17], v[196:199], v[168:171], v[14:17]
	ds_read_b128 v[148:151], v219 offset:6144
	v_mfma_f32_16x16x32_bf16 v[18:21], v[184:187], v[172:175], v[18:21]
	ds_read_b128 v[152:155], v231 offset:0
	v_mfma_f32_16x16x32_bf16 v[22:25], v[188:191], v[172:175], v[22:25]
	ds_read_b128 v[156:159], v231 offset:2048
	v_mfma_f32_16x16x32_bf16 v[26:29], v[192:195], v[172:175], v[26:29]
	ds_read_b128 v[160:163], v231 offset:4096
	v_mfma_f32_16x16x32_bf16 v[30:33], v[196:199], v[172:175], v[30:33]
	ds_read_b128 v[164:167], v231 offset:6144
	v_mfma_f32_16x16x32_bf16 v[34:37], v[184:187], v[176:179], v[34:37]
	v_mfma_f32_16x16x32_bf16 v[38:41], v[188:191], v[176:179], v[38:41]
	v_mfma_f32_16x16x32_bf16 v[42:45], v[192:195], v[176:179], v[42:45]
	v_mfma_f32_16x16x32_bf16 v[46:49], v[196:199], v[176:179], v[46:49]
	v_mfma_f32_16x16x32_bf16 v[50:53], v[184:187], v[180:183], v[50:53]
	v_mfma_f32_16x16x32_bf16 v[54:57], v[188:191], v[180:183], v[54:57]
	v_mfma_f32_16x16x32_bf16 v[58:61], v[192:195], v[180:183], v[58:61]
	v_mfma_f32_16x16x32_bf16 v[62:65], v[196:199], v[180:183], v[62:65]
	s_waitcnt lgkmcnt(0)
	v_mfma_f32_16x16x32_bf16 v[2:5], v[152:155], v[136:139], v[2:5]
	ds_read_b128 v[168:171], v228 offset:0
	v_mfma_f32_16x16x32_bf16 v[6:9], v[156:159], v[136:139], v[6:9]
	ds_read_b128 v[172:175], v228 offset:2048
	v_mfma_f32_16x16x32_bf16 v[10:13], v[160:163], v[136:139], v[10:13]
	ds_read_b128 v[176:179], v228 offset:4096
	v_mfma_f32_16x16x32_bf16 v[14:17], v[164:167], v[136:139], v[14:17]
	ds_read_b128 v[180:183], v228 offset:6144
	v_mfma_f32_16x16x32_bf16 v[18:21], v[152:155], v[140:143], v[18:21]
	ds_read_b128 v[184:187], v234 offset:0
	v_mfma_f32_16x16x32_bf16 v[22:25], v[156:159], v[140:143], v[22:25]
	ds_read_b128 v[188:191], v234 offset:2048
	v_mfma_f32_16x16x32_bf16 v[26:29], v[160:163], v[140:143], v[26:29]
	ds_read_b128 v[192:195], v234 offset:4096
	v_mfma_f32_16x16x32_bf16 v[30:33], v[164:167], v[140:143], v[30:33]
	ds_read_b128 v[196:199], v234 offset:6144
	v_mfma_f32_16x16x32_bf16 v[34:37], v[152:155], v[144:147], v[34:37]
	v_mfma_f32_16x16x32_bf16 v[38:41], v[156:159], v[144:147], v[38:41]
	v_mfma_f32_16x16x32_bf16 v[42:45], v[160:163], v[144:147], v[42:45]
	v_mfma_f32_16x16x32_bf16 v[46:49], v[164:167], v[144:147], v[46:49]
	v_mfma_f32_16x16x32_bf16 v[50:53], v[152:155], v[148:151], v[50:53]
	v_mfma_f32_16x16x32_bf16 v[54:57], v[156:159], v[148:151], v[54:57]
	v_mfma_f32_16x16x32_bf16 v[58:61], v[160:163], v[148:151], v[58:61]
	v_mfma_f32_16x16x32_bf16 v[62:65], v[164:167], v[148:151], v[62:65]
	s_waitcnt lgkmcnt(0)
	s_barrier
	v_mfma_f32_16x16x32_bf16 v[2:5], v[184:187], v[168:171], v[2:5]
	ds_read_b128 v[136:139], v224 offset:0
	v_mfma_f32_16x16x32_bf16 v[6:9], v[188:191], v[168:171], v[6:9]
	ds_read_b128 v[140:143], v224 offset:2048
	v_mfma_f32_16x16x32_bf16 v[10:13], v[192:195], v[168:171], v[10:13]
	ds_read_b128 v[144:147], v224 offset:4096
	v_mfma_f32_16x16x32_bf16 v[14:17], v[196:199], v[168:171], v[14:17]
	ds_read_b128 v[148:151], v224 offset:6144
	v_mfma_f32_16x16x32_bf16 v[18:21], v[184:187], v[172:175], v[18:21]
	ds_read_b128 v[152:155], v232 offset:0
	v_mfma_f32_16x16x32_bf16 v[22:25], v[188:191], v[172:175], v[22:25]
	ds_read_b128 v[156:159], v232 offset:2048
	v_mfma_f32_16x16x32_bf16 v[26:29], v[192:195], v[172:175], v[26:29]
	ds_read_b128 v[160:163], v232 offset:4096
	v_mfma_f32_16x16x32_bf16 v[30:33], v[196:199], v[172:175], v[30:33]
	ds_read_b128 v[164:167], v232 offset:6144
	v_mfma_f32_16x16x32_bf16 v[34:37], v[184:187], v[176:179], v[34:37]
	v_mfma_f32_16x16x32_bf16 v[38:41], v[188:191], v[176:179], v[38:41]
	v_mfma_f32_16x16x32_bf16 v[42:45], v[192:195], v[176:179], v[42:45]
	v_mfma_f32_16x16x32_bf16 v[46:49], v[196:199], v[176:179], v[46:49]
	v_mfma_f32_16x16x32_bf16 v[50:53], v[184:187], v[180:183], v[50:53]
	v_mfma_f32_16x16x32_bf16 v[54:57], v[188:191], v[180:183], v[54:57]
	v_mfma_f32_16x16x32_bf16 v[58:61], v[192:195], v[180:183], v[58:61]
	v_mfma_f32_16x16x32_bf16 v[62:65], v[196:199], v[180:183], v[62:65]
	s_waitcnt lgkmcnt(0)
	v_mfma_f32_16x16x32_bf16 v[2:5], v[152:155], v[136:139], v[2:5]
	ds_read_b128 v[168:171], v229 offset:0
	v_mfma_f32_16x16x32_bf16 v[6:9], v[156:159], v[136:139], v[6:9]
	ds_read_b128 v[172:175], v229 offset:2048
	v_mfma_f32_16x16x32_bf16 v[10:13], v[160:163], v[136:139], v[10:13]
	ds_read_b128 v[176:179], v229 offset:4096
	v_mfma_f32_16x16x32_bf16 v[14:17], v[164:167], v[136:139], v[14:17]
	ds_read_b128 v[180:183], v229 offset:6144
	v_mfma_f32_16x16x32_bf16 v[18:21], v[152:155], v[140:143], v[18:21]
	ds_read_b128 v[184:187], v235 offset:0
	v_mfma_f32_16x16x32_bf16 v[22:25], v[156:159], v[140:143], v[22:25]
	ds_read_b128 v[188:191], v235 offset:2048
	v_mfma_f32_16x16x32_bf16 v[26:29], v[160:163], v[140:143], v[26:29]
	ds_read_b128 v[192:195], v235 offset:4096
	v_mfma_f32_16x16x32_bf16 v[30:33], v[164:167], v[140:143], v[30:33]
	ds_read_b128 v[196:199], v235 offset:6144
	v_mfma_f32_16x16x32_bf16 v[34:37], v[152:155], v[144:147], v[34:37]
	v_mfma_f32_16x16x32_bf16 v[38:41], v[156:159], v[144:147], v[38:41]
	v_mfma_f32_16x16x32_bf16 v[42:45], v[160:163], v[144:147], v[42:45]
	v_mfma_f32_16x16x32_bf16 v[46:49], v[164:167], v[144:147], v[46:49]
	v_mfma_f32_16x16x32_bf16 v[50:53], v[152:155], v[148:151], v[50:53]
	v_mfma_f32_16x16x32_bf16 v[54:57], v[156:159], v[148:151], v[54:57]
	v_mfma_f32_16x16x32_bf16 v[58:61], v[160:163], v[148:151], v[58:61]
	v_mfma_f32_16x16x32_bf16 v[62:65], v[164:167], v[148:151], v[62:65]
	s_waitcnt lgkmcnt(0)
	s_barrier
	v_mfma_f32_16x16x32_bf16 v[2:5], v[184:187], v[168:171], v[2:5]
	ds_read_b128 v[136:139], v218 offset:0
	v_mfma_f32_16x16x32_bf16 v[6:9], v[188:191], v[168:171], v[6:9]
	ds_read_b128 v[140:143], v218 offset:2048
	v_mfma_f32_16x16x32_bf16 v[10:13], v[192:195], v[168:171], v[10:13]
	ds_read_b128 v[144:147], v218 offset:4096
	v_mfma_f32_16x16x32_bf16 v[14:17], v[196:199], v[168:171], v[14:17]
	ds_read_b128 v[148:151], v218 offset:6144
	v_mfma_f32_16x16x32_bf16 v[18:21], v[184:187], v[172:175], v[18:21]
	ds_read_b128 v[152:155], v230 offset:0
	v_mfma_f32_16x16x32_bf16 v[22:25], v[188:191], v[172:175], v[22:25]
	ds_read_b128 v[156:159], v230 offset:2048
	v_mfma_f32_16x16x32_bf16 v[26:29], v[192:195], v[172:175], v[26:29]
	ds_read_b128 v[160:163], v230 offset:4096
	v_mfma_f32_16x16x32_bf16 v[30:33], v[196:199], v[172:175], v[30:33]
	ds_read_b128 v[164:167], v230 offset:6144
	v_mfma_f32_16x16x32_bf16 v[34:37], v[184:187], v[176:179], v[34:37]
	v_mfma_f32_16x16x32_bf16 v[38:41], v[188:191], v[176:179], v[38:41]
	v_mfma_f32_16x16x32_bf16 v[42:45], v[192:195], v[176:179], v[42:45]
	v_mfma_f32_16x16x32_bf16 v[46:49], v[196:199], v[176:179], v[46:49]
	v_mfma_f32_16x16x32_bf16 v[50:53], v[184:187], v[180:183], v[50:53]
	v_mfma_f32_16x16x32_bf16 v[54:57], v[188:191], v[180:183], v[54:57]
	v_mfma_f32_16x16x32_bf16 v[58:61], v[192:195], v[180:183], v[58:61]
	v_mfma_f32_16x16x32_bf16 v[62:65], v[196:199], v[180:183], v[62:65]
	s_waitcnt lgkmcnt(0)
	v_mfma_f32_16x16x32_bf16 v[66:69], v[152:155], v[136:139], 0
	ds_read_b128 v[168:171], v225 offset:0
	v_mfma_f32_16x16x32_bf16 v[70:73], v[156:159], v[136:139], 0
	ds_read_b128 v[172:175], v225 offset:2048
	v_mfma_f32_16x16x32_bf16 v[74:77], v[160:163], v[136:139], 0
	ds_read_b128 v[176:179], v225 offset:4096
	v_mfma_f32_16x16x32_bf16 v[78:81], v[164:167], v[136:139], 0
	ds_read_b128 v[180:183], v225 offset:6144
	v_mfma_f32_16x16x32_bf16 v[82:85], v[152:155], v[140:143], 0
	ds_read_b128 v[184:187], v233 offset:0
	v_mfma_f32_16x16x32_bf16 v[86:89], v[156:159], v[140:143], 0
	ds_read_b128 v[188:191], v233 offset:2048
	v_mfma_f32_16x16x32_bf16 v[90:93], v[160:163], v[140:143], 0
	ds_read_b128 v[192:195], v233 offset:4096
	v_mfma_f32_16x16x32_bf16 v[94:97], v[164:167], v[140:143], 0
	ds_read_b128 v[196:199], v233 offset:6144
	v_mfma_f32_16x16x32_bf16 v[98:101], v[152:155], v[144:147], 0
	v_mfma_f32_16x16x32_bf16 v[102:105], v[156:159], v[144:147], 0
	v_mfma_f32_16x16x32_bf16 v[106:109], v[160:163], v[144:147], 0
	v_mfma_f32_16x16x32_bf16 v[110:113], v[164:167], v[144:147], 0
	v_mfma_f32_16x16x32_bf16 v[114:117], v[152:155], v[148:151], 0
	v_mfma_f32_16x16x32_bf16 v[118:121], v[156:159], v[148:151], 0
	v_mfma_f32_16x16x32_bf16 v[122:125], v[160:163], v[148:151], 0
	v_mfma_f32_16x16x32_bf16 v[126:129], v[164:167], v[148:151], 0
	s_waitcnt lgkmcnt(0)
	s_barrier
	s_add_u32 s14, s4, 0x180
	s_addc_u32 s15, s5, 0
	v_mfma_f32_16x16x32_bf16 v[66:69], v[184:187], v[168:171], v[66:69]
	ds_read_b128 v[136:139], v219 offset:0
	s_add_u32 s22, s4, 0x10180
	s_addc_u32 s23, s5, 0
	v_mfma_f32_16x16x32_bf16 v[70:73], v[188:191], v[168:171], v[70:73]
	ds_read_b128 v[140:143], v219 offset:2048
	s_add_u32 s24, s6, 0xc0180
	s_addc_u32 s25, s7, 0
	v_mfma_f32_16x16x32_bf16 v[74:77], v[192:195], v[168:171], v[74:77]
	ds_read_b128 v[144:147], v219 offset:4096
	s_add_u32 s52, s6, 0xc8180
	s_addc_u32 s53, s7, 0
	v_mfma_f32_16x16x32_bf16 v[78:81], v[196:199], v[168:171], v[78:81]
	ds_read_b128 v[148:151], v219 offset:6144
	s_mov_b32 m0, s8
	v_mfma_f32_16x16x32_bf16 v[82:85], v[184:187], v[172:175], v[82:85]
	global_load_lds_dwordx4 v200, s[14:15]
	ds_read_b128 v[152:155], v231 offset:0
	s_add_u32 m0, s8, 0x400
	v_mfma_f32_16x16x32_bf16 v[86:89], v[188:191], v[172:175], v[86:89]
	global_load_lds_dwordx4 v201, s[14:15]
	ds_read_b128 v[156:159], v231 offset:2048
	s_add_u32 m0, s8, 0x800
	v_mfma_f32_16x16x32_bf16 v[90:93], v[192:195], v[172:175], v[90:93]
	global_load_lds_dwordx4 v202, s[14:15]
	ds_read_b128 v[160:163], v231 offset:4096
	s_add_u32 m0, s8, 0xc00
	v_mfma_f32_16x16x32_bf16 v[94:97], v[196:199], v[172:175], v[94:97]
	global_load_lds_dwordx4 v203, s[14:15]
	ds_read_b128 v[164:167], v231 offset:6144
	s_add_u32 m0, s8, 0x1000
	v_mfma_f32_16x16x32_bf16 v[98:101], v[184:187], v[176:179], v[98:101]
	global_load_lds_dwordx4 v200, s[22:23]
	s_add_u32 m0, s8, 0x1400
	v_mfma_f32_16x16x32_bf16 v[102:105], v[188:191], v[176:179], v[102:105]
	global_load_lds_dwordx4 v201, s[22:23]
	s_add_u32 m0, s8, 0x1800
	v_mfma_f32_16x16x32_bf16 v[106:109], v[192:195], v[176:179], v[106:109]
	global_load_lds_dwordx4 v202, s[22:23]
	s_add_u32 m0, s8, 0x1c00
	v_mfma_f32_16x16x32_bf16 v[110:113], v[196:199], v[176:179], v[110:113]
	global_load_lds_dwordx4 v203, s[22:23]
	s_mov_b32 m0, s9
	v_mfma_f32_16x16x32_bf16 v[114:117], v[184:187], v[180:183], v[114:117]
	global_load_lds_dwordx4 v204, s[24:25]
	s_add_u32 m0, s9, 0x400
	v_mfma_f32_16x16x32_bf16 v[118:121], v[188:191], v[180:183], v[118:121]
	global_load_lds_dwordx4 v205, s[24:25]
	s_add_u32 m0, s9, 0x800
	v_mfma_f32_16x16x32_bf16 v[122:125], v[192:195], v[180:183], v[122:125]
	global_load_lds_dwordx4 v204, s[52:53]
	s_add_u32 m0, s9, 0xc00
	v_mfma_f32_16x16x32_bf16 v[126:129], v[196:199], v[180:183], v[126:129]
	global_load_lds_dwordx4 v205, s[52:53]
	s_waitcnt lgkmcnt(0)
	v_mfma_f32_16x16x32_bf16 v[66:69], v[152:155], v[136:139], v[66:69]
	ds_read_b128 v[168:171], v228 offset:0
	v_mfma_f32_16x16x32_bf16 v[70:73], v[156:159], v[136:139], v[70:73]
	ds_read_b128 v[172:175], v228 offset:2048
	v_mfma_f32_16x16x32_bf16 v[74:77], v[160:163], v[136:139], v[74:77]
	ds_read_b128 v[176:179], v228 offset:4096
	v_mfma_f32_16x16x32_bf16 v[78:81], v[164:167], v[136:139], v[78:81]
	ds_read_b128 v[180:183], v228 offset:6144
	v_mfma_f32_16x16x32_bf16 v[82:85], v[152:155], v[140:143], v[82:85]
	ds_read_b128 v[184:187], v234 offset:0
	v_mfma_f32_16x16x32_bf16 v[86:89], v[156:159], v[140:143], v[86:89]
	ds_read_b128 v[188:191], v234 offset:2048
	v_mfma_f32_16x16x32_bf16 v[90:93], v[160:163], v[140:143], v[90:93]
	ds_read_b128 v[192:195], v234 offset:4096
	v_mfma_f32_16x16x32_bf16 v[94:97], v[164:167], v[140:143], v[94:97]
	ds_read_b128 v[196:199], v234 offset:6144
	v_mfma_f32_16x16x32_bf16 v[98:101], v[152:155], v[144:147], v[98:101]
	v_mfma_f32_16x16x32_bf16 v[102:105], v[156:159], v[144:147], v[102:105]
	v_mfma_f32_16x16x32_bf16 v[106:109], v[160:163], v[144:147], v[106:109]
	v_mfma_f32_16x16x32_bf16 v[110:113], v[164:167], v[144:147], v[110:113]
	v_mfma_f32_16x16x32_bf16 v[114:117], v[152:155], v[148:151], v[114:117]
	v_mfma_f32_16x16x32_bf16 v[118:121], v[156:159], v[148:151], v[118:121]
	v_mfma_f32_16x16x32_bf16 v[122:125], v[160:163], v[148:151], v[122:125]
	v_mfma_f32_16x16x32_bf16 v[126:129], v[164:167], v[148:151], v[126:129]
	s_waitcnt lgkmcnt(0)
	s_barrier
	s_add_u32 s14, s4, 0x200
	s_addc_u32 s15, s5, 0
	v_mfma_f32_16x16x32_bf16 v[66:69], v[184:187], v[168:171], v[66:69]
	ds_read_b128 v[136:139], v224 offset:0
	s_add_u32 s22, s4, 0x10200
	s_addc_u32 s23, s5, 0
	v_mfma_f32_16x16x32_bf16 v[70:73], v[188:191], v[168:171], v[70:73]
	ds_read_b128 v[140:143], v224 offset:2048
	s_add_u32 s24, s6, 0xc0200
	s_addc_u32 s25, s7, 0
	v_mfma_f32_16x16x32_bf16 v[74:77], v[192:195], v[168:171], v[74:77]
	ds_read_b128 v[144:147], v224 offset:4096
	s_add_u32 s52, s6, 0xc8200
	s_addc_u32 s53, s7, 0
	v_mfma_f32_16x16x32_bf16 v[78:81], v[196:199], v[168:171], v[78:81]
	ds_read_b128 v[148:151], v224 offset:6144
	s_add_u32 m0, s8, 0xc000
	v_mfma_f32_16x16x32_bf16 v[82:85], v[184:187], v[172:175], v[82:85]
	global_load_lds_dwordx4 v200, s[14:15]
	ds_read_b128 v[152:155], v232 offset:0
	s_add_u32 m0, s8, 0xc400
	v_mfma_f32_16x16x32_bf16 v[86:89], v[188:191], v[172:175], v[86:89]
	global_load_lds_dwordx4 v201, s[14:15]
	ds_read_b128 v[156:159], v232 offset:2048
	s_add_u32 m0, s8, 0xc800
	v_mfma_f32_16x16x32_bf16 v[90:93], v[192:195], v[172:175], v[90:93]
	global_load_lds_dwordx4 v202, s[14:15]
	ds_read_b128 v[160:163], v232 offset:4096
	s_add_u32 m0, s8, 0xcc00
	v_mfma_f32_16x16x32_bf16 v[94:97], v[196:199], v[172:175], v[94:97]
	global_load_lds_dwordx4 v203, s[14:15]
	ds_read_b128 v[164:167], v232 offset:6144
	s_add_u32 m0, s8, 0xd000
	v_mfma_f32_16x16x32_bf16 v[98:101], v[184:187], v[176:179], v[98:101]
	global_load_lds_dwordx4 v200, s[22:23]
	s_add_u32 m0, s8, 0xd400
	v_mfma_f32_16x16x32_bf16 v[102:105], v[188:191], v[176:179], v[102:105]
	global_load_lds_dwordx4 v201, s[22:23]
	s_add_u32 m0, s8, 0xd800
	v_mfma_f32_16x16x32_bf16 v[106:109], v[192:195], v[176:179], v[106:109]
	global_load_lds_dwordx4 v202, s[22:23]
	s_add_u32 m0, s8, 0xdc00
	v_mfma_f32_16x16x32_bf16 v[110:113], v[196:199], v[176:179], v[110:113]
	global_load_lds_dwordx4 v203, s[22:23]
	s_add_u32 m0, s9, 0xc000
	v_mfma_f32_16x16x32_bf16 v[114:117], v[184:187], v[180:183], v[114:117]
	global_load_lds_dwordx4 v204, s[24:25]
	s_add_u32 m0, s9, 0xc400
	v_mfma_f32_16x16x32_bf16 v[118:121], v[188:191], v[180:183], v[118:121]
	global_load_lds_dwordx4 v205, s[24:25]
	s_add_u32 m0, s9, 0xc800
	v_mfma_f32_16x16x32_bf16 v[122:125], v[192:195], v[180:183], v[122:125]
	global_load_lds_dwordx4 v204, s[52:53]
	s_add_u32 m0, s9, 0xcc00
	v_mfma_f32_16x16x32_bf16 v[126:129], v[196:199], v[180:183], v[126:129]
	global_load_lds_dwordx4 v205, s[52:53]
	s_waitcnt lgkmcnt(0)
	v_mfma_f32_16x16x32_bf16 v[66:69], v[152:155], v[136:139], v[66:69]
	ds_read_b128 v[168:171], v229 offset:0
	v_mfma_f32_16x16x32_bf16 v[70:73], v[156:159], v[136:139], v[70:73]
	ds_read_b128 v[172:175], v229 offset:2048
	v_mfma_f32_16x16x32_bf16 v[74:77], v[160:163], v[136:139], v[74:77]
	ds_read_b128 v[176:179], v229 offset:4096
	v_mfma_f32_16x16x32_bf16 v[78:81], v[164:167], v[136:139], v[78:81]
	ds_read_b128 v[180:183], v229 offset:6144
	v_mfma_f32_16x16x32_bf16 v[82:85], v[152:155], v[140:143], v[82:85]
	ds_read_b128 v[184:187], v235 offset:0
	v_mfma_f32_16x16x32_bf16 v[86:89], v[156:159], v[140:143], v[86:89]
	ds_read_b128 v[188:191], v235 offset:2048
	v_mfma_f32_16x16x32_bf16 v[90:93], v[160:163], v[140:143], v[90:93]
	ds_read_b128 v[192:195], v235 offset:4096
	v_mfma_f32_16x16x32_bf16 v[94:97], v[164:167], v[140:143], v[94:97]
	ds_read_b128 v[196:199], v235 offset:6144
	v_mfma_f32_16x16x32_bf16 v[98:101], v[152:155], v[144:147], v[98:101]
	v_mfma_f32_16x16x32_bf16 v[102:105], v[156:159], v[144:147], v[102:105]
	v_mfma_f32_16x16x32_bf16 v[106:109], v[160:163], v[144:147], v[106:109]
	v_mfma_f32_16x16x32_bf16 v[110:113], v[164:167], v[144:147], v[110:113]
	v_mfma_f32_16x16x32_bf16 v[114:117], v[152:155], v[148:151], v[114:117]
	v_mfma_f32_16x16x32_bf16 v[118:121], v[156:159], v[148:151], v[118:121]
	v_mfma_f32_16x16x32_bf16 v[122:125], v[160:163], v[148:151], v[122:125]
	v_mfma_f32_16x16x32_bf16 v[126:129], v[164:167], v[148:151], v[126:129]
	s_waitcnt vmcnt(12) lgkmcnt(0)
	s_barrier
	s_add_u32 s14, s4, 0x280
	s_addc_u32 s15, s5, 0
	v_mfma_f32_16x16x32_bf16 v[66:69], v[184:187], v[168:171], v[66:69]
	ds_read_b128 v[136:139], v218 offset:0
	s_add_u32 s22, s4, 0x10280
	s_addc_u32 s23, s5, 0
	v_mfma_f32_16x16x32_bf16 v[70:73], v[188:191], v[168:171], v[70:73]
	ds_read_b128 v[140:143], v218 offset:2048
	s_add_u32 s24, s6, 0xc0280
	s_addc_u32 s25, s7, 0
	v_mfma_f32_16x16x32_bf16 v[74:77], v[192:195], v[168:171], v[74:77]
	ds_read_b128 v[144:147], v218 offset:4096
	s_add_u32 s52, s6, 0xc8280
	s_addc_u32 s53, s7, 0
	v_mfma_f32_16x16x32_bf16 v[78:81], v[196:199], v[168:171], v[78:81]
	ds_read_b128 v[148:151], v218 offset:6144
	s_add_u32 m0, s8, 0x18000
	v_mfma_f32_16x16x32_bf16 v[82:85], v[184:187], v[172:175], v[82:85]
	global_load_lds_dwordx4 v200, s[14:15]
	ds_read_b128 v[152:155], v230 offset:0
	s_add_u32 m0, s8, 0x18400
	v_mfma_f32_16x16x32_bf16 v[86:89], v[188:191], v[172:175], v[86:89]
	global_load_lds_dwordx4 v201, s[14:15]
	ds_read_b128 v[156:159], v230 offset:2048
	s_add_u32 m0, s8, 0x18800
	v_mfma_f32_16x16x32_bf16 v[90:93], v[192:195], v[172:175], v[90:93]
	global_load_lds_dwordx4 v202, s[14:15]
	ds_read_b128 v[160:163], v230 offset:4096
	s_add_u32 m0, s8, 0x18c00
	v_mfma_f32_16x16x32_bf16 v[94:97], v[196:199], v[172:175], v[94:97]
	global_load_lds_dwordx4 v203, s[14:15]
	ds_read_b128 v[164:167], v230 offset:6144
	s_add_u32 m0, s8, 0x19000
	v_mfma_f32_16x16x32_bf16 v[98:101], v[184:187], v[176:179], v[98:101]
	global_load_lds_dwordx4 v200, s[22:23]
	s_add_u32 m0, s8, 0x19400
	v_mfma_f32_16x16x32_bf16 v[102:105], v[188:191], v[176:179], v[102:105]
	global_load_lds_dwordx4 v201, s[22:23]
	s_add_u32 m0, s8, 0x19800
	v_mfma_f32_16x16x32_bf16 v[106:109], v[192:195], v[176:179], v[106:109]
	global_load_lds_dwordx4 v202, s[22:23]
	s_add_u32 m0, s8, 0x19c00
	v_mfma_f32_16x16x32_bf16 v[110:113], v[196:199], v[176:179], v[110:113]
	global_load_lds_dwordx4 v203, s[22:23]
	s_add_u32 m0, s9, 0x18000
	v_mfma_f32_16x16x32_bf16 v[114:117], v[184:187], v[180:183], v[114:117]
	global_load_lds_dwordx4 v204, s[24:25]
	s_add_u32 m0, s9, 0x18400
	v_mfma_f32_16x16x32_bf16 v[118:121], v[188:191], v[180:183], v[118:121]
	global_load_lds_dwordx4 v205, s[24:25]
	s_add_u32 m0, s9, 0x18800
	v_mfma_f32_16x16x32_bf16 v[122:125], v[192:195], v[180:183], v[122:125]
	global_load_lds_dwordx4 v204, s[52:53]
	s_add_u32 m0, s9, 0x18c00
	v_mfma_f32_16x16x32_bf16 v[126:129], v[196:199], v[180:183], v[126:129]
	global_load_lds_dwordx4 v205, s[52:53]
	s_waitcnt lgkmcnt(0)
	v_mfma_f32_16x16x32_bf16 v[66:69], v[152:155], v[136:139], v[66:69]
	ds_read_b128 v[168:171], v225 offset:0
	v_mfma_f32_16x16x32_bf16 v[70:73], v[156:159], v[136:139], v[70:73]
	ds_read_b128 v[172:175], v225 offset:2048
	v_mfma_f32_16x16x32_bf16 v[74:77], v[160:163], v[136:139], v[74:77]
	ds_read_b128 v[176:179], v225 offset:4096
	v_mfma_f32_16x16x32_bf16 v[78:81], v[164:167], v[136:139], v[78:81]
	ds_read_b128 v[180:183], v225 offset:6144
	v_mfma_f32_16x16x32_bf16 v[82:85], v[152:155], v[140:143], v[82:85]
	ds_read_b128 v[184:187], v233 offset:0
	v_mfma_f32_16x16x32_bf16 v[86:89], v[156:159], v[140:143], v[86:89]
	ds_read_b128 v[188:191], v233 offset:2048
	v_mfma_f32_16x16x32_bf16 v[90:93], v[160:163], v[140:143], v[90:93]
	ds_read_b128 v[192:195], v233 offset:4096
	v_mfma_f32_16x16x32_bf16 v[94:97], v[164:167], v[140:143], v[94:97]
	ds_read_b128 v[196:199], v233 offset:6144
	v_mfma_f32_16x16x32_bf16 v[98:101], v[152:155], v[144:147], v[98:101]
	v_mfma_f32_16x16x32_bf16 v[102:105], v[156:159], v[144:147], v[102:105]
	v_mfma_f32_16x16x32_bf16 v[106:109], v[160:163], v[144:147], v[106:109]
	v_mfma_f32_16x16x32_bf16 v[110:113], v[164:167], v[144:147], v[110:113]
	v_mfma_f32_16x16x32_bf16 v[114:117], v[152:155], v[148:151], v[114:117]
	v_mfma_f32_16x16x32_bf16 v[118:121], v[156:159], v[148:151], v[118:121]
	v_mfma_f32_16x16x32_bf16 v[122:125], v[160:163], v[148:151], v[122:125]
	v_mfma_f32_16x16x32_bf16 v[126:129], v[164:167], v[148:151], v[126:129]
	s_waitcnt vmcnt(12) lgkmcnt(0)
	s_barrier
	s_add_u32 s14, s4, 0x300
	s_addc_u32 s15, s5, 0
	v_mfma_f32_16x16x32_bf16 v[66:69], v[184:187], v[168:171], v[66:69]
	ds_read_b128 v[136:139], v219 offset:0
	s_add_u32 s22, s4, 0x10300
	s_addc_u32 s23, s5, 0
	v_mfma_f32_16x16x32_bf16 v[70:73], v[188:191], v[168:171], v[70:73]
	ds_read_b128 v[140:143], v219 offset:2048
	s_add_u32 s24, s6, 0xc0300
	s_addc_u32 s25, s7, 0
	v_mfma_f32_16x16x32_bf16 v[74:77], v[192:195], v[168:171], v[74:77]
	ds_read_b128 v[144:147], v219 offset:4096
	s_add_u32 s52, s6, 0xc8300
	s_addc_u32 s53, s7, 0
	v_mfma_f32_16x16x32_bf16 v[78:81], v[196:199], v[168:171], v[78:81]
	ds_read_b128 v[148:151], v219 offset:6144
	s_mov_b32 m0, s8
	v_mfma_f32_16x16x32_bf16 v[82:85], v[184:187], v[172:175], v[82:85]
	global_load_lds_dwordx4 v200, s[14:15]
	ds_read_b128 v[152:155], v231 offset:0
	s_add_u32 m0, s8, 0x400
	v_mfma_f32_16x16x32_bf16 v[86:89], v[188:191], v[172:175], v[86:89]
	global_load_lds_dwordx4 v201, s[14:15]
	ds_read_b128 v[156:159], v231 offset:2048
	s_add_u32 m0, s8, 0x800
	v_mfma_f32_16x16x32_bf16 v[90:93], v[192:195], v[172:175], v[90:93]
	global_load_lds_dwordx4 v202, s[14:15]
	ds_read_b128 v[160:163], v231 offset:4096
	s_add_u32 m0, s8, 0xc00
	v_mfma_f32_16x16x32_bf16 v[94:97], v[196:199], v[172:175], v[94:97]
	global_load_lds_dwordx4 v203, s[14:15]
	ds_read_b128 v[164:167], v231 offset:6144
	s_add_u32 m0, s8, 0x1000
	v_mfma_f32_16x16x32_bf16 v[98:101], v[184:187], v[176:179], v[98:101]
	global_load_lds_dwordx4 v200, s[22:23]
	s_add_u32 m0, s8, 0x1400
	v_mfma_f32_16x16x32_bf16 v[102:105], v[188:191], v[176:179], v[102:105]
	global_load_lds_dwordx4 v201, s[22:23]
	s_add_u32 m0, s8, 0x1800
	v_mfma_f32_16x16x32_bf16 v[106:109], v[192:195], v[176:179], v[106:109]
	global_load_lds_dwordx4 v202, s[22:23]
	s_add_u32 m0, s8, 0x1c00
	v_mfma_f32_16x16x32_bf16 v[110:113], v[196:199], v[176:179], v[110:113]
	global_load_lds_dwordx4 v203, s[22:23]
	s_mov_b32 m0, s9
	v_mfma_f32_16x16x32_bf16 v[114:117], v[184:187], v[180:183], v[114:117]
	global_load_lds_dwordx4 v204, s[24:25]
	s_add_u32 m0, s9, 0x400
	v_mfma_f32_16x16x32_bf16 v[118:121], v[188:191], v[180:183], v[118:121]
	global_load_lds_dwordx4 v205, s[24:25]
	s_add_u32 m0, s9, 0x800
	v_mfma_f32_16x16x32_bf16 v[122:125], v[192:195], v[180:183], v[122:125]
	global_load_lds_dwordx4 v204, s[52:53]
	s_add_u32 m0, s9, 0xc00
	v_mfma_f32_16x16x32_bf16 v[126:129], v[196:199], v[180:183], v[126:129]
	global_load_lds_dwordx4 v205, s[52:53]
	s_waitcnt lgkmcnt(0)
	v_mfma_f32_16x16x32_bf16 v[66:69], v[152:155], v[136:139], v[66:69]
	ds_read_b128 v[168:171], v228 offset:0
	v_mfma_f32_16x16x32_bf16 v[70:73], v[156:159], v[136:139], v[70:73]
	ds_read_b128 v[172:175], v228 offset:2048
	v_mfma_f32_16x16x32_bf16 v[74:77], v[160:163], v[136:139], v[74:77]
	ds_read_b128 v[176:179], v228 offset:4096
	v_mfma_f32_16x16x32_bf16 v[78:81], v[164:167], v[136:139], v[78:81]
	ds_read_b128 v[180:183], v228 offset:6144
	v_mfma_f32_16x16x32_bf16 v[82:85], v[152:155], v[140:143], v[82:85]
	ds_read_b128 v[184:187], v234 offset:0
	v_mfma_f32_16x16x32_bf16 v[86:89], v[156:159], v[140:143], v[86:89]
	ds_read_b128 v[188:191], v234 offset:2048
	v_mfma_f32_16x16x32_bf16 v[90:93], v[160:163], v[140:143], v[90:93]
	ds_read_b128 v[192:195], v234 offset:4096
	v_mfma_f32_16x16x32_bf16 v[94:97], v[164:167], v[140:143], v[94:97]
	ds_read_b128 v[196:199], v234 offset:6144
	v_mfma_f32_16x16x32_bf16 v[98:101], v[152:155], v[144:147], v[98:101]
	v_mfma_f32_16x16x32_bf16 v[102:105], v[156:159], v[144:147], v[102:105]
	v_mfma_f32_16x16x32_bf16 v[106:109], v[160:163], v[144:147], v[106:109]
	v_mfma_f32_16x16x32_bf16 v[110:113], v[164:167], v[144:147], v[110:113]
	v_mfma_f32_16x16x32_bf16 v[114:117], v[152:155], v[148:151], v[114:117]
	v_mfma_f32_16x16x32_bf16 v[118:121], v[156:159], v[148:151], v[118:121]
	v_mfma_f32_16x16x32_bf16 v[122:125], v[160:163], v[148:151], v[122:125]
	v_mfma_f32_16x16x32_bf16 v[126:129], v[164:167], v[148:151], v[126:129]
	s_waitcnt vmcnt(12) lgkmcnt(0)
	s_barrier
	s_add_u32 s14, s4, 0x380
	s_addc_u32 s15, s5, 0
	v_mfma_f32_16x16x32_bf16 v[66:69], v[184:187], v[168:171], v[66:69]
	ds_read_b128 v[136:139], v224 offset:0
	s_add_u32 s22, s4, 0x10380
	s_addc_u32 s23, s5, 0
	v_mfma_f32_16x16x32_bf16 v[70:73], v[188:191], v[168:171], v[70:73]
	ds_read_b128 v[140:143], v224 offset:2048
	s_add_u32 s24, s6, 0xc0380
	s_addc_u32 s25, s7, 0
	v_mfma_f32_16x16x32_bf16 v[74:77], v[192:195], v[168:171], v[74:77]
	ds_read_b128 v[144:147], v224 offset:4096
	s_add_u32 s52, s6, 0xc8380
	s_addc_u32 s53, s7, 0
	v_mfma_f32_16x16x32_bf16 v[78:81], v[196:199], v[168:171], v[78:81]
	ds_read_b128 v[148:151], v224 offset:6144
	s_add_u32 m0, s8, 0xc000
	v_mfma_f32_16x16x32_bf16 v[82:85], v[184:187], v[172:175], v[82:85]
	global_load_lds_dwordx4 v200, s[14:15]
	ds_read_b128 v[152:155], v232 offset:0
	s_add_u32 m0, s8, 0xc400
	v_mfma_f32_16x16x32_bf16 v[86:89], v[188:191], v[172:175], v[86:89]
	global_load_lds_dwordx4 v201, s[14:15]
	ds_read_b128 v[156:159], v232 offset:2048
	s_add_u32 m0, s8, 0xc800
	v_mfma_f32_16x16x32_bf16 v[90:93], v[192:195], v[172:175], v[90:93]
	global_load_lds_dwordx4 v202, s[14:15]
	ds_read_b128 v[160:163], v232 offset:4096
	s_add_u32 m0, s8, 0xcc00
	v_mfma_f32_16x16x32_bf16 v[94:97], v[196:199], v[172:175], v[94:97]
	global_load_lds_dwordx4 v203, s[14:15]
	ds_read_b128 v[164:167], v232 offset:6144
	s_add_u32 m0, s8, 0xd000
	v_mfma_f32_16x16x32_bf16 v[98:101], v[184:187], v[176:179], v[98:101]
	global_load_lds_dwordx4 v200, s[22:23]
	s_add_u32 m0, s8, 0xd400
	v_mfma_f32_16x16x32_bf16 v[102:105], v[188:191], v[176:179], v[102:105]
	global_load_lds_dwordx4 v201, s[22:23]
	s_add_u32 m0, s8, 0xd800
	v_mfma_f32_16x16x32_bf16 v[106:109], v[192:195], v[176:179], v[106:109]
	global_load_lds_dwordx4 v202, s[22:23]
	s_add_u32 m0, s8, 0xdc00
	v_mfma_f32_16x16x32_bf16 v[110:113], v[196:199], v[176:179], v[110:113]
	global_load_lds_dwordx4 v203, s[22:23]
	s_add_u32 m0, s9, 0xc000
	v_mfma_f32_16x16x32_bf16 v[114:117], v[184:187], v[180:183], v[114:117]
	global_load_lds_dwordx4 v204, s[24:25]
	s_add_u32 m0, s9, 0xc400
	v_mfma_f32_16x16x32_bf16 v[118:121], v[188:191], v[180:183], v[118:121]
	global_load_lds_dwordx4 v205, s[24:25]
	s_add_u32 m0, s9, 0xc800
	v_mfma_f32_16x16x32_bf16 v[122:125], v[192:195], v[180:183], v[122:125]
	global_load_lds_dwordx4 v204, s[52:53]
	s_add_u32 m0, s9, 0xcc00
	v_mfma_f32_16x16x32_bf16 v[126:129], v[196:199], v[180:183], v[126:129]
	global_load_lds_dwordx4 v205, s[52:53]
	s_waitcnt lgkmcnt(0)
	v_mfma_f32_16x16x32_bf16 v[66:69], v[152:155], v[136:139], v[66:69]
	ds_read_b128 v[168:171], v229 offset:0
	v_mfma_f32_16x16x32_bf16 v[70:73], v[156:159], v[136:139], v[70:73]
	ds_read_b128 v[172:175], v229 offset:2048
	v_mfma_f32_16x16x32_bf16 v[74:77], v[160:163], v[136:139], v[74:77]
	ds_read_b128 v[176:179], v229 offset:4096
	v_mfma_f32_16x16x32_bf16 v[78:81], v[164:167], v[136:139], v[78:81]
	ds_read_b128 v[180:183], v229 offset:6144
	v_mfma_f32_16x16x32_bf16 v[82:85], v[152:155], v[140:143], v[82:85]
	ds_read_b128 v[184:187], v235 offset:0
	v_mfma_f32_16x16x32_bf16 v[86:89], v[156:159], v[140:143], v[86:89]
	ds_read_b128 v[188:191], v235 offset:2048
	v_mfma_f32_16x16x32_bf16 v[90:93], v[160:163], v[140:143], v[90:93]
	ds_read_b128 v[192:195], v235 offset:4096
	v_mfma_f32_16x16x32_bf16 v[94:97], v[164:167], v[140:143], v[94:97]
	ds_read_b128 v[196:199], v235 offset:6144
	v_mfma_f32_16x16x32_bf16 v[98:101], v[152:155], v[144:147], v[98:101]
	v_mfma_f32_16x16x32_bf16 v[102:105], v[156:159], v[144:147], v[102:105]
	v_mfma_f32_16x16x32_bf16 v[106:109], v[160:163], v[144:147], v[106:109]
	v_mfma_f32_16x16x32_bf16 v[110:113], v[164:167], v[144:147], v[110:113]
	v_mfma_f32_16x16x32_bf16 v[114:117], v[152:155], v[148:151], v[114:117]
	v_mfma_f32_16x16x32_bf16 v[118:121], v[156:159], v[148:151], v[118:121]
	v_mfma_f32_16x16x32_bf16 v[122:125], v[160:163], v[148:151], v[122:125]
	v_mfma_f32_16x16x32_bf16 v[126:129], v[164:167], v[148:151], v[126:129]
	s_waitcnt vmcnt(12) lgkmcnt(0)
	s_barrier
	s_add_u32 s14, s4, 0x400
	s_addc_u32 s15, s5, 0
	v_mfma_f32_16x16x32_bf16 v[66:69], v[184:187], v[168:171], v[66:69]
	ds_read_b128 v[136:139], v218 offset:0
	s_add_u32 s22, s4, 0x10400
	s_addc_u32 s23, s5, 0
	v_mfma_f32_16x16x32_bf16 v[70:73], v[188:191], v[168:171], v[70:73]
	ds_read_b128 v[140:143], v218 offset:2048
	s_add_u32 s24, s6, 0xc0400
	s_addc_u32 s25, s7, 0
	v_mfma_f32_16x16x32_bf16 v[74:77], v[192:195], v[168:171], v[74:77]
	ds_read_b128 v[144:147], v218 offset:4096
	s_add_u32 s52, s6, 0xc8400
	s_addc_u32 s53, s7, 0
	v_mfma_f32_16x16x32_bf16 v[78:81], v[196:199], v[168:171], v[78:81]
	ds_read_b128 v[148:151], v218 offset:6144
	s_add_u32 m0, s8, 0x18000
	v_mfma_f32_16x16x32_bf16 v[82:85], v[184:187], v[172:175], v[82:85]
	global_load_lds_dwordx4 v200, s[14:15]
	ds_read_b128 v[152:155], v230 offset:0
	s_add_u32 m0, s8, 0x18400
	v_mfma_f32_16x16x32_bf16 v[86:89], v[188:191], v[172:175], v[86:89]
	global_load_lds_dwordx4 v201, s[14:15]
	ds_read_b128 v[156:159], v230 offset:2048
	s_add_u32 m0, s8, 0x18800
	v_mfma_f32_16x16x32_bf16 v[90:93], v[192:195], v[172:175], v[90:93]
	global_load_lds_dwordx4 v202, s[14:15]
	ds_read_b128 v[160:163], v230 offset:4096
	s_add_u32 m0, s8, 0x18c00
	v_mfma_f32_16x16x32_bf16 v[94:97], v[196:199], v[172:175], v[94:97]
	global_load_lds_dwordx4 v203, s[14:15]
	ds_read_b128 v[164:167], v230 offset:6144
	s_add_u32 m0, s8, 0x19000
	v_mfma_f32_16x16x32_bf16 v[98:101], v[184:187], v[176:179], v[98:101]
	global_load_lds_dwordx4 v200, s[22:23]
	s_add_u32 m0, s8, 0x19400
	v_mfma_f32_16x16x32_bf16 v[102:105], v[188:191], v[176:179], v[102:105]
	global_load_lds_dwordx4 v201, s[22:23]
	s_add_u32 m0, s8, 0x19800
	v_mfma_f32_16x16x32_bf16 v[106:109], v[192:195], v[176:179], v[106:109]
	global_load_lds_dwordx4 v202, s[22:23]
	s_add_u32 m0, s8, 0x19c00
	v_mfma_f32_16x16x32_bf16 v[110:113], v[196:199], v[176:179], v[110:113]
	global_load_lds_dwordx4 v203, s[22:23]
	s_add_u32 m0, s9, 0x18000
	v_mfma_f32_16x16x32_bf16 v[114:117], v[184:187], v[180:183], v[114:117]
	global_load_lds_dwordx4 v204, s[24:25]
	s_add_u32 m0, s9, 0x18400
	v_mfma_f32_16x16x32_bf16 v[118:121], v[188:191], v[180:183], v[118:121]
	global_load_lds_dwordx4 v205, s[24:25]
	s_add_u32 m0, s9, 0x18800
	v_mfma_f32_16x16x32_bf16 v[122:125], v[192:195], v[180:183], v[122:125]
	global_load_lds_dwordx4 v204, s[52:53]
	s_add_u32 m0, s9, 0x18c00
	v_mfma_f32_16x16x32_bf16 v[126:129], v[196:199], v[180:183], v[126:129]
	global_load_lds_dwordx4 v205, s[52:53]
	s_waitcnt lgkmcnt(0)
	v_mfma_f32_16x16x32_bf16 v[66:69], v[152:155], v[136:139], v[66:69]
	ds_read_b128 v[168:171], v225 offset:0
	v_mfma_f32_16x16x32_bf16 v[70:73], v[156:159], v[136:139], v[70:73]
	ds_read_b128 v[172:175], v225 offset:2048
	v_mfma_f32_16x16x32_bf16 v[74:77], v[160:163], v[136:139], v[74:77]
	ds_read_b128 v[176:179], v225 offset:4096
	v_mfma_f32_16x16x32_bf16 v[78:81], v[164:167], v[136:139], v[78:81]
	ds_read_b128 v[180:183], v225 offset:6144
	v_mfma_f32_16x16x32_bf16 v[82:85], v[152:155], v[140:143], v[82:85]
	ds_read_b128 v[184:187], v233 offset:0
	v_mfma_f32_16x16x32_bf16 v[86:89], v[156:159], v[140:143], v[86:89]
	ds_read_b128 v[188:191], v233 offset:2048
	v_mfma_f32_16x16x32_bf16 v[90:93], v[160:163], v[140:143], v[90:93]
	ds_read_b128 v[192:195], v233 offset:4096
	v_mfma_f32_16x16x32_bf16 v[94:97], v[164:167], v[140:143], v[94:97]
	ds_read_b128 v[196:199], v233 offset:6144
	v_mfma_f32_16x16x32_bf16 v[98:101], v[152:155], v[144:147], v[98:101]
	v_mfma_f32_16x16x32_bf16 v[102:105], v[156:159], v[144:147], v[102:105]
	v_mfma_f32_16x16x32_bf16 v[106:109], v[160:163], v[144:147], v[106:109]
	v_mfma_f32_16x16x32_bf16 v[110:113], v[164:167], v[144:147], v[110:113]
	v_mfma_f32_16x16x32_bf16 v[114:117], v[152:155], v[148:151], v[114:117]
	v_mfma_f32_16x16x32_bf16 v[118:121], v[156:159], v[148:151], v[118:121]
	v_mfma_f32_16x16x32_bf16 v[122:125], v[160:163], v[148:151], v[122:125]
	v_mfma_f32_16x16x32_bf16 v[126:129], v[164:167], v[148:151], v[126:129]
	s_waitcnt vmcnt(12) lgkmcnt(0)
	s_barrier
	s_add_u32 s14, s4, 0x480
	s_addc_u32 s15, s5, 0
	v_mfma_f32_16x16x32_bf16 v[66:69], v[184:187], v[168:171], v[66:69]
	ds_read_b128 v[136:139], v219 offset:0
	s_add_u32 s22, s4, 0x10480
	s_addc_u32 s23, s5, 0
	v_mfma_f32_16x16x32_bf16 v[70:73], v[188:191], v[168:171], v[70:73]
	ds_read_b128 v[140:143], v219 offset:2048
	s_add_u32 s24, s6, 0xc0480
	s_addc_u32 s25, s7, 0
	v_mfma_f32_16x16x32_bf16 v[74:77], v[192:195], v[168:171], v[74:77]
	ds_read_b128 v[144:147], v219 offset:4096
	s_add_u32 s52, s6, 0xc8480
	s_addc_u32 s53, s7, 0
	v_mfma_f32_16x16x32_bf16 v[78:81], v[196:199], v[168:171], v[78:81]
	ds_read_b128 v[148:151], v219 offset:6144
	s_mov_b32 m0, s8
	v_mfma_f32_16x16x32_bf16 v[82:85], v[184:187], v[172:175], v[82:85]
	global_load_lds_dwordx4 v200, s[14:15]
	ds_read_b128 v[152:155], v231 offset:0
	s_add_u32 m0, s8, 0x400
	v_mfma_f32_16x16x32_bf16 v[86:89], v[188:191], v[172:175], v[86:89]
	global_load_lds_dwordx4 v201, s[14:15]
	ds_read_b128 v[156:159], v231 offset:2048
	s_add_u32 m0, s8, 0x800
	v_mfma_f32_16x16x32_bf16 v[90:93], v[192:195], v[172:175], v[90:93]
	global_load_lds_dwordx4 v202, s[14:15]
	ds_read_b128 v[160:163], v231 offset:4096
	s_add_u32 m0, s8, 0xc00
	v_mfma_f32_16x16x32_bf16 v[94:97], v[196:199], v[172:175], v[94:97]
	global_load_lds_dwordx4 v203, s[14:15]
	ds_read_b128 v[164:167], v231 offset:6144
	s_add_u32 m0, s8, 0x1000
	v_mfma_f32_16x16x32_bf16 v[98:101], v[184:187], v[176:179], v[98:101]
	global_load_lds_dwordx4 v200, s[22:23]
	s_add_u32 m0, s8, 0x1400
	v_mfma_f32_16x16x32_bf16 v[102:105], v[188:191], v[176:179], v[102:105]
	global_load_lds_dwordx4 v201, s[22:23]
	s_add_u32 m0, s8, 0x1800
	v_mfma_f32_16x16x32_bf16 v[106:109], v[192:195], v[176:179], v[106:109]
	global_load_lds_dwordx4 v202, s[22:23]
	s_add_u32 m0, s8, 0x1c00
	v_mfma_f32_16x16x32_bf16 v[110:113], v[196:199], v[176:179], v[110:113]
	global_load_lds_dwordx4 v203, s[22:23]
	s_mov_b32 m0, s9
	v_mfma_f32_16x16x32_bf16 v[114:117], v[184:187], v[180:183], v[114:117]
	global_load_lds_dwordx4 v204, s[24:25]
	s_add_u32 m0, s9, 0x400
	v_mfma_f32_16x16x32_bf16 v[118:121], v[188:191], v[180:183], v[118:121]
	global_load_lds_dwordx4 v205, s[24:25]
	s_add_u32 m0, s9, 0x800
	v_mfma_f32_16x16x32_bf16 v[122:125], v[192:195], v[180:183], v[122:125]
	global_load_lds_dwordx4 v204, s[52:53]
	s_add_u32 m0, s9, 0xc00
	v_mfma_f32_16x16x32_bf16 v[126:129], v[196:199], v[180:183], v[126:129]
	global_load_lds_dwordx4 v205, s[52:53]
	s_waitcnt lgkmcnt(0)
	v_mfma_f32_16x16x32_bf16 v[66:69], v[152:155], v[136:139], v[66:69]
	ds_read_b128 v[168:171], v228 offset:0
	v_mfma_f32_16x16x32_bf16 v[70:73], v[156:159], v[136:139], v[70:73]
	ds_read_b128 v[172:175], v228 offset:2048
	v_mfma_f32_16x16x32_bf16 v[74:77], v[160:163], v[136:139], v[74:77]
	ds_read_b128 v[176:179], v228 offset:4096
	v_mfma_f32_16x16x32_bf16 v[78:81], v[164:167], v[136:139], v[78:81]
	ds_read_b128 v[180:183], v228 offset:6144
	v_mfma_f32_16x16x32_bf16 v[82:85], v[152:155], v[140:143], v[82:85]
	ds_read_b128 v[184:187], v234 offset:0
	v_mfma_f32_16x16x32_bf16 v[86:89], v[156:159], v[140:143], v[86:89]
	ds_read_b128 v[188:191], v234 offset:2048
	v_mfma_f32_16x16x32_bf16 v[90:93], v[160:163], v[140:143], v[90:93]
	ds_read_b128 v[192:195], v234 offset:4096
	v_mfma_f32_16x16x32_bf16 v[94:97], v[164:167], v[140:143], v[94:97]
	ds_read_b128 v[196:199], v234 offset:6144
	v_mfma_f32_16x16x32_bf16 v[98:101], v[152:155], v[144:147], v[98:101]
	v_mfma_f32_16x16x32_bf16 v[102:105], v[156:159], v[144:147], v[102:105]
	v_mfma_f32_16x16x32_bf16 v[106:109], v[160:163], v[144:147], v[106:109]
	v_mfma_f32_16x16x32_bf16 v[110:113], v[164:167], v[144:147], v[110:113]
	v_mfma_f32_16x16x32_bf16 v[114:117], v[152:155], v[148:151], v[114:117]
	v_mfma_f32_16x16x32_bf16 v[118:121], v[156:159], v[148:151], v[118:121]
	v_mfma_f32_16x16x32_bf16 v[122:125], v[160:163], v[148:151], v[122:125]
	v_mfma_f32_16x16x32_bf16 v[126:129], v[164:167], v[148:151], v[126:129]
	s_waitcnt vmcnt(12) lgkmcnt(0)
	s_barrier
	s_add_u32 s14, s4, 0x500
	s_addc_u32 s15, s5, 0
	v_mfma_f32_16x16x32_bf16 v[66:69], v[184:187], v[168:171], v[66:69]
	ds_read_b128 v[136:139], v224 offset:0
	s_add_u32 s22, s4, 0x10500
	s_addc_u32 s23, s5, 0
	v_mfma_f32_16x16x32_bf16 v[70:73], v[188:191], v[168:171], v[70:73]
	ds_read_b128 v[140:143], v224 offset:2048
	s_add_u32 s24, s6, 0xc0500
	s_addc_u32 s25, s7, 0
	v_mfma_f32_16x16x32_bf16 v[74:77], v[192:195], v[168:171], v[74:77]
	ds_read_b128 v[144:147], v224 offset:4096
	s_add_u32 s52, s6, 0xc8500
	s_addc_u32 s53, s7, 0
	v_mfma_f32_16x16x32_bf16 v[78:81], v[196:199], v[168:171], v[78:81]
	ds_read_b128 v[148:151], v224 offset:6144
	s_add_u32 m0, s8, 0xc000
	v_mfma_f32_16x16x32_bf16 v[82:85], v[184:187], v[172:175], v[82:85]
	global_load_lds_dwordx4 v200, s[14:15]
	ds_read_b128 v[152:155], v232 offset:0
	s_add_u32 m0, s8, 0xc400
	v_mfma_f32_16x16x32_bf16 v[86:89], v[188:191], v[172:175], v[86:89]
	global_load_lds_dwordx4 v201, s[14:15]
	ds_read_b128 v[156:159], v232 offset:2048
	s_add_u32 m0, s8, 0xc800
	v_mfma_f32_16x16x32_bf16 v[90:93], v[192:195], v[172:175], v[90:93]
	global_load_lds_dwordx4 v202, s[14:15]
	ds_read_b128 v[160:163], v232 offset:4096
	s_add_u32 m0, s8, 0xcc00
	v_mfma_f32_16x16x32_bf16 v[94:97], v[196:199], v[172:175], v[94:97]
	global_load_lds_dwordx4 v203, s[14:15]
	ds_read_b128 v[164:167], v232 offset:6144
	s_add_u32 m0, s8, 0xd000
	v_mfma_f32_16x16x32_bf16 v[98:101], v[184:187], v[176:179], v[98:101]
	global_load_lds_dwordx4 v200, s[22:23]
	s_add_u32 m0, s8, 0xd400
	v_mfma_f32_16x16x32_bf16 v[102:105], v[188:191], v[176:179], v[102:105]
	global_load_lds_dwordx4 v201, s[22:23]
	s_add_u32 m0, s8, 0xd800
	v_mfma_f32_16x16x32_bf16 v[106:109], v[192:195], v[176:179], v[106:109]
	global_load_lds_dwordx4 v202, s[22:23]
	s_add_u32 m0, s8, 0xdc00
	v_mfma_f32_16x16x32_bf16 v[110:113], v[196:199], v[176:179], v[110:113]
	global_load_lds_dwordx4 v203, s[22:23]
	s_add_u32 m0, s9, 0xc000
	v_mfma_f32_16x16x32_bf16 v[114:117], v[184:187], v[180:183], v[114:117]
	global_load_lds_dwordx4 v204, s[24:25]
	s_add_u32 m0, s9, 0xc400
	v_mfma_f32_16x16x32_bf16 v[118:121], v[188:191], v[180:183], v[118:121]
	global_load_lds_dwordx4 v205, s[24:25]
	s_add_u32 m0, s9, 0xc800
	v_mfma_f32_16x16x32_bf16 v[122:125], v[192:195], v[180:183], v[122:125]
	global_load_lds_dwordx4 v204, s[52:53]
	s_add_u32 m0, s9, 0xcc00
	v_mfma_f32_16x16x32_bf16 v[126:129], v[196:199], v[180:183], v[126:129]
	global_load_lds_dwordx4 v205, s[52:53]
	s_waitcnt lgkmcnt(0)
	v_mfma_f32_16x16x32_bf16 v[66:69], v[152:155], v[136:139], v[66:69]
	ds_read_b128 v[168:171], v229 offset:0
	s_add_u32 s10, s28, s13
	s_addc_u32 s11, s29, 0
	s_add_u32 s13, s13, 0x10000
	v_mfma_f32_16x16x32_bf16 v[70:73], v[156:159], v[136:139], v[70:73]
	ds_read_b128 v[172:175], v229 offset:2048
	v_mul_f32_e32 v2, s12, v2
	v_mul_f32_e32 v3, s12, v3
	v_mfma_f32_16x16x32_bf16 v[74:77], v[160:163], v[136:139], v[74:77]
	ds_read_b128 v[176:179], v229 offset:4096
	v_mul_f32_e32 v4, s12, v4
	v_mul_f32_e32 v5, s12, v5
	v_mul_f32_e32 v6, s12, v6
	v_mfma_f32_16x16x32_bf16 v[78:81], v[164:167], v[136:139], v[78:81]
	ds_read_b128 v[180:183], v229 offset:6144
	v_mul_f32_e32 v7, s12, v7
	v_mul_f32_e32 v8, s12, v8
	v_mfma_f32_16x16x32_bf16 v[82:85], v[152:155], v[140:143], v[82:85]
	ds_read_b128 v[184:187], v235 offset:0
	v_mul_f32_e32 v9, s12, v9
	v_exp_f32_e32 v2, v2
	v_mfma_f32_16x16x32_bf16 v[86:89], v[156:159], v[140:143], v[86:89]
	ds_read_b128 v[188:191], v235 offset:2048
	v_exp_f32_e32 v3, v3
	v_exp_f32_e32 v4, v4
	v_exp_f32_e32 v5, v5
	v_mfma_f32_16x16x32_bf16 v[90:93], v[160:163], v[140:143], v[90:93]
	ds_read_b128 v[192:195], v235 offset:4096
	v_exp_f32_e32 v6, v6
	v_exp_f32_e32 v7, v7
	v_mfma_f32_16x16x32_bf16 v[94:97], v[164:167], v[140:143], v[94:97]
	ds_read_b128 v[196:199], v235 offset:6144
	v_exp_f32_e32 v8, v8
	v_exp_f32_e32 v9, v9
	v_add_f32_e32 v2, 1.0, v2
	v_mfma_f32_16x16x32_bf16 v[98:101], v[152:155], v[144:147], v[98:101]
	v_add_f32_e32 v3, 1.0, v3
	v_add_f32_e32 v4, 1.0, v4
	v_mfma_f32_16x16x32_bf16 v[102:105], v[156:159], v[144:147], v[102:105]
	v_add_f32_e32 v5, 1.0, v5
	v_add_f32_e32 v6, 1.0, v6
	v_mfma_f32_16x16x32_bf16 v[106:109], v[160:163], v[144:147], v[106:109]
	v_add_f32_e32 v7, 1.0, v7
	v_add_f32_e32 v8, 1.0, v8
	v_add_f32_e32 v9, 1.0, v9
	v_mfma_f32_16x16x32_bf16 v[110:113], v[164:167], v[144:147], v[110:113]
	v_rcp_f32_e32 v2, v2
	v_rcp_f32_e32 v3, v3
	v_mfma_f32_16x16x32_bf16 v[114:117], v[152:155], v[148:151], v[114:117]
	v_rcp_f32_e32 v4, v4
	v_rcp_f32_e32 v5, v5
	v_mfma_f32_16x16x32_bf16 v[118:121], v[156:159], v[148:151], v[118:121]
	v_rcp_f32_e32 v6, v6
	v_rcp_f32_e32 v7, v7
	v_rcp_f32_e32 v8, v8
	v_mfma_f32_16x16x32_bf16 v[122:125], v[160:163], v[148:151], v[122:125]
	v_rcp_f32_e32 v9, v9
	v_cvt_pk_bf16_f32 v2, v2, v3
	v_mfma_f32_16x16x32_bf16 v[126:129], v[164:167], v[148:151], v[126:129]
	v_cvt_pk_bf16_f32 v3, v4, v5
	v_cvt_pk_bf16_f32 v4, v6, v7
	v_cvt_pk_bf16_f32 v5, v8, v9
	s_waitcnt vmcnt(12) lgkmcnt(0)
	s_barrier
	v_mfma_f32_16x16x32_bf16 v[66:69], v[184:187], v[168:171], v[66:69]
	ds_read_b128 v[136:139], v218 offset:0
	global_store_dwordx4 v240, v[2:5], s[10:11] offset:0
	v_mul_f32_e32 v10, s12, v10
	v_mfma_f32_16x16x32_bf16 v[70:73], v[188:191], v[168:171], v[70:73]
	ds_read_b128 v[140:143], v218 offset:2048
	v_mul_f32_e32 v11, s12, v11
	v_mul_f32_e32 v12, s12, v12
	v_mfma_f32_16x16x32_bf16 v[74:77], v[192:195], v[168:171], v[74:77]
	ds_read_b128 v[144:147], v218 offset:4096
	v_mul_f32_e32 v13, s12, v13
	v_mul_f32_e32 v14, s12, v14
	v_mfma_f32_16x16x32_bf16 v[78:81], v[196:199], v[168:171], v[78:81]
	ds_read_b128 v[148:151], v218 offset:6144
	v_mul_f32_e32 v15, s12, v15
	v_mul_f32_e32 v16, s12, v16
	v_mul_f32_e32 v17, s12, v17
	v_mfma_f32_16x16x32_bf16 v[82:85], v[184:187], v[172:175], v[82:85]
	ds_read_b128 v[152:155], v230 offset:0
	v_exp_f32_e32 v10, v10
	v_exp_f32_e32 v11, v11
	v_mfma_f32_16x16x32_bf16 v[86:89], v[188:191], v[172:175], v[86:89]
	ds_read_b128 v[156:159], v230 offset:2048
	v_exp_f32_e32 v12, v12
	v_exp_f32_e32 v13, v13
	v_mfma_f32_16x16x32_bf16 v[90:93], v[192:195], v[172:175], v[90:93]
	ds_read_b128 v[160:163], v230 offset:4096
	v_exp_f32_e32 v14, v14
	v_exp_f32_e32 v15, v15
	v_exp_f32_e32 v16, v16
	v_mfma_f32_16x16x32_bf16 v[94:97], v[196:199], v[172:175], v[94:97]
	ds_read_b128 v[164:167], v230 offset:6144
	v_exp_f32_e32 v17, v17
	v_add_f32_e32 v10, 1.0, v10
	v_mfma_f32_16x16x32_bf16 v[98:101], v[184:187], v[176:179], v[98:101]
	v_add_f32_e32 v11, 1.0, v11
	v_add_f32_e32 v12, 1.0, v12
	v_mfma_f32_16x16x32_bf16 v[102:105], v[188:191], v[176:179], v[102:105]
	v_add_f32_e32 v13, 1.0, v13
	v_add_f32_e32 v14, 1.0, v14
	v_add_f32_e32 v15, 1.0, v15
	v_mfma_f32_16x16x32_bf16 v[106:109], v[192:195], v[176:179], v[106:109]
	v_add_f32_e32 v16, 1.0, v16
	v_add_f32_e32 v17, 1.0, v17
	v_mfma_f32_16x16x32_bf16 v[110:113], v[196:199], v[176:179], v[110:113]
	v_rcp_f32_e32 v10, v10
	v_rcp_f32_e32 v11, v11
	v_mfma_f32_16x16x32_bf16 v[114:117], v[184:187], v[180:183], v[114:117]
	v_rcp_f32_e32 v12, v12
	v_rcp_f32_e32 v13, v13
	v_rcp_f32_e32 v14, v14
	v_mfma_f32_16x16x32_bf16 v[118:121], v[188:191], v[180:183], v[118:121]
	v_rcp_f32_e32 v15, v15
	v_rcp_f32_e32 v16, v16
	v_mfma_f32_16x16x32_bf16 v[122:125], v[192:195], v[180:183], v[122:125]
	v_rcp_f32_e32 v17, v17
	v_cvt_pk_bf16_f32 v10, v10, v11
	v_mfma_f32_16x16x32_bf16 v[126:129], v[196:199], v[180:183], v[126:129]
	v_cvt_pk_bf16_f32 v11, v12, v13
	v_cvt_pk_bf16_f32 v12, v14, v15
	v_cvt_pk_bf16_f32 v13, v16, v17
	s_waitcnt lgkmcnt(0)
	v_mfma_f32_16x16x32_bf16 v[66:69], v[152:155], v[136:139], v[66:69]
	ds_read_b128 v[168:171], v225 offset:0
	global_store_dwordx4 v240, v[10:13], s[10:11] offset:16
	v_mul_f32_e32 v18, s12, v18
	v_mfma_f32_16x16x32_bf16 v[70:73], v[156:159], v[136:139], v[70:73]
	ds_read_b128 v[172:175], v225 offset:2048
	v_mul_f32_e32 v19, s12, v19
	v_mul_f32_e32 v20, s12, v20
	v_mfma_f32_16x16x32_bf16 v[74:77], v[160:163], v[136:139], v[74:77]
	ds_read_b128 v[176:179], v225 offset:4096
	v_mul_f32_e32 v21, s12, v21
	v_mul_f32_e32 v22, s12, v22
	v_mul_f32_e32 v23, s12, v23
	v_mfma_f32_16x16x32_bf16 v[78:81], v[164:167], v[136:139], v[78:81]
	ds_read_b128 v[180:183], v225 offset:6144
	v_mul_f32_e32 v24, s12, v24
	v_mul_f32_e32 v25, s12, v25
	v_mfma_f32_16x16x32_bf16 v[82:85], v[152:155], v[140:143], v[82:85]
	ds_read_b128 v[184:187], v233 offset:0
	v_exp_f32_e32 v18, v18
	v_exp_f32_e32 v19, v19
	v_mfma_f32_16x16x32_bf16 v[86:89], v[156:159], v[140:143], v[86:89]
	ds_read_b128 v[188:191], v233 offset:2048
	v_exp_f32_e32 v20, v20
	v_exp_f32_e32 v21, v21
	v_exp_f32_e32 v22, v22
	v_mfma_f32_16x16x32_bf16 v[90:93], v[160:163], v[140:143], v[90:93]
	ds_read_b128 v[192:195], v233 offset:4096
	v_exp_f32_e32 v23, v23
	v_exp_f32_e32 v24, v24
	v_mfma_f32_16x16x32_bf16 v[94:97], v[164:167], v[140:143], v[94:97]
	ds_read_b128 v[196:199], v233 offset:6144
	v_exp_f32_e32 v25, v25
	v_add_f32_e32 v18, 1.0, v18
	v_add_f32_e32 v19, 1.0, v19
	v_mfma_f32_16x16x32_bf16 v[98:101], v[152:155], v[144:147], v[98:101]
	v_add_f32_e32 v20, 1.0, v20
	v_add_f32_e32 v21, 1.0, v21
	v_mfma_f32_16x16x32_bf16 v[102:105], v[156:159], v[144:147], v[102:105]
	v_add_f32_e32 v22, 1.0, v22
	v_add_f32_e32 v23, 1.0, v23
	v_mfma_f32_16x16x32_bf16 v[106:109], v[160:163], v[144:147], v[106:109]
	v_add_f32_e32 v24, 1.0, v24
	v_add_f32_e32 v25, 1.0, v25
	v_rcp_f32_e32 v18, v18
	v_mfma_f32_16x16x32_bf16 v[110:113], v[164:167], v[144:147], v[110:113]
	v_rcp_f32_e32 v19, v19
	v_rcp_f32_e32 v20, v20
	v_mfma_f32_16x16x32_bf16 v[114:117], v[152:155], v[148:151], v[114:117]
	v_rcp_f32_e32 v21, v21
	v_rcp_f32_e32 v22, v22
	v_mfma_f32_16x16x32_bf16 v[118:121], v[156:159], v[148:151], v[118:121]
	v_rcp_f32_e32 v23, v23
	v_rcp_f32_e32 v24, v24
	v_rcp_f32_e32 v25, v25
	v_mfma_f32_16x16x32_bf16 v[122:125], v[160:163], v[148:151], v[122:125]
	v_cvt_pk_bf16_f32 v18, v18, v19
	v_cvt_pk_bf16_f32 v19, v20, v21
	v_mfma_f32_16x16x32_bf16 v[126:129], v[164:167], v[148:151], v[126:129]
	v_cvt_pk_bf16_f32 v20, v22, v23
	v_cvt_pk_bf16_f32 v21, v24, v25
	global_store_dwordx4 v240, v[18:21], s[10:11] offset:2048
	s_waitcnt vmcnt(3) lgkmcnt(0)
	s_barrier
	v_mfma_f32_16x16x32_bf16 v[66:69], v[184:187], v[168:171], v[66:69]
	ds_read_b128 v[136:139], v219 offset:0
	v_mul_f32_e32 v26, s12, v26
	v_mul_f32_e32 v27, s12, v27
	v_mfma_f32_16x16x32_bf16 v[70:73], v[188:191], v[168:171], v[70:73]
	ds_read_b128 v[140:143], v219 offset:2048
	v_mul_f32_e32 v28, s12, v28
	v_mul_f32_e32 v29, s12, v29
	v_mfma_f32_16x16x32_bf16 v[74:77], v[192:195], v[168:171], v[74:77]
	ds_read_b128 v[144:147], v219 offset:4096
	v_mul_f32_e32 v30, s12, v30
	v_mul_f32_e32 v31, s12, v31
	v_mfma_f32_16x16x32_bf16 v[78:81], v[196:199], v[168:171], v[78:81]
	ds_read_b128 v[148:151], v219 offset:6144
	v_mul_f32_e32 v32, s12, v32
	v_mul_f32_e32 v33, s12, v33
	v_exp_f32_e32 v26, v26
	v_mfma_f32_16x16x32_bf16 v[82:85], v[184:187], v[172:175], v[82:85]
	ds_read_b128 v[152:155], v231 offset:0
	v_exp_f32_e32 v27, v27
	v_exp_f32_e32 v28, v28
	v_mfma_f32_16x16x32_bf16 v[86:89], v[188:191], v[172:175], v[86:89]
	ds_read_b128 v[156:159], v231 offset:2048
	v_exp_f32_e32 v29, v29
	v_exp_f32_e32 v30, v30
	v_mfma_f32_16x16x32_bf16 v[90:93], v[192:195], v[172:175], v[90:93]
	ds_read_b128 v[160:163], v231 offset:4096
	v_exp_f32_e32 v31, v31
	v_exp_f32_e32 v32, v32
	v_exp_f32_e32 v33, v33
	v_mfma_f32_16x16x32_bf16 v[94:97], v[196:199], v[172:175], v[94:97]
	ds_read_b128 v[164:167], v231 offset:6144
	v_add_f32_e32 v26, 1.0, v26
	v_add_f32_e32 v27, 1.0, v27
	v_mfma_f32_16x16x32_bf16 v[98:101], v[184:187], v[176:179], v[98:101]
	v_add_f32_e32 v28, 1.0, v28
	v_add_f32_e32 v29, 1.0, v29
	v_mfma_f32_16x16x32_bf16 v[102:105], v[188:191], v[176:179], v[102:105]
	v_add_f32_e32 v30, 1.0, v30
	v_add_f32_e32 v31, 1.0, v31
	v_add_f32_e32 v32, 1.0, v32
	v_mfma_f32_16x16x32_bf16 v[106:109], v[192:195], v[176:179], v[106:109]
	v_add_f32_e32 v33, 1.0, v33
	v_rcp_f32_e32 v26, v26
	v_mfma_f32_16x16x32_bf16 v[110:113], v[196:199], v[176:179], v[110:113]
	v_rcp_f32_e32 v27, v27
	v_rcp_f32_e32 v28, v28
	v_mfma_f32_16x16x32_bf16 v[114:117], v[184:187], v[180:183], v[114:117]
	v_rcp_f32_e32 v29, v29
	v_rcp_f32_e32 v30, v30
	v_rcp_f32_e32 v31, v31
	v_mfma_f32_16x16x32_bf16 v[118:121], v[188:191], v[180:183], v[118:121]
	v_rcp_f32_e32 v32, v32
	v_rcp_f32_e32 v33, v33
	v_mfma_f32_16x16x32_bf16 v[122:125], v[192:195], v[180:183], v[122:125]
	v_cvt_pk_bf16_f32 v26, v26, v27
	v_cvt_pk_bf16_f32 v27, v28, v29
	v_mfma_f32_16x16x32_bf16 v[126:129], v[196:199], v[180:183], v[126:129]
	v_cvt_pk_bf16_f32 v28, v30, v31
	v_cvt_pk_bf16_f32 v29, v32, v33
	global_store_dwordx4 v240, v[26:29], s[10:11] offset:2064
	s_waitcnt lgkmcnt(0)
	v_mfma_f32_16x16x32_bf16 v[66:69], v[152:155], v[136:139], v[66:69]
	ds_read_b128 v[168:171], v228 offset:0
	v_mul_f32_e32 v34, s12, v34
	v_mul_f32_e32 v35, s12, v35
	v_mfma_f32_16x16x32_bf16 v[70:73], v[156:159], v[136:139], v[70:73]
	ds_read_b128 v[172:175], v228 offset:2048
	v_mul_f32_e32 v36, s12, v36
	v_mul_f32_e32 v37, s12, v37
	v_mfma_f32_16x16x32_bf16 v[74:77], v[160:163], v[136:139], v[74:77]
	ds_read_b128 v[176:179], v228 offset:4096
	v_mul_f32_e32 v38, s12, v38
	v_mul_f32_e32 v39, s12, v39
	v_mfma_f32_16x16x32_bf16 v[78:81], v[164:167], v[136:139], v[78:81]
	ds_read_b128 v[180:183], v228 offset:6144
	v_mul_f32_e32 v40, s12, v40
	v_mul_f32_e32 v41, s12, v41
	v_exp_f32_e32 v34, v34
	v_mfma_f32_16x16x32_bf16 v[82:85], v[152:155], v[140:143], v[82:85]
	ds_read_b128 v[184:187], v234 offset:0
	v_exp_f32_e32 v35, v35
	v_exp_f32_e32 v36, v36
	v_mfma_f32_16x16x32_bf16 v[86:89], v[156:159], v[140:143], v[86:89]
	ds_read_b128 v[188:191], v234 offset:2048
	v_exp_f32_e32 v37, v37
	v_exp_f32_e32 v38, v38
	v_mfma_f32_16x16x32_bf16 v[90:93], v[160:163], v[140:143], v[90:93]
	ds_read_b128 v[192:195], v234 offset:4096
	v_exp_f32_e32 v39, v39
	v_exp_f32_e32 v40, v40
	v_exp_f32_e32 v41, v41
	v_mfma_f32_16x16x32_bf16 v[94:97], v[164:167], v[140:143], v[94:97]
	ds_read_b128 v[196:199], v234 offset:6144
	v_add_f32_e32 v34, 1.0, v34
	v_add_f32_e32 v35, 1.0, v35
	v_mfma_f32_16x16x32_bf16 v[98:101], v[152:155], v[144:147], v[98:101]
	v_add_f32_e32 v36, 1.0, v36
	v_add_f32_e32 v37, 1.0, v37
	v_mfma_f32_16x16x32_bf16 v[102:105], v[156:159], v[144:147], v[102:105]
	v_add_f32_e32 v38, 1.0, v38
	v_add_f32_e32 v39, 1.0, v39
	v_add_f32_e32 v40, 1.0, v40
	v_mfma_f32_16x16x32_bf16 v[106:109], v[160:163], v[144:147], v[106:109]
	v_add_f32_e32 v41, 1.0, v41
	v_rcp_f32_e32 v34, v34
	v_mfma_f32_16x16x32_bf16 v[110:113], v[164:167], v[144:147], v[110:113]
	v_rcp_f32_e32 v35, v35
	v_rcp_f32_e32 v36, v36
	v_mfma_f32_16x16x32_bf16 v[114:117], v[152:155], v[148:151], v[114:117]
	v_rcp_f32_e32 v37, v37
	v_rcp_f32_e32 v38, v38
	v_rcp_f32_e32 v39, v39
	v_mfma_f32_16x16x32_bf16 v[118:121], v[156:159], v[148:151], v[118:121]
	v_rcp_f32_e32 v40, v40
	v_rcp_f32_e32 v41, v41
	v_mfma_f32_16x16x32_bf16 v[122:125], v[160:163], v[148:151], v[122:125]
	v_cvt_pk_bf16_f32 v34, v34, v35
	v_cvt_pk_bf16_f32 v35, v36, v37
	v_mfma_f32_16x16x32_bf16 v[126:129], v[164:167], v[148:151], v[126:129]
	v_cvt_pk_bf16_f32 v36, v38, v39
	v_cvt_pk_bf16_f32 v37, v40, v41
	global_store_dwordx4 v241, v[34:37], s[10:11] offset:0
	s_waitcnt lgkmcnt(0)
	s_barrier
	v_mfma_f32_16x16x32_bf16 v[66:69], v[184:187], v[168:171], v[66:69]
	ds_read_b128 v[136:139], v224 offset:0
	v_mul_f32_e32 v42, s12, v42
	v_mul_f32_e32 v43, s12, v43
	v_mfma_f32_16x16x32_bf16 v[70:73], v[188:191], v[168:171], v[70:73]
	ds_read_b128 v[140:143], v224 offset:2048
	v_mul_f32_e32 v44, s12, v44
	v_mul_f32_e32 v45, s12, v45
	v_mfma_f32_16x16x32_bf16 v[74:77], v[192:195], v[168:171], v[74:77]
	ds_read_b128 v[144:147], v224 offset:4096
	v_mul_f32_e32 v46, s12, v46
	v_mul_f32_e32 v47, s12, v47
	v_mfma_f32_16x16x32_bf16 v[78:81], v[196:199], v[168:171], v[78:81]
	ds_read_b128 v[148:151], v224 offset:6144
	v_mul_f32_e32 v48, s12, v48
	v_mul_f32_e32 v49, s12, v49
	v_exp_f32_e32 v42, v42
	v_mfma_f32_16x16x32_bf16 v[82:85], v[184:187], v[172:175], v[82:85]
	ds_read_b128 v[152:155], v232 offset:0
	v_exp_f32_e32 v43, v43
	v_exp_f32_e32 v44, v44
	v_mfma_f32_16x16x32_bf16 v[86:89], v[188:191], v[172:175], v[86:89]
	ds_read_b128 v[156:159], v232 offset:2048
	v_exp_f32_e32 v45, v45
	v_exp_f32_e32 v46, v46
	v_mfma_f32_16x16x32_bf16 v[90:93], v[192:195], v[172:175], v[90:93]
	ds_read_b128 v[160:163], v232 offset:4096
	v_exp_f32_e32 v47, v47
	v_exp_f32_e32 v48, v48
	v_exp_f32_e32 v49, v49
	v_mfma_f32_16x16x32_bf16 v[94:97], v[196:199], v[172:175], v[94:97]
	ds_read_b128 v[164:167], v232 offset:6144
	v_add_f32_e32 v42, 1.0, v42
	v_add_f32_e32 v43, 1.0, v43
	v_mfma_f32_16x16x32_bf16 v[98:101], v[184:187], v[176:179], v[98:101]
	v_add_f32_e32 v44, 1.0, v44
	v_add_f32_e32 v45, 1.0, v45
	v_mfma_f32_16x16x32_bf16 v[102:105], v[188:191], v[176:179], v[102:105]
	v_add_f32_e32 v46, 1.0, v46
	v_add_f32_e32 v47, 1.0, v47
	v_add_f32_e32 v48, 1.0, v48
	v_mfma_f32_16x16x32_bf16 v[106:109], v[192:195], v[176:179], v[106:109]
	v_add_f32_e32 v49, 1.0, v49
	v_rcp_f32_e32 v42, v42
	v_mfma_f32_16x16x32_bf16 v[110:113], v[196:199], v[176:179], v[110:113]
	v_rcp_f32_e32 v43, v43
	v_rcp_f32_e32 v44, v44
	v_mfma_f32_16x16x32_bf16 v[114:117], v[184:187], v[180:183], v[114:117]
	v_rcp_f32_e32 v45, v45
	v_rcp_f32_e32 v46, v46
	v_rcp_f32_e32 v47, v47
	v_mfma_f32_16x16x32_bf16 v[118:121], v[188:191], v[180:183], v[118:121]
	v_rcp_f32_e32 v48, v48
	v_rcp_f32_e32 v49, v49
	v_mfma_f32_16x16x32_bf16 v[122:125], v[192:195], v[180:183], v[122:125]
	v_cvt_pk_bf16_f32 v42, v42, v43
	v_cvt_pk_bf16_f32 v43, v44, v45
	v_mfma_f32_16x16x32_bf16 v[126:129], v[196:199], v[180:183], v[126:129]
	v_cvt_pk_bf16_f32 v44, v46, v47
	v_cvt_pk_bf16_f32 v45, v48, v49
	global_store_dwordx4 v241, v[42:45], s[10:11] offset:16
	s_waitcnt lgkmcnt(0)
	v_mfma_f32_16x16x32_bf16 v[66:69], v[152:155], v[136:139], v[66:69]
	ds_read_b128 v[168:171], v229 offset:0
	v_mul_f32_e32 v50, s12, v50
	v_mul_f32_e32 v51, s12, v51
	v_mfma_f32_16x16x32_bf16 v[70:73], v[156:159], v[136:139], v[70:73]
	ds_read_b128 v[172:175], v229 offset:2048
	v_mul_f32_e32 v52, s12, v52
	v_mul_f32_e32 v53, s12, v53
	v_mfma_f32_16x16x32_bf16 v[74:77], v[160:163], v[136:139], v[74:77]
	ds_read_b128 v[176:179], v229 offset:4096
	v_mul_f32_e32 v54, s12, v54
	v_mul_f32_e32 v55, s12, v55
	v_mfma_f32_16x16x32_bf16 v[78:81], v[164:167], v[136:139], v[78:81]
	ds_read_b128 v[180:183], v229 offset:6144
	v_mul_f32_e32 v56, s12, v56
	v_mul_f32_e32 v57, s12, v57
	v_exp_f32_e32 v50, v50
	v_mfma_f32_16x16x32_bf16 v[82:85], v[152:155], v[140:143], v[82:85]
	ds_read_b128 v[184:187], v235 offset:0
	v_exp_f32_e32 v51, v51
	v_exp_f32_e32 v52, v52
	v_mfma_f32_16x16x32_bf16 v[86:89], v[156:159], v[140:143], v[86:89]
	ds_read_b128 v[188:191], v235 offset:2048
	v_exp_f32_e32 v53, v53
	v_exp_f32_e32 v54, v54
	v_mfma_f32_16x16x32_bf16 v[90:93], v[160:163], v[140:143], v[90:93]
	ds_read_b128 v[192:195], v235 offset:4096
	v_exp_f32_e32 v55, v55
	v_exp_f32_e32 v56, v56
	v_exp_f32_e32 v57, v57
	v_mfma_f32_16x16x32_bf16 v[94:97], v[164:167], v[140:143], v[94:97]
	ds_read_b128 v[196:199], v235 offset:6144
	v_add_f32_e32 v50, 1.0, v50
	v_add_f32_e32 v51, 1.0, v51
	v_mfma_f32_16x16x32_bf16 v[98:101], v[152:155], v[144:147], v[98:101]
	v_add_f32_e32 v52, 1.0, v52
	v_add_f32_e32 v53, 1.0, v53
	v_mfma_f32_16x16x32_bf16 v[102:105], v[156:159], v[144:147], v[102:105]
	v_add_f32_e32 v54, 1.0, v54
	v_add_f32_e32 v55, 1.0, v55
	v_add_f32_e32 v56, 1.0, v56
	v_mfma_f32_16x16x32_bf16 v[106:109], v[160:163], v[144:147], v[106:109]
	v_add_f32_e32 v57, 1.0, v57
	v_rcp_f32_e32 v50, v50
	v_mfma_f32_16x16x32_bf16 v[110:113], v[164:167], v[144:147], v[110:113]
	v_rcp_f32_e32 v51, v51
	v_rcp_f32_e32 v52, v52
	v_mfma_f32_16x16x32_bf16 v[114:117], v[152:155], v[148:151], v[114:117]
	v_rcp_f32_e32 v53, v53
	v_rcp_f32_e32 v54, v54
	v_rcp_f32_e32 v55, v55
	v_mfma_f32_16x16x32_bf16 v[118:121], v[156:159], v[148:151], v[118:121]
	v_rcp_f32_e32 v56, v56
	v_rcp_f32_e32 v57, v57
	v_mfma_f32_16x16x32_bf16 v[122:125], v[160:163], v[148:151], v[122:125]
	v_cvt_pk_bf16_f32 v50, v50, v51
	v_cvt_pk_bf16_f32 v51, v52, v53
	v_mfma_f32_16x16x32_bf16 v[126:129], v[164:167], v[148:151], v[126:129]
	v_cvt_pk_bf16_f32 v52, v54, v55
	v_cvt_pk_bf16_f32 v53, v56, v57
	global_store_dwordx4 v241, v[50:53], s[10:11] offset:2048
	s_waitcnt lgkmcnt(0)
	s_barrier
	v_mfma_f32_16x16x32_bf16 v[66:69], v[184:187], v[168:171], v[66:69]
	ds_read_b128 v[136:139], v218 offset:0
	v_mul_f32_e32 v58, s12, v58
	v_mul_f32_e32 v59, s12, v59
	v_mfma_f32_16x16x32_bf16 v[70:73], v[188:191], v[168:171], v[70:73]
	ds_read_b128 v[140:143], v218 offset:2048
	v_mul_f32_e32 v60, s12, v60
	v_mul_f32_e32 v61, s12, v61
	v_mfma_f32_16x16x32_bf16 v[74:77], v[192:195], v[168:171], v[74:77]
	ds_read_b128 v[144:147], v218 offset:4096
	v_mul_f32_e32 v62, s12, v62
	v_mul_f32_e32 v63, s12, v63
	v_mfma_f32_16x16x32_bf16 v[78:81], v[196:199], v[168:171], v[78:81]
	ds_read_b128 v[148:151], v218 offset:6144
	v_mul_f32_e32 v64, s12, v64
	v_mul_f32_e32 v65, s12, v65
	v_exp_f32_e32 v58, v58
	v_mfma_f32_16x16x32_bf16 v[82:85], v[184:187], v[172:175], v[82:85]
	ds_read_b128 v[152:155], v230 offset:0
	v_exp_f32_e32 v59, v59
	v_exp_f32_e32 v60, v60
	v_mfma_f32_16x16x32_bf16 v[86:89], v[188:191], v[172:175], v[86:89]
	ds_read_b128 v[156:159], v230 offset:2048
	v_exp_f32_e32 v61, v61
	v_exp_f32_e32 v62, v62
	v_mfma_f32_16x16x32_bf16 v[90:93], v[192:195], v[172:175], v[90:93]
	ds_read_b128 v[160:163], v230 offset:4096
	v_exp_f32_e32 v63, v63
	v_exp_f32_e32 v64, v64
	v_exp_f32_e32 v65, v65
	v_mfma_f32_16x16x32_bf16 v[94:97], v[196:199], v[172:175], v[94:97]
	ds_read_b128 v[164:167], v230 offset:6144
	v_add_f32_e32 v58, 1.0, v58
	v_add_f32_e32 v59, 1.0, v59
	v_mfma_f32_16x16x32_bf16 v[98:101], v[184:187], v[176:179], v[98:101]
	v_add_f32_e32 v60, 1.0, v60
	v_add_f32_e32 v61, 1.0, v61
	v_mfma_f32_16x16x32_bf16 v[102:105], v[188:191], v[176:179], v[102:105]
	v_add_f32_e32 v62, 1.0, v62
	v_add_f32_e32 v63, 1.0, v63
	v_add_f32_e32 v64, 1.0, v64
	v_mfma_f32_16x16x32_bf16 v[106:109], v[192:195], v[176:179], v[106:109]
	v_add_f32_e32 v65, 1.0, v65
	v_rcp_f32_e32 v58, v58
	v_mfma_f32_16x16x32_bf16 v[110:113], v[196:199], v[176:179], v[110:113]
	v_rcp_f32_e32 v59, v59
	v_rcp_f32_e32 v60, v60
	v_mfma_f32_16x16x32_bf16 v[114:117], v[184:187], v[180:183], v[114:117]
	v_rcp_f32_e32 v61, v61
	v_rcp_f32_e32 v62, v62
	v_rcp_f32_e32 v63, v63
	v_mfma_f32_16x16x32_bf16 v[118:121], v[188:191], v[180:183], v[118:121]
	v_rcp_f32_e32 v64, v64
	v_rcp_f32_e32 v65, v65
	v_mfma_f32_16x16x32_bf16 v[122:125], v[192:195], v[180:183], v[122:125]
	v_cvt_pk_bf16_f32 v58, v58, v59
	v_cvt_pk_bf16_f32 v59, v60, v61
	v_mfma_f32_16x16x32_bf16 v[126:129], v[196:199], v[180:183], v[126:129]
	v_cvt_pk_bf16_f32 v60, v62, v63
	v_cvt_pk_bf16_f32 v61, v64, v65
	global_store_dwordx4 v241, v[58:61], s[10:11] offset:2064
	s_waitcnt lgkmcnt(0)
	v_mfma_f32_16x16x32_bf16 v[66:69], v[152:155], v[136:139], v[66:69]
	ds_read_b128 v[168:171], v225 offset:0
	v_mfma_f32_16x16x32_bf16 v[70:73], v[156:159], v[136:139], v[70:73]
	ds_read_b128 v[172:175], v225 offset:2048
	v_mfma_f32_16x16x32_bf16 v[74:77], v[160:163], v[136:139], v[74:77]
	ds_read_b128 v[176:179], v225 offset:4096
	v_mfma_f32_16x16x32_bf16 v[78:81], v[164:167], v[136:139], v[78:81]
	ds_read_b128 v[180:183], v225 offset:6144
	v_mfma_f32_16x16x32_bf16 v[82:85], v[152:155], v[140:143], v[82:85]
	ds_read_b128 v[184:187], v233 offset:0
	v_mfma_f32_16x16x32_bf16 v[86:89], v[156:159], v[140:143], v[86:89]
	ds_read_b128 v[188:191], v233 offset:2048
	v_mfma_f32_16x16x32_bf16 v[90:93], v[160:163], v[140:143], v[90:93]
	ds_read_b128 v[192:195], v233 offset:4096
	v_mfma_f32_16x16x32_bf16 v[94:97], v[164:167], v[140:143], v[94:97]
	ds_read_b128 v[196:199], v233 offset:6144
	v_mfma_f32_16x16x32_bf16 v[98:101], v[152:155], v[144:147], v[98:101]
	v_mfma_f32_16x16x32_bf16 v[102:105], v[156:159], v[144:147], v[102:105]
	v_mfma_f32_16x16x32_bf16 v[106:109], v[160:163], v[144:147], v[106:109]
	v_mfma_f32_16x16x32_bf16 v[110:113], v[164:167], v[144:147], v[110:113]
	v_mfma_f32_16x16x32_bf16 v[114:117], v[152:155], v[148:151], v[114:117]
	v_mfma_f32_16x16x32_bf16 v[118:121], v[156:159], v[148:151], v[118:121]
	v_mfma_f32_16x16x32_bf16 v[122:125], v[160:163], v[148:151], v[122:125]
	v_mfma_f32_16x16x32_bf16 v[126:129], v[164:167], v[148:151], v[126:129]
	s_waitcnt lgkmcnt(0)
	s_barrier
	v_mfma_f32_16x16x32_bf16 v[66:69], v[184:187], v[168:171], v[66:69]
	ds_read_b128 v[136:139], v219 offset:0
	v_mfma_f32_16x16x32_bf16 v[70:73], v[188:191], v[168:171], v[70:73]
	ds_read_b128 v[140:143], v219 offset:2048
	v_mfma_f32_16x16x32_bf16 v[74:77], v[192:195], v[168:171], v[74:77]
	ds_read_b128 v[144:147], v219 offset:4096
	v_mfma_f32_16x16x32_bf16 v[78:81], v[196:199], v[168:171], v[78:81]
	ds_read_b128 v[148:151], v219 offset:6144
	v_mfma_f32_16x16x32_bf16 v[82:85], v[184:187], v[172:175], v[82:85]
	ds_read_b128 v[152:155], v231 offset:0
	v_mfma_f32_16x16x32_bf16 v[86:89], v[188:191], v[172:175], v[86:89]
	ds_read_b128 v[156:159], v231 offset:2048
	v_mfma_f32_16x16x32_bf16 v[90:93], v[192:195], v[172:175], v[90:93]
	ds_read_b128 v[160:163], v231 offset:4096
	v_mfma_f32_16x16x32_bf16 v[94:97], v[196:199], v[172:175], v[94:97]
	ds_read_b128 v[164:167], v231 offset:6144
	v_mfma_f32_16x16x32_bf16 v[98:101], v[184:187], v[176:179], v[98:101]
	v_mfma_f32_16x16x32_bf16 v[102:105], v[188:191], v[176:179], v[102:105]
	v_mfma_f32_16x16x32_bf16 v[106:109], v[192:195], v[176:179], v[106:109]
	v_mfma_f32_16x16x32_bf16 v[110:113], v[196:199], v[176:179], v[110:113]
	v_mfma_f32_16x16x32_bf16 v[114:117], v[184:187], v[180:183], v[114:117]
	v_mfma_f32_16x16x32_bf16 v[118:121], v[188:191], v[180:183], v[118:121]
	v_mfma_f32_16x16x32_bf16 v[122:125], v[192:195], v[180:183], v[122:125]
	v_mfma_f32_16x16x32_bf16 v[126:129], v[196:199], v[180:183], v[126:129]
	s_waitcnt lgkmcnt(0)
	v_mfma_f32_16x16x32_bf16 v[66:69], v[152:155], v[136:139], v[66:69]
	ds_read_b128 v[168:171], v228 offset:0
	v_mfma_f32_16x16x32_bf16 v[70:73], v[156:159], v[136:139], v[70:73]
	ds_read_b128 v[172:175], v228 offset:2048
	v_mfma_f32_16x16x32_bf16 v[74:77], v[160:163], v[136:139], v[74:77]
	ds_read_b128 v[176:179], v228 offset:4096
	v_mfma_f32_16x16x32_bf16 v[78:81], v[164:167], v[136:139], v[78:81]
	ds_read_b128 v[180:183], v228 offset:6144
	v_mfma_f32_16x16x32_bf16 v[82:85], v[152:155], v[140:143], v[82:85]
	ds_read_b128 v[184:187], v234 offset:0
	v_mfma_f32_16x16x32_bf16 v[86:89], v[156:159], v[140:143], v[86:89]
	ds_read_b128 v[188:191], v234 offset:2048
	v_mfma_f32_16x16x32_bf16 v[90:93], v[160:163], v[140:143], v[90:93]
	ds_read_b128 v[192:195], v234 offset:4096
	v_mfma_f32_16x16x32_bf16 v[94:97], v[164:167], v[140:143], v[94:97]
	ds_read_b128 v[196:199], v234 offset:6144
	v_mfma_f32_16x16x32_bf16 v[98:101], v[152:155], v[144:147], v[98:101]
	v_mfma_f32_16x16x32_bf16 v[102:105], v[156:159], v[144:147], v[102:105]
	v_mfma_f32_16x16x32_bf16 v[106:109], v[160:163], v[144:147], v[106:109]
	v_mfma_f32_16x16x32_bf16 v[110:113], v[164:167], v[144:147], v[110:113]
	v_mfma_f32_16x16x32_bf16 v[114:117], v[152:155], v[148:151], v[114:117]
	v_mfma_f32_16x16x32_bf16 v[118:121], v[156:159], v[148:151], v[118:121]
	v_mfma_f32_16x16x32_bf16 v[122:125], v[160:163], v[148:151], v[122:125]
	v_mfma_f32_16x16x32_bf16 v[126:129], v[164:167], v[148:151], v[126:129]
	s_waitcnt lgkmcnt(0)
	s_barrier
	v_mfma_f32_16x16x32_bf16 v[66:69], v[184:187], v[168:171], v[66:69]
	ds_read_b128 v[136:139], v224 offset:0
	v_mfma_f32_16x16x32_bf16 v[70:73], v[188:191], v[168:171], v[70:73]
	ds_read_b128 v[140:143], v224 offset:2048
	v_mfma_f32_16x16x32_bf16 v[74:77], v[192:195], v[168:171], v[74:77]
	ds_read_b128 v[144:147], v224 offset:4096
	v_mfma_f32_16x16x32_bf16 v[78:81], v[196:199], v[168:171], v[78:81]
	ds_read_b128 v[148:151], v224 offset:6144
	v_mfma_f32_16x16x32_bf16 v[82:85], v[184:187], v[172:175], v[82:85]
	ds_read_b128 v[152:155], v232 offset:0
	v_mfma_f32_16x16x32_bf16 v[86:89], v[188:191], v[172:175], v[86:89]
	ds_read_b128 v[156:159], v232 offset:2048
	v_mfma_f32_16x16x32_bf16 v[90:93], v[192:195], v[172:175], v[90:93]
	ds_read_b128 v[160:163], v232 offset:4096
	v_mfma_f32_16x16x32_bf16 v[94:97], v[196:199], v[172:175], v[94:97]
	ds_read_b128 v[164:167], v232 offset:6144
	v_mfma_f32_16x16x32_bf16 v[98:101], v[184:187], v[176:179], v[98:101]
	v_mfma_f32_16x16x32_bf16 v[102:105], v[188:191], v[176:179], v[102:105]
	v_mfma_f32_16x16x32_bf16 v[106:109], v[192:195], v[176:179], v[106:109]
	v_mfma_f32_16x16x32_bf16 v[110:113], v[196:199], v[176:179], v[110:113]
	v_mfma_f32_16x16x32_bf16 v[114:117], v[184:187], v[180:183], v[114:117]
	v_mfma_f32_16x16x32_bf16 v[118:121], v[188:191], v[180:183], v[118:121]
	v_mfma_f32_16x16x32_bf16 v[122:125], v[192:195], v[180:183], v[122:125]
	v_mfma_f32_16x16x32_bf16 v[126:129], v[196:199], v[180:183], v[126:129]
	s_waitcnt lgkmcnt(0)
	v_mfma_f32_16x16x32_bf16 v[66:69], v[152:155], v[136:139], v[66:69]
	ds_read_b128 v[168:171], v229 offset:0
	v_mfma_f32_16x16x32_bf16 v[70:73], v[156:159], v[136:139], v[70:73]
	ds_read_b128 v[172:175], v229 offset:2048
	v_mfma_f32_16x16x32_bf16 v[74:77], v[160:163], v[136:139], v[74:77]
	ds_read_b128 v[176:179], v229 offset:4096
	v_mfma_f32_16x16x32_bf16 v[78:81], v[164:167], v[136:139], v[78:81]
	ds_read_b128 v[180:183], v229 offset:6144
	v_mfma_f32_16x16x32_bf16 v[82:85], v[152:155], v[140:143], v[82:85]
	ds_read_b128 v[184:187], v235 offset:0
	v_mfma_f32_16x16x32_bf16 v[86:89], v[156:159], v[140:143], v[86:89]
	ds_read_b128 v[188:191], v235 offset:2048
	v_mfma_f32_16x16x32_bf16 v[90:93], v[160:163], v[140:143], v[90:93]
	ds_read_b128 v[192:195], v235 offset:4096
	v_mfma_f32_16x16x32_bf16 v[94:97], v[164:167], v[140:143], v[94:97]
	ds_read_b128 v[196:199], v235 offset:6144
	v_mfma_f32_16x16x32_bf16 v[98:101], v[152:155], v[144:147], v[98:101]
	v_mfma_f32_16x16x32_bf16 v[102:105], v[156:159], v[144:147], v[102:105]
	v_mfma_f32_16x16x32_bf16 v[106:109], v[160:163], v[144:147], v[106:109]
	v_mfma_f32_16x16x32_bf16 v[110:113], v[164:167], v[144:147], v[110:113]
	v_mfma_f32_16x16x32_bf16 v[114:117], v[152:155], v[148:151], v[114:117]
	v_mfma_f32_16x16x32_bf16 v[118:121], v[156:159], v[148:151], v[118:121]
	v_mfma_f32_16x16x32_bf16 v[122:125], v[160:163], v[148:151], v[122:125]
	v_mfma_f32_16x16x32_bf16 v[126:129], v[164:167], v[148:151], v[126:129]
	s_waitcnt lgkmcnt(0)
	s_barrier
	v_mfma_f32_16x16x32_bf16 v[66:69], v[184:187], v[168:171], v[66:69]
	ds_read_b128 v[136:139], v218 offset:0
	v_mfma_f32_16x16x32_bf16 v[70:73], v[188:191], v[168:171], v[70:73]
	ds_read_b128 v[140:143], v218 offset:2048
	v_mfma_f32_16x16x32_bf16 v[74:77], v[192:195], v[168:171], v[74:77]
	ds_read_b128 v[144:147], v218 offset:4096
	v_mfma_f32_16x16x32_bf16 v[78:81], v[196:199], v[168:171], v[78:81]
	ds_read_b128 v[148:151], v218 offset:6144
	v_mfma_f32_16x16x32_bf16 v[82:85], v[184:187], v[172:175], v[82:85]
	ds_read_b128 v[152:155], v230 offset:0
	v_mfma_f32_16x16x32_bf16 v[86:89], v[188:191], v[172:175], v[86:89]
	ds_read_b128 v[156:159], v230 offset:2048
	v_mfma_f32_16x16x32_bf16 v[90:93], v[192:195], v[172:175], v[90:93]
	ds_read_b128 v[160:163], v230 offset:4096
	v_mfma_f32_16x16x32_bf16 v[94:97], v[196:199], v[172:175], v[94:97]
	ds_read_b128 v[164:167], v230 offset:6144
	v_mfma_f32_16x16x32_bf16 v[98:101], v[184:187], v[176:179], v[98:101]
	v_mfma_f32_16x16x32_bf16 v[102:105], v[188:191], v[176:179], v[102:105]
	v_mfma_f32_16x16x32_bf16 v[106:109], v[192:195], v[176:179], v[106:109]
	v_mfma_f32_16x16x32_bf16 v[110:113], v[196:199], v[176:179], v[110:113]
	v_mfma_f32_16x16x32_bf16 v[114:117], v[184:187], v[180:183], v[114:117]
	v_mfma_f32_16x16x32_bf16 v[118:121], v[188:191], v[180:183], v[118:121]
	v_mfma_f32_16x16x32_bf16 v[122:125], v[192:195], v[180:183], v[122:125]
	v_mfma_f32_16x16x32_bf16 v[126:129], v[196:199], v[180:183], v[126:129]
	s_waitcnt lgkmcnt(0)
	v_mfma_f32_16x16x32_bf16 v[66:69], v[152:155], v[136:139], v[66:69]
	ds_read_b128 v[168:171], v225 offset:0
	v_mfma_f32_16x16x32_bf16 v[70:73], v[156:159], v[136:139], v[70:73]
	ds_read_b128 v[172:175], v225 offset:2048
	v_mfma_f32_16x16x32_bf16 v[74:77], v[160:163], v[136:139], v[74:77]
	ds_read_b128 v[176:179], v225 offset:4096
	v_mfma_f32_16x16x32_bf16 v[78:81], v[164:167], v[136:139], v[78:81]
	ds_read_b128 v[180:183], v225 offset:6144
	v_mfma_f32_16x16x32_bf16 v[82:85], v[152:155], v[140:143], v[82:85]
	ds_read_b128 v[184:187], v233 offset:0
	v_mfma_f32_16x16x32_bf16 v[86:89], v[156:159], v[140:143], v[86:89]
	ds_read_b128 v[188:191], v233 offset:2048
	v_mfma_f32_16x16x32_bf16 v[90:93], v[160:163], v[140:143], v[90:93]
	ds_read_b128 v[192:195], v233 offset:4096
	v_mfma_f32_16x16x32_bf16 v[94:97], v[164:167], v[140:143], v[94:97]
	ds_read_b128 v[196:199], v233 offset:6144
	v_mfma_f32_16x16x32_bf16 v[98:101], v[152:155], v[144:147], v[98:101]
	v_mfma_f32_16x16x32_bf16 v[102:105], v[156:159], v[144:147], v[102:105]
	v_mfma_f32_16x16x32_bf16 v[106:109], v[160:163], v[144:147], v[106:109]
	v_mfma_f32_16x16x32_bf16 v[110:113], v[164:167], v[144:147], v[110:113]
	v_mfma_f32_16x16x32_bf16 v[114:117], v[152:155], v[148:151], v[114:117]
	v_mfma_f32_16x16x32_bf16 v[118:121], v[156:159], v[148:151], v[118:121]
	v_mfma_f32_16x16x32_bf16 v[122:125], v[160:163], v[148:151], v[122:125]
	v_mfma_f32_16x16x32_bf16 v[126:129], v[164:167], v[148:151], v[126:129]
	s_waitcnt lgkmcnt(0)
	v_mfma_f32_16x16x32_bf16 v[66:69], v[184:187], v[168:171], v[66:69]
	v_mfma_f32_16x16x32_bf16 v[70:73], v[188:191], v[168:171], v[70:73]
	v_mfma_f32_16x16x32_bf16 v[74:77], v[192:195], v[168:171], v[74:77]
	v_mfma_f32_16x16x32_bf16 v[78:81], v[196:199], v[168:171], v[78:81]
	v_mfma_f32_16x16x32_bf16 v[82:85], v[184:187], v[172:175], v[82:85]
	v_mfma_f32_16x16x32_bf16 v[86:89], v[188:191], v[172:175], v[86:89]
	v_mfma_f32_16x16x32_bf16 v[90:93], v[192:195], v[172:175], v[90:93]
	v_mfma_f32_16x16x32_bf16 v[94:97], v[196:199], v[172:175], v[94:97]
	v_mfma_f32_16x16x32_bf16 v[98:101], v[184:187], v[176:179], v[98:101]
	v_mfma_f32_16x16x32_bf16 v[102:105], v[188:191], v[176:179], v[102:105]
	v_mfma_f32_16x16x32_bf16 v[106:109], v[192:195], v[176:179], v[106:109]
	v_mfma_f32_16x16x32_bf16 v[110:113], v[196:199], v[176:179], v[110:113]
	v_mfma_f32_16x16x32_bf16 v[114:117], v[184:187], v[180:183], v[114:117]
	v_mfma_f32_16x16x32_bf16 v[118:121], v[188:191], v[180:183], v[118:121]
	v_mfma_f32_16x16x32_bf16 v[122:125], v[192:195], v[180:183], v[122:125]
	v_mfma_f32_16x16x32_bf16 v[126:129], v[196:199], v[180:183], v[126:129]
	s_add_u32 s10, s28, s13
	s_addc_u32 s11, s29, 0
	s_add_u32 s13, s13, 0x10000
	v_mul_f32_e32 v66, s12, v66
	v_mul_f32_e32 v67, s12, v67
	v_mul_f32_e32 v68, s12, v68
	v_mul_f32_e32 v69, s12, v69
	v_mul_f32_e32 v70, s12, v70
	v_mul_f32_e32 v71, s12, v71
	v_mul_f32_e32 v72, s12, v72
	v_mul_f32_e32 v73, s12, v73
	v_exp_f32_e32 v66, v66
	v_exp_f32_e32 v67, v67
	v_exp_f32_e32 v68, v68
	v_exp_f32_e32 v69, v69
	v_exp_f32_e32 v70, v70
	v_exp_f32_e32 v71, v71
	v_exp_f32_e32 v72, v72
	v_exp_f32_e32 v73, v73
	v_add_f32_e32 v66, 1.0, v66
	v_add_f32_e32 v67, 1.0, v67
	v_add_f32_e32 v68, 1.0, v68
	v_add_f32_e32 v69, 1.0, v69
	v_add_f32_e32 v70, 1.0, v70
	v_add_f32_e32 v71, 1.0, v71
	v_add_f32_e32 v72, 1.0, v72
	v_add_f32_e32 v73, 1.0, v73
	v_rcp_f32_e32 v66, v66
	v_rcp_f32_e32 v67, v67
	v_rcp_f32_e32 v68, v68
	v_rcp_f32_e32 v69, v69
	v_rcp_f32_e32 v70, v70
	v_rcp_f32_e32 v71, v71
	v_rcp_f32_e32 v72, v72
	v_rcp_f32_e32 v73, v73
	v_cvt_pk_bf16_f32 v66, v66, v67
	v_cvt_pk_bf16_f32 v67, v68, v69
	v_cvt_pk_bf16_f32 v68, v70, v71
	v_cvt_pk_bf16_f32 v69, v72, v73
	global_store_dwordx4 v240, v[66:69], s[10:11] offset:0
	v_mul_f32_e32 v74, s12, v74
	v_mul_f32_e32 v75, s12, v75
	v_mul_f32_e32 v76, s12, v76
	v_mul_f32_e32 v77, s12, v77
	v_mul_f32_e32 v78, s12, v78
	v_mul_f32_e32 v79, s12, v79
	v_mul_f32_e32 v80, s12, v80
	v_mul_f32_e32 v81, s12, v81
	v_exp_f32_e32 v74, v74
	v_exp_f32_e32 v75, v75
	v_exp_f32_e32 v76, v76
	v_exp_f32_e32 v77, v77
	v_exp_f32_e32 v78, v78
	v_exp_f32_e32 v79, v79
	v_exp_f32_e32 v80, v80
	v_exp_f32_e32 v81, v81
	v_add_f32_e32 v74, 1.0, v74
	v_add_f32_e32 v75, 1.0, v75
	v_add_f32_e32 v76, 1.0, v76
	v_add_f32_e32 v77, 1.0, v77
	v_add_f32_e32 v78, 1.0, v78
	v_add_f32_e32 v79, 1.0, v79
	v_add_f32_e32 v80, 1.0, v80
	v_add_f32_e32 v81, 1.0, v81
	v_rcp_f32_e32 v74, v74
	v_rcp_f32_e32 v75, v75
	v_rcp_f32_e32 v76, v76
	v_rcp_f32_e32 v77, v77
	v_rcp_f32_e32 v78, v78
	v_rcp_f32_e32 v79, v79
	v_rcp_f32_e32 v80, v80
	v_rcp_f32_e32 v81, v81
	v_cvt_pk_bf16_f32 v74, v74, v75
	v_cvt_pk_bf16_f32 v75, v76, v77
	v_cvt_pk_bf16_f32 v76, v78, v79
	v_cvt_pk_bf16_f32 v77, v80, v81
	global_store_dwordx4 v240, v[74:77], s[10:11] offset:16
	v_mul_f32_e32 v82, s12, v82
	v_mul_f32_e32 v83, s12, v83
	v_mul_f32_e32 v84, s12, v84
	v_mul_f32_e32 v85, s12, v85
	v_mul_f32_e32 v86, s12, v86
	v_mul_f32_e32 v87, s12, v87
	v_mul_f32_e32 v88, s12, v88
	v_mul_f32_e32 v89, s12, v89
	v_exp_f32_e32 v82, v82
	v_exp_f32_e32 v83, v83
	v_exp_f32_e32 v84, v84
	v_exp_f32_e32 v85, v85
	v_exp_f32_e32 v86, v86
	v_exp_f32_e32 v87, v87
	v_exp_f32_e32 v88, v88
	v_exp_f32_e32 v89, v89
	v_add_f32_e32 v82, 1.0, v82
	v_add_f32_e32 v83, 1.0, v83
	v_add_f32_e32 v84, 1.0, v84
	v_add_f32_e32 v85, 1.0, v85
	v_add_f32_e32 v86, 1.0, v86
	v_add_f32_e32 v87, 1.0, v87
	v_add_f32_e32 v88, 1.0, v88
	v_add_f32_e32 v89, 1.0, v89
	v_rcp_f32_e32 v82, v82
	v_rcp_f32_e32 v83, v83
	v_rcp_f32_e32 v84, v84
	v_rcp_f32_e32 v85, v85
	v_rcp_f32_e32 v86, v86
	v_rcp_f32_e32 v87, v87
	v_rcp_f32_e32 v88, v88
	v_rcp_f32_e32 v89, v89
	v_cvt_pk_bf16_f32 v82, v82, v83
	v_cvt_pk_bf16_f32 v83, v84, v85
	v_cvt_pk_bf16_f32 v84, v86, v87
	v_cvt_pk_bf16_f32 v85, v88, v89
	global_store_dwordx4 v240, v[82:85], s[10:11] offset:2048
	v_mul_f32_e32 v90, s12, v90
	v_mul_f32_e32 v91, s12, v91
	v_mul_f32_e32 v92, s12, v92
	v_mul_f32_e32 v93, s12, v93
	v_mul_f32_e32 v94, s12, v94
	v_mul_f32_e32 v95, s12, v95
	v_mul_f32_e32 v96, s12, v96
	v_mul_f32_e32 v97, s12, v97
	v_exp_f32_e32 v90, v90
	v_exp_f32_e32 v91, v91
	v_exp_f32_e32 v92, v92
	v_exp_f32_e32 v93, v93
	v_exp_f32_e32 v94, v94
	v_exp_f32_e32 v95, v95
	v_exp_f32_e32 v96, v96
	v_exp_f32_e32 v97, v97
	v_add_f32_e32 v90, 1.0, v90
	v_add_f32_e32 v91, 1.0, v91
	v_add_f32_e32 v92, 1.0, v92
	v_add_f32_e32 v93, 1.0, v93
	v_add_f32_e32 v94, 1.0, v94
	v_add_f32_e32 v95, 1.0, v95
	v_add_f32_e32 v96, 1.0, v96
	v_add_f32_e32 v97, 1.0, v97
	v_rcp_f32_e32 v90, v90
	v_rcp_f32_e32 v91, v91
	v_rcp_f32_e32 v92, v92
	v_rcp_f32_e32 v93, v93
	v_rcp_f32_e32 v94, v94
	v_rcp_f32_e32 v95, v95
	v_rcp_f32_e32 v96, v96
	v_rcp_f32_e32 v97, v97
	v_cvt_pk_bf16_f32 v90, v90, v91
	v_cvt_pk_bf16_f32 v91, v92, v93
	v_cvt_pk_bf16_f32 v92, v94, v95
	v_cvt_pk_bf16_f32 v93, v96, v97
	global_store_dwordx4 v240, v[90:93], s[10:11] offset:2064
	v_mul_f32_e32 v98, s12, v98
	v_mul_f32_e32 v99, s12, v99
	v_mul_f32_e32 v100, s12, v100
	v_mul_f32_e32 v101, s12, v101
	v_mul_f32_e32 v102, s12, v102
	v_mul_f32_e32 v103, s12, v103
	v_mul_f32_e32 v104, s12, v104
	v_mul_f32_e32 v105, s12, v105
	v_exp_f32_e32 v98, v98
	v_exp_f32_e32 v99, v99
	v_exp_f32_e32 v100, v100
	v_exp_f32_e32 v101, v101
	v_exp_f32_e32 v102, v102
	v_exp_f32_e32 v103, v103
	v_exp_f32_e32 v104, v104
	v_exp_f32_e32 v105, v105
	v_add_f32_e32 v98, 1.0, v98
	v_add_f32_e32 v99, 1.0, v99
	v_add_f32_e32 v100, 1.0, v100
	v_add_f32_e32 v101, 1.0, v101
	v_add_f32_e32 v102, 1.0, v102
	v_add_f32_e32 v103, 1.0, v103
	v_add_f32_e32 v104, 1.0, v104
	v_add_f32_e32 v105, 1.0, v105
	v_rcp_f32_e32 v98, v98
	v_rcp_f32_e32 v99, v99
	v_rcp_f32_e32 v100, v100
	v_rcp_f32_e32 v101, v101
	v_rcp_f32_e32 v102, v102
	v_rcp_f32_e32 v103, v103
	v_rcp_f32_e32 v104, v104
	v_rcp_f32_e32 v105, v105
	v_cvt_pk_bf16_f32 v98, v98, v99
	v_cvt_pk_bf16_f32 v99, v100, v101
	v_cvt_pk_bf16_f32 v100, v102, v103
	v_cvt_pk_bf16_f32 v101, v104, v105
	global_store_dwordx4 v241, v[98:101], s[10:11] offset:0
	v_mul_f32_e32 v106, s12, v106
	v_mul_f32_e32 v107, s12, v107
	v_mul_f32_e32 v108, s12, v108
	v_mul_f32_e32 v109, s12, v109
	v_mul_f32_e32 v110, s12, v110
	v_mul_f32_e32 v111, s12, v111
	v_mul_f32_e32 v112, s12, v112
	v_mul_f32_e32 v113, s12, v113
	v_exp_f32_e32 v106, v106
	v_exp_f32_e32 v107, v107
	v_exp_f32_e32 v108, v108
	v_exp_f32_e32 v109, v109
	v_exp_f32_e32 v110, v110
	v_exp_f32_e32 v111, v111
	v_exp_f32_e32 v112, v112
	v_exp_f32_e32 v113, v113
	v_add_f32_e32 v106, 1.0, v106
	v_add_f32_e32 v107, 1.0, v107
	v_add_f32_e32 v108, 1.0, v108
	v_add_f32_e32 v109, 1.0, v109
	v_add_f32_e32 v110, 1.0, v110
	v_add_f32_e32 v111, 1.0, v111
	v_add_f32_e32 v112, 1.0, v112
	v_add_f32_e32 v113, 1.0, v113
	v_rcp_f32_e32 v106, v106
	v_rcp_f32_e32 v107, v107
	v_rcp_f32_e32 v108, v108
	v_rcp_f32_e32 v109, v109
	v_rcp_f32_e32 v110, v110
	v_rcp_f32_e32 v111, v111
	v_rcp_f32_e32 v112, v112
	v_rcp_f32_e32 v113, v113
	v_cvt_pk_bf16_f32 v106, v106, v107
	v_cvt_pk_bf16_f32 v107, v108, v109
	v_cvt_pk_bf16_f32 v108, v110, v111
	v_cvt_pk_bf16_f32 v109, v112, v113
	global_store_dwordx4 v241, v[106:109], s[10:11] offset:16
	v_mul_f32_e32 v114, s12, v114
	v_mul_f32_e32 v115, s12, v115
	v_mul_f32_e32 v116, s12, v116
	v_mul_f32_e32 v117, s12, v117
	v_mul_f32_e32 v118, s12, v118
	v_mul_f32_e32 v119, s12, v119
	v_mul_f32_e32 v120, s12, v120
	v_mul_f32_e32 v121, s12, v121
	v_exp_f32_e32 v114, v114
	v_exp_f32_e32 v115, v115
	v_exp_f32_e32 v116, v116
	v_exp_f32_e32 v117, v117
	v_exp_f32_e32 v118, v118
	v_exp_f32_e32 v119, v119
	v_exp_f32_e32 v120, v120
	v_exp_f32_e32 v121, v121
	v_add_f32_e32 v114, 1.0, v114
	v_add_f32_e32 v115, 1.0, v115
	v_add_f32_e32 v116, 1.0, v116
	v_add_f32_e32 v117, 1.0, v117
	v_add_f32_e32 v118, 1.0, v118
	v_add_f32_e32 v119, 1.0, v119
	v_add_f32_e32 v120, 1.0, v120
	v_add_f32_e32 v121, 1.0, v121
	v_rcp_f32_e32 v114, v114
	v_rcp_f32_e32 v115, v115
	v_rcp_f32_e32 v116, v116
	v_rcp_f32_e32 v117, v117
	v_rcp_f32_e32 v118, v118
	v_rcp_f32_e32 v119, v119
	v_rcp_f32_e32 v120, v120
	v_rcp_f32_e32 v121, v121
	v_cvt_pk_bf16_f32 v114, v114, v115
	v_cvt_pk_bf16_f32 v115, v116, v117
	v_cvt_pk_bf16_f32 v116, v118, v119
	v_cvt_pk_bf16_f32 v117, v120, v121
	global_store_dwordx4 v241, v[114:117], s[10:11] offset:2048
	v_mul_f32_e32 v122, s12, v122
	v_mul_f32_e32 v123, s12, v123
	v_mul_f32_e32 v124, s12, v124
	v_mul_f32_e32 v125, s12, v125
	v_mul_f32_e32 v126, s12, v126
	v_mul_f32_e32 v127, s12, v127
	v_mul_f32_e32 v128, s12, v128
	v_mul_f32_e32 v129, s12, v129
	v_exp_f32_e32 v122, v122
	v_exp_f32_e32 v123, v123
	v_exp_f32_e32 v124, v124
	v_exp_f32_e32 v125, v125
	v_exp_f32_e32 v126, v126
	v_exp_f32_e32 v127, v127
	v_exp_f32_e32 v128, v128
	v_exp_f32_e32 v129, v129
	v_add_f32_e32 v122, 1.0, v122
	v_add_f32_e32 v123, 1.0, v123
	v_add_f32_e32 v124, 1.0, v124
	v_add_f32_e32 v125, 1.0, v125
	v_add_f32_e32 v126, 1.0, v126
	v_add_f32_e32 v127, 1.0, v127
	v_add_f32_e32 v128, 1.0, v128
	v_add_f32_e32 v129, 1.0, v129
	v_rcp_f32_e32 v122, v122
	v_rcp_f32_e32 v123, v123
	v_rcp_f32_e32 v124, v124
	v_rcp_f32_e32 v125, v125
	v_rcp_f32_e32 v126, v126
	v_rcp_f32_e32 v127, v127
	v_rcp_f32_e32 v128, v128
	v_rcp_f32_e32 v129, v129
	v_cvt_pk_bf16_f32 v122, v122, v123
	v_cvt_pk_bf16_f32 v123, v124, v125
	v_cvt_pk_bf16_f32 v124, v126, v127
	v_cvt_pk_bf16_f32 v125, v128, v129
	global_store_dwordx4 v241, v[122:125], s[10:11] offset:2064
.Lc1_join0:
	s_waitcnt vmcnt(0)
	s_barrier
	v_mov_b32_e32 v236, s20
	v_mov_b32_e32 v237, s21
	v_mov_b32_e32 v238, 0x200f0
	ds_write_b64 v238, v[236:237]
	s_waitcnt vmcnt(0)
	v_readlane_b32 s60, v254, 32
	v_readlane_b32 s58, v254, 46
	s_mov_b32 s64, s44
	s_mov_b32 s72, s67
	s_cmpk_gt_u32 s50, 0xff
	v_readlane_b32 s61, v254, 33
	v_readlane_b32 s59, v254, 47
	s_movk_i32 s73, 0xf0
	v_readlane_b32 s79, v254, 50
